# rotate fold via a spare VGPR pair (v246:247) where the consumer pair is still read by older instructions: 19 more sites
# baseline (speedup 1.0000x reference)
.LBB0_499:
	v_mov_b32_e32 v2, v210
	s_mov_b32 s43, s8
	v_and_b32_e32 v3, 0x1ff, v2
	v_lshlrev_b32_e32 v2, 5, v2
	v_and_or_b32 v2, v2, s94, v3
	v_ashrrev_i32_e32 v4, 5, v2
	v_lshlrev_b32_e32 v2, 3, v2
	v_lshlrev_b32_e32 v4, 3, v4
	v_add3_u32 v18, 0, v2, v4
	ds_read_b64 v[128:129], v18
	ds_read_b64 v[134:135], v18 offset:4224
	ds_read_b64 v[136:137], v18 offset:8448
	ds_read_b64 v[138:139], v18 offset:12672
	ds_read_b64 v[140:141], v18 offset:16896
	ds_read_b64 v[142:143], v18 offset:21120
	ds_read_b64 v[132:133], v18 offset:25344
	ds_read_b64 v[130:131], v18 offset:29568
	ds_read_b64 v[144:145], v18 offset:33792
	ds_read_b64 v[148:149], v18 offset:38016
	ds_read_b64 v[150:151], v18 offset:42240
	ds_read_b64 v[152:153], v18 offset:46464
	s_waitcnt lgkmcnt(10)
	v_pk_mul_f32 v[162:163], v[134:135], s[10:11]
	s_mov_b32 s74, s11
	v_pk_fma_f32 v[162:163], v[134:135], s[8:9], v[162:163] op_sel:[0,0,1] op_sel_hi:[1,0,0]
	s_waitcnt lgkmcnt(2)
	v_pk_mul_f32 v[178:179], v[148:149], s[42:43]
	v_pk_add_f32 v[194:195], v[134:135], v[148:149]
	v_pk_add_f32 v[134:135], v[134:135], v[148:149] neg_lo:[0,1] neg_hi:[0,1]
	v_pk_mul_f32 v[164:165], v[136:137], s[18:19]
	s_mov_b32 s41, s16
	v_pk_fma_f32 v[178:179], v[148:149], s[74:75], v[178:179] op_sel:[0,0,1] op_sel_hi:[1,0,0] neg_lo:[1,0,0] neg_hi:[1,0,0]
	v_pk_mul_f32 v[148:149], v[134:135], s[18:19]
	v_pk_fma_f32 v[164:165], v[136:137], s[16:17], v[164:165] op_sel:[0,0,1] op_sel_hi:[1,0,0]
	s_mov_b32 s80, s19
	s_waitcnt lgkmcnt(1)
	v_pk_mul_f32 v[180:181], v[150:151], s[40:41]
	v_pk_fma_f32 v[134:135], v[134:135], s[16:17], v[148:149] op_sel:[0,0,1] op_sel_hi:[1,0,0]
	v_pk_add_f32 v[148:149], v[136:137], v[150:151]
	v_pk_add_f32 v[136:137], v[136:137], v[150:151] neg_lo:[0,1] neg_hi:[0,1]
	v_pk_mul_f32 v[166:167], v[138:139], s[26:27]
	s_mov_b32 s78, s37
	s_mov_b32 s39, s24
	v_pk_fma_f32 v[180:181], v[150:151], s[80:81], v[180:181] op_sel:[0,0,1] op_sel_hi:[1,0,0] neg_lo:[1,0,0] neg_hi:[1,0,0]
	v_pk_mul_f32 v[150:151], v[136:137], s[36:37]
	ds_read_b64 v[154:155], v18 offset:50688
	ds_read_b64 v[156:157], v18 offset:54912
	ds_read_b64 v[158:159], v18 offset:59136
	ds_read_b64 v[160:161], v18 offset:63360
	v_pk_fma_f32 v[166:167], v[138:139], s[24:25], v[166:167] op_sel:[0,0,1] op_sel_hi:[1,0,0]
	s_mov_b32 s0, s27
	s_waitcnt lgkmcnt(4)
	v_pk_mul_f32 v[182:183], v[152:153], s[38:39]
	v_pk_fma_f32 v[136:137], v[136:137], s[78:79], v[150:151] op_sel:[0,0,1] op_sel_hi:[1,0,0]
	v_pk_add_f32 v[150:151], v[138:139], v[152:153]
	v_pk_add_f32 v[138:139], v[138:139], v[152:153] neg_lo:[0,1] neg_hi:[0,1]
	v_pk_mul_f32 v[168:169], v[140:141], s[36:37]
	v_pk_fma_f32 v[182:183], v[152:153], s[0:1], v[182:183] op_sel:[0,0,1] op_sel_hi:[1,0,0] neg_lo:[1,0,0] neg_hi:[1,0,0]
	v_pk_mul_f32 v[152:153], v[138:139], s[40:41]
	v_pk_fma_f32 v[168:169], v[140:141], s[78:79], v[168:169] op_sel:[0,0,1] op_sel_hi:[1,0,0]
	v_pk_mul_f32 v[170:171], v[142:143], s[38:39]
	s_waitcnt lgkmcnt(3)
	v_pk_mul_f32 v[184:185], v[154:155], s[36:37]
	v_pk_fma_f32 v[138:139], v[138:139], s[80:81], v[152:153] op_sel:[0,0,1] op_sel_hi:[1,0,0]
	v_pk_add_f32 v[152:153], v[140:141], v[154:155]
	v_pk_add_f32 v[246:247], v[140:141], v[154:155] neg_lo:[0,1] neg_hi:[0,1]
	v_pk_fma_f32 v[170:171], v[142:143], s[0:1], v[170:171] op_sel:[0,0,1] op_sel_hi:[1,0,0]
	v_pk_fma_f32 v[184:185], v[154:155], s[78:79], v[184:185] op_sel:[0,0,1] op_sel_hi:[1,0,0] neg_lo:[1,0,0] neg_hi:[1,0,0]
	s_waitcnt lgkmcnt(2)
	v_pk_mul_f32 v[186:187], v[156:157], s[26:27]
	v_pk_add_f32 v[140:141], v[142:143], v[156:157]
	v_pk_add_f32 v[142:143], v[142:143], v[156:157] neg_lo:[0,1] neg_hi:[0,1]
	v_pk_mul_f32 v[172:173], v[132:133], s[40:41]
	v_pk_fma_f32 v[186:187], v[156:157], s[24:25], v[186:187] op_sel:[0,0,1] op_sel_hi:[1,0,0] neg_lo:[1,0,0] neg_hi:[1,0,0]
	v_pk_mul_f32 v[156:157], v[142:143], s[40:41]
	v_pk_fma_f32 v[172:173], v[132:133], s[80:81], v[172:173] op_sel:[0,0,1] op_sel_hi:[1,0,0]
	s_waitcnt lgkmcnt(1)
	v_pk_mul_f32 v[188:189], v[158:159], s[18:19]
	v_pk_fma_f32 v[142:143], v[142:143], s[80:81], v[156:157] op_sel:[0,0,1] op_sel_hi:[1,0,0] neg_lo:[1,0,0] neg_hi:[1,0,0]
	v_pk_add_f32 v[156:157], v[132:133], v[158:159]
	v_pk_add_f32 v[132:133], v[132:133], v[158:159] neg_lo:[0,1] neg_hi:[0,1]
	v_pk_mul_f32 v[174:175], v[130:131], s[42:43]
	v_pk_fma_f32 v[188:189], v[158:159], s[16:17], v[188:189] op_sel:[0,0,1] op_sel_hi:[1,0,0] neg_lo:[1,0,0] neg_hi:[1,0,0]
	v_pk_mul_f32 v[158:159], v[132:133], s[36:37]
	v_pk_fma_f32 v[174:175], v[130:131], s[74:75], v[174:175] op_sel:[0,0,1] op_sel_hi:[1,0,0]
	s_waitcnt lgkmcnt(0)
	v_pk_mul_f32 v[190:191], v[160:161], s[10:11]
	v_pk_fma_f32 v[132:133], v[132:133], s[78:79], v[158:159] op_sel:[0,0,1] op_sel_hi:[1,0,0] neg_lo:[1,0,0] neg_hi:[1,0,0]
	v_pk_add_f32 v[158:159], v[130:131], v[160:161]
	v_pk_add_f32 v[130:131], v[130:131], v[160:161] neg_lo:[0,1] neg_hi:[0,1]
	v_xor_b32_e32 v177, 0x80000000, v144
	v_mov_b32_e32 v176, v145
	v_pk_fma_f32 v[190:191], v[160:161], s[8:9], v[190:191] op_sel:[0,0,1] op_sel_hi:[1,0,0] neg_lo:[1,0,0] neg_hi:[1,0,0]
	v_pk_mul_f32 v[160:161], v[130:131], s[18:19]
	v_pk_add_f32 v[192:193], v[128:129], v[144:145]
	v_pk_add_f32 v[144:145], v[128:129], v[144:145] neg_lo:[0,1] neg_hi:[0,1]
	v_pk_fma_f32 v[130:131], v[130:131], s[16:17], v[160:161] op_sel:[0,0,1] op_sel_hi:[1,0,0] neg_lo:[1,0,0] neg_hi:[1,0,0]
	v_pk_add_f32 v[160:161], v[128:129], v[176:177]
	v_pk_add_f32 v[128:129], v[128:129], v[176:177] neg_lo:[0,1] neg_hi:[0,1]
	v_pk_add_f32 v[176:177], v[162:163], v[178:179]
	v_pk_add_f32 v[162:163], v[162:163], v[178:179] neg_lo:[0,1] neg_hi:[0,1]
	v_cvt_f32_u32_e32 v2, v3
	v_pk_mul_f32 v[178:179], v[162:163], s[18:19]
	s_add_i32 s76, s72, s48
	v_pk_fma_f32 v[162:163], v[162:163], s[16:17], v[178:179] op_sel:[0,0,1] op_sel_hi:[1,0,0]
	v_pk_add_f32 v[178:179], v[164:165], v[180:181]
	v_pk_add_f32 v[164:165], v[164:165], v[180:181] neg_lo:[0,1] neg_hi:[0,1]
	v_mul_f32_e32 v2, 0x38800000, v2
	v_pk_mul_f32 v[180:181], v[164:165], s[36:37]
	v_sin_f32_e32 v34, v2
	v_pk_fma_f32 v[164:165], v[164:165], s[78:79], v[180:181] op_sel:[0,0,1] op_sel_hi:[1,0,0]
	v_pk_add_f32 v[180:181], v[166:167], v[182:183]
	v_pk_add_f32 v[166:167], v[166:167], v[182:183] neg_lo:[0,1] neg_hi:[0,1]
	v_cos_f32_e32 v30, v2
	v_pk_mul_f32 v[182:183], v[166:167], s[40:41]
	v_xor_b32_e32 v31, 0x80000000, v34
	v_pk_fma_f32 v[166:167], v[166:167], s[80:81], v[182:183] op_sel:[0,0,1] op_sel_hi:[1,0,0]
	v_pk_add_f32 v[182:183], v[168:169], v[184:185]
	v_pk_add_f32 v[184:185], v[168:169], v[184:185] neg_lo:[0,1] neg_hi:[0,1]
	v_mov_b32_e32 v35, v31
	v_pk_add_f32 v[168:169], v[170:171], v[186:187]
	v_pk_add_f32 v[170:171], v[170:171], v[186:187] neg_lo:[0,1] neg_hi:[0,1]
	v_pk_mul_f32 v[2:3], v[30:31], v[34:35] op_sel:[1,0] op_sel_hi:[0,1]
	v_pk_mul_f32 v[186:187], v[170:171], s[40:41]
	v_pk_fma_f32 v[44:45], v[30:31], v[30:31], v[2:3] op_sel_hi:[1,0,1]
	v_pk_fma_f32 v[170:171], v[170:171], s[80:81], v[186:187] op_sel:[0,0,1] op_sel_hi:[1,0,0] neg_lo:[1,0,0] neg_hi:[1,0,0]
	v_pk_add_f32 v[186:187], v[172:173], v[188:189]
	v_pk_add_f32 v[172:173], v[172:173], v[188:189] neg_lo:[0,1] neg_hi:[0,1]
	v_pk_mul_f32 v[2:3], v[34:35], v[44:45] op_sel:[0,1] op_sel_hi:[1,0]
	v_pk_mul_f32 v[188:189], v[172:173], s[36:37]
	v_xor_b32_e32 v54, 0x80000000, v45
	v_pk_fma_f32 v[172:173], v[172:173], s[78:79], v[188:189] op_sel:[0,0,1] op_sel_hi:[1,0,0] neg_lo:[1,0,0] neg_hi:[1,0,0]
	v_pk_add_f32 v[188:189], v[174:175], v[190:191]
	v_pk_add_f32 v[174:175], v[174:175], v[190:191] neg_lo:[0,1] neg_hi:[0,1]
	v_mov_b32_e32 v55, v45
	v_pk_mul_f32 v[190:191], v[174:175], s[18:19]
	v_pk_fma_f32 v[46:47], v[30:31], v[44:45], v[2:3] op_sel_hi:[0,1,1]
	v_pk_fma_f32 v[174:175], v[174:175], s[16:17], v[190:191] op_sel:[0,0,1] op_sel_hi:[1,0,0] neg_lo:[1,0,0] neg_hi:[1,0,0]
	v_pk_add_f32 v[190:191], v[192:193], v[152:153]
	v_pk_add_f32 v[152:153], v[192:193], v[152:153] neg_lo:[0,1] neg_hi:[0,1]
	v_pk_add_f32 v[192:193], v[194:195], v[140:141]
	v_pk_add_f32 v[140:141], v[194:195], v[140:141] neg_lo:[0,1] neg_hi:[0,1]
	v_pk_mul_f32 v[2:3], v[44:45], v[54:55] op_sel:[1,0] op_sel_hi:[0,1]
	v_pk_mul_f32 v[194:195], v[140:141], s[36:37]
	v_pk_fma_f32 v[52:53], v[44:45], v[44:45], v[2:3] op_sel_hi:[1,0,1]
	v_pk_fma_f32 v[140:141], v[140:141], s[78:79], v[194:195] op_sel:[0,0,1] op_sel_hi:[1,0,0]
	v_pk_add_f32 v[194:195], v[148:149], v[156:157]
	v_pk_add_f32 v[156:157], v[148:149], v[156:157] neg_lo:[0,1] neg_hi:[0,1]
	v_xor_b32_e32 v58, 0x80000000, v53
	v_pk_add_f32 v[148:149], v[150:151], v[158:159]
	v_pk_add_f32 v[150:151], v[150:151], v[158:159] neg_lo:[0,1] neg_hi:[0,1]
	v_mov_b32_e32 v59, v53
	v_pk_mul_f32 v[158:159], v[150:151], s[36:37]
	v_pk_mul_f32 v[2:3], v[52:53], v[58:59] op_sel:[1,0] op_sel_hi:[0,1]
	v_pk_fma_f32 v[150:151], v[150:151], s[78:79], v[158:159] op_sel:[0,0,1] op_sel_hi:[1,0,0] neg_lo:[1,0,0] neg_hi:[1,0,0]
	v_pk_add_f32 v[158:159], v[144:145], v[246:247] op_sel:[0,1] op_sel_hi:[1,0] neg_hi:[0,1]
	v_pk_add_f32 v[144:145], v[144:145], v[246:247] op_sel:[0,1] op_sel_hi:[1,0] neg_lo:[0,1]
	v_pk_add_f32 v[154:155], v[134:135], v[142:143]
	v_pk_add_f32 v[134:135], v[134:135], v[142:143] neg_lo:[0,1] neg_hi:[0,1]
	v_pk_fma_f32 v[48:49], v[52:53], v[52:53], v[2:3] op_sel_hi:[1,0,1]
	v_pk_mul_f32 v[142:143], v[134:135], s[36:37]
	v_pk_mul_f32 v[2:3], v[58:59], v[48:49] op_sel:[0,1] op_sel_hi:[1,0]
	v_pk_fma_f32 v[134:135], v[134:135], s[78:79], v[142:143] op_sel:[0,0,1] op_sel_hi:[1,0,0]
	v_pk_add_f32 v[142:143], v[136:137], v[132:133]
	v_pk_add_f32 v[136:137], v[136:137], v[132:133] neg_lo:[0,1] neg_hi:[0,1]
	v_pk_fma_f32 v[36:37], v[52:53], v[48:49], v[2:3] op_sel_hi:[0,1,1]
	v_pk_add_f32 v[132:133], v[138:139], v[130:131]
	v_pk_add_f32 v[130:131], v[138:139], v[130:131] neg_lo:[0,1] neg_hi:[0,1]
	v_pk_mul_f32 v[2:3], v[58:59], v[36:37] op_sel:[0,1] op_sel_hi:[1,0]
	v_pk_mul_f32 v[138:139], v[130:131], s[36:37]
	v_pk_fma_f32 v[26:27], v[52:53], v[36:37], v[2:3] op_sel_hi:[0,1,1]
	v_pk_fma_f32 v[130:131], v[130:131], s[78:79], v[138:139] op_sel:[0,0,1] op_sel_hi:[1,0,0] neg_lo:[1,0,0] neg_hi:[1,0,0]
	v_pk_add_f32 v[138:139], v[160:161], v[182:183]
	v_pk_add_f32 v[160:161], v[160:161], v[182:183] neg_lo:[0,1] neg_hi:[0,1]
	v_pk_add_f32 v[182:183], v[176:177], v[168:169]
	v_pk_add_f32 v[168:169], v[176:177], v[168:169] neg_lo:[0,1] neg_hi:[0,1]
	v_pk_mul_f32 v[2:3], v[58:59], v[26:27] op_sel:[0,1] op_sel_hi:[1,0]
	v_pk_mul_f32 v[176:177], v[168:169], s[36:37]
	v_pk_fma_f32 v[20:21], v[52:53], v[26:27], v[2:3] op_sel_hi:[0,1,1]
	v_pk_fma_f32 v[168:169], v[168:169], s[78:79], v[176:177] op_sel:[0,0,1] op_sel_hi:[1,0,0]
	v_pk_add_f32 v[176:177], v[178:179], v[186:187]
	v_pk_add_f32 v[186:187], v[178:179], v[186:187] neg_lo:[0,1] neg_hi:[0,1]
	v_pk_mul_f32 v[2:3], v[58:59], v[20:21] op_sel:[0,1] op_sel_hi:[1,0]
	v_pk_add_f32 v[178:179], v[180:181], v[188:189]
	v_pk_add_f32 v[180:181], v[180:181], v[188:189] neg_lo:[0,1] neg_hi:[0,1]
	v_pk_fma_f32 v[10:11], v[52:53], v[20:21], v[2:3] op_sel_hi:[0,1,1]
	v_pk_mul_f32 v[188:189], v[180:181], s[36:37]
	v_pk_mul_f32 v[2:3], v[58:59], v[10:11] op_sel:[0,1] op_sel_hi:[1,0]
	v_pk_fma_f32 v[180:181], v[180:181], s[78:79], v[188:189] op_sel:[0,0,1] op_sel_hi:[1,0,0] neg_lo:[1,0,0] neg_hi:[1,0,0]
	v_pk_add_f32 v[188:189], v[128:129], v[184:185] op_sel:[0,1] op_sel_hi:[1,0] neg_hi:[0,1]
	v_pk_add_f32 v[128:129], v[128:129], v[184:185] op_sel:[0,1] op_sel_hi:[1,0] neg_lo:[0,1]
	v_pk_add_f32 v[184:185], v[162:163], v[170:171]
	v_pk_add_f32 v[162:163], v[162:163], v[170:171] neg_lo:[0,1] neg_hi:[0,1]
	v_pk_fma_f32 v[4:5], v[52:53], v[10:11], v[2:3] op_sel_hi:[0,1,1]
	v_pk_mul_f32 v[170:171], v[162:163], s[36:37]
	v_pk_mul_f32 v[8:9], v[54:55], v[4:5] op_sel:[0,1] op_sel_hi:[1,0]
	v_pk_fma_f32 v[162:163], v[162:163], s[78:79], v[170:171] op_sel:[0,0,1] op_sel_hi:[1,0,0]
	v_pk_add_f32 v[170:171], v[164:165], v[172:173]
	v_pk_add_f32 v[172:173], v[164:165], v[172:173] neg_lo:[0,1] neg_hi:[0,1]
	v_pk_mul_f32 v[14:15], v[34:35], v[4:5] op_sel:[0,1] op_sel_hi:[1,0]
	v_pk_add_f32 v[164:165], v[166:167], v[174:175]
	v_pk_add_f32 v[166:167], v[166:167], v[174:175] neg_lo:[0,1] neg_hi:[0,1]
	v_pk_mul_f32 v[32:33], v[54:55], v[10:11] op_sel:[0,1] op_sel_hi:[1,0]
	v_pk_mul_f32 v[174:175], v[166:167], s[36:37]
	v_pk_mul_f32 v[40:41], v[34:35], v[10:11] op_sel:[0,1] op_sel_hi:[1,0]
	v_pk_fma_f32 v[166:167], v[166:167], s[78:79], v[174:175] op_sel:[0,0,1] op_sel_hi:[1,0,0] neg_lo:[1,0,0] neg_hi:[1,0,0]
	v_pk_add_f32 v[174:175], v[190:191], v[194:195]
	v_pk_add_f32 v[190:191], v[190:191], v[194:195] neg_lo:[0,1] neg_hi:[0,1]
	v_pk_add_f32 v[194:195], v[192:193], v[148:149]
	v_pk_add_f32 v[192:193], v[192:193], v[148:149] neg_lo:[0,1] neg_hi:[0,1]
	v_pk_mul_f32 v[62:63], v[54:55], v[20:21] op_sel:[0,1] op_sel_hi:[1,0]
	v_pk_add_f32 v[148:149], v[152:153], v[156:157] op_sel:[0,1] op_sel_hi:[1,0] neg_hi:[0,1]
	v_pk_add_f32 v[152:153], v[152:153], v[156:157] op_sel:[0,1] op_sel_hi:[1,0] neg_lo:[0,1]
	v_pk_add_f32 v[156:157], v[140:141], v[150:151]
	v_pk_add_f32 v[150:151], v[140:141], v[150:151] neg_lo:[0,1] neg_hi:[0,1]
	v_pk_mul_f32 v[66:67], v[34:35], v[20:21] op_sel:[0,1] op_sel_hi:[1,0]
	v_pk_add_f32 v[140:141], v[158:159], v[142:143]
	v_pk_add_f32 v[142:143], v[158:159], v[142:143] neg_lo:[0,1] neg_hi:[0,1]
	v_pk_add_f32 v[158:159], v[154:155], v[132:133]
	v_pk_add_f32 v[154:155], v[154:155], v[132:133] neg_lo:[0,1] neg_hi:[0,1]
	v_pk_mul_f32 v[78:79], v[54:55], v[26:27] op_sel:[0,1] op_sel_hi:[1,0]
	v_pk_add_f32 v[132:133], v[144:145], v[136:137] op_sel:[0,1] op_sel_hi:[1,0] neg_hi:[0,1]
	v_pk_add_f32 v[136:137], v[144:145], v[136:137] op_sel:[0,1] op_sel_hi:[1,0] neg_lo:[0,1]
	v_pk_add_f32 v[144:145], v[134:135], v[130:131]
	v_pk_add_f32 v[134:135], v[134:135], v[130:131] neg_lo:[0,1] neg_hi:[0,1]
	v_pk_mul_f32 v[82:83], v[34:35], v[26:27] op_sel:[0,1] op_sel_hi:[1,0]
	v_pk_add_f32 v[130:131], v[138:139], v[176:177]
	v_pk_add_f32 v[138:139], v[138:139], v[176:177] neg_lo:[0,1] neg_hi:[0,1]
	v_pk_add_f32 v[176:177], v[182:183], v[178:179]
	v_pk_add_f32 v[182:183], v[182:183], v[178:179] neg_lo:[0,1] neg_hi:[0,1]
	v_pk_mul_f32 v[92:93], v[54:55], v[36:37] op_sel:[0,1] op_sel_hi:[1,0]
	v_pk_add_f32 v[178:179], v[160:161], v[186:187] op_sel:[0,1] op_sel_hi:[1,0] neg_hi:[0,1]
	v_pk_add_f32 v[160:161], v[160:161], v[186:187] op_sel:[0,1] op_sel_hi:[1,0] neg_lo:[0,1]
	v_pk_add_f32 v[186:187], v[168:169], v[180:181]
	v_pk_add_f32 v[180:181], v[168:169], v[180:181] neg_lo:[0,1] neg_hi:[0,1]
	v_pk_mul_f32 v[96:97], v[34:35], v[36:37] op_sel:[0,1] op_sel_hi:[1,0]
	v_pk_add_f32 v[168:169], v[188:189], v[170:171]
	v_pk_add_f32 v[170:171], v[188:189], v[170:171] neg_lo:[0,1] neg_hi:[0,1]
	v_pk_add_f32 v[188:189], v[184:185], v[164:165]
	v_pk_add_f32 v[184:185], v[184:185], v[164:165] neg_lo:[0,1] neg_hi:[0,1]
	v_pk_mul_f32 v[106:107], v[54:55], v[48:49] op_sel:[0,1] op_sel_hi:[1,0]
	v_pk_add_f32 v[164:165], v[128:129], v[172:173] op_sel:[0,1] op_sel_hi:[1,0] neg_hi:[0,1]
	v_pk_add_f32 v[128:129], v[128:129], v[172:173] op_sel:[0,1] op_sel_hi:[1,0] neg_lo:[0,1]
	v_pk_add_f32 v[172:173], v[162:163], v[166:167]
	v_pk_add_f32 v[166:167], v[162:163], v[166:167] neg_lo:[0,1] neg_hi:[0,1]
	v_pk_mul_f32 v[110:111], v[34:35], v[48:49] op_sel:[0,1] op_sel_hi:[1,0]
	v_pk_add_f32 v[162:163], v[174:175], v[194:195]
	v_pk_add_f32 v[174:175], v[174:175], v[194:195] neg_lo:[0,1] neg_hi:[0,1]
	v_pk_add_f32 v[194:195], v[190:191], v[192:193] op_sel:[0,1] op_sel_hi:[1,0] neg_hi:[0,1]
	v_pk_add_f32 v[190:191], v[190:191], v[192:193] op_sel:[0,1] op_sel_hi:[1,0] neg_lo:[0,1]
	v_pk_add_f32 v[192:193], v[148:149], v[156:157]
	v_pk_add_f32 v[148:149], v[148:149], v[156:157] neg_lo:[0,1] neg_hi:[0,1]
	v_pk_add_f32 v[156:157], v[152:153], v[150:151] op_sel:[0,1] op_sel_hi:[1,0] neg_hi:[0,1]
	v_pk_add_f32 v[150:151], v[152:153], v[150:151] op_sel:[0,1] op_sel_hi:[1,0] neg_lo:[0,1]
	v_pk_add_f32 v[152:153], v[140:141], v[158:159]
	v_pk_add_f32 v[140:141], v[140:141], v[158:159] neg_lo:[0,1] neg_hi:[0,1]
	v_pk_add_f32 v[158:159], v[142:143], v[154:155] op_sel:[0,1] op_sel_hi:[1,0] neg_hi:[0,1]
	v_pk_add_f32 v[142:143], v[142:143], v[154:155] op_sel:[0,1] op_sel_hi:[1,0] neg_lo:[0,1]
	v_pk_add_f32 v[154:155], v[132:133], v[144:145]
	v_pk_add_f32 v[132:133], v[132:133], v[144:145] neg_lo:[0,1] neg_hi:[0,1]
	v_pk_add_f32 v[144:145], v[136:137], v[134:135] op_sel:[0,1] op_sel_hi:[1,0] neg_hi:[0,1]
	v_pk_add_f32 v[134:135], v[136:137], v[134:135] op_sel:[0,1] op_sel_hi:[1,0] neg_lo:[0,1]
	v_pk_add_f32 v[136:137], v[130:131], v[176:177]
	v_pk_mul_f32 v[120:121], v[54:55], v[52:53] op_sel:[0,1] op_sel_hi:[1,0]
	v_pk_mul_f32 v[124:125], v[34:35], v[52:53] op_sel:[0,1] op_sel_hi:[1,0]
	v_pk_mul_f32 v[34:35], v[34:35], v[136:137] op_sel:[0,1] op_sel_hi:[1,0]
	v_xor_b32_e32 v72, 0x80000000, v47
	v_mov_b32_e32 v73, v47
	v_pk_fma_f32 v[8:9], v[44:45], v[4:5], v[8:9] op_sel_hi:[0,1,1]
	v_pk_fma_f32 v[14:15], v[30:31], v[4:5], v[14:15] op_sel_hi:[0,1,1]
	v_xor_b32_e32 v22, 0x80000000, v5
	v_pk_fma_f32 v[32:33], v[44:45], v[10:11], v[32:33] op_sel_hi:[0,1,1]
	v_pk_fma_f32 v[40:41], v[30:31], v[10:11], v[40:41] op_sel_hi:[0,1,1]
	v_pk_fma_f32 v[62:63], v[44:45], v[20:21], v[62:63] op_sel_hi:[0,1,1]
	v_pk_fma_f32 v[66:67], v[30:31], v[20:21], v[66:67] op_sel_hi:[0,1,1]
	v_pk_fma_f32 v[78:79], v[44:45], v[26:27], v[78:79] op_sel_hi:[0,1,1]
	v_pk_fma_f32 v[82:83], v[30:31], v[26:27], v[82:83] op_sel_hi:[0,1,1]
	v_pk_fma_f32 v[92:93], v[44:45], v[36:37], v[92:93] op_sel_hi:[0,1,1]
	v_pk_fma_f32 v[96:97], v[30:31], v[36:37], v[96:97] op_sel_hi:[0,1,1]
	v_pk_fma_f32 v[106:107], v[44:45], v[48:49], v[106:107] op_sel_hi:[0,1,1]
	v_pk_fma_f32 v[110:111], v[30:31], v[48:49], v[110:111] op_sel_hi:[0,1,1]
	v_pk_fma_f32 v[120:121], v[44:45], v[52:53], v[120:121] op_sel_hi:[0,1,1]
	v_pk_fma_f32 v[124:125], v[30:31], v[52:53], v[124:125] op_sel_hi:[0,1,1]
	v_mov_b32_e32 v23, v5
	v_pk_add_f32 v[130:131], v[130:131], v[176:177] neg_lo:[0,1] neg_hi:[0,1]
	v_pk_add_f32 v[176:177], v[138:139], v[182:183] op_sel:[0,1] op_sel_hi:[1,0] neg_hi:[0,1]
	v_pk_add_f32 v[138:139], v[138:139], v[182:183] op_sel:[0,1] op_sel_hi:[1,0] neg_lo:[0,1]
	v_pk_add_f32 v[182:183], v[178:179], v[186:187]
	v_pk_add_f32 v[178:179], v[178:179], v[186:187] neg_lo:[0,1] neg_hi:[0,1]
	v_pk_add_f32 v[186:187], v[160:161], v[180:181] op_sel:[0,1] op_sel_hi:[1,0] neg_hi:[0,1]
	v_pk_add_f32 v[160:161], v[160:161], v[180:181] op_sel:[0,1] op_sel_hi:[1,0] neg_lo:[0,1]
	v_pk_add_f32 v[180:181], v[168:169], v[188:189]
	v_pk_fma_f32 v[30:31], v[30:31], v[136:137], v[34:35] op_sel_hi:[0,1,1]
	v_pk_mul_f32 v[34:35], v[54:55], v[152:153] op_sel:[0,1] op_sel_hi:[1,0]
	v_pk_mul_f32 v[2:3], v[72:73], v[4:5] op_sel:[0,1] op_sel_hi:[1,0]
	v_xor_b32_e32 v12, 0x80000000, v9
	v_pk_mul_f32 v[24:25], v[72:73], v[10:11] op_sel:[0,1] op_sel_hi:[1,0]
	v_xor_b32_e32 v38, 0x80000000, v33
	v_xor_b32_e32 v50, 0x80000000, v11
	v_pk_mul_f32 v[56:57], v[72:73], v[20:21] op_sel:[0,1] op_sel_hi:[1,0]
	v_xor_b32_e32 v64, 0x80000000, v63
	v_xor_b32_e32 v70, 0x80000000, v21
	v_pk_mul_f32 v[74:75], v[72:73], v[26:27] op_sel:[0,1] op_sel_hi:[1,0]
	v_xor_b32_e32 v80, 0x80000000, v79
	v_xor_b32_e32 v86, 0x80000000, v27
	v_pk_mul_f32 v[88:89], v[72:73], v[36:37] op_sel:[0,1] op_sel_hi:[1,0]
	v_xor_b32_e32 v94, 0x80000000, v93
	v_xor_b32_e32 v100, 0x80000000, v37
	v_pk_mul_f32 v[102:103], v[72:73], v[48:49] op_sel:[0,1] op_sel_hi:[1,0]
	v_xor_b32_e32 v108, 0x80000000, v107
	v_xor_b32_e32 v114, 0x80000000, v49
	v_pk_mul_f32 v[116:117], v[52:53], v[72:73] op_sel:[1,0] op_sel_hi:[0,1]
	v_xor_b32_e32 v122, 0x80000000, v121
	v_mov_b32_e32 v123, v121
	v_mov_b32_e32 v115, v49
	v_mov_b32_e32 v109, v107
	v_mov_b32_e32 v101, v37
	v_mov_b32_e32 v95, v93
	v_mov_b32_e32 v87, v27
	v_mov_b32_e32 v81, v79
	v_mov_b32_e32 v71, v21
	v_mov_b32_e32 v65, v63
	v_mov_b32_e32 v51, v11
	v_mov_b32_e32 v39, v33
	v_mov_b32_e32 v13, v9
	v_pk_fma_f32 v[34:35], v[44:45], v[152:153], v[34:35] op_sel_hi:[0,1,1]
	v_pk_mul_f32 v[44:45], v[72:73], v[180:181] op_sel:[0,1] op_sel_hi:[1,0]
	v_pk_mul_f32 v[22:23], v[150:151], v[22:23] op_sel:[1,0] op_sel_hi:[0,1]
	v_pk_fma_f32 v[2:3], v[46:47], v[4:5], v[2:3] op_sel_hi:[0,1,1]
	v_pk_fma_f32 v[24:25], v[46:47], v[10:11], v[24:25] op_sel_hi:[0,1,1]
	v_pk_fma_f32 v[56:57], v[46:47], v[20:21], v[56:57] op_sel_hi:[0,1,1]
	v_pk_fma_f32 v[74:75], v[46:47], v[26:27], v[74:75] op_sel_hi:[0,1,1]
	v_xor_b32_e32 v84, 0x80000000, v83
	v_pk_fma_f32 v[88:89], v[46:47], v[36:37], v[88:89] op_sel_hi:[0,1,1]
	v_pk_fma_f32 v[102:103], v[46:47], v[48:49], v[102:103] op_sel_hi:[0,1,1]
	v_pk_fma_f32 v[116:117], v[52:53], v[46:47], v[116:117] op_sel_hi:[1,0,1]
	v_mov_b32_e32 v85, v83
	v_pk_fma_f32 v[44:45], v[46:47], v[180:181], v[44:45] op_sel_hi:[0,1,1]
	v_pk_mul_f32 v[46:47], v[58:59], v[192:193] op_sel:[0,1] op_sel_hi:[1,0]
	v_pk_mul_f32 v[54:55], v[122:123], v[154:155] op_sel:[0,1] op_sel_hi:[1,0]
	v_pk_mul_f32 v[72:73], v[114:115], v[194:195] op_sel:[0,1] op_sel_hi:[1,0]
	v_pk_mul_f32 v[108:109], v[108:109], v[158:159] op_sel:[0,1] op_sel_hi:[1,0]
	v_pk_mul_f32 v[100:101], v[100:101], v[156:157] op_sel:[0,1] op_sel_hi:[1,0]
	v_pk_mul_f32 v[94:95], v[94:95], v[144:145] op_sel:[0,1] op_sel_hi:[1,0]
	v_pk_mul_f32 v[86:87], v[174:175], v[86:87] op_sel:[1,0] op_sel_hi:[0,1]
	v_pk_mul_f32 v[80:81], v[140:141], v[80:81] op_sel:[1,0] op_sel_hi:[0,1]
	v_pk_mul_f32 v[70:71], v[148:149], v[70:71] op_sel:[1,0] op_sel_hi:[0,1]
	v_pk_mul_f32 v[64:65], v[132:133], v[64:65] op_sel:[1,0] op_sel_hi:[0,1]
	v_pk_mul_f32 v[50:51], v[190:191], v[50:51] op_sel:[1,0] op_sel_hi:[0,1]
	v_pk_mul_f32 v[38:39], v[142:143], v[38:39] op_sel:[1,0] op_sel_hi:[0,1]
	v_pk_fma_f32 v[4:5], v[150:151], v[4:5], v[22:23] op_sel_hi:[1,0,1]
	v_pk_mul_f32 v[12:13], v[134:135], v[12:13] op_sel:[1,0] op_sel_hi:[0,1]
	v_xor_b32_e32 v112, 0x80000000, v111
	v_mov_b32_e32 v113, v111
	v_pk_fma_f32 v[46:47], v[52:53], v[192:193], v[46:47] op_sel_hi:[0,1,1]
	v_pk_fma_f32 v[54:55], v[120:121], v[154:155], v[54:55] op_sel_hi:[0,1,1]
	v_pk_fma_f32 v[48:49], v[48:49], v[194:195], v[72:73] op_sel_hi:[0,1,1]
	v_pk_fma_f32 v[106:107], v[106:107], v[158:159], v[108:109] op_sel_hi:[0,1,1]
	v_pk_fma_f32 v[36:37], v[36:37], v[156:157], v[100:101] op_sel_hi:[0,1,1]
	v_pk_fma_f32 v[92:93], v[92:93], v[144:145], v[94:95] op_sel_hi:[0,1,1]
	v_pk_fma_f32 v[26:27], v[174:175], v[26:27], v[86:87] op_sel_hi:[1,0,1]
	v_pk_mul_f32 v[84:85], v[130:131], v[84:85] op_sel:[1,0] op_sel_hi:[0,1]
	v_pk_fma_f32 v[78:79], v[140:141], v[78:79], v[80:81] op_sel_hi:[1,0,1]
	v_pk_fma_f32 v[20:21], v[148:149], v[20:21], v[70:71] op_sel_hi:[1,0,1]
	v_pk_fma_f32 v[62:63], v[132:133], v[62:63], v[64:65] op_sel_hi:[1,0,1]
	v_pk_fma_f32 v[10:11], v[190:191], v[10:11], v[50:51] op_sel_hi:[1,0,1]
	v_pk_fma_f32 v[32:33], v[142:143], v[32:33], v[38:39] op_sel_hi:[1,0,1]
	v_pk_fma_f32 v[8:9], v[134:135], v[8:9], v[12:13] op_sel_hi:[1,0,1]
	ds_write_b64 v18, v[162:163]
	ds_write_b64 v18, v[26:27] offset:4224
	ds_write_b64 v18, v[48:49] offset:8448
	ds_write_b64 v18, v[10:11] offset:12672
	ds_write_b64 v18, v[46:47] offset:16896
	ds_write_b64 v18, v[20:21] offset:21120
	ds_write_b64 v18, v[36:37] offset:25344
	ds_write_b64 v18, v[4:5] offset:29568
	ds_write_b64 v18, v[34:35] offset:33792
	ds_write_b64 v18, v[78:79] offset:38016
	ds_write_b64 v18, v[106:107] offset:42240
	ds_write_b64 v18, v[32:33] offset:46464
	ds_write_b64 v18, v[54:55] offset:50688
	ds_write_b64 v18, v[62:63] offset:54912
	ds_write_b64 v18, v[92:93] offset:59136
	ds_write_b64 v18, v[8:9] offset:63360
	v_add_u32_e32 v4, 0x10800, v18
	v_xor_b32_e32 v42, 0x80000000, v41
	v_mov_b32_e32 v43, v41
	v_pk_mul_f32 v[72:73], v[112:113], v[176:177] op_sel:[0,1] op_sel_hi:[1,0]
	v_pk_fma_f32 v[82:83], v[130:131], v[82:83], v[84:85] op_sel_hi:[1,0,1]
	ds_write_b64 v4, v[30:31]
	v_add_u32_e32 v4, 0x11880, v18
	v_xor_b32_e32 v126, 0x80000000, v125
	v_mov_b32_e32 v127, v125
	v_pk_fma_f32 v[72:73], v[110:111], v[176:177], v[72:73] op_sel_hi:[0,1,1]
	v_pk_mul_f32 v[42:43], v[138:139], v[42:43] op_sel:[1,0] op_sel_hi:[0,1]
	ds_write_b64 v4, v[82:83]
	v_add_u32_e32 v4, 0x12900, v18
	v_xor_b32_e32 v68, 0x80000000, v67
	v_mov_b32_e32 v69, v67
	v_pk_mul_f32 v[52:53], v[126:127], v[182:183] op_sel:[0,1] op_sel_hi:[1,0]
	v_pk_fma_f32 v[40:41], v[138:139], v[40:41], v[42:43] op_sel_hi:[1,0,1]
	ds_write_b64 v4, v[72:73]
	v_add_u32_e32 v4, 0x13980, v18
	v_xor_b32_e32 v98, 0x80000000, v97
	v_mov_b32_e32 v99, v97
	v_pk_fma_f32 v[52:53], v[124:125], v[182:183], v[52:53] op_sel_hi:[0,1,1]
	v_pk_mul_f32 v[68:69], v[178:179], v[68:69] op_sel:[1,0] op_sel_hi:[0,1]
	ds_write_b64 v4, v[40:41]
	v_add_u32_e32 v4, 0x14a00, v18
	v_xor_b32_e32 v16, 0x80000000, v15
	v_mov_b32_e32 v17, v15
	v_pk_mul_f32 v[98:99], v[98:99], v[186:187] op_sel:[0,1] op_sel_hi:[1,0]
	v_pk_fma_f32 v[66:67], v[178:179], v[66:67], v[68:69] op_sel_hi:[1,0,1]
	ds_write_b64 v4, v[52:53]
	v_add_u32_e32 v4, 0x15a80, v18
	v_pk_fma_f32 v[96:97], v[96:97], v[186:187], v[98:99] op_sel_hi:[0,1,1]
	v_pk_mul_f32 v[16:17], v[160:161], v[16:17] op_sel:[1,0] op_sel_hi:[0,1]
	ds_write_b64 v4, v[66:67]
	v_add_u32_e32 v4, 0x16b00, v18
	v_xor_b32_e32 v76, 0x80000000, v75
	v_mov_b32_e32 v77, v75
	v_pk_add_f32 v[168:169], v[168:169], v[188:189] neg_lo:[0,1] neg_hi:[0,1]
	v_pk_fma_f32 v[14:15], v[160:161], v[14:15], v[16:17] op_sel_hi:[1,0,1]
	ds_write_b64 v4, v[96:97]
	v_add_u32_e32 v4, 0x17b80, v18
	v_xor_b32_e32 v104, 0x80000000, v103
	v_mov_b32_e32 v105, v103
	v_pk_add_f32 v[188:189], v[170:171], v[184:185] op_sel:[0,1] op_sel_hi:[1,0] neg_hi:[0,1]
	v_pk_mul_f32 v[76:77], v[168:169], v[76:77] op_sel:[1,0] op_sel_hi:[0,1]
	ds_write_b64 v4, v[14:15]
	v_add_u32_e32 v4, 0x18c00, v18
	v_xor_b32_e32 v28, 0x80000000, v25
	v_mov_b32_e32 v29, v25
	v_pk_add_f32 v[170:171], v[170:171], v[184:185] op_sel:[0,1] op_sel_hi:[1,0] neg_lo:[0,1]
	v_pk_mul_f32 v[104:105], v[104:105], v[188:189] op_sel:[0,1] op_sel_hi:[1,0]
	v_pk_fma_f32 v[74:75], v[168:169], v[74:75], v[76:77] op_sel_hi:[1,0,1]
	ds_write_b64 v4, v[44:45]
	v_add_u32_e32 v4, 0x19c80, v18
	v_xor_b32_e32 v118, 0x80000000, v117
	v_mov_b32_e32 v119, v117
	v_pk_add_f32 v[184:185], v[164:165], v[172:173]
	v_pk_fma_f32 v[102:103], v[102:103], v[188:189], v[104:105] op_sel_hi:[0,1,1]
	v_pk_mul_f32 v[28:29], v[170:171], v[28:29] op_sel:[1,0] op_sel_hi:[0,1]
	ds_write_b64 v4, v[74:75]
	v_add_u32_e32 v4, 0x1ad00, v18
	v_xor_b32_e32 v60, 0x80000000, v57
	v_mov_b32_e32 v61, v57
	v_pk_add_f32 v[164:165], v[164:165], v[172:173] neg_lo:[0,1] neg_hi:[0,1]
	v_pk_mul_f32 v[58:59], v[118:119], v[184:185] op_sel:[0,1] op_sel_hi:[1,0]
	v_pk_fma_f32 v[24:25], v[170:171], v[24:25], v[28:29] op_sel_hi:[1,0,1]
	ds_write_b64 v4, v[102:103]
	v_add_u32_e32 v4, 0x1bd80, v18
	v_xor_b32_e32 v90, 0x80000000, v89
	v_mov_b32_e32 v91, v89
	v_pk_add_f32 v[172:173], v[128:129], v[166:167] op_sel:[0,1] op_sel_hi:[1,0] neg_hi:[0,1]
	v_pk_fma_f32 v[58:59], v[116:117], v[184:185], v[58:59] op_sel_hi:[0,1,1]
	v_pk_mul_f32 v[60:61], v[164:165], v[60:61] op_sel:[1,0] op_sel_hi:[0,1]
	ds_write_b64 v4, v[24:25]
	v_add_u32_e32 v4, 0x1ce00, v18
	v_xor_b32_e32 v6, 0x80000000, v3
	v_mov_b32_e32 v7, v3
	v_pk_add_f32 v[128:129], v[128:129], v[166:167] op_sel:[0,1] op_sel_hi:[1,0] neg_lo:[0,1]
	v_pk_mul_f32 v[90:91], v[90:91], v[172:173] op_sel:[0,1] op_sel_hi:[1,0]
	v_pk_fma_f32 v[56:57], v[164:165], v[56:57], v[60:61] op_sel_hi:[1,0,1]
	ds_write_b64 v4, v[58:59]
	v_add_u32_e32 v4, 0x1de80, v18
	v_pk_fma_f32 v[88:89], v[88:89], v[172:173], v[90:91] op_sel_hi:[0,1,1]
	v_pk_mul_f32 v[6:7], v[128:129], v[6:7] op_sel:[1,0] op_sel_hi:[0,1]
	ds_write_b64 v4, v[56:57]
	v_add_u32_e32 v4, 0x1ef00, v18
	v_pk_fma_f32 v[2:3], v[128:129], v[2:3], v[6:7] op_sel_hi:[1,0,1]
	ds_write_b64 v4, v[88:89]
	v_add_u32_e32 v4, 0x1ff80, v18
	ds_write_b64 v4, v[2:3]
	v_mov_b32_e32 v2, v210
	s_waitcnt lgkmcnt(0)
	s_barrier
	s_ashr_i32 s77, s76, 31
	v_and_b32_e32 v3, 15, v2
	v_lshlrev_b32_e32 v2, 5, v2
	v_and_b32_e32 v4, 0xfffffe00, v2
	v_lshl_add_u32 v5, v4, 3, 0
	v_lshlrev_b32_e32 v6, 3, v3
	v_ashrrev_i32_e32 v7, 2, v4
	v_add3_u32 v18, v5, v6, v7
	v_add_u32_e32 v196, 0x800, v18
	ds_read2_b64 v[128:131], v18 offset1:16
	ds_read2_b64 v[132:135], v18 offset0:33 offset1:49
	ds_read2_b64 v[136:139], v18 offset0:66 offset1:82
	ds_read2_b64 v[140:143], v18 offset0:99 offset1:115
	ds_read2_b64 v[148:151], v18 offset0:132 offset1:148
	ds_read2_b64 v[152:155], v18 offset0:165 offset1:181
	ds_read2_b64 v[156:159], v18 offset0:198 offset1:214
	ds_read2_b64 v[160:163], v18 offset0:231 offset1:247
	ds_read2_b64 v[164:167], v196 offset0:8 offset1:24
	ds_read2_b64 v[168:171], v196 offset0:41 offset1:57
	ds_read2_b64 v[172:175], v196 offset0:74 offset1:90
	ds_read2_b64 v[176:179], v196 offset0:107 offset1:123
	ds_read2_b64 v[180:183], v196 offset0:140 offset1:156
	ds_read2_b64 v[184:187], v196 offset0:173 offset1:189
	ds_read2_b64 v[188:191], v196 offset0:206 offset1:222
	ds_read2_b64 v[192:195], v196 offset0:239 offset1:255
	s_waitcnt lgkmcnt(7)
	v_pk_add_f32 v[144:145], v[128:129], v[164:165]
	v_pk_add_f32 v[128:129], v[128:129], v[164:165] neg_lo:[0,1] neg_hi:[0,1]
	v_pk_add_f32 v[164:165], v[130:131], v[166:167]
	v_pk_add_f32 v[130:131], v[130:131], v[166:167] neg_lo:[0,1] neg_hi:[0,1]
	v_cvt_f32_ubyte0_e32 v2, v3
	v_pk_mul_f32 v[166:167], v[130:131], s[10:11]
	v_mul_f32_e32 v3, 0x3b000000, v2
	v_pk_fma_f32 v[130:131], v[130:131], s[8:9], v[166:167] op_sel:[0,0,1] op_sel_hi:[1,0,0]
	s_waitcnt lgkmcnt(6)
	v_pk_add_f32 v[166:167], v[132:133], v[168:169]
	v_pk_add_f32 v[132:133], v[132:133], v[168:169] neg_lo:[0,1] neg_hi:[0,1]
	v_sin_f32_e32 v2, v3
	v_pk_mul_f32 v[168:169], v[132:133], s[18:19]
	v_cos_f32_e32 v4, v3
	v_pk_fma_f32 v[132:133], v[132:133], s[16:17], v[168:169] op_sel:[0,0,1] op_sel_hi:[1,0,0]
	v_pk_add_f32 v[168:169], v[134:135], v[170:171]
	v_pk_add_f32 v[134:135], v[134:135], v[170:171] neg_lo:[0,1] neg_hi:[0,1]
	v_xor_b32_e32 v5, 0x80000000, v2
	v_pk_mul_f32 v[170:171], v[134:135], s[26:27]
	v_mov_b32_e32 v3, v5
	v_pk_fma_f32 v[134:135], v[134:135], s[24:25], v[170:171] op_sel:[0,0,1] op_sel_hi:[1,0,0]
	s_waitcnt lgkmcnt(5)
	v_pk_add_f32 v[170:171], v[136:137], v[172:173]
	v_pk_add_f32 v[136:137], v[136:137], v[172:173] neg_lo:[0,1] neg_hi:[0,1]
	v_pk_mul_f32 v[6:7], v[4:5], v[2:3] op_sel:[1,0] op_sel_hi:[0,1]
	v_pk_mul_f32 v[172:173], v[136:137], s[36:37]
	v_pk_fma_f32 v[6:7], v[4:5], v[4:5], v[6:7] op_sel_hi:[1,0,1]
	v_pk_fma_f32 v[136:137], v[136:137], s[78:79], v[172:173] op_sel:[0,0,1] op_sel_hi:[1,0,0]
	v_pk_add_f32 v[172:173], v[138:139], v[174:175]
	v_pk_add_f32 v[138:139], v[138:139], v[174:175] neg_lo:[0,1] neg_hi:[0,1]
	v_xor_b32_e32 v12, 0x80000000, v7
	v_pk_mul_f32 v[174:175], v[138:139], s[38:39]
	v_mov_b32_e32 v13, v7
	v_pk_fma_f32 v[138:139], v[138:139], s[0:1], v[174:175] op_sel:[0,0,1] op_sel_hi:[1,0,0]
	s_waitcnt lgkmcnt(4)
	v_pk_add_f32 v[174:175], v[140:141], v[176:177]
	v_pk_add_f32 v[140:141], v[140:141], v[176:177] neg_lo:[0,1] neg_hi:[0,1]
	v_pk_mul_f32 v[10:11], v[6:7], v[12:13] op_sel:[1,0] op_sel_hi:[0,1]
	v_pk_mul_f32 v[176:177], v[140:141], s[40:41]
	v_pk_fma_f32 v[10:11], v[6:7], v[6:7], v[10:11] op_sel_hi:[1,0,1]
	v_pk_fma_f32 v[140:141], v[140:141], s[80:81], v[176:177] op_sel:[0,0,1] op_sel_hi:[1,0,0]
	v_pk_add_f32 v[176:177], v[142:143], v[178:179]
	v_pk_add_f32 v[142:143], v[142:143], v[178:179] neg_lo:[0,1] neg_hi:[0,1]
	v_xor_b32_e32 v14, 0x80000000, v11
	v_pk_mul_f32 v[178:179], v[142:143], s[42:43]
	v_mov_b32_e32 v15, v11
	v_pk_fma_f32 v[142:143], v[142:143], s[74:75], v[178:179] op_sel:[0,0,1] op_sel_hi:[1,0,0]
	s_waitcnt lgkmcnt(3)
	v_pk_add_f32 v[178:179], v[148:149], v[180:181]
	v_pk_add_f32 v[180:181], v[148:149], v[180:181] neg_lo:[0,1] neg_hi:[0,1]
	v_pk_mul_f32 v[28:29], v[10:11], v[14:15] op_sel:[1,0] op_sel_hi:[0,1]
	v_pk_add_f32 v[148:149], v[150:151], v[182:183]
	v_pk_add_f32 v[150:151], v[150:151], v[182:183] neg_lo:[0,1] neg_hi:[0,1]
	v_pk_fma_f32 v[28:29], v[10:11], v[10:11], v[28:29] op_sel_hi:[1,0,1]
	v_pk_mul_f32 v[182:183], v[150:151], s[42:43]
	v_pk_mul_f32 v[44:45], v[14:15], v[28:29] op_sel:[0,1] op_sel_hi:[1,0]
	v_pk_fma_f32 v[150:151], v[150:151], s[74:75], v[182:183] op_sel:[0,0,1] op_sel_hi:[1,0,0] neg_lo:[1,0,0] neg_hi:[1,0,0]
	s_waitcnt lgkmcnt(2)
	v_pk_add_f32 v[182:183], v[152:153], v[184:185]
	v_pk_add_f32 v[152:153], v[152:153], v[184:185] neg_lo:[0,1] neg_hi:[0,1]
	v_pk_fma_f32 v[44:45], v[10:11], v[28:29], v[44:45] op_sel_hi:[0,1,1]
	v_pk_mul_f32 v[184:185], v[152:153], s[40:41]
	v_pk_mul_f32 v[60:61], v[14:15], v[44:45] op_sel:[0,1] op_sel_hi:[1,0]
	v_pk_fma_f32 v[152:153], v[152:153], s[80:81], v[184:185] op_sel:[0,0,1] op_sel_hi:[1,0,0] neg_lo:[1,0,0] neg_hi:[1,0,0]
	v_pk_add_f32 v[184:185], v[154:155], v[186:187]
	v_pk_add_f32 v[154:155], v[154:155], v[186:187] neg_lo:[0,1] neg_hi:[0,1]
	v_pk_fma_f32 v[60:61], v[10:11], v[44:45], v[60:61] op_sel_hi:[0,1,1]
	v_pk_mul_f32 v[186:187], v[154:155], s[38:39]
	v_pk_mul_f32 v[76:77], v[14:15], v[60:61] op_sel:[0,1] op_sel_hi:[1,0]
	v_pk_fma_f32 v[154:155], v[154:155], s[0:1], v[186:187] op_sel:[0,0,1] op_sel_hi:[1,0,0] neg_lo:[1,0,0] neg_hi:[1,0,0]
	s_waitcnt lgkmcnt(1)
	v_pk_add_f32 v[186:187], v[156:157], v[188:189]
	v_pk_add_f32 v[156:157], v[156:157], v[188:189] neg_lo:[0,1] neg_hi:[0,1]
	v_pk_fma_f32 v[76:77], v[10:11], v[60:61], v[76:77] op_sel_hi:[0,1,1]
	v_pk_mul_f32 v[188:189], v[156:157], s[36:37]
	v_pk_mul_f32 v[92:93], v[14:15], v[76:77] op_sel:[0,1] op_sel_hi:[1,0]
	v_pk_fma_f32 v[156:157], v[156:157], s[78:79], v[188:189] op_sel:[0,0,1] op_sel_hi:[1,0,0] neg_lo:[1,0,0] neg_hi:[1,0,0]
	v_pk_add_f32 v[188:189], v[158:159], v[190:191]
	v_pk_add_f32 v[158:159], v[158:159], v[190:191] neg_lo:[0,1] neg_hi:[0,1]
	v_pk_fma_f32 v[92:93], v[10:11], v[76:77], v[92:93] op_sel_hi:[0,1,1]
	v_pk_mul_f32 v[190:191], v[158:159], s[26:27]
	v_pk_mul_f32 v[108:109], v[14:15], v[92:93] op_sel:[0,1] op_sel_hi:[1,0]
	v_pk_fma_f32 v[158:159], v[158:159], s[24:25], v[190:191] op_sel:[0,0,1] op_sel_hi:[1,0,0] neg_lo:[1,0,0] neg_hi:[1,0,0]
	s_waitcnt lgkmcnt(0)
	v_pk_add_f32 v[190:191], v[160:161], v[192:193]
	v_pk_add_f32 v[160:161], v[160:161], v[192:193] neg_lo:[0,1] neg_hi:[0,1]
	v_pk_mul_f32 v[8:9], v[2:3], v[6:7] op_sel:[0,1] op_sel_hi:[1,0]
	v_pk_mul_f32 v[192:193], v[160:161], s[18:19]
	v_pk_fma_f32 v[108:109], v[10:11], v[92:93], v[108:109] op_sel_hi:[0,1,1]
	v_pk_fma_f32 v[160:161], v[160:161], s[16:17], v[192:193] op_sel:[0,0,1] op_sel_hi:[1,0,0] neg_lo:[1,0,0] neg_hi:[1,0,0]
	v_pk_add_f32 v[192:193], v[162:163], v[194:195]
	v_pk_add_f32 v[162:163], v[162:163], v[194:195] neg_lo:[0,1] neg_hi:[0,1]
	v_pk_fma_f32 v[8:9], v[4:5], v[6:7], v[8:9] op_sel_hi:[0,1,1]
	v_pk_mul_f32 v[194:195], v[162:163], s[10:11]
	v_pk_mul_f32 v[16:17], v[2:3], v[10:11] op_sel:[0,1] op_sel_hi:[1,0]
	v_pk_fma_f32 v[162:163], v[162:163], s[8:9], v[194:195] op_sel:[0,0,1] op_sel_hi:[1,0,0] neg_lo:[1,0,0] neg_hi:[1,0,0]
	v_pk_add_f32 v[194:195], v[144:145], v[178:179]
	v_pk_add_f32 v[144:145], v[144:145], v[178:179] neg_lo:[0,1] neg_hi:[0,1]
	v_pk_add_f32 v[178:179], v[164:165], v[148:149]
	v_pk_add_f32 v[148:149], v[164:165], v[148:149] neg_lo:[0,1] neg_hi:[0,1]
	v_pk_mul_f32 v[32:33], v[2:3], v[28:29] op_sel:[0,1] op_sel_hi:[1,0]
	v_pk_mul_f32 v[164:165], v[148:149], s[18:19]
	v_pk_mul_f32 v[48:49], v[2:3], v[44:45] op_sel:[0,1] op_sel_hi:[1,0]
	v_pk_fma_f32 v[148:149], v[148:149], s[16:17], v[164:165] op_sel:[0,0,1] op_sel_hi:[1,0,0]
	v_pk_add_f32 v[164:165], v[166:167], v[182:183]
	v_pk_add_f32 v[166:167], v[166:167], v[182:183] neg_lo:[0,1] neg_hi:[0,1]
	v_pk_mul_f32 v[64:65], v[2:3], v[60:61] op_sel:[0,1] op_sel_hi:[1,0]
	v_pk_mul_f32 v[182:183], v[166:167], s[36:37]
	v_pk_mul_f32 v[80:81], v[2:3], v[76:77] op_sel:[0,1] op_sel_hi:[1,0]
	v_pk_fma_f32 v[166:167], v[166:167], s[78:79], v[182:183] op_sel:[0,0,1] op_sel_hi:[1,0,0]
	v_pk_add_f32 v[182:183], v[168:169], v[184:185]
	v_pk_add_f32 v[168:169], v[168:169], v[184:185] neg_lo:[0,1] neg_hi:[0,1]
	v_pk_mul_f32 v[96:97], v[2:3], v[92:93] op_sel:[0,1] op_sel_hi:[1,0]
	v_pk_mul_f32 v[184:185], v[168:169], s[40:41]
	v_pk_mul_f32 v[112:113], v[2:3], v[108:109] op_sel:[0,1] op_sel_hi:[1,0]
	v_pk_fma_f32 v[168:169], v[168:169], s[80:81], v[184:185] op_sel:[0,0,1] op_sel_hi:[1,0,0]
	v_pk_add_f32 v[184:185], v[170:171], v[186:187]
	v_pk_add_f32 v[186:187], v[170:171], v[186:187] neg_lo:[0,1] neg_hi:[0,1]
	v_xor_b32_e32 v22, 0x80000000, v9
	v_pk_add_f32 v[170:171], v[172:173], v[188:189]
	v_pk_add_f32 v[172:173], v[172:173], v[188:189] neg_lo:[0,1] neg_hi:[0,1]
	v_mov_b32_e32 v23, v9
	v_pk_mul_f32 v[188:189], v[172:173], s[40:41]
	v_pk_fma_f32 v[16:17], v[4:5], v[10:11], v[16:17] op_sel_hi:[0,1,1]
	v_pk_fma_f32 v[172:173], v[172:173], s[80:81], v[188:189] op_sel:[0,0,1] op_sel_hi:[1,0,0] neg_lo:[1,0,0] neg_hi:[1,0,0]
	v_pk_add_f32 v[188:189], v[174:175], v[190:191]
	v_pk_add_f32 v[174:175], v[174:175], v[190:191] neg_lo:[0,1] neg_hi:[0,1]
	v_pk_mul_f32 v[20:21], v[12:13], v[10:11] op_sel:[0,1] op_sel_hi:[1,0]
	v_pk_mul_f32 v[190:191], v[174:175], s[36:37]
	v_pk_fma_f32 v[32:33], v[4:5], v[28:29], v[32:33] op_sel_hi:[0,1,1]
	v_pk_fma_f32 v[174:175], v[174:175], s[78:79], v[190:191] op_sel:[0,0,1] op_sel_hi:[1,0,0] neg_lo:[1,0,0] neg_hi:[1,0,0]
	v_pk_add_f32 v[190:191], v[176:177], v[192:193]
	v_pk_add_f32 v[176:177], v[176:177], v[192:193] neg_lo:[0,1] neg_hi:[0,1]
	v_pk_mul_f32 v[36:37], v[12:13], v[28:29] op_sel:[0,1] op_sel_hi:[1,0]
	v_pk_mul_f32 v[192:193], v[176:177], s[18:19]
	v_pk_fma_f32 v[48:49], v[4:5], v[44:45], v[48:49] op_sel_hi:[0,1,1]
	v_pk_fma_f32 v[176:177], v[176:177], s[16:17], v[192:193] op_sel:[0,0,1] op_sel_hi:[1,0,0] neg_lo:[1,0,0] neg_hi:[1,0,0]
	v_pk_add_f32 v[192:193], v[128:129], v[180:181] op_sel:[0,1] op_sel_hi:[1,0] neg_hi:[0,1]
	v_pk_add_f32 v[128:129], v[128:129], v[180:181] op_sel:[0,1] op_sel_hi:[1,0] neg_lo:[0,1]
	v_pk_add_f32 v[180:181], v[130:131], v[150:151]
	v_pk_add_f32 v[130:131], v[130:131], v[150:151] neg_lo:[0,1] neg_hi:[0,1]
	v_pk_mul_f32 v[52:53], v[12:13], v[44:45] op_sel:[0,1] op_sel_hi:[1,0]
	v_pk_mul_f32 v[150:151], v[130:131], s[18:19]
	v_pk_fma_f32 v[64:65], v[4:5], v[60:61], v[64:65] op_sel_hi:[0,1,1]
	v_pk_fma_f32 v[130:131], v[130:131], s[16:17], v[150:151] op_sel:[0,0,1] op_sel_hi:[1,0,0]
	v_pk_add_f32 v[150:151], v[132:133], v[152:153]
	v_pk_add_f32 v[132:133], v[132:133], v[152:153] neg_lo:[0,1] neg_hi:[0,1]
	v_pk_mul_f32 v[68:69], v[12:13], v[60:61] op_sel:[0,1] op_sel_hi:[1,0]
	v_pk_mul_f32 v[152:153], v[132:133], s[36:37]
	v_pk_fma_f32 v[80:81], v[4:5], v[76:77], v[80:81] op_sel_hi:[0,1,1]
	v_pk_fma_f32 v[132:133], v[132:133], s[78:79], v[152:153] op_sel:[0,0,1] op_sel_hi:[1,0,0]
	v_pk_add_f32 v[152:153], v[134:135], v[154:155]
	v_pk_add_f32 v[134:135], v[134:135], v[154:155] neg_lo:[0,1] neg_hi:[0,1]
	v_pk_mul_f32 v[84:85], v[12:13], v[76:77] op_sel:[0,1] op_sel_hi:[1,0]
	v_pk_mul_f32 v[154:155], v[134:135], s[40:41]
	v_pk_fma_f32 v[96:97], v[4:5], v[92:93], v[96:97] op_sel_hi:[0,1,1]
	v_pk_fma_f32 v[134:135], v[134:135], s[80:81], v[154:155] op_sel:[0,0,1] op_sel_hi:[1,0,0]
	v_pk_add_f32 v[154:155], v[136:137], v[156:157]
	v_pk_add_f32 v[156:157], v[136:137], v[156:157] neg_lo:[0,1] neg_hi:[0,1]
	v_pk_mul_f32 v[100:101], v[12:13], v[92:93] op_sel:[0,1] op_sel_hi:[1,0]
	v_pk_add_f32 v[136:137], v[138:139], v[158:159]
	v_pk_add_f32 v[138:139], v[138:139], v[158:159] neg_lo:[0,1] neg_hi:[0,1]
	v_pk_fma_f32 v[112:113], v[4:5], v[108:109], v[112:113] op_sel_hi:[0,1,1]
	v_pk_mul_f32 v[158:159], v[138:139], s[40:41]
	v_pk_mul_f32 v[116:117], v[12:13], v[108:109] op_sel:[0,1] op_sel_hi:[1,0]
	v_pk_fma_f32 v[138:139], v[138:139], s[80:81], v[158:159] op_sel:[0,0,1] op_sel_hi:[1,0,0] neg_lo:[1,0,0] neg_hi:[1,0,0]
	v_pk_add_f32 v[158:159], v[140:141], v[160:161]
	v_pk_add_f32 v[140:141], v[140:141], v[160:161] neg_lo:[0,1] neg_hi:[0,1]
	v_pk_fma_f32 v[20:21], v[6:7], v[10:11], v[20:21] op_sel_hi:[0,1,1]
	v_pk_mul_f32 v[160:161], v[140:141], s[36:37]
	v_pk_mul_f32 v[24:25], v[10:11], v[22:23] op_sel:[1,0] op_sel_hi:[0,1]
	v_pk_fma_f32 v[140:141], v[140:141], s[78:79], v[160:161] op_sel:[0,0,1] op_sel_hi:[1,0,0] neg_lo:[1,0,0] neg_hi:[1,0,0]
	v_pk_add_f32 v[160:161], v[142:143], v[162:163]
	v_pk_add_f32 v[142:143], v[142:143], v[162:163] neg_lo:[0,1] neg_hi:[0,1]
	v_pk_fma_f32 v[36:37], v[6:7], v[28:29], v[36:37] op_sel_hi:[0,1,1]
	v_pk_mul_f32 v[162:163], v[142:143], s[18:19]
	v_pk_mul_f32 v[40:41], v[22:23], v[28:29] op_sel:[0,1] op_sel_hi:[1,0]
	v_pk_fma_f32 v[142:143], v[142:143], s[16:17], v[162:163] op_sel:[0,0,1] op_sel_hi:[1,0,0] neg_lo:[1,0,0] neg_hi:[1,0,0]
	v_pk_add_f32 v[162:163], v[194:195], v[184:185]
	v_pk_add_f32 v[184:185], v[194:195], v[184:185] neg_lo:[0,1] neg_hi:[0,1]
	v_pk_add_f32 v[194:195], v[178:179], v[170:171]
	v_pk_add_f32 v[170:171], v[178:179], v[170:171] neg_lo:[0,1] neg_hi:[0,1]
	v_pk_fma_f32 v[52:53], v[6:7], v[44:45], v[52:53] op_sel_hi:[0,1,1]
	v_pk_mul_f32 v[178:179], v[170:171], s[36:37]
	v_pk_mul_f32 v[56:57], v[22:23], v[44:45] op_sel:[0,1] op_sel_hi:[1,0]
	v_pk_fma_f32 v[170:171], v[170:171], s[78:79], v[178:179] op_sel:[0,0,1] op_sel_hi:[1,0,0]
	v_pk_add_f32 v[178:179], v[164:165], v[188:189]
	v_pk_add_f32 v[188:189], v[164:165], v[188:189] neg_lo:[0,1] neg_hi:[0,1]
	v_pk_fma_f32 v[68:69], v[6:7], v[60:61], v[68:69] op_sel_hi:[0,1,1]
	v_pk_add_f32 v[164:165], v[182:183], v[190:191]
	v_pk_add_f32 v[182:183], v[182:183], v[190:191] neg_lo:[0,1] neg_hi:[0,1]
	v_pk_mul_f32 v[72:73], v[22:23], v[60:61] op_sel:[0,1] op_sel_hi:[1,0]
	v_pk_mul_f32 v[190:191], v[182:183], s[36:37]
	v_pk_fma_f32 v[84:85], v[6:7], v[76:77], v[84:85] op_sel_hi:[0,1,1]
	v_pk_fma_f32 v[182:183], v[182:183], s[78:79], v[190:191] op_sel:[0,0,1] op_sel_hi:[1,0,0] neg_lo:[1,0,0] neg_hi:[1,0,0]
	v_pk_add_f32 v[190:191], v[144:145], v[186:187] op_sel:[0,1] op_sel_hi:[1,0] neg_hi:[0,1]
	v_pk_add_f32 v[144:145], v[144:145], v[186:187] op_sel:[0,1] op_sel_hi:[1,0] neg_lo:[0,1]
	v_pk_add_f32 v[186:187], v[148:149], v[172:173]
	v_pk_add_f32 v[148:149], v[148:149], v[172:173] neg_lo:[0,1] neg_hi:[0,1]
	v_pk_mul_f32 v[88:89], v[22:23], v[76:77] op_sel:[0,1] op_sel_hi:[1,0]
	v_pk_mul_f32 v[172:173], v[148:149], s[36:37]
	v_pk_fma_f32 v[100:101], v[6:7], v[92:93], v[100:101] op_sel_hi:[0,1,1]
	v_pk_fma_f32 v[148:149], v[148:149], s[78:79], v[172:173] op_sel:[0,0,1] op_sel_hi:[1,0,0]
	v_pk_add_f32 v[172:173], v[166:167], v[174:175]
	v_pk_add_f32 v[174:175], v[166:167], v[174:175] neg_lo:[0,1] neg_hi:[0,1]
	v_pk_mul_f32 v[104:105], v[22:23], v[92:93] op_sel:[0,1] op_sel_hi:[1,0]
	v_pk_add_f32 v[166:167], v[168:169], v[176:177]
	v_pk_add_f32 v[168:169], v[168:169], v[176:177] neg_lo:[0,1] neg_hi:[0,1]
	v_pk_fma_f32 v[116:117], v[6:7], v[108:109], v[116:117] op_sel_hi:[0,1,1]
	v_pk_mul_f32 v[176:177], v[168:169], s[36:37]
	v_pk_mul_f32 v[120:121], v[22:23], v[108:109] op_sel:[0,1] op_sel_hi:[1,0]
	v_pk_fma_f32 v[168:169], v[168:169], s[78:79], v[176:177] op_sel:[0,0,1] op_sel_hi:[1,0,0] neg_lo:[1,0,0] neg_hi:[1,0,0]
	v_pk_add_f32 v[176:177], v[192:193], v[154:155]
	v_pk_add_f32 v[154:155], v[192:193], v[154:155] neg_lo:[0,1] neg_hi:[0,1]
	v_pk_add_f32 v[192:193], v[180:181], v[136:137]
	v_pk_add_f32 v[136:137], v[180:181], v[136:137] neg_lo:[0,1] neg_hi:[0,1]
	v_xor_b32_e32 v26, 0x80000000, v17
	v_pk_mul_f32 v[180:181], v[136:137], s[36:37]
	v_xor_b32_e32 v30, 0x80000000, v21
	v_pk_fma_f32 v[136:137], v[136:137], s[78:79], v[180:181] op_sel:[0,0,1] op_sel_hi:[1,0,0]
	v_pk_add_f32 v[180:181], v[150:151], v[158:159]
	v_pk_add_f32 v[158:159], v[150:151], v[158:159] neg_lo:[0,1] neg_hi:[0,1]
	v_pk_fma_f32 v[24:25], v[10:11], v[8:9], v[24:25] op_sel_hi:[1,0,1]
	v_pk_add_f32 v[150:151], v[152:153], v[160:161]
	v_pk_add_f32 v[152:153], v[152:153], v[160:161] neg_lo:[0,1] neg_hi:[0,1]
	v_pk_fma_f32 v[40:41], v[8:9], v[28:29], v[40:41] op_sel_hi:[0,1,1]
	v_pk_mul_f32 v[160:161], v[152:153], s[36:37]
	v_pk_fma_f32 v[56:57], v[8:9], v[44:45], v[56:57] op_sel_hi:[0,1,1]
	v_pk_fma_f32 v[152:153], v[152:153], s[78:79], v[160:161] op_sel:[0,0,1] op_sel_hi:[1,0,0] neg_lo:[1,0,0] neg_hi:[1,0,0]
	v_pk_add_f32 v[160:161], v[128:129], v[156:157] op_sel:[0,1] op_sel_hi:[1,0] neg_hi:[0,1]
	v_pk_add_f32 v[128:129], v[128:129], v[156:157] op_sel:[0,1] op_sel_hi:[1,0] neg_lo:[0,1]
	v_pk_add_f32 v[156:157], v[130:131], v[138:139]
	v_pk_add_f32 v[130:131], v[130:131], v[138:139] neg_lo:[0,1] neg_hi:[0,1]
	v_pk_fma_f32 v[72:73], v[8:9], v[60:61], v[72:73] op_sel_hi:[0,1,1]
	v_pk_mul_f32 v[138:139], v[130:131], s[36:37]
	v_pk_fma_f32 v[88:89], v[8:9], v[76:77], v[88:89] op_sel_hi:[0,1,1]
	v_pk_fma_f32 v[130:131], v[130:131], s[78:79], v[138:139] op_sel:[0,0,1] op_sel_hi:[1,0,0]
	v_pk_add_f32 v[138:139], v[132:133], v[140:141]
	v_pk_add_f32 v[140:141], v[132:133], v[140:141] neg_lo:[0,1] neg_hi:[0,1]
	v_pk_fma_f32 v[104:105], v[8:9], v[92:93], v[104:105] op_sel_hi:[0,1,1]
	v_pk_add_f32 v[132:133], v[134:135], v[142:143]
	v_pk_add_f32 v[134:135], v[134:135], v[142:143] neg_lo:[0,1] neg_hi:[0,1]
	v_pk_fma_f32 v[120:121], v[8:9], v[108:109], v[120:121] op_sel_hi:[0,1,1]
	v_pk_mul_f32 v[142:143], v[134:135], s[36:37]
	v_mov_b32_e32 v27, v17
	v_pk_fma_f32 v[134:135], v[134:135], s[78:79], v[142:143] op_sel:[0,0,1] op_sel_hi:[1,0,0] neg_lo:[1,0,0] neg_hi:[1,0,0]
	v_pk_add_f32 v[142:143], v[162:163], v[178:179]
	v_pk_add_f32 v[162:163], v[162:163], v[178:179] neg_lo:[0,1] neg_hi:[0,1]
	v_pk_add_f32 v[178:179], v[194:195], v[164:165]
	v_pk_add_f32 v[194:195], v[194:195], v[164:165] neg_lo:[0,1] neg_hi:[0,1]
	v_mov_b32_e32 v31, v21
	v_pk_add_f32 v[164:165], v[184:185], v[188:189] op_sel:[0,1] op_sel_hi:[1,0] neg_hi:[0,1]
	v_pk_add_f32 v[184:185], v[184:185], v[188:189] op_sel:[0,1] op_sel_hi:[1,0] neg_lo:[0,1]
	v_pk_add_f32 v[188:189], v[170:171], v[182:183]
	v_pk_add_f32 v[182:183], v[170:171], v[182:183] neg_lo:[0,1] neg_hi:[0,1]
	v_xor_b32_e32 v34, 0x80000000, v25
	v_pk_add_f32 v[170:171], v[190:191], v[172:173]
	v_pk_add_f32 v[172:173], v[190:191], v[172:173] neg_lo:[0,1] neg_hi:[0,1]
	v_pk_add_f32 v[190:191], v[186:187], v[166:167]
	v_pk_add_f32 v[186:187], v[186:187], v[166:167] neg_lo:[0,1] neg_hi:[0,1]
	v_xor_b32_e32 v38, 0x80000000, v29
	v_pk_add_f32 v[166:167], v[144:145], v[174:175] op_sel:[0,1] op_sel_hi:[1,0] neg_hi:[0,1]
	v_pk_add_f32 v[144:145], v[144:145], v[174:175] op_sel:[0,1] op_sel_hi:[1,0] neg_lo:[0,1]
	v_pk_add_f32 v[174:175], v[148:149], v[168:169]
	v_pk_add_f32 v[168:169], v[148:149], v[168:169] neg_lo:[0,1] neg_hi:[0,1]
	v_xor_b32_e32 v42, 0x80000000, v33
	v_pk_add_f32 v[148:149], v[176:177], v[180:181]
	v_pk_add_f32 v[176:177], v[176:177], v[180:181] neg_lo:[0,1] neg_hi:[0,1]
	v_pk_add_f32 v[180:181], v[192:193], v[150:151]
	v_pk_add_f32 v[192:193], v[192:193], v[150:151] neg_lo:[0,1] neg_hi:[0,1]
	v_xor_b32_e32 v46, 0x80000000, v37
	v_pk_add_f32 v[150:151], v[154:155], v[158:159] op_sel:[0,1] op_sel_hi:[1,0] neg_hi:[0,1]
	v_pk_add_f32 v[154:155], v[154:155], v[158:159] op_sel:[0,1] op_sel_hi:[1,0] neg_lo:[0,1]
	v_pk_add_f32 v[158:159], v[136:137], v[152:153]
	v_pk_add_f32 v[152:153], v[136:137], v[152:153] neg_lo:[0,1] neg_hi:[0,1]
	v_mov_b32_e32 v35, v25
	v_pk_add_f32 v[136:137], v[160:161], v[138:139]
	v_pk_add_f32 v[138:139], v[160:161], v[138:139] neg_lo:[0,1] neg_hi:[0,1]
	v_pk_add_f32 v[160:161], v[156:157], v[132:133]
	v_pk_add_f32 v[156:157], v[156:157], v[132:133] neg_lo:[0,1] neg_hi:[0,1]
	v_mov_b32_e32 v39, v29
	v_pk_add_f32 v[132:133], v[128:129], v[140:141] op_sel:[0,1] op_sel_hi:[1,0] neg_hi:[0,1]
	v_pk_add_f32 v[128:129], v[128:129], v[140:141] op_sel:[0,1] op_sel_hi:[1,0] neg_lo:[0,1]
	v_pk_add_f32 v[140:141], v[130:131], v[134:135]
	v_pk_add_f32 v[134:135], v[130:131], v[134:135] neg_lo:[0,1] neg_hi:[0,1]
	v_mov_b32_e32 v43, v33
	v_pk_add_f32 v[130:131], v[142:143], v[178:179]
	v_pk_add_f32 v[142:143], v[142:143], v[178:179] neg_lo:[0,1] neg_hi:[0,1]
	v_pk_add_f32 v[178:179], v[162:163], v[194:195] op_sel:[0,1] op_sel_hi:[1,0] neg_hi:[0,1]
	v_pk_add_f32 v[162:163], v[162:163], v[194:195] op_sel:[0,1] op_sel_hi:[1,0] neg_lo:[0,1]
	v_pk_add_f32 v[194:195], v[164:165], v[188:189]
	v_pk_add_f32 v[164:165], v[164:165], v[188:189] neg_lo:[0,1] neg_hi:[0,1]
	v_pk_add_f32 v[188:189], v[184:185], v[182:183] op_sel:[0,1] op_sel_hi:[1,0] neg_hi:[0,1]
	v_pk_add_f32 v[182:183], v[184:185], v[182:183] op_sel:[0,1] op_sel_hi:[1,0] neg_lo:[0,1]
	v_pk_add_f32 v[184:185], v[170:171], v[190:191]
	v_pk_add_f32 v[170:171], v[170:171], v[190:191] neg_lo:[0,1] neg_hi:[0,1]
	v_pk_add_f32 v[190:191], v[172:173], v[186:187] op_sel:[0,1] op_sel_hi:[1,0] neg_hi:[0,1]
	v_pk_add_f32 v[172:173], v[172:173], v[186:187] op_sel:[0,1] op_sel_hi:[1,0] neg_lo:[0,1]
	v_pk_add_f32 v[186:187], v[166:167], v[174:175]
	v_pk_add_f32 v[166:167], v[166:167], v[174:175] neg_lo:[0,1] neg_hi:[0,1]
	v_pk_add_f32 v[174:175], v[144:145], v[168:169] op_sel:[0,1] op_sel_hi:[1,0] neg_hi:[0,1]
	v_pk_add_f32 v[144:145], v[144:145], v[168:169] op_sel:[0,1] op_sel_hi:[1,0] neg_lo:[0,1]
	v_pk_add_f32 v[168:169], v[148:149], v[180:181]
	v_pk_add_f32 v[148:149], v[148:149], v[180:181] neg_lo:[0,1] neg_hi:[0,1]
	v_pk_mul_f32 v[2:3], v[2:3], v[168:169] op_sel:[0,1] op_sel_hi:[1,0]
	v_pk_add_f32 v[180:181], v[176:177], v[192:193] op_sel:[0,1] op_sel_hi:[1,0] neg_hi:[0,1]
	v_pk_add_f32 v[176:177], v[176:177], v[192:193] op_sel:[0,1] op_sel_hi:[1,0] neg_lo:[0,1]
	v_pk_add_f32 v[192:193], v[150:151], v[158:159]
	v_pk_add_f32 v[150:151], v[150:151], v[158:159] neg_lo:[0,1] neg_hi:[0,1]
	v_pk_add_f32 v[158:159], v[154:155], v[152:153] op_sel:[0,1] op_sel_hi:[1,0] neg_hi:[0,1]
	v_pk_add_f32 v[152:153], v[154:155], v[152:153] op_sel:[0,1] op_sel_hi:[1,0] neg_lo:[0,1]
	v_pk_add_f32 v[154:155], v[136:137], v[160:161]
	v_pk_fma_f32 v[2:3], v[4:5], v[168:169], v[2:3] op_sel_hi:[0,1,1]
	v_pk_mul_f32 v[4:5], v[12:13], v[184:185] op_sel:[0,1] op_sel_hi:[1,0]
	v_mov_b32_e32 v47, v37
	v_pk_fma_f32 v[4:5], v[6:7], v[184:185], v[4:5] op_sel_hi:[0,1,1]
	v_pk_mul_f32 v[6:7], v[22:23], v[154:155] op_sel:[0,1] op_sel_hi:[1,0]
	v_pk_add_f32 v[136:137], v[136:137], v[160:161] neg_lo:[0,1] neg_hi:[0,1]
	v_pk_fma_f32 v[6:7], v[8:9], v[154:155], v[6:7] op_sel_hi:[0,1,1]
	v_pk_mul_f32 v[8:9], v[14:15], v[194:195] op_sel:[0,1] op_sel_hi:[1,0]
	v_pk_add_f32 v[160:161], v[138:139], v[156:157] op_sel:[0,1] op_sel_hi:[1,0] neg_hi:[0,1]
	v_pk_add_f32 v[138:139], v[138:139], v[156:157] op_sel:[0,1] op_sel_hi:[1,0] neg_lo:[0,1]
	v_pk_add_f32 v[156:157], v[132:133], v[140:141]
	v_pk_fma_f32 v[8:9], v[10:11], v[194:195], v[8:9] op_sel_hi:[0,1,1]
	v_pk_mul_f32 v[10:11], v[26:27], v[192:193] op_sel:[0,1] op_sel_hi:[1,0]
	v_pk_mul_f32 v[12:13], v[30:31], v[186:187] op_sel:[0,1] op_sel_hi:[1,0]
	v_xor_b32_e32 v50, 0x80000000, v41
	v_xor_b32_e32 v54, 0x80000000, v45
	v_xor_b32_e32 v58, 0x80000000, v49
	v_xor_b32_e32 v62, 0x80000000, v53
	v_xor_b32_e32 v66, 0x80000000, v57
	v_xor_b32_e32 v70, 0x80000000, v61
	v_xor_b32_e32 v74, 0x80000000, v65
	v_mov_b32_e32 v51, v41
	v_mov_b32_e32 v55, v45
	v_mov_b32_e32 v59, v49
	v_mov_b32_e32 v63, v53
	v_mov_b32_e32 v67, v57
	v_mov_b32_e32 v71, v61
	v_mov_b32_e32 v75, v65
	v_pk_add_f32 v[132:133], v[132:133], v[140:141] neg_lo:[0,1] neg_hi:[0,1]
	v_pk_add_f32 v[140:141], v[128:129], v[134:135] op_sel:[0,1] op_sel_hi:[1,0] neg_hi:[0,1]
	v_pk_fma_f32 v[10:11], v[16:17], v[192:193], v[10:11] op_sel_hi:[0,1,1]
	v_pk_fma_f32 v[12:13], v[20:21], v[186:187], v[12:13] op_sel_hi:[0,1,1]
	v_pk_mul_f32 v[14:15], v[34:35], v[156:157] op_sel:[0,1] op_sel_hi:[1,0]
	v_pk_mul_f32 v[16:17], v[38:39], v[178:179] op_sel:[0,1] op_sel_hi:[1,0]
	v_pk_mul_f32 v[20:21], v[42:43], v[180:181] op_sel:[0,1] op_sel_hi:[1,0]
	v_pk_mul_f32 v[22:23], v[46:47], v[190:191] op_sel:[0,1] op_sel_hi:[1,0]
	v_xor_b32_e32 v78, 0x80000000, v69
	v_xor_b32_e32 v82, 0x80000000, v73
	v_xor_b32_e32 v86, 0x80000000, v77
	v_xor_b32_e32 v90, 0x80000000, v81
	v_xor_b32_e32 v94, 0x80000000, v85
	v_xor_b32_e32 v98, 0x80000000, v89
	v_xor_b32_e32 v102, 0x80000000, v93
	v_xor_b32_e32 v106, 0x80000000, v97
	v_xor_b32_e32 v110, 0x80000000, v101
	v_xor_b32_e32 v114, 0x80000000, v105
	v_xor_b32_e32 v118, 0x80000000, v109
	v_xor_b32_e32 v122, 0x80000000, v113
	v_xor_b32_e32 v124, 0x80000000, v117
	v_xor_b32_e32 v126, 0x80000000, v121
	v_mov_b32_e32 v79, v69
	v_mov_b32_e32 v83, v73
	v_mov_b32_e32 v87, v77
	v_mov_b32_e32 v91, v81
	v_mov_b32_e32 v95, v85
	v_mov_b32_e32 v99, v89
	v_mov_b32_e32 v103, v93
	v_mov_b32_e32 v107, v97
	v_mov_b32_e32 v111, v101
	v_mov_b32_e32 v115, v105
	v_mov_b32_e32 v119, v109
	v_mov_b32_e32 v123, v113
	v_mov_b32_e32 v125, v117
	v_mov_b32_e32 v127, v121
	v_pk_add_f32 v[128:129], v[128:129], v[134:135] op_sel:[0,1] op_sel_hi:[1,0] neg_lo:[0,1]
	v_pk_fma_f32 v[14:15], v[24:25], v[156:157], v[14:15] op_sel_hi:[0,1,1]
	v_pk_fma_f32 v[16:17], v[28:29], v[178:179], v[16:17] op_sel_hi:[0,1,1]
	v_pk_fma_f32 v[20:21], v[32:33], v[180:181], v[20:21] op_sel_hi:[0,1,1]
	v_pk_fma_f32 v[22:23], v[36:37], v[190:191], v[22:23] op_sel_hi:[0,1,1]
	v_pk_mul_f32 v[24:25], v[50:51], v[160:161] op_sel:[0,1] op_sel_hi:[1,0]
	v_pk_mul_f32 v[26:27], v[54:55], v[188:189] op_sel:[0,1] op_sel_hi:[1,0]
	v_pk_mul_f32 v[28:29], v[58:59], v[158:159] op_sel:[0,1] op_sel_hi:[1,0]
	v_pk_mul_f32 v[30:31], v[62:63], v[174:175] op_sel:[0,1] op_sel_hi:[1,0]
	v_pk_mul_f32 v[32:33], v[66:67], v[140:141] op_sel:[0,1] op_sel_hi:[1,0]
	v_pk_mul_f32 v[34:35], v[70:71], v[142:143] op_sel:[0,1] op_sel_hi:[1,0]
	v_pk_mul_f32 v[36:37], v[74:75], v[148:149] op_sel:[0,1] op_sel_hi:[1,0]
	v_pk_fma_f32 v[24:25], v[40:41], v[160:161], v[24:25] op_sel_hi:[0,1,1]
	v_pk_fma_f32 v[26:27], v[44:45], v[188:189], v[26:27] op_sel_hi:[0,1,1]
	v_pk_fma_f32 v[28:29], v[48:49], v[158:159], v[28:29] op_sel_hi:[0,1,1]
	v_pk_fma_f32 v[30:31], v[52:53], v[174:175], v[30:31] op_sel_hi:[0,1,1]
	v_pk_fma_f32 v[32:33], v[56:57], v[140:141], v[32:33] op_sel_hi:[0,1,1]
	v_pk_fma_f32 v[34:35], v[60:61], v[142:143], v[34:35] op_sel_hi:[0,1,1]
	v_pk_fma_f32 v[36:37], v[64:65], v[148:149], v[36:37] op_sel_hi:[0,1,1]
	v_pk_mul_f32 v[38:39], v[78:79], v[170:171] op_sel:[0,1] op_sel_hi:[1,0]
	v_pk_mul_f32 v[40:41], v[82:83], v[136:137] op_sel:[0,1] op_sel_hi:[1,0]
	v_pk_mul_f32 v[42:43], v[86:87], v[164:165] op_sel:[0,1] op_sel_hi:[1,0]
	v_pk_mul_f32 v[44:45], v[90:91], v[150:151] op_sel:[0,1] op_sel_hi:[1,0]
	v_pk_mul_f32 v[46:47], v[94:95], v[166:167] op_sel:[0,1] op_sel_hi:[1,0]
	v_pk_mul_f32 v[48:49], v[98:99], v[132:133] op_sel:[0,1] op_sel_hi:[1,0]
	v_pk_mul_f32 v[50:51], v[102:103], v[162:163] op_sel:[0,1] op_sel_hi:[1,0]
	v_pk_mul_f32 v[52:53], v[106:107], v[176:177] op_sel:[0,1] op_sel_hi:[1,0]
	v_pk_mul_f32 v[54:55], v[110:111], v[172:173] op_sel:[0,1] op_sel_hi:[1,0]
	v_pk_mul_f32 v[56:57], v[114:115], v[138:139] op_sel:[0,1] op_sel_hi:[1,0]
	v_pk_mul_f32 v[58:59], v[118:119], v[182:183] op_sel:[0,1] op_sel_hi:[1,0]
	v_pk_mul_f32 v[60:61], v[122:123], v[152:153] op_sel:[0,1] op_sel_hi:[1,0]
	v_pk_mul_f32 v[62:63], v[124:125], v[144:145] op_sel:[0,1] op_sel_hi:[1,0]
	v_pk_mul_f32 v[64:65], v[126:127], v[128:129] op_sel:[0,1] op_sel_hi:[1,0]
	v_pk_fma_f32 v[38:39], v[68:69], v[170:171], v[38:39] op_sel_hi:[0,1,1]
	v_pk_fma_f32 v[40:41], v[72:73], v[136:137], v[40:41] op_sel_hi:[0,1,1]
	v_pk_fma_f32 v[42:43], v[76:77], v[164:165], v[42:43] op_sel_hi:[0,1,1]
	v_pk_fma_f32 v[44:45], v[80:81], v[150:151], v[44:45] op_sel_hi:[0,1,1]
	v_pk_fma_f32 v[46:47], v[84:85], v[166:167], v[46:47] op_sel_hi:[0,1,1]
	v_pk_fma_f32 v[48:49], v[88:89], v[132:133], v[48:49] op_sel_hi:[0,1,1]
	v_pk_fma_f32 v[50:51], v[92:93], v[162:163], v[50:51] op_sel_hi:[0,1,1]
	v_pk_fma_f32 v[52:53], v[96:97], v[176:177], v[52:53] op_sel_hi:[0,1,1]
	v_pk_fma_f32 v[54:55], v[100:101], v[172:173], v[54:55] op_sel_hi:[0,1,1]
	v_pk_fma_f32 v[56:57], v[104:105], v[138:139], v[56:57] op_sel_hi:[0,1,1]
	v_pk_fma_f32 v[58:59], v[108:109], v[182:183], v[58:59] op_sel_hi:[0,1,1]
	v_pk_fma_f32 v[60:61], v[112:113], v[152:153], v[60:61] op_sel_hi:[0,1,1]
	v_pk_fma_f32 v[62:63], v[116:117], v[144:145], v[62:63] op_sel_hi:[0,1,1]
	v_pk_fma_f32 v[64:65], v[120:121], v[128:129], v[64:65] op_sel_hi:[0,1,1]
	ds_write2_b64 v18, v[130:131], v[34:35] offset1:16
	ds_write2_b64 v18, v[16:17], v[50:51] offset0:33 offset1:49
	ds_write2_b64 v18, v[8:9], v[42:43] offset0:66 offset1:82
	ds_write2_b64 v18, v[26:27], v[58:59] offset0:99 offset1:115
	ds_write2_b64 v18, v[4:5], v[38:39] offset0:132 offset1:148
	ds_write2_b64 v18, v[22:23], v[54:55] offset0:165 offset1:181
	ds_write2_b64 v18, v[12:13], v[46:47] offset0:198 offset1:214
	ds_write2_b64 v18, v[30:31], v[62:63] offset0:231 offset1:247
	ds_write2_b64 v196, v[2:3], v[36:37] offset0:8 offset1:24
	ds_write2_b64 v196, v[20:21], v[52:53] offset0:41 offset1:57
	ds_write2_b64 v196, v[10:11], v[44:45] offset0:74 offset1:90
	ds_write2_b64 v196, v[28:29], v[60:61] offset0:107 offset1:123
	ds_write2_b64 v196, v[6:7], v[40:41] offset0:140 offset1:156
	ds_write2_b64 v196, v[24:25], v[56:57] offset0:173 offset1:189
	ds_write2_b64 v196, v[14:15], v[48:49] offset0:206 offset1:222
	ds_write2_b64 v196, v[32:33], v[64:65] offset0:239 offset1:255
	v_ashrrev_i32_e32 v2, 31, v210
	v_lshrrev_b32_e32 v2, 23, v2
	v_add_u32_e32 v2, v210, v2
	s_lshl_b64 s[74:75], s[76:77], 16
	v_and_b32_e32 v2, 0xfffffe00, v2
	s_add_u32 s0, s54, s74
	v_sub_u32_e32 v2, v210, v2
	s_addc_u32 s1, s55, s75
	v_ashrrev_i32_e32 v3, 31, v2
	v_lshl_add_u64 v[14:15], v[2:3], 3, s[0:1]
	v_add_co_u32_e32 v2, vcc, s92, v14
	s_mov_b32 s0, 0x8000
	s_nop 0
	v_addc_co_u32_e32 v3, vcc, 0, v15, vcc
	v_add_co_u32_e32 v4, vcc, s95, v14
	s_waitcnt lgkmcnt(0)
	s_nop 0
	v_addc_co_u32_e32 v5, vcc, 0, v15, vcc
	v_add_co_u32_e32 v8, vcc, s96, v14
	s_barrier
	s_nop 0
	v_addc_co_u32_e32 v9, vcc, 0, v15, vcc
	global_load_dwordx2 v[24:25], v[4:5], off offset:-4096 nt
	global_load_dwordx2 v[12:13], v[4:5], off nt
	global_load_dwordx2 v[6:7], v[8:9], off offset:-4096 nt
	s_nop 0
	global_load_dwordx2 v[4:5], v[8:9], off nt
	v_add_co_u32_e32 v8, vcc, s0, v14
	s_waitcnt vmcnt(3)
	v_cvt_f32_f16_sdwa v174, v24 dst_sel:DWORD dst_unused:UNUSED_PAD src0_sel:WORD_1
	v_addc_co_u32_e32 v9, vcc, 0, v15, vcc
	v_add_co_u32_e32 v10, vcc, s34, v14
	v_cvt_f32_f16_e32 v175, v25
	s_nop 0
	v_addc_co_u32_e32 v11, vcc, 0, v15, vcc
	global_load_dwordx2 v[16:17], v[8:9], off offset:-4096 nt
	global_load_dwordx2 v[122:123], v[8:9], off nt
	global_load_dwordx2 v[46:47], v[10:11], off offset:-4096 nt
	global_load_dwordx2 v[36:37], v[10:11], off nt
	v_add_co_u32_e32 v8, vcc, s35, v14
	v_cvt_f32_f16_sdwa v177, v25 dst_sel:DWORD dst_unused:UNUSED_PAD src0_sel:WORD_1
	s_nop 0
	v_addc_co_u32_e32 v9, vcc, 0, v15, vcc
	v_add_co_u32_e32 v22, vcc, s30, v14
	v_cvt_f32_f16_e32 v176, v24
	s_nop 0
	v_addc_co_u32_e32 v23, vcc, 0, v15, vcc
	global_load_dwordx2 v[26:27], v[8:9], off offset:-4096 nt
	global_load_dwordx2 v[20:21], v[8:9], off nt
	global_load_dwordx2 v[10:11], v[22:23], off offset:-4096 nt
	s_nop 0
	global_load_dwordx2 v[8:9], v[22:23], off nt
	v_add_co_u32_e32 v22, vcc, s31, v14
	s_waitcnt vmcnt(10)
	v_cvt_f32_f16_sdwa v164, v12 dst_sel:DWORD dst_unused:UNUSED_PAD src0_sel:WORD_1
	v_addc_co_u32_e32 v23, vcc, 0, v15, vcc
	global_load_dwordx2 v[30:31], v[2:3], off offset:-4096 nt
	global_load_dwordx2 v[28:29], v[2:3], off nt
	s_nop 0
	global_load_dwordx2 v[2:3], v[22:23], off nt
	global_load_dwordx2 v[32:33], v[14:15], off nt
	v_mov_b32_e32 v14, v210
	v_cvt_f32_f16_e32 v165, v13
	v_ashrrev_i32_e32 v15, 31, v14
	v_lshrrev_b32_e32 v15, 23, v15
	v_add_u32_e32 v15, v14, v15
	v_ashrrev_i32_e32 v15, 9, v15
	v_mul_i32_i24_e32 v18, 0x200, v15
	v_sub_u32_e32 v18, v14, v18
	v_lshlrev_b32_e32 v14, 14, v15
	v_lshlrev_b32_e32 v15, 1, v18
	v_bfrev_b32_e32 v15, v15
	v_lshrrev_b32_e32 v15, 22, v15
	v_sub_u32_e32 v15, 0x400, v15
	v_bfrev_b32_e32 v15, v15
	v_lshrrev_b32_e32 v15, 18, v15
	v_and_b32_e32 v15, 0x3ff0, v15
	v_cmp_eq_u32_e64 s[0:1], 0, v18
	v_lshl_add_u32 v22, v18, 5, v14
	v_lshl_add_u32 v23, v22, 3, 0
	v_cndmask_b32_e64 v15, v15, 16, s[0:1]
	v_or_b32_e32 v14, v15, v14
	v_ashrrev_i32_e32 v22, 2, v22
	v_ashrrev_i32_e32 v15, 5, v14
	v_add_u32_e32 v211, v23, v22
	v_lshlrev_b32_e32 v14, 3, v14
	v_lshlrev_b32_e32 v15, 3, v15
	v_add3_u32 v212, 0, v14, v15
	ds_read2_b64 v[38:41], v211 offset1:1
	ds_read2_b64 v[42:45], v211 offset0:2 offset1:3
	ds_read2_b64 v[48:51], v212 offset1:1
	ds_read2_b64 v[52:55], v212 offset0:2 offset1:3
	ds_read2_b64 v[56:59], v211 offset0:4 offset1:5
	ds_read2_b64 v[60:63], v211 offset0:6 offset1:7
	ds_read2_b64 v[68:71], v212 offset0:4 offset1:5
	ds_read2_b64 v[72:75], v212 offset0:6 offset1:7
	ds_read2_b64 v[64:67], v211 offset0:8 offset1:9
	ds_read2_b64 v[76:79], v211 offset0:10 offset1:11
	ds_read2_b64 v[80:83], v212 offset0:8 offset1:9
	ds_read2_b64 v[98:101], v212 offset0:10 offset1:11
	ds_read2_b64 v[84:87], v211 offset0:12 offset1:13
	ds_read2_b64 v[88:91], v211 offset0:14 offset1:15
	ds_read2_b64 v[102:105], v212 offset0:12 offset1:13
	ds_read2_b64 v[106:109], v212 offset0:14 offset1:15
	s_waitcnt lgkmcnt(7)
	v_pk_add_f32 v[14:15], v[38:39], v[64:65]
	v_pk_add_f32 v[22:23], v[38:39], v[64:65] neg_lo:[0,1] neg_hi:[0,1]
	v_pk_add_f32 v[38:39], v[40:41], v[66:67] neg_lo:[0,1] neg_hi:[0,1]
	v_pk_add_f32 v[34:35], v[40:41], v[66:67]
	v_pk_mul_f32 v[40:41], v[38:39], s[18:19]
	v_cmp_ne_u32_e32 vcc, 0, v18
	v_pk_fma_f32 v[38:39], v[38:39], s[16:17], v[40:41] op_sel:[0,0,1] op_sel_hi:[1,0,0]
	s_waitcnt lgkmcnt(6)
	v_pk_add_f32 v[40:41], v[42:43], v[76:77]
	v_pk_add_f32 v[42:43], v[42:43], v[76:77] neg_lo:[0,1] neg_hi:[0,1]
	v_bfrev_b32_e32 v18, v18
	v_pk_mul_f32 v[64:65], v[42:43], s[36:37]
	v_lshrrev_b32_e32 v18, 23, v18
	v_pk_fma_f32 v[42:43], v[42:43], s[78:79], v[64:65] op_sel:[0,0,1] op_sel_hi:[1,0,0]
	v_pk_add_f32 v[64:65], v[44:45], v[78:79]
	v_pk_add_f32 v[44:45], v[44:45], v[78:79] neg_lo:[0,1] neg_hi:[0,1]
	s_waitcnt lgkmcnt(3)
	v_pk_add_f32 v[78:79], v[58:59], v[86:87]
	v_pk_mul_f32 v[66:67], v[44:45], s[40:41]
	v_pk_add_f32 v[58:59], v[58:59], v[86:87] neg_lo:[0,1] neg_hi:[0,1]
	v_pk_fma_f32 v[44:45], v[44:45], s[80:81], v[66:67] op_sel:[0,0,1] op_sel_hi:[1,0,0]
	v_pk_add_f32 v[66:67], v[56:57], v[84:85]
	v_pk_add_f32 v[76:77], v[56:57], v[84:85] neg_lo:[0,1] neg_hi:[0,1]
	v_pk_mul_f32 v[84:85], v[58:59], s[40:41]
	s_nop 0
	v_pk_fma_f32 v[58:59], v[58:59], s[80:81], v[84:85] op_sel:[0,0,1] op_sel_hi:[1,0,0] neg_lo:[1,0,0] neg_hi:[1,0,0]
	s_waitcnt lgkmcnt(2)
	v_pk_add_f32 v[84:85], v[60:61], v[88:89]
	v_pk_add_f32 v[60:61], v[60:61], v[88:89] neg_lo:[0,1] neg_hi:[0,1]
	s_nop 0
	v_pk_mul_f32 v[86:87], v[60:61], s[36:37]
	v_pk_add_f32 v[56:57], v[22:23], v[76:77] op_sel:[0,1] op_sel_hi:[1,0] neg_hi:[0,1]
	v_pk_fma_f32 v[60:61], v[60:61], s[78:79], v[86:87] op_sel:[0,0,1] op_sel_hi:[1,0,0] neg_lo:[1,0,0] neg_hi:[1,0,0]
	v_pk_add_f32 v[86:87], v[62:63], v[90:91]
	v_pk_add_f32 v[62:63], v[62:63], v[90:91] neg_lo:[0,1] neg_hi:[0,1]
	v_pk_add_f32 v[90:91], v[64:65], v[86:87]
	v_pk_mul_f32 v[88:89], v[62:63], s[18:19]
	v_pk_add_f32 v[64:65], v[64:65], v[86:87] neg_lo:[0,1] neg_hi:[0,1]
	v_pk_fma_f32 v[62:63], v[62:63], s[16:17], v[88:89] op_sel:[0,0,1] op_sel_hi:[1,0,0] neg_lo:[1,0,0] neg_hi:[1,0,0]
	v_pk_add_f32 v[88:89], v[14:15], v[66:67]
	v_pk_add_f32 v[14:15], v[14:15], v[66:67] neg_lo:[0,1] neg_hi:[0,1]
	v_pk_add_f32 v[66:67], v[34:35], v[78:79]
	v_pk_add_f32 v[34:35], v[34:35], v[78:79] neg_lo:[0,1] neg_hi:[0,1]
	v_pk_add_f32 v[22:23], v[22:23], v[76:77] op_sel:[0,1] op_sel_hi:[1,0] neg_lo:[0,1]
	v_pk_mul_f32 v[78:79], v[34:35], s[36:37]
	v_pk_add_f32 v[76:77], v[38:39], v[58:59]
	v_pk_add_f32 v[38:39], v[38:39], v[58:59] neg_lo:[0,1] neg_hi:[0,1]
	v_pk_fma_f32 v[34:35], v[34:35], s[78:79], v[78:79] op_sel:[0,0,1] op_sel_hi:[1,0,0]
	v_pk_add_f32 v[78:79], v[40:41], v[84:85]
	v_pk_add_f32 v[84:85], v[40:41], v[84:85] neg_lo:[0,1] neg_hi:[0,1]
	v_pk_mul_f32 v[86:87], v[64:65], s[36:37]
	v_pk_mul_f32 v[58:59], v[38:39], s[36:37]
	v_pk_fma_f32 v[64:65], v[64:65], s[78:79], v[86:87] op_sel:[0,0,1] op_sel_hi:[1,0,0] neg_lo:[1,0,0] neg_hi:[1,0,0]
	v_pk_fma_f32 v[38:39], v[38:39], s[78:79], v[58:59] op_sel:[0,0,1] op_sel_hi:[1,0,0]
	v_pk_add_f32 v[58:59], v[42:43], v[60:61]
	v_pk_add_f32 v[86:87], v[44:45], v[62:63]
	v_pk_add_f32 v[44:45], v[44:45], v[62:63] neg_lo:[0,1] neg_hi:[0,1]
	s_nop 0
	v_pk_mul_f32 v[62:63], v[44:45], s[36:37]
	v_pk_add_f32 v[40:41], v[14:15], v[84:85] op_sel:[0,1] op_sel_hi:[1,0] neg_hi:[0,1]
	v_pk_add_f32 v[14:15], v[14:15], v[84:85] op_sel:[0,1] op_sel_hi:[1,0] neg_lo:[0,1]
	v_pk_add_f32 v[84:85], v[34:35], v[64:65]
	v_pk_add_f32 v[64:65], v[34:35], v[64:65] neg_lo:[0,1] neg_hi:[0,1]
	v_pk_add_f32 v[94:95], v[56:57], v[58:59]
	v_pk_add_f32 v[56:57], v[56:57], v[58:59] neg_lo:[0,1] neg_hi:[0,1]
	v_pk_add_f32 v[58:59], v[76:77], v[86:87]
	v_pk_fma_f32 v[44:45], v[44:45], s[78:79], v[62:63] op_sel:[0,0,1] op_sel_hi:[1,0,0] neg_lo:[1,0,0] neg_hi:[1,0,0]
	v_pk_add_f32 v[62:63], v[88:89], v[78:79]
	v_pk_add_f32 v[78:79], v[88:89], v[78:79] neg_lo:[0,1] neg_hi:[0,1]
	v_pk_add_f32 v[88:89], v[66:67], v[90:91]
	v_pk_add_f32 v[110:111], v[76:77], v[86:87] neg_lo:[0,1] neg_hi:[0,1]
	v_pk_add_f32 v[86:87], v[94:95], v[58:59]
	v_pk_add_f32 v[34:35], v[94:95], v[58:59] neg_lo:[0,1] neg_hi:[0,1]
	v_pk_add_f32 v[58:59], v[50:51], v[82:83]
	v_pk_add_f32 v[50:51], v[50:51], v[82:83] neg_lo:[0,1] neg_hi:[0,1]
	v_pk_add_f32 v[60:61], v[42:43], v[60:61] neg_lo:[0,1] neg_hi:[0,1]
	v_pk_add_f32 v[148:149], v[62:63], v[88:89]
	v_pk_add_f32 v[138:139], v[62:63], v[88:89] neg_lo:[0,1] neg_hi:[0,1]
	v_pk_mul_f32 v[62:63], v[50:51], s[18:19]
	v_pk_add_f32 v[90:91], v[66:67], v[90:91] neg_lo:[0,1] neg_hi:[0,1]
	v_pk_fma_f32 v[50:51], v[50:51], s[16:17], v[62:63] op_sel:[0,0,1] op_sel_hi:[1,0,0]
	v_pk_add_f32 v[62:63], v[52:53], v[98:99]
	v_pk_add_f32 v[52:53], v[52:53], v[98:99] neg_lo:[0,1] neg_hi:[0,1]
	v_pk_add_f32 v[112:113], v[22:23], v[60:61] op_sel:[0,1] op_sel_hi:[1,0] neg_hi:[0,1]
	v_pk_add_f32 v[114:115], v[22:23], v[60:61] op_sel:[0,1] op_sel_hi:[1,0] neg_lo:[0,1]
	v_pk_add_f32 v[96:97], v[40:41], v[84:85]
	v_pk_add_f32 v[66:67], v[40:41], v[84:85] neg_lo:[0,1] neg_hi:[0,1]
	v_pk_add_f32 v[60:61], v[14:15], v[64:65] op_sel:[0,1] op_sel_hi:[1,0] neg_hi:[0,1]
	v_pk_add_f32 v[84:85], v[14:15], v[64:65] op_sel:[0,1] op_sel_hi:[1,0] neg_lo:[0,1]
	v_pk_mul_f32 v[64:65], v[52:53], s[36:37]
	s_nop 0
	v_pk_fma_f32 v[52:53], v[52:53], s[78:79], v[64:65] op_sel:[0,0,1] op_sel_hi:[1,0,0]
	v_pk_add_f32 v[64:65], v[54:55], v[100:101]
	v_pk_add_f32 v[54:55], v[54:55], v[100:101] neg_lo:[0,1] neg_hi:[0,1]
	s_nop 0
	v_pk_mul_f32 v[76:77], v[54:55], s[40:41]
	v_pk_add_f32 v[92:93], v[78:79], v[90:91] op_sel:[0,1] op_sel_hi:[1,0] neg_hi:[0,1]
	v_pk_fma_f32 v[54:55], v[54:55], s[80:81], v[76:77] op_sel:[0,0,1] op_sel_hi:[1,0,0]
	s_waitcnt lgkmcnt(1)
	v_pk_add_f32 v[76:77], v[68:69], v[102:103]
	v_pk_add_f32 v[88:89], v[78:79], v[90:91] op_sel:[0,1] op_sel_hi:[1,0] neg_lo:[0,1]
	v_pk_add_f32 v[78:79], v[68:69], v[102:103] neg_lo:[0,1] neg_hi:[0,1]
	v_pk_add_f32 v[68:69], v[70:71], v[104:105]
	v_pk_add_f32 v[70:71], v[70:71], v[104:105] neg_lo:[0,1] neg_hi:[0,1]
	v_pk_add_f32 v[22:23], v[38:39], v[44:45]
	v_pk_add_f32 v[116:117], v[38:39], v[44:45] neg_lo:[0,1] neg_hi:[0,1]
	v_pk_add_f32 v[40:41], v[56:57], v[110:111] op_sel:[0,1] op_sel_hi:[1,0] neg_hi:[0,1]
	v_pk_add_f32 v[44:45], v[56:57], v[110:111] op_sel:[0,1] op_sel_hi:[1,0] neg_lo:[0,1]
	v_pk_add_f32 v[56:57], v[48:49], v[80:81]
	v_pk_add_f32 v[48:49], v[48:49], v[80:81] neg_lo:[0,1] neg_hi:[0,1]
	v_pk_mul_f32 v[80:81], v[70:71], s[40:41]
	v_cvt_f32_u32_e32 v18, v18
	v_pk_fma_f32 v[70:71], v[70:71], s[80:81], v[80:81] op_sel:[0,0,1] op_sel_hi:[1,0,0] neg_lo:[1,0,0] neg_hi:[1,0,0]
	s_waitcnt lgkmcnt(0)
	v_pk_add_f32 v[80:81], v[72:73], v[106:107]
	v_pk_add_f32 v[72:73], v[72:73], v[106:107] neg_lo:[0,1] neg_hi:[0,1]
	v_mul_f32_e32 v18, 0x38000000, v18
	v_pk_mul_f32 v[82:83], v[72:73], s[36:37]
	v_cndmask_b32_e64 v18, v18, v208, s[0:1]
	v_pk_fma_f32 v[72:73], v[72:73], s[78:79], v[82:83] op_sel:[0,0,1] op_sel_hi:[1,0,0] neg_lo:[1,0,0] neg_hi:[1,0,0]
	v_pk_add_f32 v[82:83], v[74:75], v[108:109]
	v_pk_add_f32 v[74:75], v[74:75], v[108:109] neg_lo:[0,1] neg_hi:[0,1]
	s_nop 0
	v_pk_mul_f32 v[90:91], v[74:75], s[18:19]
	s_nop 0
	v_pk_fma_f32 v[74:75], v[74:75], s[16:17], v[90:91] op_sel:[0,0,1] op_sel_hi:[1,0,0] neg_lo:[1,0,0] neg_hi:[1,0,0]
	v_pk_add_f32 v[90:91], v[56:57], v[76:77]
	v_pk_add_f32 v[56:57], v[56:57], v[76:77] neg_lo:[0,1] neg_hi:[0,1]
	v_pk_add_f32 v[76:77], v[58:59], v[68:69]
	v_pk_add_f32 v[58:59], v[58:59], v[68:69] neg_lo:[0,1] neg_hi:[0,1]
	v_pk_add_f32 v[14:15], v[114:115], v[116:117] op_sel:[0,1] op_sel_hi:[1,0] neg_hi:[0,1]
	v_pk_mul_f32 v[68:69], v[58:59], s[36:37]
	v_pk_add_f32 v[38:39], v[114:115], v[116:117] op_sel:[0,1] op_sel_hi:[1,0] neg_lo:[0,1]
	v_pk_fma_f32 v[58:59], v[58:59], s[78:79], v[68:69] op_sel:[0,0,1] op_sel_hi:[1,0,0]
	v_pk_add_f32 v[68:69], v[62:63], v[80:81]
	v_pk_add_f32 v[80:81], v[62:63], v[80:81] neg_lo:[0,1] neg_hi:[0,1]
	s_waitcnt vmcnt(0)
	v_cvt_f32_f16_e32 v193, v33
	s_nop 0
	s_nop 0
	v_pk_add_f32 v[62:63], v[64:65], v[82:83]
	v_pk_add_f32 v[64:65], v[64:65], v[82:83] neg_lo:[0,1] neg_hi:[0,1]
	v_cvt_f32_f16_sdwa v192, v32 dst_sel:DWORD dst_unused:UNUSED_PAD src0_sel:WORD_1
	v_pk_mul_f32 v[82:83], v[64:65], s[36:37]
	v_cvt_f32_f16_e32 v194, v32
	v_pk_fma_f32 v[64:65], v[64:65], s[78:79], v[82:83] op_sel:[0,0,1] op_sel_hi:[1,0,0] neg_lo:[1,0,0] neg_hi:[1,0,0]
	v_pk_add_f32 v[82:83], v[48:49], v[78:79] op_sel:[0,1] op_sel_hi:[1,0] neg_hi:[0,1]
	v_pk_add_f32 v[48:49], v[48:49], v[78:79] op_sel:[0,1] op_sel_hi:[1,0] neg_lo:[0,1]
	v_pk_add_f32 v[78:79], v[50:51], v[70:71]
	v_pk_add_f32 v[50:51], v[50:51], v[70:71] neg_lo:[0,1] neg_hi:[0,1]
	v_cvt_f32_f16_sdwa v195, v33 dst_sel:DWORD dst_unused:UNUSED_PAD src0_sel:WORD_1
	v_pk_mul_f32 v[70:71], v[50:51], s[36:37]
	v_cvt_f32_f16_sdwa v170, v30 dst_sel:DWORD dst_unused:UNUSED_PAD src0_sel:WORD_1
	v_pk_fma_f32 v[50:51], v[50:51], s[78:79], v[70:71] op_sel:[0,0,1] op_sel_hi:[1,0,0]
	v_pk_add_f32 v[70:71], v[52:53], v[72:73]
	v_pk_add_f32 v[72:73], v[52:53], v[72:73] neg_lo:[0,1] neg_hi:[0,1]
	v_cvt_f32_f16_e32 v171, v31
	s_nop 0
	s_nop 0
	v_pk_add_f32 v[52:53], v[54:55], v[74:75]
	v_pk_add_f32 v[54:55], v[54:55], v[74:75] neg_lo:[0,1] neg_hi:[0,1]
	v_cvt_f32_f16_sdwa v185, v31 dst_sel:DWORD dst_unused:UNUSED_PAD src0_sel:WORD_1
	v_pk_mul_f32 v[74:75], v[54:55], s[36:37]
	v_cvt_f32_f16_e32 v184, v30
	v_pk_fma_f32 v[54:55], v[54:55], s[78:79], v[74:75] op_sel:[0,0,1] op_sel_hi:[1,0,0] neg_lo:[1,0,0] neg_hi:[1,0,0]
	v_pk_add_f32 v[74:75], v[90:91], v[68:69]
	v_pk_add_f32 v[68:69], v[90:91], v[68:69] neg_lo:[0,1] neg_hi:[0,1]
	v_pk_add_f32 v[90:91], v[76:77], v[62:63]
	v_pk_add_f32 v[62:63], v[76:77], v[62:63] neg_lo:[0,1] neg_hi:[0,1]
	v_cvt_f32_f16_sdwa v172, v28 dst_sel:DWORD dst_unused:UNUSED_PAD src0_sel:WORD_1
	v_xor_b32_e32 v77, 0x80000000, v62
	v_mov_b32_e32 v76, v63
	v_pk_add_f32 v[62:63], v[56:57], v[80:81] op_sel:[0,1] op_sel_hi:[1,0] neg_hi:[0,1]
	v_pk_add_f32 v[56:57], v[56:57], v[80:81] op_sel:[0,1] op_sel_hi:[1,0] neg_lo:[0,1]
	v_pk_add_f32 v[80:81], v[58:59], v[64:65]
	v_pk_add_f32 v[58:59], v[58:59], v[64:65] neg_lo:[0,1] neg_hi:[0,1]
	v_cvt_f32_f16_e32 v173, v29
	v_xor_b32_e32 v65, 0x80000000, v58
	v_mov_b32_e32 v64, v59
	v_pk_add_f32 v[58:59], v[82:83], v[70:71]
	v_pk_add_f32 v[70:71], v[82:83], v[70:71] neg_lo:[0,1] neg_hi:[0,1]
	v_pk_add_f32 v[82:83], v[78:79], v[52:53]
	v_pk_add_f32 v[52:53], v[78:79], v[52:53] neg_lo:[0,1] neg_hi:[0,1]
	v_pk_add_f32 v[118:119], v[58:59], v[82:83]
	v_pk_add_f32 v[134:135], v[58:59], v[82:83] neg_lo:[0,1] neg_hi:[0,1]
	v_cos_f32_e32 v83, v18
	v_sin_f32_e32 v82, v18
	v_cvt_f32_f16_sdwa v181, v29 dst_sel:DWORD dst_unused:UNUSED_PAD src0_sel:WORD_1
	v_cvt_f32_f16_e32 v180, v28
	v_cvt_f32_f16_sdwa v167, v13 dst_sel:DWORD dst_unused:UNUSED_PAD src0_sel:WORD_1
	v_cvt_f32_f16_e32 v166, v12
	v_cvt_f32_f16_e32 v154, v6
	v_cvt_f32_f16_e32 v155, v7
	v_cvt_f32_f16_sdwa v157, v7 dst_sel:DWORD dst_unused:UNUSED_PAD src0_sel:WORD_1
	v_cvt_f32_f16_sdwa v156, v6 dst_sel:DWORD dst_unused:UNUSED_PAD src0_sel:WORD_1
	v_cvt_f32_f16_sdwa v140, v4 dst_sel:DWORD dst_unused:UNUSED_PAD src0_sel:WORD_1
	v_cvt_f32_f16_e32 v141, v5
	v_cvt_f32_f16_sdwa v143, v5 dst_sel:DWORD dst_unused:UNUSED_PAD src0_sel:WORD_1
	v_cvt_f32_f16_e32 v142, v4
	v_cvt_f32_f16_e32 v124, v16
	v_cvt_f32_f16_e32 v125, v17
	v_cvt_f32_f16_sdwa v127, v17 dst_sel:DWORD dst_unused:UNUSED_PAD src0_sel:WORD_1
	v_cvt_f32_f16_sdwa v126, v16 dst_sel:DWORD dst_unused:UNUSED_PAD src0_sel:WORD_1
	v_cvt_f32_f16_sdwa v114, v122 dst_sel:DWORD dst_unused:UNUSED_PAD src0_sel:WORD_1
	v_cvt_f32_f16_e32 v115, v123
	v_cvt_f32_f16_sdwa v117, v123 dst_sel:DWORD dst_unused:UNUSED_PAD src0_sel:WORD_1
	v_cvt_f32_f16_e32 v116, v122
	v_xor_b32_e32 v79, 0x80000000, v52
	v_mov_b32_e32 v78, v53
	v_pk_add_f32 v[52:53], v[48:49], v[72:73] op_sel:[0,1] op_sel_hi:[1,0] neg_hi:[0,1]
	v_pk_add_f32 v[48:49], v[48:49], v[72:73] op_sel:[0,1] op_sel_hi:[1,0] neg_lo:[0,1]
	v_pk_add_f32 v[72:73], v[50:51], v[54:55]
	v_pk_add_f32 v[50:51], v[50:51], v[54:55] neg_lo:[0,1] neg_hi:[0,1]
	v_pk_fma_f32 v[160:161], v[82:83], 0, v[82:83] op_sel:[0,0,1] op_sel_hi:[1,0,0] neg_lo:[1,0,0] neg_hi:[1,0,0]
	v_xor_b32_e32 v55, 0x80000000, v50
	v_mov_b32_e32 v54, v51
	v_pk_fma_f32 v[198:199], v[82:83], 0, v[82:83] op_sel:[0,0,1] op_sel_hi:[1,0,0]
	v_pk_add_f32 v[42:43], v[112:113], v[22:23]
	v_pk_add_f32 v[22:23], v[112:113], v[22:23] neg_lo:[0,1] neg_hi:[0,1]
	v_pk_add_f32 v[98:99], v[74:75], v[90:91]
	v_pk_add_f32 v[100:101], v[74:75], v[90:91] neg_lo:[0,1] neg_hi:[0,1]
	v_pk_add_f32 v[102:103], v[68:69], v[76:77]
	v_pk_add_f32 v[106:107], v[68:69], v[76:77] neg_lo:[0,1] neg_hi:[0,1]
	v_pk_add_f32 v[104:105], v[62:63], v[80:81]
	v_pk_add_f32 v[108:109], v[62:63], v[80:81] neg_lo:[0,1] neg_hi:[0,1]
	v_pk_add_f32 v[110:111], v[56:57], v[64:65]
	v_pk_add_f32 v[112:113], v[56:57], v[64:65] neg_lo:[0,1] neg_hi:[0,1]
	v_pk_add_f32 v[152:153], v[70:71], v[78:79]
	v_pk_add_f32 v[162:163], v[70:71], v[78:79] neg_lo:[0,1] neg_hi:[0,1]
	v_pk_add_f32 v[178:179], v[52:53], v[72:73]
	v_pk_add_f32 v[182:183], v[52:53], v[72:73] neg_lo:[0,1] neg_hi:[0,1]
	v_pk_add_f32 v[188:189], v[48:49], v[54:55]
	v_pk_add_f32 v[196:197], v[48:49], v[54:55] neg_lo:[0,1] neg_hi:[0,1]
	v_pk_mul_f32 v[186:187], v[82:83], 0 op_sel_hi:[1,0]
	v_mov_b32_e32 v190, v160
	v_mov_b32_e32 v191, v199
	v_mul_f32_e32 v18, 0x3f3504f3, v83
	v_mul_f32_e32 v158, 0xbec3ef15, v83
	v_mul_f32_e32 v132, 0xbf6c835e, v83
	s_and_saveexec_b64 s[0:1], vcc
	s_xor_b64 s[0:1], exec, s[0:1]
	s_cbranch_execz .LBB0_501
	v_pk_add_f32 v[4:5], v[148:149], v[196:197]
	v_pk_add_f32 v[6:7], v[148:149], v[196:197] neg_lo:[0,1] neg_hi:[0,1]
	v_mul_f32_e32 v4, 0.5, v4
	v_mul_f32_e32 v12, 0.5, v7
	v_mov_b32_e32 v7, v5
	v_pk_mul_f32 v[6:7], v[6:7], s[44:45]
	v_pk_mov_b32 v[16:17], v[198:199], v[160:161] op_sel:[1,0]
	v_pk_mul_f32 v[24:25], v[190:191], v[6:7] op_sel:[0,1] op_sel_hi:[1,0]
	v_pk_mul_f32 v[6:7], v[190:191], v[6:7]
	v_pk_add_f32 v[24:25], v[24:25], v[24:25] op_sel:[0,1] op_sel_hi:[0,1]
	v_pk_add_f32 v[28:29], v[4:5], v[24:25] op_sel_hi:[0,1] neg_hi:[0,1]
	v_pk_add_f32 v[4:5], v[6:7], v[6:7] op_sel:[0,1] op_sel_hi:[0,1] neg_lo:[0,1] neg_hi:[0,1]
	v_pk_add_f32 v[6:7], v[12:13], v[4:5] op_sel_hi:[0,1] neg_hi:[0,1]
	v_pk_mul_f32 v[4:5], v[6:7], v[194:195]
	v_pk_mul_f32 v[6:7], v[6:7], v[192:193]
	v_pk_fma_f32 v[4:5], v[28:29], v[192:193], v[4:5]
	v_pk_fma_f32 v[6:7], v[28:29], v[194:195], v[6:7] neg_lo:[0,0,1] neg_hi:[0,0,1]
	s_mov_b32 s78, s19
	v_pk_add_f32 v[12:13], v[6:7], v[4:5] op_sel:[0,1] op_sel_hi:[1,0] neg_lo:[0,1]
	v_pk_add_f32 v[28:29], v[6:7], v[4:5] op_sel:[0,1] op_sel_hi:[1,0]
	v_pk_add_f32 v[4:5], v[4:5], v[6:7] op_sel:[1,0] op_sel_hi:[0,1] neg_lo:[0,1] neg_hi:[0,1]
	s_nop 0
	v_pk_mul_f32 v[12:13], v[12:13], 0.5 op_sel_hi:[1,0]
	v_mov_b32_e32 v29, v5
	v_mul_f32_e32 v24, v190, v12
	v_pk_fma_f32 v[30:31], v[190:191], v[12:13], v[24:25] op_sel_hi:[1,1,0] neg_lo:[1,0,0] neg_hi:[1,0,0]
	v_mul_f32_e32 v24, v160, v13
	v_pk_fma_f32 v[12:13], v[16:17], v[12:13], v[24:25] op_sel_hi:[1,1,0]
	v_mov_b32_e32 v16, v83
	v_mov_b32_e32 v30, v12
	v_pk_fma_f32 v[4:5], v[28:29], 0.5, v[12:13] op_sel_hi:[1,0,1] neg_lo:[0,0,1] neg_hi:[0,0,1]
	v_pk_fma_f32 v[122:123], v[28:29], 0.5, v[30:31] op_sel_hi:[1,0,1]
	v_pk_fma_f32 v[6:7], v[28:29], 0.5, v[30:31] op_sel_hi:[1,0,1] neg_lo:[1,0,0] neg_hi:[1,0,0]
	v_mov_b32_e32 v5, v123
	v_pk_mul_f32 v[24:25], v[4:5], s[6:7] op_sel_hi:[1,0]
	v_pk_add_f32 v[4:5], v[138:139], v[188:189]
	v_pk_add_f32 v[12:13], v[138:139], v[188:189] neg_lo:[0,1] neg_hi:[0,1]
	v_mov_b32_e32 v17, v82
	v_mul_f32_e32 v6, 0.5, v13
	v_pk_add_f32 v[28:29], v[186:187], v[16:17] neg_lo:[0,1] neg_hi:[0,1]
	v_pk_add_f32 v[30:31], v[186:187], v[16:17]
	v_mov_b32_e32 v13, v5
	v_pk_mov_b32 v[32:33], v[28:29], v[30:31] op_sel:[1,0]
	v_pk_mul_f32 v[12:13], v[12:13], s[44:45]
	v_mul_f32_e32 v4, 0.5, v4
	v_pk_mul_f32 v[48:49], v[32:33], v[12:13] op_sel:[0,1] op_sel_hi:[1,0]
	v_pk_mul_f32 v[12:13], v[32:33], v[12:13]
	v_pk_add_f32 v[48:49], v[48:49], v[48:49] op_sel:[0,1] op_sel_hi:[0,1]
	v_pk_add_f32 v[50:51], v[4:5], v[48:49] op_sel_hi:[0,1] neg_hi:[0,1]
	v_pk_add_f32 v[4:5], v[12:13], v[12:13] op_sel:[0,1] op_sel_hi:[0,1] neg_lo:[0,1] neg_hi:[0,1]
	v_pk_add_f32 v[12:13], v[6:7], v[4:5] op_sel_hi:[0,1] neg_hi:[0,1]
	v_pk_mul_f32 v[4:5], v[12:13], v[184:185]
	v_pk_mul_f32 v[12:13], v[12:13], v[170:171]
	v_pk_fma_f32 v[4:5], v[50:51], v[170:171], v[4:5]
	v_pk_fma_f32 v[12:13], v[50:51], v[184:185], v[12:13] neg_lo:[0,0,1] neg_hi:[0,0,1]
	v_mov_b32_e32 v31, v29
	v_pk_add_f32 v[48:49], v[12:13], v[4:5] op_sel:[0,1] op_sel_hi:[1,0] neg_lo:[0,1]
	v_pk_add_f32 v[50:51], v[12:13], v[4:5] op_sel:[0,1] op_sel_hi:[1,0]
	v_pk_add_f32 v[4:5], v[4:5], v[12:13] op_sel:[1,0] op_sel_hi:[0,1] neg_lo:[0,1] neg_hi:[0,1]
	v_pk_mul_f32 v[48:49], v[48:49], 0.5 op_sel_hi:[1,0]
	v_mov_b32_e32 v51, v5
	v_mul_f32_e32 v6, v29, v48
	v_pk_fma_f32 v[32:33], v[32:33], v[48:49], v[6:7] op_sel_hi:[1,1,0] neg_lo:[1,0,0] neg_hi:[1,0,0]
	v_mul_f32_e32 v6, v29, v49
	v_pk_fma_f32 v[28:29], v[30:31], v[48:49], v[6:7] op_sel_hi:[1,1,0]
	v_pk_mul_f32 v[12:13], v[16:17], s[36:37]
	v_mov_b32_e32 v32, v28
	v_pk_fma_f32 v[4:5], v[50:51], 0.5, v[28:29] op_sel_hi:[1,0,1] neg_lo:[0,0,1] neg_hi:[0,0,1]
	v_pk_fma_f32 v[138:139], v[50:51], 0.5, v[32:33] op_sel_hi:[1,0,1]
	v_pk_add_f32 v[16:17], v[92:93], v[182:183]
	v_mov_b32_e32 v5, v139
	v_pk_add_f32 v[28:29], v[92:93], v[182:183] neg_lo:[0,1] neg_hi:[0,1]
	v_pk_mul_f32 v[30:31], v[4:5], s[6:7] op_sel_hi:[1,0]
	v_pk_fma_f32 v[4:5], v[50:51], 0.5, v[32:33] op_sel_hi:[1,0,1] neg_lo:[1,0,0] neg_hi:[1,0,0]
	v_mul_f32_e32 v6, 0.5, v29
	v_pk_add_f32 v[32:33], v[18:19], v[12:13] op_sel:[0,1] op_sel_hi:[0,1] neg_lo:[0,1] neg_hi:[0,1]
	v_pk_add_f32 v[48:49], v[18:19], v[12:13] op_sel:[0,1] op_sel_hi:[0,1]
	v_mov_b32_e32 v29, v17
	v_mul_f32_e32 v4, 0.5, v16
	v_mov_b32_e32 v50, v32
	v_mov_b32_e32 v51, v49
	v_pk_mul_f32 v[16:17], v[28:29], s[44:45]
	v_pk_mov_b32 v[48:49], v[48:49], v[32:33] op_sel:[1,0]
	v_pk_mul_f32 v[28:29], v[50:51], v[16:17] op_sel:[0,1] op_sel_hi:[1,0]
	v_pk_mul_f32 v[16:17], v[50:51], v[16:17]
	v_pk_add_f32 v[28:29], v[28:29], v[28:29] op_sel:[0,1] op_sel_hi:[0,1]
	v_pk_add_f32 v[52:53], v[4:5], v[28:29] op_sel_hi:[0,1] neg_hi:[0,1]
	v_pk_add_f32 v[16:17], v[16:17], v[16:17] op_sel:[0,1] op_sel_hi:[0,1] neg_lo:[0,1] neg_hi:[0,1]
	v_pk_add_f32 v[28:29], v[6:7], v[16:17] op_sel_hi:[0,1] neg_hi:[0,1]
	v_pk_mul_f32 v[16:17], v[28:29], v[180:181]
	v_pk_mul_f32 v[28:29], v[28:29], v[172:173]
	v_pk_fma_f32 v[16:17], v[52:53], v[172:173], v[16:17]
	v_pk_fma_f32 v[28:29], v[52:53], v[180:181], v[28:29] neg_lo:[0,0,1] neg_hi:[0,0,1]
	v_sub_f32_e32 v6, v89, v179
	v_pk_add_f32 v[52:53], v[28:29], v[16:17] op_sel:[0,1] op_sel_hi:[1,0] neg_lo:[0,1]
	v_pk_add_f32 v[54:55], v[28:29], v[16:17] op_sel:[0,1] op_sel_hi:[1,0]
	v_pk_add_f32 v[16:17], v[16:17], v[28:29] op_sel:[1,0] op_sel_hi:[0,1] neg_lo:[0,1] neg_hi:[0,1]
	v_pk_mul_f32 v[52:53], v[52:53], 0.5 op_sel_hi:[1,0]
	v_mov_b32_e32 v55, v17
	v_mul_f32_e32 v4, v32, v52
	v_pk_fma_f32 v[56:57], v[50:51], v[52:53], v[4:5] op_sel_hi:[1,1,0] neg_lo:[1,0,0] neg_hi:[1,0,0]
	v_mul_f32_e32 v4, v32, v53
	v_pk_fma_f32 v[48:49], v[48:49], v[52:53], v[4:5] op_sel_hi:[1,1,0]
	v_pk_add_f32 v[28:29], v[88:89], v[178:179]
	v_mov_b32_e32 v56, v48
	v_pk_fma_f32 v[16:17], v[54:55], 0.5, v[48:49] op_sel_hi:[1,0,1] neg_lo:[0,0,1] neg_hi:[0,0,1]
	v_mov_b32_e32 v48, v12
	v_mov_b32_e32 v49, v88
	v_pk_mov_b32 v[12:13], v[12:13], v[178:179] op_sel:[1,0]
	v_mul_f32_e32 v18, 0.5, v29
	v_pk_add_f32 v[12:13], v[48:49], v[12:13] neg_lo:[0,1] neg_hi:[0,1]
	v_mul_f32_e32 v4, 0.5, v28
	v_pk_mul_f32 v[48:49], v[12:13], v[18:19]
	v_mov_b32_e32 v13, v32
	v_pk_fma_f32 v[50:51], v[50:51], v[48:49], v[48:49] op_sel:[0,1,0] op_sel_hi:[1,0,1]
	v_mov_b32_e32 v48, v49
	v_mov_b32_e32 v49, v18
	v_pk_mul_f32 v[48:49], v[12:13], v[48:49]
	v_pk_add_f32 v[52:53], v[4:5], v[50:51]
	v_mul_f32_e32 v6, 0.5, v6
	v_fma_f32 v53, v28, 0.5, -v50
	v_pk_add_f32 v[28:29], v[48:49], v[48:49] op_sel:[0,1] op_sel_hi:[0,1] neg_lo:[0,1] neg_hi:[0,1]
	v_pk_add_f32 v[48:49], v[6:7], v[28:29] op_sel_hi:[0,1] neg_hi:[0,1]
	v_pk_mul_f32 v[28:29], v[48:49], v[176:177]
	v_pk_mul_f32 v[48:49], v[48:49], v[174:175]
	v_pk_fma_f32 v[28:29], v[52:53], v[174:175], v[28:29]
	v_pk_fma_f32 v[48:49], v[52:53], v[176:177], v[48:49] neg_lo:[0,0,1] neg_hi:[0,0,1]
	v_pk_fma_f32 v[92:93], v[54:55], 0.5, v[56:57] op_sel_hi:[1,0,1]
	v_pk_add_f32 v[50:51], v[48:49], v[28:29] op_sel:[0,1] op_sel_hi:[1,0] neg_lo:[0,1]
	v_pk_add_f32 v[52:53], v[48:49], v[28:29] op_sel:[0,1] op_sel_hi:[1,0]
	v_mov_b32_e32 v17, v93
	v_pk_mul_f32 v[50:51], v[50:51], 0.5 op_sel_hi:[1,0]
	v_pk_mul_f32 v[64:65], v[16:17], s[6:7] op_sel_hi:[1,0]
	v_mul_f32_e32 v4, v12, v50
	v_pk_fma_f32 v[16:17], v[54:55], 0.5, v[56:57] op_sel_hi:[1,0,1] neg_lo:[1,0,0] neg_hi:[1,0,0]
	v_pk_fma_f32 v[54:55], v[12:13], v[50:51], v[4:5] op_sel_hi:[1,1,0] neg_lo:[1,0,0] neg_hi:[1,0,0]
	v_mov_b32_e32 v33, v12
	v_mul_f32_e32 v4, v12, v51
	v_pk_fma_f32 v[12:13], v[32:33], v[50:51], v[4:5] op_sel_hi:[1,1,0]
	v_pk_add_f32 v[28:29], v[28:29], v[48:49] op_sel:[1,0] op_sel_hi:[0,1] neg_lo:[0,1] neg_hi:[0,1]
	v_mov_b32_e32 v53, v29
	v_mov_b32_e32 v54, v12
	v_pk_fma_f32 v[12:13], v[52:53], 0.5, v[12:13] op_sel_hi:[1,0,1] neg_lo:[0,0,1] neg_hi:[0,0,1]
	v_pk_fma_f32 v[88:89], v[52:53], 0.5, v[54:55] op_sel_hi:[1,0,1]
	s_mov_b32 s79, s16
	v_mov_b32_e32 v13, v89
	v_pk_mul_f32 v[68:69], v[12:13], s[6:7] op_sel_hi:[1,0]
	v_pk_fma_f32 v[12:13], v[52:53], 0.5, v[54:55] op_sel_hi:[1,0,1] neg_lo:[1,0,0] neg_hi:[1,0,0]
	v_mov_b32_e32 v4, v83
	s_mov_b32 s17, s19
	v_pk_mul_f32 v[48:49], v[82:83], s[78:79] op_sel_hi:[0,1]
	v_pk_add_f32 v[28:29], v[96:97], v[162:163]
	v_pk_add_f32 v[32:33], v[96:97], v[162:163] neg_lo:[0,1] neg_hi:[0,1]
	v_pk_fma_f32 v[52:53], v[4:5], s[16:17], v[48:49] op_sel_hi:[0,1,1] neg_lo:[0,0,1] neg_hi:[0,0,1]
	v_mul_f32_e32 v12, 0.5, v33
	v_pk_fma_f32 v[50:51], v[4:5], s[16:17], v[48:49] op_sel_hi:[0,1,1]
	v_mov_b32_e32 v33, v29
	v_mul_f32_e32 v6, 0.5, v28
	v_mov_b32_e32 v54, v52
	v_mov_b32_e32 v55, v51
	v_pk_mul_f32 v[28:29], v[32:33], s[44:45]
	v_pk_mov_b32 v[56:57], v[50:51], v[52:53] op_sel:[1,0]
	v_pk_mul_f32 v[32:33], v[54:55], v[28:29] op_sel:[0,1] op_sel_hi:[1,0]
	v_pk_mul_f32 v[28:29], v[54:55], v[28:29]
	v_pk_add_f32 v[32:33], v[32:33], v[32:33] op_sel:[0,1] op_sel_hi:[0,1]
	v_pk_add_f32 v[58:59], v[6:7], v[32:33] op_sel_hi:[0,1] neg_hi:[0,1]
	v_pk_add_f32 v[28:29], v[28:29], v[28:29] op_sel:[0,1] op_sel_hi:[0,1] neg_lo:[0,1] neg_hi:[0,1]
	v_pk_add_f32 v[32:33], v[12:13], v[28:29] op_sel_hi:[0,1] neg_hi:[0,1]
	v_pk_mul_f32 v[28:29], v[32:33], v[166:167]
	v_pk_mul_f32 v[32:33], v[32:33], v[164:165]
	v_pk_fma_f32 v[28:29], v[58:59], v[164:165], v[28:29]
	v_pk_fma_f32 v[32:33], v[58:59], v[166:167], v[32:33] neg_lo:[0,0,1] neg_hi:[0,0,1]
	v_mov_b32_e32 v159, v66
	v_pk_add_f32 v[58:59], v[32:33], v[28:29] op_sel:[0,1] op_sel_hi:[1,0] neg_lo:[0,1]
	v_pk_add_f32 v[70:71], v[32:33], v[28:29] op_sel:[0,1] op_sel_hi:[1,0]
	v_pk_add_f32 v[28:29], v[28:29], v[32:33] op_sel:[1,0] op_sel_hi:[0,1] neg_lo:[0,1] neg_hi:[0,1]
	v_pk_mul_f32 v[58:59], v[58:59], 0.5 op_sel_hi:[1,0]
	v_mov_b32_e32 v71, v29
	v_mul_f32_e32 v6, v52, v58
	v_pk_fma_f32 v[72:73], v[54:55], v[58:59], v[6:7] op_sel_hi:[1,1,0] neg_lo:[1,0,0] neg_hi:[1,0,0]
	v_mul_f32_e32 v6, v52, v59
	v_pk_fma_f32 v[56:57], v[56:57], v[58:59], v[6:7] op_sel_hi:[1,1,0]
	v_sub_f32_e32 v12, v67, v153
	v_mov_b32_e32 v72, v56
	v_pk_fma_f32 v[28:29], v[70:71], 0.5, v[56:57] op_sel_hi:[1,0,1] neg_lo:[0,0,1] neg_hi:[0,0,1]
	v_pk_fma_f32 v[96:97], v[70:71], 0.5, v[72:73] op_sel_hi:[1,0,1]
	v_pk_mov_b32 v[56:57], v[48:49], v[152:153] op_sel:[1,0]
	v_mov_b32_e32 v29, v97
	v_pk_mul_f32 v[62:63], v[28:29], s[6:7] op_sel_hi:[1,0]
	v_pk_add_f32 v[28:29], v[66:67], v[152:153]
	v_pk_add_f32 v[56:57], v[158:159], v[56:57] neg_lo:[0,1] neg_hi:[0,1]
	v_mul_f32_e32 v18, 0.5, v29
	v_pk_mul_f32 v[58:59], v[56:57], v[18:19]
	v_mul_f32_e32 v6, 0.5, v28
	v_pk_fma_f32 v[54:55], v[54:55], v[58:59], v[58:59] op_sel:[0,1,0] op_sel_hi:[1,0,1]
	v_mov_b32_e32 v66, v56
	v_mov_b32_e32 v67, v52
	v_mov_b32_e32 v58, v59
	v_mov_b32_e32 v59, v18
	v_pk_mul_f32 v[58:59], v[66:67], v[58:59]
	v_pk_add_f32 v[66:67], v[6:7], v[54:55]
	v_mul_f32_e32 v12, 0.5, v12
	v_fma_f32 v67, v28, 0.5, -v54
	v_pk_add_f32 v[28:29], v[58:59], v[58:59] op_sel:[0,1] op_sel_hi:[0,1] neg_lo:[0,1] neg_hi:[0,1]
	v_pk_add_f32 v[54:55], v[12:13], v[28:29] op_sel_hi:[0,1] neg_hi:[0,1]
	v_pk_mul_f32 v[28:29], v[54:55], v[156:157]
	v_pk_mul_f32 v[54:55], v[54:55], v[154:155]
	v_pk_fma_f32 v[32:33], v[70:71], 0.5, v[72:73] op_sel_hi:[1,0,1] neg_lo:[1,0,0] neg_hi:[1,0,0]
	v_pk_fma_f32 v[58:59], v[66:67], v[154:155], v[28:29] neg_lo:[0,0,1] neg_hi:[0,0,1]
	v_pk_fma_f32 v[28:29], v[66:67], v[154:155], v[28:29]
	v_pk_fma_f32 v[70:71], v[66:67], v[156:157], v[54:55]
	v_pk_fma_f32 v[54:55], v[66:67], v[156:157], v[54:55] neg_lo:[0,0,1] neg_hi:[0,0,1]
	v_pk_add_f32 v[72:73], v[58:59], v[28:29] op_sel:[0,1] op_sel_hi:[1,0]
	v_pk_add_f32 v[66:67], v[70:71], v[54:55] op_sel_hi:[0,1] neg_lo:[0,1] neg_hi:[0,1]
	v_pk_add_f32 v[28:29], v[58:59], v[28:29] op_sel_hi:[0,1] neg_lo:[0,1] neg_hi:[0,1]
	v_pk_add_f32 v[54:55], v[70:71], v[54:55] op_sel:[0,1] op_sel_hi:[1,0]
	v_mov_b32_e32 v73, v67
	v_mov_b32_e32 v55, v29
	v_pk_mul_f32 v[28:29], v[54:55], 0.5 op_sel_hi:[1,0]
	v_mov_b32_e32 v133, v84
	v_pk_mul_f32 v[54:55], v[52:53], v[28:29] op_sel:[0,1] op_sel_hi:[0,0]
	v_pk_fma_f32 v[58:59], v[56:57], v[28:29], v[54:55] op_sel_hi:[0,1,1]
	v_pk_fma_f32 v[28:29], v[56:57], v[28:29], v[54:55] op_sel_hi:[0,1,1] neg_hi:[0,0,1]
	v_pk_fma_f32 v[54:55], v[72:73], 0.5, v[58:59] op_sel_hi:[1,0,1] neg_lo:[0,0,1] neg_hi:[0,0,1]
	v_pk_fma_f32 v[66:67], v[72:73], 0.5, v[28:29] op_sel_hi:[1,0,1]
	v_pk_add_f32 v[56:57], v[60:61], v[134:135] neg_lo:[0,1] neg_hi:[0,1]
	v_mov_b32_e32 v55, v67
	v_pk_mul_f32 v[90:91], v[54:55], s[6:7] op_sel_hi:[1,0]
	v_pk_add_f32 v[54:55], v[134:135], v[60:61]
	v_mul_f32_e32 v12, 0.5, v57
	v_mov_b32_e32 v57, v55
	v_mul_f32_e32 v6, 0.5, v54
	v_pk_mov_b32 v[58:59], v[52:53], v[50:51] op_sel:[1,0]
	v_pk_mul_f32 v[54:55], v[56:57], s[44:45]
	v_pk_fma_f32 v[28:29], v[72:73], 0.5, v[28:29] op_sel_hi:[1,0,1] neg_lo:[1,0,0] neg_hi:[1,0,0]
	v_pk_mul_f32 v[56:57], v[58:59], v[54:55] op_sel:[0,1] op_sel_hi:[1,0]
	v_pk_mul_f32 v[54:55], v[58:59], v[54:55]
	v_pk_add_f32 v[56:57], v[56:57], v[56:57] op_sel:[0,1] op_sel_hi:[0,1]
	v_pk_add_f32 v[60:61], v[6:7], v[56:57] op_sel_hi:[0,1] neg_hi:[0,1]
	v_pk_add_f32 v[54:55], v[54:55], v[54:55] op_sel:[0,1] op_sel_hi:[0,1] neg_lo:[0,1] neg_hi:[0,1]
	v_pk_add_f32 v[56:57], v[12:13], v[54:55] op_sel_hi:[0,1] neg_hi:[0,1]
	v_pk_mul_f32 v[54:55], v[56:57], v[142:143]
	v_pk_mul_f32 v[56:57], v[56:57], v[140:141]
	v_pk_fma_f32 v[54:55], v[60:61], v[140:141], v[54:55]
	v_pk_fma_f32 v[56:57], v[60:61], v[142:143], v[56:57] neg_lo:[0,0,1] neg_hi:[0,0,1]
	v_mov_b32_e32 v51, v53
	v_pk_add_f32 v[60:61], v[56:57], v[54:55] op_sel:[0,1] op_sel_hi:[1,0] neg_lo:[0,1]
	v_pk_add_f32 v[70:71], v[56:57], v[54:55] op_sel:[0,1] op_sel_hi:[1,0]
	v_pk_add_f32 v[54:55], v[54:55], v[56:57] op_sel:[1,0] op_sel_hi:[0,1] neg_lo:[0,1] neg_hi:[0,1]
	v_pk_mul_f32 v[60:61], v[60:61], 0.5 op_sel_hi:[1,0]
	v_mov_b32_e32 v71, v55
	v_mul_f32_e32 v6, v53, v60
	v_pk_fma_f32 v[72:73], v[58:59], v[60:61], v[6:7] op_sel_hi:[1,1,0] neg_lo:[1,0,0] neg_hi:[1,0,0]
	v_mul_f32_e32 v6, v53, v61
	v_pk_fma_f32 v[50:51], v[50:51], v[60:61], v[6:7] op_sel_hi:[1,1,0]
	v_pk_add_f32 v[54:55], v[118:119], v[84:85]
	v_mov_b32_e32 v72, v50
	v_mov_b32_e32 v49, v118
	v_pk_fma_f32 v[50:51], v[70:71], 0.5, v[50:51] op_sel_hi:[1,0,1] neg_lo:[0,0,1] neg_hi:[0,0,1]
	v_pk_fma_f32 v[60:61], v[70:71], 0.5, v[72:73] op_sel_hi:[1,0,1]
	v_mul_f32_e32 v18, 0.5, v55
	v_pk_add_f32 v[48:49], v[132:133], v[48:49] neg_lo:[0,1] neg_hi:[0,1]
	v_mov_b32_e32 v51, v61
	v_pk_mul_f32 v[56:57], v[48:49], v[18:19]
	v_pk_mul_f32 v[94:95], v[50:51], s[6:7] op_sel_hi:[1,0]
	v_pk_fma_f32 v[50:51], v[70:71], 0.5, v[72:73] op_sel_hi:[1,0,1] neg_lo:[1,0,0] neg_hi:[1,0,0]
	v_mul_f32_e32 v6, 0.5, v54
	v_pk_fma_f32 v[58:59], v[58:59], v[56:57], v[56:57] op_sel:[0,1,0] op_sel_hi:[1,0,1]
	v_mov_b32_e32 v70, v48
	v_mov_b32_e32 v71, v53
	v_mov_b32_e32 v56, v57
	v_mov_b32_e32 v57, v18
	v_sub_f32_e32 v12, v85, v119
	v_pk_mul_f32 v[56:57], v[70:71], v[56:57]
	v_pk_add_f32 v[70:71], v[6:7], v[58:59]
	v_mul_f32_e32 v12, 0.5, v12
	v_fma_f32 v71, v54, 0.5, -v58
	v_pk_add_f32 v[54:55], v[56:57], v[56:57] op_sel:[0,1] op_sel_hi:[0,1] neg_lo:[0,1] neg_hi:[0,1]
	v_pk_add_f32 v[56:57], v[12:13], v[54:55] op_sel_hi:[0,1] neg_hi:[0,1]
	v_pk_mul_f32 v[54:55], v[56:57], v[126:127]
	v_pk_mul_f32 v[56:57], v[56:57], v[124:125]
	v_pk_fma_f32 v[58:59], v[70:71], v[124:125], v[54:55] neg_lo:[0,0,1] neg_hi:[0,0,1]
	v_pk_fma_f32 v[54:55], v[70:71], v[124:125], v[54:55]
	v_pk_fma_f32 v[72:73], v[70:71], v[126:127], v[56:57]
	v_pk_fma_f32 v[56:57], v[70:71], v[126:127], v[56:57] neg_lo:[0,0,1] neg_hi:[0,0,1]
	v_pk_add_f32 v[70:71], v[58:59], v[54:55] op_sel:[0,1] op_sel_hi:[1,0]
	v_pk_add_f32 v[74:75], v[72:73], v[56:57] op_sel_hi:[0,1] neg_lo:[0,1] neg_hi:[0,1]
	v_pk_add_f32 v[54:55], v[58:59], v[54:55] op_sel_hi:[0,1] neg_lo:[0,1] neg_hi:[0,1]
	v_pk_add_f32 v[56:57], v[72:73], v[56:57] op_sel:[0,1] op_sel_hi:[1,0]
	v_mov_b32_e32 v71, v75
	v_mov_b32_e32 v57, v55
	v_pk_mul_f32 v[54:55], v[56:57], 0.5 op_sel_hi:[1,0]
	s_mov_b32 s78, s11
	v_pk_mul_f32 v[52:53], v[52:53], v[54:55] op_sel:[1,1] op_sel_hi:[1,0]
	s_mov_b32 s79, s8
	v_pk_fma_f32 v[56:57], v[48:49], v[54:55], v[52:53] op_sel_hi:[0,1,1]
	v_pk_fma_f32 v[48:49], v[48:49], v[54:55], v[52:53] op_sel_hi:[0,1,1] neg_hi:[0,0,1]
	s_nop 0
	v_pk_fma_f32 v[52:53], v[70:71], 0.5, v[56:57] op_sel_hi:[1,0,1] neg_lo:[0,0,1] neg_hi:[0,0,1]
	v_pk_fma_f32 v[84:85], v[70:71], 0.5, v[48:49] op_sel_hi:[1,0,1]
	s_mov_b32 s9, s11
	v_mov_b32_e32 v53, v85
	v_pk_mul_f32 v[80:81], v[52:53], s[6:7] op_sel_hi:[1,0]
	v_pk_mul_f32 v[118:119], v[82:83], s[78:79] op_sel_hi:[0,1]
	v_pk_add_f32 v[52:53], v[86:87], v[112:113]
	v_pk_add_f32 v[54:55], v[86:87], v[112:113] neg_lo:[0,1] neg_hi:[0,1]
	v_pk_fma_f32 v[58:59], v[4:5], s[8:9], v[118:119] op_sel_hi:[0,1,1] neg_lo:[0,0,1] neg_hi:[0,0,1]
	v_mul_f32_e32 v12, 0.5, v55
	v_pk_fma_f32 v[72:73], v[4:5], s[8:9], v[118:119] op_sel_hi:[0,1,1]
	v_mov_b32_e32 v55, v53
	v_mul_f32_e32 v6, 0.5, v52
	v_mov_b32_e32 v56, v58
	v_mov_b32_e32 v57, v73
	v_pk_mul_f32 v[52:53], v[54:55], s[44:45]
	v_pk_fma_f32 v[48:49], v[70:71], 0.5, v[48:49] op_sel_hi:[1,0,1] neg_lo:[1,0,0] neg_hi:[1,0,0]
	v_pk_mul_f32 v[54:55], v[56:57], v[52:53] op_sel:[0,1] op_sel_hi:[1,0]
	v_pk_mul_f32 v[52:53], v[56:57], v[52:53]
	v_pk_add_f32 v[54:55], v[54:55], v[54:55] op_sel:[0,1] op_sel_hi:[0,1]
	v_pk_add_f32 v[74:75], v[6:7], v[54:55] op_sel_hi:[0,1] neg_hi:[0,1]
	v_pk_add_f32 v[52:53], v[52:53], v[52:53] op_sel:[0,1] op_sel_hi:[0,1] neg_lo:[0,1] neg_hi:[0,1]
	v_pk_add_f32 v[54:55], v[12:13], v[52:53] op_sel_hi:[0,1] neg_hi:[0,1]
	v_pk_mul_f32 v[52:53], v[54:55], v[116:117]
	v_pk_mul_f32 v[54:55], v[54:55], v[114:115]
	v_pk_fma_f32 v[52:53], v[74:75], v[114:115], v[52:53]
	v_pk_fma_f32 v[54:55], v[74:75], v[116:117], v[54:55] neg_lo:[0,0,1] neg_hi:[0,0,1]
	v_pk_mov_b32 v[70:71], v[72:73], v[58:59] op_sel:[1,0]
	v_pk_add_f32 v[74:75], v[54:55], v[52:53] op_sel:[0,1] op_sel_hi:[1,0] neg_lo:[0,1]
	v_pk_add_f32 v[76:77], v[54:55], v[52:53] op_sel:[0,1] op_sel_hi:[1,0]
	v_pk_add_f32 v[52:53], v[52:53], v[54:55] op_sel:[1,0] op_sel_hi:[0,1] neg_lo:[0,1] neg_hi:[0,1]
	v_pk_mul_f32 v[74:75], v[74:75], 0.5 op_sel_hi:[1,0]
	v_mov_b32_e32 v77, v53
	v_mul_f32_e32 v6, v58, v74
	v_pk_fma_f32 v[112:113], v[56:57], v[74:75], v[6:7] op_sel_hi:[1,1,0] neg_lo:[1,0,0] neg_hi:[1,0,0]
	v_mul_f32_e32 v6, v58, v75
	v_pk_fma_f32 v[70:71], v[70:71], v[74:75], v[6:7] op_sel_hi:[1,1,0]
	v_pk_add_f32 v[54:55], v[34:35], v[110:111]
	v_mov_b32_e32 v112, v70
	v_pk_fma_f32 v[52:53], v[76:77], 0.5, v[70:71] op_sel_hi:[1,0,1] neg_lo:[0,0,1] neg_hi:[0,0,1]
	v_pk_fma_f32 v[86:87], v[76:77], 0.5, v[112:113] op_sel_hi:[1,0,1]
	v_sub_f32_e32 v12, v35, v111
	v_mov_b32_e32 v53, v87
	v_pk_mul_f32 v[78:79], v[52:53], s[6:7] op_sel_hi:[1,0]
	v_mul_f32_e32 v52, 0xbe47c5c2, v83
	v_mov_b32_e32 v53, v34
	v_pk_mov_b32 v[34:35], v[118:119], v[110:111] op_sel:[1,0]
	v_mul_f32_e32 v18, 0.5, v55
	v_pk_add_f32 v[34:35], v[52:53], v[34:35] neg_lo:[0,1] neg_hi:[0,1]
	v_mov_b32_e32 v71, v58
	v_pk_mul_f32 v[52:53], v[34:35], v[18:19]
	v_mov_b32_e32 v70, v34
	v_pk_fma_f32 v[56:57], v[56:57], v[52:53], v[52:53] op_sel:[0,1,0] op_sel_hi:[1,0,1]
	v_mov_b32_e32 v52, v53
	v_mov_b32_e32 v53, v18
	v_mul_f32_e32 v6, 0.5, v54
	v_pk_mul_f32 v[52:53], v[70:71], v[52:53]
	v_cvt_f32_f16_e32 v70, v46
	v_cvt_f32_f16_e32 v71, v47
	v_cvt_f32_f16_sdwa v47, v47 dst_sel:DWORD dst_unused:UNUSED_PAD src0_sel:WORD_1
	v_cvt_f32_f16_sdwa v46, v46 dst_sel:DWORD dst_unused:UNUSED_PAD src0_sel:WORD_1
	v_pk_fma_f32 v[74:75], v[76:77], 0.5, v[112:113] op_sel_hi:[1,0,1] neg_lo:[1,0,0] neg_hi:[1,0,0]
	v_mul_f32_e32 v12, 0.5, v12
	v_pk_add_f32 v[76:77], v[6:7], v[56:57]
	v_pk_add_f32 v[52:53], v[52:53], v[52:53] op_sel:[0,1] op_sel_hi:[0,1] neg_lo:[0,1] neg_hi:[0,1]
	v_fma_f32 v77, v54, 0.5, -v56
	v_pk_add_f32 v[54:55], v[12:13], v[52:53] op_sel_hi:[0,1] neg_hi:[0,1]
	v_pk_mul_f32 v[52:53], v[54:55], v[46:47]
	v_pk_mul_f32 v[54:55], v[54:55], v[70:71]
	v_pk_fma_f32 v[56:57], v[76:77], v[70:71], v[52:53] neg_lo:[0,0,1] neg_hi:[0,0,1]
	v_pk_fma_f32 v[52:53], v[76:77], v[70:71], v[52:53]
	v_pk_fma_f32 v[70:71], v[76:77], v[46:47], v[54:55]
	v_pk_fma_f32 v[46:47], v[76:77], v[46:47], v[54:55] neg_lo:[0,0,1] neg_hi:[0,0,1]
	v_pk_add_f32 v[54:55], v[56:57], v[52:53] op_sel:[0,1] op_sel_hi:[1,0]
	v_pk_add_f32 v[76:77], v[70:71], v[46:47] op_sel_hi:[0,1] neg_lo:[0,1] neg_hi:[0,1]
	v_pk_add_f32 v[52:53], v[56:57], v[52:53] op_sel_hi:[0,1] neg_lo:[0,1] neg_hi:[0,1]
	v_pk_add_f32 v[46:47], v[70:71], v[46:47] op_sel:[0,1] op_sel_hi:[1,0]
	v_mov_b32_e32 v55, v77
	v_mov_b32_e32 v47, v53
	v_pk_mul_f32 v[46:47], v[46:47], 0.5 op_sel_hi:[1,0]
	s_mov_b32 s25, s27
	v_pk_mul_f32 v[52:53], v[58:59], v[46:47] op_sel:[0,1] op_sel_hi:[0,0]
	v_pk_fma_f32 v[56:57], v[34:35], v[46:47], v[52:53] op_sel_hi:[0,1,1]
	v_pk_fma_f32 v[46:47], v[34:35], v[46:47], v[52:53] op_sel_hi:[0,1,1] neg_hi:[0,0,1]
	s_nop 0
	v_pk_fma_f32 v[52:53], v[54:55], 0.5, v[56:57] op_sel_hi:[1,0,1] neg_lo:[0,0,1] neg_hi:[0,0,1]
	v_pk_fma_f32 v[34:35], v[54:55], 0.5, v[46:47] op_sel_hi:[1,0,1]
	s_mov_b32 s78, s27
	v_mov_b32_e32 v53, v35
	v_pk_mul_f32 v[136:137], v[52:53], s[6:7] op_sel_hi:[1,0]
	v_pk_fma_f32 v[52:53], v[54:55], 0.5, v[46:47] op_sel_hi:[1,0,1] neg_lo:[1,0,0] neg_hi:[1,0,0]
	s_mov_b32 s79, s24
	v_pk_mul_f32 v[46:47], v[82:83], s[24:25] op_sel_hi:[0,1]
	v_pk_add_f32 v[54:55], v[108:109], v[40:41]
	v_pk_add_f32 v[40:41], v[40:41], v[108:109] neg_lo:[0,1] neg_hi:[0,1]
	v_pk_fma_f32 v[108:109], v[4:5], s[78:79], v[46:47] op_sel_hi:[0,1,1] neg_lo:[0,0,1] neg_hi:[0,0,1]
	v_mul_f32_e32 v12, 0.5, v41
	v_pk_fma_f32 v[70:71], v[4:5], s[78:79], v[46:47] op_sel_hi:[0,1,1]
	v_mov_b32_e32 v41, v55
	v_mov_b32_e32 v56, v108
	v_mov_b32_e32 v57, v71
	v_pk_mul_f32 v[40:41], v[40:41], s[44:45]
	v_mul_f32_e32 v6, 0.5, v54
	v_pk_mul_f32 v[54:55], v[56:57], v[40:41] op_sel:[0,1] op_sel_hi:[1,0]
	v_cvt_f32_f16_sdwa v76, v36 dst_sel:DWORD dst_unused:UNUSED_PAD src0_sel:WORD_1
	v_cvt_f32_f16_e32 v77, v37
	v_cvt_f32_f16_sdwa v37, v37 dst_sel:DWORD dst_unused:UNUSED_PAD src0_sel:WORD_1
	v_cvt_f32_f16_e32 v36, v36
	v_pk_mul_f32 v[40:41], v[56:57], v[40:41]
	v_pk_add_f32 v[54:55], v[54:55], v[54:55] op_sel:[0,1] op_sel_hi:[0,1]
	v_pk_add_f32 v[112:113], v[6:7], v[54:55] op_sel_hi:[0,1] neg_hi:[0,1]
	s_nop 0
	v_pk_add_f32 v[40:41], v[40:41], v[40:41] op_sel:[0,1] op_sel_hi:[0,1] neg_lo:[0,1] neg_hi:[0,1]
	v_pk_add_f32 v[54:55], v[12:13], v[40:41] op_sel_hi:[0,1] neg_hi:[0,1]
	v_pk_mul_f32 v[40:41], v[54:55], v[36:37]
	v_pk_mul_f32 v[54:55], v[54:55], v[76:77]
	v_pk_fma_f32 v[40:41], v[112:113], v[76:77], v[40:41]
	v_pk_fma_f32 v[36:37], v[112:113], v[36:37], v[54:55] neg_lo:[0,0,1] neg_hi:[0,0,1]
	v_pk_mov_b32 v[110:111], v[70:71], v[108:109] op_sel:[1,0]
	v_pk_add_f32 v[54:55], v[36:37], v[40:41] op_sel:[0,1] op_sel_hi:[1,0] neg_lo:[0,1]
	v_pk_add_f32 v[76:77], v[36:37], v[40:41] op_sel:[0,1] op_sel_hi:[1,0]
	v_pk_add_f32 v[36:37], v[40:41], v[36:37] op_sel:[1,0] op_sel_hi:[0,1] neg_lo:[0,1] neg_hi:[0,1]
	v_pk_mul_f32 v[54:55], v[54:55], 0.5 op_sel_hi:[1,0]
	v_mov_b32_e32 v77, v37
	v_mul_f32_e32 v4, v108, v54
	v_pk_fma_f32 v[112:113], v[56:57], v[54:55], v[4:5] op_sel_hi:[1,1,0] neg_lo:[1,0,0] neg_hi:[1,0,0]
	v_mul_f32_e32 v4, v108, v55
	v_pk_fma_f32 v[54:55], v[110:111], v[54:55], v[4:5] op_sel_hi:[1,1,0]
	v_sub_f32_e32 v6, v45, v105
	v_mov_b32_e32 v112, v54
	v_pk_fma_f32 v[40:41], v[76:77], 0.5, v[54:55] op_sel_hi:[1,0,1] neg_lo:[0,0,1] neg_hi:[0,0,1]
	v_pk_fma_f32 v[36:37], v[76:77], 0.5, v[112:113] op_sel_hi:[1,0,1]
	v_pk_add_f32 v[54:55], v[104:105], v[44:45]
	v_mov_b32_e32 v41, v37
	v_pk_mul_f32 v[130:131], v[40:41], s[6:7] op_sel_hi:[1,0]
	v_mul_f32_e32 v40, 0xbf54db31, v83
	v_mov_b32_e32 v41, v44
	v_pk_mov_b32 v[44:45], v[46:47], v[104:105] op_sel:[1,0]
	v_mul_f32_e32 v18, 0.5, v55
	v_pk_add_f32 v[40:41], v[40:41], v[44:45] neg_lo:[0,1] neg_hi:[0,1]
	v_mov_b32_e32 v105, v108
	v_pk_mul_f32 v[44:45], v[40:41], v[18:19]
	v_mov_b32_e32 v104, v40
	v_pk_fma_f32 v[56:57], v[56:57], v[44:45], v[44:45] op_sel:[0,1,0] op_sel_hi:[1,0,1]
	v_mov_b32_e32 v44, v45
	v_mov_b32_e32 v45, v18
	v_mul_f32_e32 v4, 0.5, v54
	v_pk_mul_f32 v[44:45], v[104:105], v[44:45]
	v_cvt_f32_f16_e32 v104, v26
	v_cvt_f32_f16_e32 v105, v27
	v_cvt_f32_f16_sdwa v27, v27 dst_sel:DWORD dst_unused:UNUSED_PAD src0_sel:WORD_1
	v_cvt_f32_f16_sdwa v26, v26 dst_sel:DWORD dst_unused:UNUSED_PAD src0_sel:WORD_1
	v_mul_f32_e32 v6, 0.5, v6
	v_pk_add_f32 v[110:111], v[4:5], v[56:57]
	v_pk_add_f32 v[44:45], v[44:45], v[44:45] op_sel:[0,1] op_sel_hi:[0,1] neg_lo:[0,1] neg_hi:[0,1]
	v_fma_f32 v111, v54, 0.5, -v56
	v_pk_add_f32 v[54:55], v[6:7], v[44:45] op_sel_hi:[0,1] neg_hi:[0,1]
	v_pk_mul_f32 v[44:45], v[54:55], v[26:27]
	v_pk_mul_f32 v[54:55], v[54:55], v[104:105]
	v_pk_fma_f32 v[56:57], v[110:111], v[104:105], v[44:45] neg_lo:[0,0,1] neg_hi:[0,0,1]
	v_pk_fma_f32 v[44:45], v[110:111], v[104:105], v[44:45]
	v_pk_fma_f32 v[104:105], v[110:111], v[26:27], v[54:55]
	v_pk_fma_f32 v[26:27], v[110:111], v[26:27], v[54:55] neg_lo:[0,0,1] neg_hi:[0,0,1]
	v_pk_add_f32 v[54:55], v[56:57], v[44:45] op_sel:[0,1] op_sel_hi:[1,0]
	v_pk_add_f32 v[110:111], v[104:105], v[26:27] op_sel_hi:[0,1] neg_lo:[0,1] neg_hi:[0,1]
	v_pk_add_f32 v[44:45], v[56:57], v[44:45] op_sel_hi:[0,1] neg_lo:[0,1] neg_hi:[0,1]
	v_pk_add_f32 v[26:27], v[104:105], v[26:27] op_sel:[0,1] op_sel_hi:[1,0]
	v_mov_b32_e32 v55, v111
	v_mov_b32_e32 v27, v45
	v_pk_mul_f32 v[26:27], v[26:27], 0.5 op_sel_hi:[1,0]
	v_mov_b32_e32 v47, v102
	v_pk_mul_f32 v[44:45], v[108:109], v[26:27] op_sel:[0,1] op_sel_hi:[0,0]
	v_pk_fma_f32 v[56:57], v[40:41], v[26:27], v[44:45] op_sel_hi:[0,1,1]
	v_pk_fma_f32 v[40:41], v[40:41], v[26:27], v[44:45] op_sel_hi:[0,1,1] neg_hi:[0,0,1]
	v_pk_fma_f32 v[44:45], v[54:55], 0.5, v[56:57] op_sel_hi:[1,0,1] neg_lo:[0,0,1] neg_hi:[0,0,1]
	v_pk_fma_f32 v[26:27], v[54:55], 0.5, v[40:41] op_sel_hi:[1,0,1]
	v_pk_fma_f32 v[56:57], v[54:55], 0.5, v[40:41] op_sel_hi:[1,0,1] neg_lo:[1,0,0] neg_hi:[1,0,0]
	v_pk_add_f32 v[40:41], v[106:107], v[42:43]
	v_pk_add_f32 v[42:43], v[42:43], v[106:107] neg_lo:[0,1] neg_hi:[0,1]
	v_mov_b32_e32 v45, v27
	v_mul_f32_e32 v6, 0.5, v43
	v_mov_b32_e32 v43, v41
	v_pk_mul_f32 v[120:121], v[44:45], s[6:7] op_sel_hi:[1,0]
	v_mul_f32_e32 v4, 0.5, v40
	v_pk_mov_b32 v[44:45], v[108:109], v[70:71] op_sel:[1,0]
	v_pk_mul_f32 v[40:41], v[42:43], s[44:45]
	v_cvt_f32_f16_sdwa v54, v20 dst_sel:DWORD dst_unused:UNUSED_PAD src0_sel:WORD_1
	v_pk_mul_f32 v[42:43], v[44:45], v[40:41] op_sel:[0,1] op_sel_hi:[1,0]
	v_cvt_f32_f16_e32 v55, v21
	v_cvt_f32_f16_sdwa v21, v21 dst_sel:DWORD dst_unused:UNUSED_PAD src0_sel:WORD_1
	v_cvt_f32_f16_e32 v20, v20
	v_pk_mul_f32 v[40:41], v[44:45], v[40:41]
	v_pk_add_f32 v[42:43], v[42:43], v[42:43] op_sel:[0,1] op_sel_hi:[0,1]
	v_pk_add_f32 v[104:105], v[4:5], v[42:43] op_sel_hi:[0,1] neg_hi:[0,1]
	s_nop 0
	v_pk_add_f32 v[40:41], v[40:41], v[40:41] op_sel:[0,1] op_sel_hi:[0,1] neg_lo:[0,1] neg_hi:[0,1]
	v_pk_add_f32 v[42:43], v[6:7], v[40:41] op_sel_hi:[0,1] neg_hi:[0,1]
	v_pk_mul_f32 v[40:41], v[42:43], v[20:21]
	v_pk_mul_f32 v[42:43], v[42:43], v[54:55]
	v_pk_fma_f32 v[40:41], v[104:105], v[54:55], v[40:41]
	v_pk_fma_f32 v[20:21], v[104:105], v[20:21], v[42:43] neg_lo:[0,0,1] neg_hi:[0,0,1]
	v_mov_b32_e32 v71, v109
	v_pk_add_f32 v[42:43], v[20:21], v[40:41] op_sel:[0,1] op_sel_hi:[1,0] neg_lo:[0,1]
	v_pk_add_f32 v[54:55], v[20:21], v[40:41] op_sel:[0,1] op_sel_hi:[1,0]
	v_pk_add_f32 v[20:21], v[40:41], v[20:21] op_sel:[1,0] op_sel_hi:[0,1] neg_lo:[0,1] neg_hi:[0,1]
	v_pk_mul_f32 v[42:43], v[42:43], 0.5 op_sel_hi:[1,0]
	v_mov_b32_e32 v55, v21
	v_mul_f32_e32 v4, v109, v42
	v_pk_fma_f32 v[104:105], v[44:45], v[42:43], v[4:5] op_sel_hi:[1,1,0] neg_lo:[1,0,0] neg_hi:[1,0,0]
	v_mul_f32_e32 v4, v109, v43
	v_pk_fma_f32 v[42:43], v[70:71], v[42:43], v[4:5] op_sel_hi:[1,1,0]
	v_sub_f32_e32 v6, v23, v103
	v_mov_b32_e32 v104, v42
	v_pk_fma_f32 v[40:41], v[54:55], 0.5, v[42:43] op_sel_hi:[1,0,1] neg_lo:[0,0,1] neg_hi:[0,0,1]
	v_pk_fma_f32 v[20:21], v[54:55], 0.5, v[104:105] op_sel_hi:[1,0,1]
	v_pk_add_f32 v[42:43], v[102:103], v[22:23]
	v_mov_b32_e32 v41, v21
	v_pk_mul_f32 v[128:129], v[40:41], s[6:7] op_sel_hi:[1,0]
	v_mul_f32_e32 v40, 0xbf0e39da, v83
	v_mov_b32_e32 v41, v22
	v_mul_f32_e32 v18, 0.5, v43
	v_pk_add_f32 v[22:23], v[40:41], v[46:47] neg_lo:[0,1] neg_hi:[0,1]
	v_mov_b32_e32 v47, v109
	v_pk_mul_f32 v[40:41], v[22:23], v[18:19]
	v_mov_b32_e32 v46, v22
	v_pk_fma_f32 v[44:45], v[44:45], v[40:41], v[40:41] op_sel:[0,1,0] op_sel_hi:[1,0,1]
	v_mov_b32_e32 v40, v41
	v_mov_b32_e32 v41, v18
	v_mul_f32_e32 v4, 0.5, v42
	v_pk_mul_f32 v[40:41], v[46:47], v[40:41]
	v_cvt_f32_f16_e32 v46, v10
	v_cvt_f32_f16_e32 v47, v11
	v_cvt_f32_f16_sdwa v11, v11 dst_sel:DWORD dst_unused:UNUSED_PAD src0_sel:WORD_1
	v_cvt_f32_f16_sdwa v10, v10 dst_sel:DWORD dst_unused:UNUSED_PAD src0_sel:WORD_1
	v_pk_fma_f32 v[70:71], v[54:55], 0.5, v[104:105] op_sel_hi:[1,0,1] neg_lo:[1,0,0] neg_hi:[1,0,0]
	v_mul_f32_e32 v6, 0.5, v6
	v_pk_add_f32 v[54:55], v[4:5], v[44:45]
	v_pk_add_f32 v[40:41], v[40:41], v[40:41] op_sel:[0,1] op_sel_hi:[0,1] neg_lo:[0,1] neg_hi:[0,1]
	v_fma_f32 v55, v42, 0.5, -v44
	v_pk_add_f32 v[42:43], v[6:7], v[40:41] op_sel_hi:[0,1] neg_hi:[0,1]
	v_pk_mul_f32 v[40:41], v[42:43], v[10:11]
	v_pk_mul_f32 v[42:43], v[42:43], v[46:47]
	v_pk_fma_f32 v[44:45], v[54:55], v[46:47], v[40:41] neg_lo:[0,0,1] neg_hi:[0,0,1]
	v_pk_fma_f32 v[40:41], v[54:55], v[46:47], v[40:41]
	v_pk_fma_f32 v[46:47], v[54:55], v[10:11], v[42:43]
	v_pk_fma_f32 v[10:11], v[54:55], v[10:11], v[42:43] neg_lo:[0,0,1] neg_hi:[0,0,1]
	v_pk_add_f32 v[42:43], v[44:45], v[40:41] op_sel:[0,1] op_sel_hi:[1,0]
	v_pk_add_f32 v[54:55], v[46:47], v[10:11] op_sel_hi:[0,1] neg_lo:[0,1] neg_hi:[0,1]
	v_pk_add_f32 v[40:41], v[44:45], v[40:41] op_sel_hi:[0,1] neg_lo:[0,1] neg_hi:[0,1]
	v_pk_add_f32 v[10:11], v[46:47], v[10:11] op_sel:[0,1] op_sel_hi:[1,0]
	v_mov_b32_e32 v43, v55
	v_mov_b32_e32 v11, v41
	v_pk_mul_f32 v[10:11], v[10:11], 0.5 op_sel_hi:[1,0]
	v_mov_b32_e32 v119, v98
	v_pk_mul_f32 v[40:41], v[108:109], v[10:11] op_sel:[1,1] op_sel_hi:[1,0]
	v_pk_fma_f32 v[76:77], v[76:77], 0.5, v[112:113] op_sel_hi:[1,0,1] neg_lo:[1,0,0] neg_hi:[1,0,0]
	v_pk_fma_f32 v[44:45], v[22:23], v[10:11], v[40:41] op_sel_hi:[0,1,1]
	v_pk_fma_f32 v[10:11], v[22:23], v[10:11], v[40:41] op_sel_hi:[0,1,1] neg_hi:[0,0,1]
	v_pk_fma_f32 v[22:23], v[42:43], 0.5, v[44:45] op_sel_hi:[1,0,1] neg_lo:[0,0,1] neg_hi:[0,0,1]
	v_pk_fma_f32 v[40:41], v[42:43], 0.5, v[10:11] op_sel_hi:[1,0,1]
	v_pk_fma_f32 v[54:55], v[42:43], 0.5, v[10:11] op_sel_hi:[1,0,1] neg_lo:[1,0,0] neg_hi:[1,0,0]
	v_pk_add_f32 v[10:11], v[100:101], v[14:15]
	v_pk_add_f32 v[14:15], v[14:15], v[100:101] neg_lo:[0,1] neg_hi:[0,1]
	v_mov_b32_e32 v23, v41
	v_mul_f32_e32 v6, 0.5, v15
	v_mov_b32_e32 v15, v11
	v_pk_mul_f32 v[150:151], v[22:23], s[6:7] op_sel_hi:[1,0]
	v_mul_f32_e32 v4, 0.5, v10
	v_pk_mov_b32 v[22:23], v[58:59], v[72:73] op_sel:[1,0]
	v_pk_mul_f32 v[10:11], v[14:15], s[44:45]
	v_cvt_f32_f16_sdwa v42, v8 dst_sel:DWORD dst_unused:UNUSED_PAD src0_sel:WORD_1
	v_pk_mul_f32 v[14:15], v[22:23], v[10:11] op_sel:[0,1] op_sel_hi:[1,0]
	v_cvt_f32_f16_e32 v43, v9
	v_cvt_f32_f16_sdwa v9, v9 dst_sel:DWORD dst_unused:UNUSED_PAD src0_sel:WORD_1
	v_cvt_f32_f16_e32 v8, v8
	v_pk_mul_f32 v[10:11], v[22:23], v[10:11]
	v_pk_add_f32 v[14:15], v[14:15], v[14:15] op_sel:[0,1] op_sel_hi:[0,1]
	v_pk_add_f32 v[44:45], v[4:5], v[14:15] op_sel_hi:[0,1] neg_hi:[0,1]
	s_nop 0
	v_pk_add_f32 v[10:11], v[10:11], v[10:11] op_sel:[0,1] op_sel_hi:[0,1] neg_lo:[0,1] neg_hi:[0,1]
	v_pk_add_f32 v[14:15], v[6:7], v[10:11] op_sel_hi:[0,1] neg_hi:[0,1]
	v_pk_mul_f32 v[10:11], v[14:15], v[8:9]
	v_pk_mul_f32 v[14:15], v[14:15], v[42:43]
	v_pk_fma_f32 v[10:11], v[44:45], v[42:43], v[10:11]
	v_pk_fma_f32 v[8:9], v[44:45], v[8:9], v[14:15] neg_lo:[0,0,1] neg_hi:[0,0,1]
	v_mov_b32_e32 v73, v59
	v_pk_add_f32 v[14:15], v[8:9], v[10:11] op_sel:[0,1] op_sel_hi:[1,0] neg_lo:[0,1]
	v_pk_add_f32 v[42:43], v[8:9], v[10:11] op_sel:[0,1] op_sel_hi:[1,0]
	v_pk_add_f32 v[8:9], v[10:11], v[8:9] op_sel:[1,0] op_sel_hi:[0,1] neg_lo:[0,1] neg_hi:[0,1]
	v_pk_mul_f32 v[14:15], v[14:15], 0.5 op_sel_hi:[1,0]
	v_mov_b32_e32 v43, v9
	v_mul_f32_e32 v4, v59, v14
	v_pk_fma_f32 v[44:45], v[22:23], v[14:15], v[4:5] op_sel_hi:[1,1,0] neg_lo:[1,0,0] neg_hi:[1,0,0]
	v_mul_f32_e32 v4, v59, v15
	v_pk_fma_f32 v[14:15], v[72:73], v[14:15], v[4:5] op_sel_hi:[1,1,0]
	v_sub_f32_e32 v6, v39, v99
	v_mov_b32_e32 v44, v14
	v_pk_fma_f32 v[8:9], v[42:43], 0.5, v[14:15] op_sel_hi:[1,0,1] neg_lo:[0,0,1] neg_hi:[0,0,1]
	v_pk_fma_f32 v[10:11], v[42:43], 0.5, v[44:45] op_sel_hi:[1,0,1]
	v_pk_add_f32 v[14:15], v[98:99], v[38:39]
	v_mov_b32_e32 v9, v11
	v_pk_mul_f32 v[168:169], v[8:9], s[6:7] op_sel_hi:[1,0]
	v_mul_f32_e32 v8, 0xbf7b14be, v83
	v_mov_b32_e32 v9, v38
	v_mul_f32_e32 v18, 0.5, v15
	v_pk_add_f32 v[8:9], v[8:9], v[118:119] neg_lo:[0,1] neg_hi:[0,1]
	v_pk_fma_f32 v[72:73], v[42:43], 0.5, v[44:45] op_sel_hi:[1,0,1] neg_lo:[1,0,0] neg_hi:[1,0,0]
	v_pk_mul_f32 v[38:39], v[8:9], v[18:19]
	v_mov_b32_e32 v42, v8
	v_pk_fma_f32 v[22:23], v[22:23], v[38:39], v[38:39] op_sel:[0,1,0] op_sel_hi:[1,0,1]
	v_mov_b32_e32 v43, v59
	v_mov_b32_e32 v38, v39
	v_mov_b32_e32 v39, v18
	v_mul_f32_e32 v4, 0.5, v14
	v_pk_mul_f32 v[38:39], v[42:43], v[38:39]
	v_cvt_f32_f16_e32 v44, v2
	v_cvt_f32_f16_e32 v45, v3
	v_cvt_f32_f16_sdwa v3, v3 dst_sel:DWORD dst_unused:UNUSED_PAD src0_sel:WORD_1
	v_cvt_f32_f16_sdwa v2, v2 dst_sel:DWORD dst_unused:UNUSED_PAD src0_sel:WORD_1
	v_mul_f32_e32 v6, 0.5, v6
	v_pk_add_f32 v[46:47], v[4:5], v[22:23]
	v_fma_f32 v4, v14, 0.5, -v22
	v_pk_add_f32 v[22:23], v[38:39], v[38:39] op_sel:[0,1] op_sel_hi:[0,1] neg_lo:[0,1] neg_hi:[0,1]
	v_pk_add_f32 v[38:39], v[6:7], v[22:23] op_sel_hi:[0,1] neg_hi:[0,1]
	v_mov_b32_e32 v14, v46
	v_mov_b32_e32 v15, v4
	v_pk_mul_f32 v[22:23], v[4:5], v[44:45] op_sel_hi:[0,1]
	v_pk_mul_f32 v[82:83], v[38:39], v[2:3]
	v_pk_mul_f32 v[46:47], v[46:47], v[2:3]
	v_pk_mul_f32 v[38:39], v[38:39], v[44:45]
	v_pk_fma_f32 v[98:99], v[14:15], v[44:45], v[82:83] neg_lo:[0,0,1] neg_hi:[0,0,1]
	v_pk_fma_f32 v[2:3], v[14:15], v[2:3], v[38:39] neg_lo:[0,0,1] neg_hi:[0,0,1]
	v_add_f32_e32 v4, v23, v83
	v_add_f32_e32 v6, v46, v38
	v_pk_add_f32 v[22:23], v[6:7], v[2:3] op_sel_hi:[0,1] neg_lo:[0,1] neg_hi:[0,1]
	v_pk_add_f32 v[38:39], v[98:99], v[4:5] op_sel_hi:[1,0] neg_lo:[0,1] neg_hi:[0,1]
	v_pk_add_f32 v[2:3], v[6:7], v[2:3] op_sel_hi:[0,1]
	v_mov_b32_e32 v39, v3
	v_pk_mul_f32 v[2:3], v[38:39], 0.5 op_sel_hi:[1,0]
	v_pk_add_f32 v[14:15], v[98:99], v[4:5] op_sel_hi:[1,0]
	v_mul_f32_e32 v4, v59, v3
	v_pk_fma_f32 v[38:39], v[42:43], v[2:3], v[4:5] op_sel_hi:[1,1,0] neg_lo:[0,0,1] neg_hi:[0,0,1]
	v_pk_mov_b32 v[42:43], v[58:59], v[8:9] op_sel:[1,0]
	v_mul_f32_e32 v4, v8, v3
	v_pk_fma_f32 v[2:3], v[42:43], v[2:3], v[4:5] op_sel_hi:[1,1,0]
	v_mov_b32_e32 v15, v23
	v_pk_fma_f32 v[8:9], v[14:15], 0.5, v[2:3] op_sel_hi:[1,0,1] neg_lo:[0,0,1] neg_hi:[0,0,1]
	v_pk_fma_f32 v[42:43], v[14:15], 0.5, v[38:39] op_sel_hi:[1,0,0]
	v_pk_fma_f32 v[2:3], v[14:15], 0.5, v[2:3] op_sel_hi:[1,0,1]
	v_mov_b32_e32 v9, v43
	v_pk_fma_f32 v[58:59], v[22:23], 0.5, v[38:39] op_sel_hi:[1,0,0] neg_lo:[1,0,0] neg_hi:[1,0,0]
	v_pk_mul_f32 v[144:145], v[8:9], s[6:7] op_sel_hi:[1,0]
	v_mov_b32_e32 v58, v2
	v_mov_b32_e32 v72, v10
	v_mov_b32_e32 v54, v40
	v_mov_b32_e32 v70, v20
	v_mov_b32_e32 v56, v26
	v_mov_b32_e32 v76, v36
	v_mov_b32_e32 v52, v34
	v_mov_b32_e32 v74, v86
	v_mov_b32_e32 v48, v84
	v_mov_b32_e32 v50, v60
	v_mov_b32_e32 v28, v66
	v_mov_b32_e32 v32, v96
	v_mov_b32_e32 v12, v88
	v_mov_b32_e32 v16, v92
	v_mov_b32_e32 v4, v138
	v_mov_b32_e32 v6, v122

.LBB0_503:
	s_or_b64 exec, exec, s[0:1]
	v_pk_mul_f32 v[22:23], v[32:33], s[6:7] op_sel_hi:[1,0]
	v_pk_add_f32 v[26:27], v[24:25], v[30:31]
	v_pk_add_f32 v[24:25], v[24:25], v[30:31] neg_lo:[0,1] neg_hi:[0,1]
	v_pk_add_f32 v[30:31], v[64:65], v[68:69]
	v_pk_add_f32 v[246:247], v[64:65], v[68:69] neg_lo:[0,1] neg_hi:[0,1]
	v_pk_add_f32 v[34:35], v[62:63], v[90:91]
	v_pk_add_f32 v[38:39], v[94:95], v[80:81]
	v_pk_add_f32 v[68:69], v[26:27], v[30:31]
	v_pk_add_f32 v[26:27], v[26:27], v[30:31] neg_lo:[0,1] neg_hi:[0,1]
	v_pk_mul_f32 v[20:21], v[50:51], s[6:7] op_sel_hi:[1,0]
	v_pk_add_f32 v[36:37], v[62:63], v[90:91] neg_lo:[0,1] neg_hi:[0,1]
	v_pk_add_f32 v[42:43], v[78:79], v[136:137]
	v_pk_add_f32 v[46:47], v[130:131], v[120:121]
	v_pk_add_f32 v[32:33], v[24:25], v[246:247] op_sel:[0,1] op_sel_hi:[1,0] neg_lo:[0,1]
	v_pk_add_f32 v[24:25], v[24:25], v[246:247] op_sel:[0,1] op_sel_hi:[1,0] neg_hi:[0,1]
	v_pk_add_f32 v[30:31], v[34:35], v[38:39]
	v_pk_add_f32 v[34:35], v[34:35], v[38:39] neg_lo:[0,1] neg_hi:[0,1]
	v_pk_add_f32 v[38:39], v[94:95], v[80:81] neg_lo:[0,1] neg_hi:[0,1]
	v_pk_add_f32 v[44:45], v[78:79], v[136:137] neg_lo:[0,1] neg_hi:[0,1]
	v_pk_add_f32 v[60:61], v[128:129], v[150:151]
	v_pk_add_f32 v[64:65], v[168:169], v[144:145]
	v_pk_add_f32 v[40:41], v[36:37], v[38:39] op_sel:[0,1] op_sel_hi:[1,0] neg_lo:[0,1]
	v_pk_add_f32 v[36:37], v[36:37], v[38:39] op_sel:[0,1] op_sel_hi:[1,0] neg_hi:[0,1]
	v_pk_add_f32 v[38:39], v[42:43], v[46:47]
	v_pk_add_f32 v[42:43], v[42:43], v[46:47] neg_lo:[0,1] neg_hi:[0,1]
	v_pk_add_f32 v[46:47], v[130:131], v[120:121] neg_lo:[0,1] neg_hi:[0,1]
	v_pk_add_f32 v[62:63], v[128:129], v[150:151] neg_lo:[0,1] neg_hi:[0,1]
	v_pk_add_f32 v[50:51], v[44:45], v[46:47] op_sel:[0,1] op_sel_hi:[1,0] neg_lo:[0,1]
	v_pk_add_f32 v[44:45], v[44:45], v[46:47] op_sel:[0,1] op_sel_hi:[1,0] neg_hi:[0,1]
	v_pk_add_f32 v[46:47], v[60:61], v[64:65]
	v_pk_add_f32 v[246:247], v[60:61], v[64:65] neg_lo:[0,1] neg_hi:[0,1]
	v_pk_add_f32 v[64:65], v[168:169], v[144:145] neg_lo:[0,1] neg_hi:[0,1]
	s_mov_b32 s78, s37
	s_mov_b32 s79, s36
	v_pk_add_f32 v[66:67], v[62:63], v[64:65] op_sel:[0,1] op_sel_hi:[1,0] neg_lo:[0,1]
	v_pk_add_f32 v[62:63], v[62:63], v[64:65] op_sel:[0,1] op_sel_hi:[1,0] neg_hi:[0,1]
	v_pk_add_f32 v[64:65], v[68:69], v[30:31]
	v_pk_add_f32 v[30:31], v[68:69], v[30:31] neg_lo:[0,1] neg_hi:[0,1]
	s_mov_b32 s0, s37
	v_pk_mul_f32 v[68:69], v[40:41], s[78:79]
	s_mov_b32 s80, s19
	v_pk_fma_f32 v[40:41], v[40:41], s[0:1], v[68:69] op_sel:[0,0,1] op_sel_hi:[1,0,0]
	s_mov_b32 s81, s18
	v_pk_add_f32 v[68:69], v[32:33], v[40:41]
	v_pk_add_f32 v[32:33], v[32:33], v[40:41] neg_lo:[0,1] neg_hi:[0,1]
	v_xor_b32_e32 v40, 0x80000000, v35
	v_mov_b32_e32 v41, v34
	v_pk_add_f32 v[34:35], v[26:27], v[40:41]
	v_pk_add_f32 v[26:27], v[26:27], v[40:41] neg_lo:[0,1] neg_hi:[0,1]
	v_pk_mul_f32 v[40:41], v[36:37], s[78:79]
	s_mov_b32 s82, s19
	v_pk_fma_f32 v[36:37], v[36:37], s[0:1], v[40:41] op_sel:[0,0,1] op_sel_hi:[1,0,0] neg_lo:[1,0,0] neg_hi:[1,0,0]
	v_pk_mul_f32 v[2:3], v[72:73], s[6:7] op_sel_hi:[1,0]
	v_pk_add_f32 v[40:41], v[24:25], v[36:37]
	v_pk_add_f32 v[24:25], v[24:25], v[36:37] neg_lo:[0,1] neg_hi:[0,1]
	v_pk_add_f32 v[36:37], v[38:39], v[46:47]
	v_pk_add_f32 v[38:39], v[38:39], v[46:47] neg_lo:[0,1] neg_hi:[0,1]
	v_pk_mul_f32 v[46:47], v[66:67], s[78:79]
	v_pk_mul_f32 v[8:9], v[70:71], s[6:7] op_sel_hi:[1,0]
	v_pk_fma_f32 v[46:47], v[66:67], s[0:1], v[46:47] op_sel:[0,0,1] op_sel_hi:[1,0,0]
	v_pk_mul_f32 v[10:11], v[76:77], s[6:7] op_sel_hi:[1,0]
	v_pk_add_f32 v[66:67], v[50:51], v[46:47]
	v_pk_add_f32 v[46:47], v[50:51], v[46:47] neg_lo:[0,1] neg_hi:[0,1]
	v_pk_add_f32 v[60:61], v[42:43], v[246:247] op_sel:[0,1] op_sel_hi:[1,0] neg_lo:[0,1]
	v_pk_add_f32 v[42:43], v[42:43], v[246:247] op_sel:[0,1] op_sel_hi:[1,0] neg_hi:[0,1]
	v_pk_mul_f32 v[50:51], v[62:63], s[78:79]
	v_pk_mul_f32 v[14:15], v[74:75], s[6:7] op_sel_hi:[1,0]
	v_pk_fma_f32 v[50:51], v[62:63], s[0:1], v[50:51] op_sel:[0,0,1] op_sel_hi:[1,0,0] neg_lo:[1,0,0] neg_hi:[1,0,0]
	v_pk_mul_f32 v[16:17], v[16:17], s[6:7] op_sel_hi:[1,0]
	v_pk_add_f32 v[62:63], v[44:45], v[50:51]
	v_pk_add_f32 v[44:45], v[44:45], v[50:51] neg_lo:[0,1] neg_hi:[0,1]
	v_pk_add_f32 v[50:51], v[64:65], v[36:37]
	v_pk_add_f32 v[36:37], v[64:65], v[36:37] neg_lo:[0,1] neg_hi:[0,1]
	v_pk_mul_f32 v[64:65], v[66:67], s[80:81]
	v_pk_mul_f32 v[6:7], v[6:7], s[6:7] op_sel_hi:[1,0]
	v_pk_fma_f32 v[64:65], v[66:67], s[16:17], v[64:65] op_sel:[0,0,1] op_sel_hi:[1,0,0]
	s_mov_b32 s17, s40
	v_pk_add_f32 v[66:67], v[68:69], v[64:65]
	v_pk_add_f32 v[64:65], v[68:69], v[64:65] neg_lo:[0,1] neg_hi:[0,1]
	v_pk_mul_f32 v[68:69], v[60:61], s[78:79]
	s_mov_b32 s88, s11
	v_pk_fma_f32 v[60:61], v[60:61], s[0:1], v[68:69] op_sel:[0,0,1] op_sel_hi:[1,0,0]
	s_mov_b32 s89, s10
	v_pk_add_f32 v[68:69], v[34:35], v[60:61]
	v_pk_add_f32 v[34:35], v[34:35], v[60:61] neg_lo:[0,1] neg_hi:[0,1]
	v_pk_mul_f32 v[60:61], v[62:63], s[16:17]
	s_mov_b32 s62, s27
	v_pk_fma_f32 v[60:61], v[62:63], s[82:83], v[60:61] op_sel:[0,0,1] op_sel_hi:[1,0,0]
	s_mov_b32 s63, s26
	v_pk_add_f32 v[62:63], v[40:41], v[60:61]
	v_pk_add_f32 v[40:41], v[40:41], v[60:61] neg_lo:[0,1] neg_hi:[0,1]
	v_xor_b32_e32 v60, 0x80000000, v39
	v_mov_b32_e32 v61, v38
	v_pk_add_f32 v[38:39], v[30:31], v[60:61]
	v_pk_add_f32 v[30:31], v[30:31], v[60:61] neg_lo:[0,1] neg_hi:[0,1]
	v_pk_mul_f32 v[60:61], v[46:47], s[16:17]
	s_mov_b32 s84, s27
	v_pk_fma_f32 v[46:47], v[46:47], s[82:83], v[60:61] op_sel:[0,0,1] op_sel_hi:[1,0,0] neg_lo:[1,0,0] neg_hi:[1,0,0]
	s_mov_b32 s86, s11
	v_pk_add_f32 v[60:61], v[32:33], v[46:47]
	v_pk_add_f32 v[32:33], v[32:33], v[46:47] neg_lo:[0,1] neg_hi:[0,1]
	v_pk_mul_f32 v[46:47], v[42:43], s[78:79]
	s_ashr_i32 s73, s72, 31
	v_pk_fma_f32 v[42:43], s[0:1], v[42:43], v[46:47] op_sel:[0,0,1] op_sel_hi:[0,1,0] neg_lo:[0,1,0] neg_hi:[0,1,0]
	v_pk_add_f32 v[46:47], v[26:27], v[42:43]
	v_pk_add_f32 v[26:27], v[26:27], v[42:43] neg_lo:[0,1] neg_hi:[0,1]
	v_pk_mul_f32 v[42:43], v[44:45], s[80:81]
	s_nop 0
	v_pk_fma_f32 v[42:43], s[16:17], v[44:45], v[42:43] op_sel:[0,0,1] op_sel_hi:[0,1,0] neg_lo:[0,1,0] neg_hi:[0,1,0]
	v_pk_add_f32 v[44:45], v[24:25], v[42:43]
	v_pk_add_f32 v[24:25], v[24:25], v[42:43] neg_lo:[0,1] neg_hi:[0,1]
	v_pk_fma_f32 v[42:43], v[58:59], s[6:7], v[2:3] op_sel_hi:[1,0,1]
	v_pk_fma_f32 v[2:3], v[58:59], s[6:7], v[2:3] op_sel_hi:[1,0,1] neg_lo:[0,0,1] neg_hi:[0,0,1]
	v_pk_fma_f32 v[58:59], v[54:55], s[6:7], v[8:9] op_sel_hi:[1,0,1]
	v_pk_fma_f32 v[246:247], v[54:55], s[6:7], v[8:9] op_sel_hi:[1,0,1] neg_lo:[0,0,1] neg_hi:[0,0,1]
	v_pk_fma_f32 v[54:55], v[56:57], s[6:7], v[10:11] op_sel_hi:[1,0,1]
	v_pk_fma_f32 v[10:11], v[56:57], s[6:7], v[10:11] op_sel_hi:[1,0,1] neg_lo:[0,0,1] neg_hi:[0,0,1]
	v_pk_fma_f32 v[56:57], v[52:53], s[6:7], v[14:15] op_sel_hi:[1,0,1]
	v_pk_fma_f32 v[14:15], v[52:53], s[6:7], v[14:15] op_sel_hi:[1,0,1] neg_lo:[0,0,1] neg_hi:[0,0,1]
	v_pk_fma_f32 v[52:53], v[48:49], s[6:7], v[20:21] op_sel_hi:[1,0,1]
	v_pk_fma_f32 v[20:21], v[48:49], s[6:7], v[20:21] op_sel_hi:[1,0,1] neg_lo:[0,0,1] neg_hi:[0,0,1]
	v_pk_fma_f32 v[48:49], v[28:29], s[6:7], v[22:23] op_sel_hi:[1,0,1]
	v_pk_fma_f32 v[22:23], v[28:29], s[6:7], v[22:23] op_sel_hi:[1,0,1] neg_lo:[0,0,1] neg_hi:[0,0,1]
	v_pk_fma_f32 v[28:29], v[12:13], s[6:7], v[16:17] op_sel_hi:[1,0,1]
	v_pk_fma_f32 v[12:13], v[12:13], s[6:7], v[16:17] op_sel_hi:[1,0,1] neg_lo:[0,0,1] neg_hi:[0,0,1]
	v_pk_fma_f32 v[16:17], v[4:5], s[6:7], v[6:7] op_sel_hi:[1,0,1]
	v_pk_fma_f32 v[4:5], v[4:5], s[6:7], v[6:7] op_sel_hi:[1,0,1] neg_lo:[0,0,1] neg_hi:[0,0,1]
	v_pk_add_f32 v[6:7], v[58:59], v[42:43]
	v_pk_add_f32 v[42:43], v[42:43], v[58:59] neg_lo:[0,1] neg_hi:[0,1]
	v_pk_add_f32 v[8:9], v[2:3], v[246:247] op_sel:[0,1] op_sel_hi:[1,0] neg_lo:[0,1]
	v_pk_add_f32 v[2:3], v[2:3], v[246:247] op_sel:[0,1] op_sel_hi:[1,0] neg_hi:[0,1]
	v_pk_add_f32 v[58:59], v[56:57], v[54:55]
	v_pk_add_f32 v[54:55], v[54:55], v[56:57] neg_lo:[0,1] neg_hi:[0,1]
	v_xor_b32_e32 v56, 0x80000000, v15
	v_mov_b32_e32 v57, v14
	v_pk_add_f32 v[14:15], v[10:11], v[56:57]
	v_pk_add_f32 v[10:11], v[10:11], v[56:57] neg_lo:[0,1] neg_hi:[0,1]
	v_pk_add_f32 v[56:57], v[48:49], v[52:53]
	v_pk_add_f32 v[48:49], v[52:53], v[48:49] neg_lo:[0,1] neg_hi:[0,1]
	v_xor_b32_e32 v52, 0x80000000, v23
	v_mov_b32_e32 v53, v22
	v_pk_add_f32 v[22:23], v[20:21], v[52:53]
	v_pk_add_f32 v[20:21], v[20:21], v[52:53] neg_lo:[0,1] neg_hi:[0,1]
	v_pk_add_f32 v[52:53], v[16:17], v[28:29]
	v_pk_add_f32 v[246:247], v[28:29], v[16:17] neg_lo:[0,1] neg_hi:[0,1]
	v_xor_b32_e32 v28, 0x80000000, v5
	v_mov_b32_e32 v29, v4
	v_pk_add_f32 v[4:5], v[12:13], v[28:29]
	v_pk_add_f32 v[12:13], v[12:13], v[28:29] neg_lo:[0,1] neg_hi:[0,1]
	v_pk_add_f32 v[28:29], v[58:59], v[6:7]
	v_pk_add_f32 v[6:7], v[6:7], v[58:59] neg_lo:[0,1] neg_hi:[0,1]
	v_pk_mul_f32 v[58:59], v[14:15], s[78:79]
	s_nop 0
	v_pk_fma_f32 v[14:15], s[0:1], v[14:15], v[58:59] op_sel:[0,0,1] op_sel_hi:[0,1,0]
	v_pk_add_f32 v[58:59], v[14:15], v[8:9]
	v_pk_add_f32 v[8:9], v[8:9], v[14:15] neg_lo:[0,1] neg_hi:[0,1]
	v_xor_b32_e32 v14, 0x80000000, v55
	v_mov_b32_e32 v15, v54
	v_pk_add_f32 v[54:55], v[14:15], v[42:43]
	v_pk_add_f32 v[14:15], v[42:43], v[14:15] neg_lo:[0,1] neg_hi:[0,1]
	v_pk_mul_f32 v[42:43], v[10:11], s[78:79]
	s_nop 0
	v_pk_fma_f32 v[10:11], s[0:1], v[10:11], v[42:43] op_sel:[0,0,1] op_sel_hi:[0,1,0] neg_lo:[0,1,0] neg_hi:[0,1,0]
	v_pk_add_f32 v[42:43], v[10:11], v[2:3]
	v_pk_add_f32 v[2:3], v[2:3], v[10:11] neg_lo:[0,1] neg_hi:[0,1]
	v_pk_add_f32 v[10:11], v[52:53], v[56:57]
	v_pk_add_f32 v[52:53], v[56:57], v[52:53] neg_lo:[0,1] neg_hi:[0,1]
	v_pk_mul_f32 v[56:57], v[4:5], s[78:79]
	s_nop 0
	v_pk_fma_f32 v[4:5], s[0:1], v[4:5], v[56:57] op_sel:[0,0,1] op_sel_hi:[0,1,0]
	v_pk_add_f32 v[56:57], v[4:5], v[22:23]
	v_pk_add_f32 v[4:5], v[22:23], v[4:5] neg_lo:[0,1] neg_hi:[0,1]
	v_pk_add_f32 v[16:17], v[246:247], v[48:49] op_sel:[1,0] op_sel_hi:[0,1] neg_lo:[1,0]
	v_pk_add_f32 v[22:23], v[48:49], v[246:247] op_sel:[0,1] op_sel_hi:[1,0] neg_hi:[0,1]
	v_pk_mul_f32 v[48:49], v[12:13], s[78:79]
	s_nop 0
	v_pk_fma_f32 v[12:13], s[0:1], v[12:13], v[48:49] op_sel:[0,0,1] op_sel_hi:[0,1,0] neg_lo:[0,1,0] neg_hi:[0,1,0]
	v_pk_add_f32 v[48:49], v[12:13], v[20:21]
	v_pk_add_f32 v[12:13], v[20:21], v[12:13] neg_lo:[0,1] neg_hi:[0,1]
	v_pk_add_f32 v[20:21], v[10:11], v[28:29]
	v_pk_add_f32 v[10:11], v[28:29], v[10:11] neg_lo:[0,1] neg_hi:[0,1]
	v_pk_mul_f32 v[28:29], v[56:57], s[80:81]
	s_nop 0
	v_pk_fma_f32 v[28:29], s[16:17], v[56:57], v[28:29] op_sel:[0,0,1] op_sel_hi:[0,1,0]
	v_pk_add_f32 v[56:57], v[28:29], v[58:59]
	v_pk_add_f32 v[28:29], v[58:59], v[28:29] neg_lo:[0,1] neg_hi:[0,1]
	v_pk_mul_f32 v[58:59], v[16:17], s[78:79]
	s_nop 0
	v_pk_fma_f32 v[16:17], s[0:1], v[16:17], v[58:59] op_sel:[0,0,1] op_sel_hi:[0,1,0]
	v_pk_add_f32 v[58:59], v[16:17], v[54:55]
	v_pk_add_f32 v[16:17], v[54:55], v[16:17] neg_lo:[0,1] neg_hi:[0,1]
	v_pk_mul_f32 v[54:55], v[48:49], s[16:17]
	s_nop 0
	v_pk_fma_f32 v[48:49], s[82:83], v[48:49], v[54:55] op_sel:[0,0,1] op_sel_hi:[0,1,0]
	v_pk_add_f32 v[54:55], v[48:49], v[42:43]
	v_pk_add_f32 v[42:43], v[42:43], v[48:49] neg_lo:[0,1] neg_hi:[0,1]
	v_xor_b32_e32 v48, 0x80000000, v53
	v_mov_b32_e32 v49, v52
	v_pk_add_f32 v[52:53], v[48:49], v[6:7]
	v_pk_add_f32 v[6:7], v[6:7], v[48:49] neg_lo:[0,1] neg_hi:[0,1]
	v_pk_mul_f32 v[48:49], v[4:5], s[16:17]
	s_nop 0
	v_pk_fma_f32 v[4:5], s[82:83], v[4:5], v[48:49] op_sel:[0,0,1] op_sel_hi:[0,1,0] neg_lo:[0,1,0] neg_hi:[0,1,0]
	v_pk_add_f32 v[48:49], v[4:5], v[8:9]
	v_pk_add_f32 v[4:5], v[8:9], v[4:5] neg_lo:[0,1] neg_hi:[0,1]
	v_pk_mul_f32 v[8:9], v[22:23], s[78:79]
	s_nop 0
	v_pk_fma_f32 v[8:9], s[0:1], v[22:23], v[8:9] op_sel:[0,0,1] op_sel_hi:[0,1,0] neg_lo:[0,1,0] neg_hi:[0,1,0]
	v_pk_add_f32 v[22:23], v[8:9], v[14:15]
	v_pk_add_f32 v[8:9], v[14:15], v[8:9] neg_lo:[0,1] neg_hi:[0,1]
	v_pk_mul_f32 v[14:15], v[12:13], s[80:81]
	s_nop 0
	v_pk_fma_f32 v[12:13], s[16:17], v[12:13], v[14:15] op_sel:[0,0,1] op_sel_hi:[0,1,0] neg_lo:[0,1,0] neg_hi:[0,1,0]
	v_pk_add_f32 v[14:15], v[12:13], v[2:3]
	v_pk_add_f32 v[2:3], v[2:3], v[12:13] neg_lo:[0,1] neg_hi:[0,1]
	ds_write_b64 v211, v[50:51]
	ds_write_b64 v212, v[20:21]
	ds_write_b64 v211, v[66:67] offset:8
	ds_write_b64 v212, v[56:57] offset:8
	ds_write_b64 v211, v[68:69] offset:16
	ds_write_b64 v212, v[58:59] offset:16
	ds_write_b64 v211, v[62:63] offset:24
	ds_write_b64 v212, v[54:55] offset:24
	ds_write_b64 v211, v[38:39] offset:32
	ds_write_b64 v212, v[52:53] offset:32
	ds_write_b64 v211, v[60:61] offset:40
	ds_write_b64 v212, v[48:49] offset:40
	ds_write_b64 v211, v[46:47] offset:48
	ds_write_b64 v212, v[22:23] offset:48
	ds_write_b64 v211, v[44:45] offset:56
	ds_write_b64 v212, v[14:15] offset:56
	ds_write_b64 v211, v[36:37] offset:64
	ds_write_b64 v212, v[10:11] offset:64
	ds_write_b64 v211, v[64:65] offset:72
	ds_write_b64 v212, v[28:29] offset:72
	ds_write_b64 v211, v[34:35] offset:80
	ds_write_b64 v212, v[16:17] offset:80
	ds_write_b64 v211, v[40:41] offset:88
	ds_write_b64 v212, v[42:43] offset:88
	ds_write_b64 v211, v[30:31] offset:96
	ds_write_b64 v212, v[6:7] offset:96
	ds_write_b64 v211, v[32:33] offset:104
	ds_write_b64 v212, v[4:5] offset:104
	ds_write_b64 v211, v[26:27] offset:112
	ds_write_b64 v212, v[8:9] offset:112
	ds_write_b64 v211, v[24:25] offset:120
	ds_write_b64 v212, v[2:3] offset:120
	v_mov_b32_e32 v2, v210
	s_waitcnt lgkmcnt(0)
	s_barrier
	s_nop 0
	v_and_b32_e32 v3, 15, v2
	v_lshlrev_b32_e32 v5, 3, v3
	v_cvt_f32_ubyte0_e32 v3, v3
	v_mul_f32_e32 v3, 0x3b000000, v3
	v_sin_f32_e32 v17, v3
	v_cos_f32_e32 v16, v3
	v_lshlrev_b32_e32 v2, 5, v2
	v_and_b32_e32 v2, 0xfffffe00, v2
	v_lshl_add_u32 v4, v2, 3, 0
	v_ashrrev_i32_e32 v2, 2, v2
	v_xor_b32_e32 v72, 0x80000000, v17
	v_mov_b32_e32 v73, v17
	v_add3_u32 v2, v4, v5, v2
	v_pk_mul_f32 v[4:5], v[16:17], v[72:73] op_sel:[1,0] op_sel_hi:[0,1]
	v_pk_fma_f32 v[74:75], v[16:17], v[16:17], v[4:5] op_sel_hi:[1,0,1]
	v_add_u32_e32 v3, 0x800, v2
	v_pk_mul_f32 v[4:5], v[72:73], v[74:75] op_sel:[0,1] op_sel_hi:[1,0]
	v_xor_b32_e32 v78, 0x80000000, v75
	v_mov_b32_e32 v79, v75
	v_pk_fma_f32 v[76:77], v[16:17], v[74:75], v[4:5] op_sel_hi:[0,1,1]
	v_pk_mul_f32 v[4:5], v[74:75], v[78:79] op_sel:[1,0] op_sel_hi:[0,1]
	v_pk_fma_f32 v[80:81], v[74:75], v[74:75], v[4:5] op_sel_hi:[1,0,1]
	v_xor_b32_e32 v84, 0x80000000, v77
	v_pk_mul_f32 v[4:5], v[72:73], v[80:81] op_sel:[0,1] op_sel_hi:[1,0]
	v_mov_b32_e32 v85, v77
	v_pk_fma_f32 v[86:87], v[16:17], v[80:81], v[4:5] op_sel_hi:[0,1,1]
	v_pk_mul_f32 v[4:5], v[78:79], v[80:81] op_sel:[0,1] op_sel_hi:[1,0]
	v_xor_b32_e32 v82, 0x80000000, v81
	v_mov_b32_e32 v83, v81
	v_pk_fma_f32 v[90:91], v[74:75], v[80:81], v[4:5] op_sel_hi:[0,1,1]
	v_pk_mul_f32 v[4:5], v[80:81], v[84:85] op_sel:[1,0] op_sel_hi:[0,1]
	v_pk_fma_f32 v[94:95], v[80:81], v[76:77], v[4:5] op_sel_hi:[1,0,1]
	v_pk_mul_f32 v[4:5], v[80:81], v[82:83] op_sel:[1,0] op_sel_hi:[0,1]
	v_pk_fma_f32 v[98:99], v[80:81], v[80:81], v[4:5] op_sel_hi:[1,0,1]
	v_xor_b32_e32 v88, 0x80000000, v87
	v_pk_mul_f32 v[4:5], v[72:73], v[98:99] op_sel:[0,1] op_sel_hi:[1,0]
	v_mov_b32_e32 v89, v87
	v_pk_fma_f32 v[102:103], v[16:17], v[98:99], v[4:5] op_sel_hi:[0,1,1]
	v_pk_mul_f32 v[4:5], v[78:79], v[98:99] op_sel:[0,1] op_sel_hi:[1,0]
	v_xor_b32_e32 v92, 0x80000000, v91
	v_pk_fma_f32 v[106:107], v[74:75], v[98:99], v[4:5] op_sel_hi:[0,1,1]
	v_pk_mul_f32 v[4:5], v[84:85], v[98:99] op_sel:[0,1] op_sel_hi:[1,0]
	v_mov_b32_e32 v93, v91
	v_pk_fma_f32 v[110:111], v[76:77], v[98:99], v[4:5] op_sel_hi:[0,1,1]
	v_pk_mul_f32 v[4:5], v[82:83], v[98:99] op_sel:[0,1] op_sel_hi:[1,0]
	v_xor_b32_e32 v96, 0x80000000, v95
	v_pk_fma_f32 v[114:115], v[80:81], v[98:99], v[4:5] op_sel_hi:[0,1,1]
	v_pk_mul_f32 v[4:5], v[72:73], v[114:115] op_sel:[0,1] op_sel_hi:[1,0]
	v_mov_b32_e32 v97, v95
	v_pk_fma_f32 v[118:119], v[16:17], v[114:115], v[4:5] op_sel_hi:[0,1,1]
	v_pk_mul_f32 v[4:5], v[78:79], v[114:115] op_sel:[0,1] op_sel_hi:[1,0]
	v_xor_b32_e32 v100, 0x80000000, v99
	v_pk_fma_f32 v[122:123], v[74:75], v[114:115], v[4:5] op_sel_hi:[0,1,1]
	v_pk_mul_f32 v[4:5], v[84:85], v[114:115] op_sel:[0,1] op_sel_hi:[1,0]
	v_mov_b32_e32 v101, v99
	v_pk_fma_f32 v[126:127], v[76:77], v[114:115], v[4:5] op_sel_hi:[0,1,1]
	v_pk_mul_f32 v[4:5], v[82:83], v[114:115] op_sel:[0,1] op_sel_hi:[1,0]
	v_xor_b32_e32 v104, 0x80000000, v103
	v_pk_fma_f32 v[130:131], v[80:81], v[114:115], v[4:5] op_sel_hi:[0,1,1]
	v_pk_mul_f32 v[4:5], v[72:73], v[130:131] op_sel:[0,1] op_sel_hi:[1,0]
	v_mov_b32_e32 v105, v103
	v_pk_fma_f32 v[134:135], v[16:17], v[130:131], v[4:5] op_sel_hi:[0,1,1]
	v_pk_mul_f32 v[4:5], v[78:79], v[130:131] op_sel:[0,1] op_sel_hi:[1,0]
	v_xor_b32_e32 v108, 0x80000000, v107
	v_pk_fma_f32 v[138:139], v[74:75], v[130:131], v[4:5] op_sel_hi:[0,1,1]
	v_pk_mul_f32 v[4:5], v[84:85], v[130:131] op_sel:[0,1] op_sel_hi:[1,0]
	v_mov_b32_e32 v109, v107
	v_pk_fma_f32 v[142:143], v[76:77], v[130:131], v[4:5] op_sel_hi:[0,1,1]
	v_pk_mul_f32 v[4:5], v[82:83], v[130:131] op_sel:[0,1] op_sel_hi:[1,0]
	v_xor_b32_e32 v112, 0x80000000, v111
	v_pk_fma_f32 v[148:149], v[80:81], v[130:131], v[4:5] op_sel_hi:[0,1,1]
	v_pk_mul_f32 v[4:5], v[72:73], v[148:149] op_sel:[0,1] op_sel_hi:[1,0]
	v_mov_b32_e32 v113, v111
	v_pk_fma_f32 v[152:153], v[16:17], v[148:149], v[4:5] op_sel_hi:[0,1,1]
	v_pk_mul_f32 v[4:5], v[78:79], v[148:149] op_sel:[0,1] op_sel_hi:[1,0]
	v_xor_b32_e32 v116, 0x80000000, v115
	v_pk_fma_f32 v[156:157], v[74:75], v[148:149], v[4:5] op_sel_hi:[0,1,1]
	v_pk_mul_f32 v[4:5], v[84:85], v[148:149] op_sel:[0,1] op_sel_hi:[1,0]
	v_mov_b32_e32 v117, v115
	v_pk_fma_f32 v[160:161], v[76:77], v[148:149], v[4:5] op_sel_hi:[0,1,1]
	v_pk_mul_f32 v[4:5], v[82:83], v[148:149] op_sel:[0,1] op_sel_hi:[1,0]
	v_xor_b32_e32 v120, 0x80000000, v119
	v_pk_fma_f32 v[164:165], v[80:81], v[148:149], v[4:5] op_sel_hi:[0,1,1]
	v_pk_mul_f32 v[4:5], v[72:73], v[164:165] op_sel:[0,1] op_sel_hi:[1,0]
	v_mov_b32_e32 v121, v119
	v_pk_fma_f32 v[168:169], v[16:17], v[164:165], v[4:5] op_sel_hi:[0,1,1]
	v_pk_mul_f32 v[4:5], v[78:79], v[164:165] op_sel:[0,1] op_sel_hi:[1,0]
	v_xor_b32_e32 v124, 0x80000000, v123
	v_pk_fma_f32 v[172:173], v[74:75], v[164:165], v[4:5] op_sel_hi:[0,1,1]
	v_pk_mul_f32 v[4:5], v[84:85], v[164:165] op_sel:[0,1] op_sel_hi:[1,0]
	v_mov_b32_e32 v125, v123
	v_pk_fma_f32 v[176:177], v[76:77], v[164:165], v[4:5] op_sel_hi:[0,1,1]
	v_pk_mul_f32 v[4:5], v[82:83], v[164:165] op_sel:[0,1] op_sel_hi:[1,0]
	v_xor_b32_e32 v128, 0x80000000, v127
	v_pk_fma_f32 v[180:181], v[80:81], v[164:165], v[4:5] op_sel_hi:[0,1,1]
	v_pk_mul_f32 v[4:5], v[72:73], v[180:181] op_sel:[0,1] op_sel_hi:[1,0]
	v_mov_b32_e32 v129, v127
	v_pk_fma_f32 v[184:185], v[16:17], v[180:181], v[4:5] op_sel_hi:[0,1,1]
	v_pk_mul_f32 v[4:5], v[78:79], v[180:181] op_sel:[0,1] op_sel_hi:[1,0]
	v_xor_b32_e32 v132, 0x80000000, v131
	v_pk_fma_f32 v[188:189], v[74:75], v[180:181], v[4:5] op_sel_hi:[0,1,1]
	v_pk_mul_f32 v[4:5], v[84:85], v[180:181] op_sel:[0,1] op_sel_hi:[1,0]
	v_mov_b32_e32 v133, v131
	v_pk_fma_f32 v[192:193], v[76:77], v[180:181], v[4:5] op_sel_hi:[0,1,1]
	ds_read2_b64 v[4:7], v2 offset1:16
	ds_read2_b64 v[8:11], v2 offset0:33 offset1:49
	ds_read2_b64 v[12:15], v2 offset0:66 offset1:82
	ds_read2_b64 v[20:23], v2 offset0:99 offset1:115
	ds_read2_b64 v[24:27], v2 offset0:132 offset1:148
	ds_read2_b64 v[28:31], v2 offset0:165 offset1:181
	ds_read2_b64 v[32:35], v2 offset0:198 offset1:214
	ds_read2_b64 v[36:39], v2 offset0:231 offset1:247
	ds_read2_b64 v[40:43], v3 offset0:8 offset1:24
	ds_read2_b64 v[44:47], v3 offset0:41 offset1:57
	ds_read2_b64 v[48:51], v3 offset0:74 offset1:90
	ds_read2_b64 v[52:55], v3 offset0:107 offset1:123
	ds_read2_b64 v[56:59], v3 offset0:140 offset1:156
	ds_read2_b64 v[60:63], v3 offset0:173 offset1:189
	ds_read2_b64 v[64:67], v3 offset0:206 offset1:222
	ds_read2_b64 v[68:71], v3 offset0:239 offset1:255
	s_waitcnt lgkmcnt(7)
	v_pk_mul_f32 v[72:73], v[72:73], v[40:41] op_sel:[0,1] op_sel_hi:[1,0]
	v_xor_b32_e32 v136, 0x80000000, v135
	v_pk_fma_f32 v[16:17], v[16:17], v[40:41], v[72:73] op_sel_hi:[0,1,1]
	v_pk_mul_f32 v[40:41], v[24:25], v[78:79] op_sel:[1,0] op_sel_hi:[0,1]
	v_pk_fma_f32 v[24:25], v[24:25], v[74:75], v[40:41] op_sel_hi:[1,0,1]
	s_waitcnt lgkmcnt(3)
	v_pk_mul_f32 v[40:41], v[84:85], v[56:57] op_sel:[0,1] op_sel_hi:[1,0]
	v_mov_b32_e32 v137, v135
	v_pk_fma_f32 v[40:41], v[76:77], v[56:57], v[40:41] op_sel_hi:[0,1,1]
	v_pk_mul_f32 v[56:57], v[12:13], v[82:83] op_sel:[1,0] op_sel_hi:[0,1]
	v_pk_fma_f32 v[12:13], v[12:13], v[80:81], v[56:57] op_sel_hi:[1,0,1]
	v_pk_mul_f32 v[56:57], v[88:89], v[48:49] op_sel:[0,1] op_sel_hi:[1,0]
	v_xor_b32_e32 v140, 0x80000000, v139
	v_pk_fma_f32 v[48:49], v[86:87], v[48:49], v[56:57] op_sel_hi:[0,1,1]
	v_pk_mul_f32 v[56:57], v[32:33], v[92:93] op_sel:[1,0] op_sel_hi:[0,1]
	v_pk_fma_f32 v[32:33], v[32:33], v[90:91], v[56:57] op_sel_hi:[1,0,1]
	s_waitcnt lgkmcnt(1)
	v_pk_mul_f32 v[56:57], v[96:97], v[64:65] op_sel:[0,1] op_sel_hi:[1,0]
	v_mov_b32_e32 v141, v139
	v_pk_fma_f32 v[56:57], v[94:95], v[64:65], v[56:57] op_sel_hi:[0,1,1]
	v_pk_mul_f32 v[64:65], v[8:9], v[100:101] op_sel:[1,0] op_sel_hi:[0,1]
	v_pk_fma_f32 v[8:9], v[8:9], v[98:99], v[64:65] op_sel_hi:[1,0,1]
	v_pk_mul_f32 v[64:65], v[44:45], v[104:105] op_sel:[1,0] op_sel_hi:[0,1]
	v_pk_fma_f32 v[44:45], v[44:45], v[102:103], v[64:65] op_sel_hi:[1,0,1]
	v_pk_mul_f32 v[64:65], v[28:29], v[108:109] op_sel:[1,0] op_sel_hi:[0,1]
	v_pk_fma_f32 v[28:29], v[28:29], v[106:107], v[64:65] op_sel_hi:[1,0,1]
	v_pk_mul_f32 v[64:65], v[112:113], v[60:61] op_sel:[0,1] op_sel_hi:[1,0]
	v_xor_b32_e32 v144, 0x80000000, v143
	v_pk_fma_f32 v[60:61], v[110:111], v[60:61], v[64:65] op_sel_hi:[0,1,1]
	v_pk_mul_f32 v[64:65], v[20:21], v[116:117] op_sel:[1,0] op_sel_hi:[0,1]
	v_pk_fma_f32 v[20:21], v[20:21], v[114:115], v[64:65] op_sel_hi:[1,0,1]
	v_pk_mul_f32 v[64:65], v[52:53], v[120:121] op_sel:[1,0] op_sel_hi:[0,1]
	v_pk_fma_f32 v[52:53], v[52:53], v[118:119], v[64:65] op_sel_hi:[1,0,1]
	v_pk_mul_f32 v[64:65], v[36:37], v[124:125] op_sel:[1,0] op_sel_hi:[0,1]
	v_pk_fma_f32 v[36:37], v[36:37], v[122:123], v[64:65] op_sel_hi:[1,0,1]
	s_waitcnt lgkmcnt(0)
	v_pk_mul_f32 v[64:65], v[128:129], v[68:69] op_sel:[0,1] op_sel_hi:[1,0]
	v_mov_b32_e32 v145, v143
	v_pk_fma_f32 v[64:65], v[126:127], v[68:69], v[64:65] op_sel_hi:[0,1,1]
	v_pk_mul_f32 v[68:69], v[6:7], v[132:133] op_sel:[1,0] op_sel_hi:[0,1]
	v_pk_fma_f32 v[6:7], v[6:7], v[130:131], v[68:69] op_sel_hi:[1,0,1]
	v_pk_mul_f32 v[68:69], v[42:43], v[136:137] op_sel:[1,0] op_sel_hi:[0,1]
	v_pk_fma_f32 v[42:43], v[42:43], v[134:135], v[68:69] op_sel_hi:[1,0,1]
	v_pk_mul_f32 v[68:69], v[26:27], v[140:141] op_sel:[1,0] op_sel_hi:[0,1]
	v_xor_b32_e32 v150, 0x80000000, v149
	v_mov_b32_e32 v151, v149
	v_pk_fma_f32 v[26:27], v[26:27], v[138:139], v[68:69] op_sel_hi:[1,0,1]
	v_pk_mul_f32 v[68:69], v[58:59], v[144:145] op_sel:[1,0] op_sel_hi:[0,1]
	v_xor_b32_e32 v154, 0x80000000, v153
	v_mov_b32_e32 v155, v153
	v_pk_fma_f32 v[58:59], v[58:59], v[142:143], v[68:69] op_sel_hi:[1,0,1]
	v_pk_mul_f32 v[68:69], v[14:15], v[150:151] op_sel:[1,0] op_sel_hi:[0,1]
	v_xor_b32_e32 v158, 0x80000000, v157
	v_mov_b32_e32 v159, v157
	v_pk_fma_f32 v[14:15], v[14:15], v[148:149], v[68:69] op_sel_hi:[1,0,1]
	v_pk_mul_f32 v[68:69], v[50:51], v[154:155] op_sel:[1,0] op_sel_hi:[0,1]
	v_xor_b32_e32 v162, 0x80000000, v161
	v_mov_b32_e32 v163, v161
	v_pk_fma_f32 v[50:51], v[50:51], v[152:153], v[68:69] op_sel_hi:[1,0,1]
	v_pk_mul_f32 v[68:69], v[34:35], v[158:159] op_sel:[1,0] op_sel_hi:[0,1]
	v_xor_b32_e32 v166, 0x80000000, v165
	v_mov_b32_e32 v167, v165
	v_pk_fma_f32 v[34:35], v[34:35], v[156:157], v[68:69] op_sel_hi:[1,0,1]
	v_pk_mul_f32 v[68:69], v[162:163], v[66:67] op_sel:[0,1] op_sel_hi:[1,0]
	v_xor_b32_e32 v170, 0x80000000, v169
	v_mov_b32_e32 v171, v169
	v_pk_fma_f32 v[66:67], v[160:161], v[66:67], v[68:69] op_sel_hi:[0,1,1]
	v_pk_mul_f32 v[68:69], v[10:11], v[166:167] op_sel:[1,0] op_sel_hi:[0,1]
	v_xor_b32_e32 v174, 0x80000000, v173
	v_mov_b32_e32 v175, v173
	v_pk_fma_f32 v[10:11], v[10:11], v[164:165], v[68:69] op_sel_hi:[1,0,1]
	v_pk_mul_f32 v[68:69], v[46:47], v[170:171] op_sel:[1,0] op_sel_hi:[0,1]
	v_xor_b32_e32 v178, 0x80000000, v177
	v_mov_b32_e32 v179, v177
	v_pk_fma_f32 v[46:47], v[46:47], v[168:169], v[68:69] op_sel_hi:[1,0,1]
	v_pk_mul_f32 v[68:69], v[30:31], v[174:175] op_sel:[1,0] op_sel_hi:[0,1]
	v_xor_b32_e32 v182, 0x80000000, v181
	v_mov_b32_e32 v183, v181
	v_pk_fma_f32 v[30:31], v[30:31], v[172:173], v[68:69] op_sel_hi:[1,0,1]
	v_pk_mul_f32 v[68:69], v[62:63], v[178:179] op_sel:[1,0] op_sel_hi:[0,1]
	v_xor_b32_e32 v186, 0x80000000, v185
	v_mov_b32_e32 v187, v185
	v_pk_fma_f32 v[62:63], v[62:63], v[176:177], v[68:69] op_sel_hi:[1,0,1]
	v_pk_mul_f32 v[68:69], v[22:23], v[182:183] op_sel:[1,0] op_sel_hi:[0,1]
	v_xor_b32_e32 v190, 0x80000000, v189
	v_mov_b32_e32 v191, v189
	v_pk_fma_f32 v[22:23], v[22:23], v[180:181], v[68:69] op_sel_hi:[1,0,1]
	v_pk_mul_f32 v[68:69], v[54:55], v[186:187] op_sel:[1,0] op_sel_hi:[0,1]
	v_xor_b32_e32 v194, 0x80000000, v193
	v_mov_b32_e32 v195, v193
	v_pk_fma_f32 v[54:55], v[54:55], v[184:185], v[68:69] op_sel_hi:[1,0,1]
	v_pk_mul_f32 v[68:69], v[38:39], v[190:191] op_sel:[1,0] op_sel_hi:[0,1]
	v_pk_fma_f32 v[38:39], v[38:39], v[188:189], v[68:69] op_sel_hi:[1,0,1]
	v_pk_mul_f32 v[68:69], v[70:71], v[194:195] op_sel:[1,0] op_sel_hi:[0,1]
	v_pk_fma_f32 v[68:69], v[70:71], v[192:193], v[68:69] op_sel_hi:[1,0,1]
	v_pk_add_f32 v[70:71], v[4:5], v[6:7]
	v_pk_add_f32 v[4:5], v[4:5], v[6:7] neg_lo:[0,1] neg_hi:[0,1]
	v_pk_add_f32 v[6:7], v[8:9], v[10:11]
	v_pk_add_f32 v[246:247], v[8:9], v[10:11] neg_lo:[0,1] neg_hi:[0,1]
	v_pk_add_f32 v[10:11], v[12:13], v[14:15]
	v_pk_add_f32 v[12:13], v[12:13], v[14:15] neg_lo:[0,1] neg_hi:[0,1]
	v_pk_add_f32 v[14:15], v[20:21], v[22:23]
	v_pk_add_f32 v[20:21], v[20:21], v[22:23] neg_lo:[0,1] neg_hi:[0,1]
	v_pk_add_f32 v[22:23], v[24:25], v[26:27]
	v_pk_add_f32 v[24:25], v[24:25], v[26:27] neg_lo:[0,1] neg_hi:[0,1]
	v_pk_add_f32 v[26:27], v[28:29], v[30:31]
	v_pk_add_f32 v[28:29], v[28:29], v[30:31] neg_lo:[0,1] neg_hi:[0,1]
	v_pk_add_f32 v[30:31], v[32:33], v[34:35]
	v_pk_add_f32 v[32:33], v[32:33], v[34:35] neg_lo:[0,1] neg_hi:[0,1]
	v_pk_add_f32 v[34:35], v[36:37], v[38:39]
	v_pk_add_f32 v[36:37], v[36:37], v[38:39] neg_lo:[0,1] neg_hi:[0,1]
	v_pk_add_f32 v[38:39], v[16:17], v[42:43]
	v_pk_add_f32 v[16:17], v[16:17], v[42:43] neg_lo:[0,1] neg_hi:[0,1]
	v_pk_add_f32 v[42:43], v[44:45], v[46:47]
	v_pk_add_f32 v[44:45], v[44:45], v[46:47] neg_lo:[0,1] neg_hi:[0,1]
	v_pk_add_f32 v[46:47], v[48:49], v[50:51]
	v_pk_add_f32 v[48:49], v[48:49], v[50:51] neg_lo:[0,1] neg_hi:[0,1]
	v_pk_add_f32 v[50:51], v[52:53], v[54:55]
	v_pk_add_f32 v[52:53], v[52:53], v[54:55] neg_lo:[0,1] neg_hi:[0,1]
	v_pk_add_f32 v[54:55], v[40:41], v[58:59]
	v_pk_add_f32 v[40:41], v[40:41], v[58:59] neg_lo:[0,1] neg_hi:[0,1]
	v_pk_add_f32 v[58:59], v[60:61], v[62:63]
	v_pk_add_f32 v[60:61], v[60:61], v[62:63] neg_lo:[0,1] neg_hi:[0,1]
	v_pk_add_f32 v[62:63], v[56:57], v[66:67]
	v_pk_add_f32 v[56:57], v[56:57], v[66:67] neg_lo:[0,1] neg_hi:[0,1]
	v_pk_add_f32 v[66:67], v[64:65], v[68:69]
	v_pk_add_f32 v[64:65], v[64:65], v[68:69] neg_lo:[0,1] neg_hi:[0,1]
	v_pk_add_f32 v[68:69], v[70:71], v[6:7]
	v_pk_add_f32 v[6:7], v[70:71], v[6:7] neg_lo:[0,1] neg_hi:[0,1]
	v_pk_add_f32 v[8:9], v[4:5], v[246:247] op_sel:[0,1] op_sel_hi:[1,0] neg_lo:[0,1]
	v_pk_add_f32 v[4:5], v[4:5], v[246:247] op_sel:[0,1] op_sel_hi:[1,0] neg_hi:[0,1]
	v_pk_add_f32 v[70:71], v[10:11], v[14:15]
	v_pk_add_f32 v[10:11], v[10:11], v[14:15] neg_lo:[0,1] neg_hi:[0,1]
	v_xor_b32_e32 v14, 0x80000000, v21
	v_mov_b32_e32 v15, v20
	v_pk_add_f32 v[20:21], v[12:13], v[14:15]
	v_pk_add_f32 v[12:13], v[12:13], v[14:15] neg_lo:[0,1] neg_hi:[0,1]
	v_pk_add_f32 v[14:15], v[22:23], v[26:27]
	v_pk_add_f32 v[22:23], v[22:23], v[26:27] neg_lo:[0,1] neg_hi:[0,1]
	v_xor_b32_e32 v26, 0x80000000, v29
	v_mov_b32_e32 v27, v28
	v_pk_add_f32 v[28:29], v[24:25], v[26:27]
	v_pk_add_f32 v[24:25], v[24:25], v[26:27] neg_lo:[0,1] neg_hi:[0,1]
	v_pk_add_f32 v[26:27], v[30:31], v[34:35]
	v_pk_add_f32 v[246:247], v[30:31], v[34:35] neg_lo:[0,1] neg_hi:[0,1]
	v_xor_b32_e32 v34, 0x80000000, v37
	v_mov_b32_e32 v35, v36
	v_pk_add_f32 v[36:37], v[32:33], v[34:35]
	v_pk_add_f32 v[32:33], v[32:33], v[34:35] neg_lo:[0,1] neg_hi:[0,1]
	v_pk_add_f32 v[34:35], v[38:39], v[42:43]
	v_pk_add_f32 v[38:39], v[38:39], v[42:43] neg_lo:[0,1] neg_hi:[0,1]
	v_xor_b32_e32 v42, 0x80000000, v45
	v_mov_b32_e32 v43, v44
	v_pk_add_f32 v[44:45], v[16:17], v[42:43]
	v_pk_add_f32 v[16:17], v[16:17], v[42:43] neg_lo:[0,1] neg_hi:[0,1]
	v_pk_add_f32 v[42:43], v[46:47], v[50:51]
	v_pk_add_f32 v[46:47], v[46:47], v[50:51] neg_lo:[0,1] neg_hi:[0,1]
	v_xor_b32_e32 v50, 0x80000000, v53
	v_mov_b32_e32 v51, v52
	v_pk_add_f32 v[52:53], v[48:49], v[50:51]
	v_pk_add_f32 v[48:49], v[48:49], v[50:51] neg_lo:[0,1] neg_hi:[0,1]
	v_pk_add_f32 v[50:51], v[54:55], v[58:59]
	v_pk_add_f32 v[54:55], v[54:55], v[58:59] neg_lo:[0,1] neg_hi:[0,1]
	v_xor_b32_e32 v58, 0x80000000, v61
	v_mov_b32_e32 v59, v60
	v_pk_add_f32 v[60:61], v[40:41], v[58:59]
	v_pk_add_f32 v[40:41], v[40:41], v[58:59] neg_lo:[0,1] neg_hi:[0,1]
	v_pk_add_f32 v[58:59], v[62:63], v[66:67]
	v_pk_add_f32 v[62:63], v[62:63], v[66:67] neg_lo:[0,1] neg_hi:[0,1]
	v_xor_b32_e32 v66, 0x80000000, v65
	v_mov_b32_e32 v67, v64
	v_pk_add_f32 v[64:65], v[56:57], v[66:67]
	v_pk_add_f32 v[56:57], v[56:57], v[66:67] neg_lo:[0,1] neg_hi:[0,1]
	v_pk_add_f32 v[66:67], v[68:69], v[70:71]
	v_pk_add_f32 v[68:69], v[68:69], v[70:71] neg_lo:[0,1] neg_hi:[0,1]
	v_pk_mul_f32 v[70:71], v[20:21], s[78:79]
	s_nop 0
	v_pk_fma_f32 v[20:21], s[0:1], v[20:21], v[70:71] op_sel:[0,0,1] op_sel_hi:[0,1,0]
	v_pk_add_f32 v[70:71], v[8:9], v[20:21]
	v_pk_add_f32 v[8:9], v[8:9], v[20:21] neg_lo:[0,1] neg_hi:[0,1]
	v_xor_b32_e32 v20, 0x80000000, v11
	v_mov_b32_e32 v21, v10
	v_pk_add_f32 v[10:11], v[6:7], v[20:21]
	v_pk_add_f32 v[6:7], v[6:7], v[20:21] neg_lo:[0,1] neg_hi:[0,1]
	v_pk_mul_f32 v[20:21], v[12:13], s[78:79]
	s_nop 0
	v_pk_fma_f32 v[12:13], s[0:1], v[12:13], v[20:21] op_sel:[0,0,1] op_sel_hi:[0,1,0] neg_lo:[0,1,0] neg_hi:[0,1,0]
	v_pk_add_f32 v[20:21], v[4:5], v[12:13]
	v_pk_add_f32 v[4:5], v[4:5], v[12:13] neg_lo:[0,1] neg_hi:[0,1]
	v_pk_add_f32 v[12:13], v[14:15], v[26:27]
	v_pk_add_f32 v[14:15], v[14:15], v[26:27] neg_lo:[0,1] neg_hi:[0,1]
	v_pk_mul_f32 v[26:27], v[36:37], s[78:79]
	s_nop 0
	v_pk_fma_f32 v[26:27], s[0:1], v[36:37], v[26:27] op_sel:[0,0,1] op_sel_hi:[0,1,0]
	v_pk_add_f32 v[36:37], v[28:29], v[26:27]
	v_pk_add_f32 v[26:27], v[28:29], v[26:27] neg_lo:[0,1] neg_hi:[0,1]
	v_pk_add_f32 v[30:31], v[22:23], v[246:247] op_sel:[0,1] op_sel_hi:[1,0] neg_lo:[0,1]
	v_pk_add_f32 v[22:23], v[22:23], v[246:247] op_sel:[0,1] op_sel_hi:[1,0] neg_hi:[0,1]
	v_pk_mul_f32 v[28:29], v[32:33], s[78:79]
	s_nop 0
	v_pk_fma_f32 v[28:29], s[0:1], v[32:33], v[28:29] op_sel:[0,0,1] op_sel_hi:[0,1,0] neg_lo:[0,1,0] neg_hi:[0,1,0]
	v_pk_add_f32 v[32:33], v[24:25], v[28:29]
	v_pk_add_f32 v[24:25], v[24:25], v[28:29] neg_lo:[0,1] neg_hi:[0,1]
	v_pk_add_f32 v[28:29], v[34:35], v[42:43]
	v_pk_add_f32 v[34:35], v[34:35], v[42:43] neg_lo:[0,1] neg_hi:[0,1]
	v_pk_mul_f32 v[42:43], v[52:53], s[78:79]
	s_nop 0
	v_pk_fma_f32 v[42:43], s[0:1], v[52:53], v[42:43] op_sel:[0,0,1] op_sel_hi:[0,1,0]
	v_pk_add_f32 v[52:53], v[44:45], v[42:43]
	v_pk_add_f32 v[42:43], v[44:45], v[42:43] neg_lo:[0,1] neg_hi:[0,1]
	v_xor_b32_e32 v44, 0x80000000, v47
	v_mov_b32_e32 v45, v46
	v_pk_add_f32 v[46:47], v[38:39], v[44:45]
	v_pk_add_f32 v[38:39], v[38:39], v[44:45] neg_lo:[0,1] neg_hi:[0,1]
	v_pk_mul_f32 v[44:45], v[48:49], s[78:79]
	s_nop 0
	v_pk_fma_f32 v[44:45], s[0:1], v[48:49], v[44:45] op_sel:[0,0,1] op_sel_hi:[0,1,0] neg_lo:[0,1,0] neg_hi:[0,1,0]
	v_pk_add_f32 v[48:49], v[16:17], v[44:45]
	v_pk_add_f32 v[16:17], v[16:17], v[44:45] neg_lo:[0,1] neg_hi:[0,1]
	v_pk_add_f32 v[44:45], v[50:51], v[58:59]
	v_pk_add_f32 v[50:51], v[50:51], v[58:59] neg_lo:[0,1] neg_hi:[0,1]
	v_pk_mul_f32 v[58:59], v[64:65], s[78:79]
	s_nop 0
	v_pk_fma_f32 v[58:59], s[0:1], v[64:65], v[58:59] op_sel:[0,0,1] op_sel_hi:[0,1,0]
	v_pk_add_f32 v[64:65], v[60:61], v[58:59]
	v_pk_add_f32 v[58:59], v[60:61], v[58:59] neg_lo:[0,1] neg_hi:[0,1]
	v_xor_b32_e32 v60, 0x80000000, v63
	v_mov_b32_e32 v61, v62
	v_pk_add_f32 v[62:63], v[54:55], v[60:61]
	v_pk_add_f32 v[54:55], v[54:55], v[60:61] neg_lo:[0,1] neg_hi:[0,1]
	v_pk_mul_f32 v[60:61], v[56:57], s[78:79]
	s_nop 0
	v_pk_fma_f32 v[56:57], s[0:1], v[56:57], v[60:61] op_sel:[0,0,1] op_sel_hi:[0,1,0] neg_lo:[0,1,0] neg_hi:[0,1,0]
	v_pk_add_f32 v[60:61], v[40:41], v[56:57]
	v_pk_add_f32 v[40:41], v[40:41], v[56:57] neg_lo:[0,1] neg_hi:[0,1]
	v_pk_add_f32 v[56:57], v[66:67], v[12:13]
	v_pk_add_f32 v[12:13], v[66:67], v[12:13] neg_lo:[0,1] neg_hi:[0,1]
	v_pk_mul_f32 v[66:67], v[36:37], s[80:81]
	s_nop 0
	v_pk_fma_f32 v[36:37], s[16:17], v[36:37], v[66:67] op_sel:[0,0,1] op_sel_hi:[0,1,0]
	v_pk_add_f32 v[66:67], v[70:71], v[36:37]
	v_pk_add_f32 v[36:37], v[70:71], v[36:37] neg_lo:[0,1] neg_hi:[0,1]
	v_pk_mul_f32 v[70:71], v[30:31], s[78:79]
	s_nop 0
	v_pk_fma_f32 v[30:31], s[0:1], v[30:31], v[70:71] op_sel:[0,0,1] op_sel_hi:[0,1,0]
	v_pk_add_f32 v[70:71], v[10:11], v[30:31]
	v_pk_add_f32 v[10:11], v[10:11], v[30:31] neg_lo:[0,1] neg_hi:[0,1]
	v_pk_mul_f32 v[30:31], v[32:33], s[16:17]
	s_nop 0
	v_pk_fma_f32 v[30:31], s[82:83], v[32:33], v[30:31] op_sel:[0,0,1] op_sel_hi:[0,1,0]
	v_pk_add_f32 v[32:33], v[20:21], v[30:31]
	v_pk_add_f32 v[20:21], v[20:21], v[30:31] neg_lo:[0,1] neg_hi:[0,1]
	v_xor_b32_e32 v30, 0x80000000, v15
	v_mov_b32_e32 v31, v14
	v_pk_add_f32 v[14:15], v[68:69], v[30:31]
	v_pk_add_f32 v[30:31], v[68:69], v[30:31] neg_lo:[0,1] neg_hi:[0,1]
	v_pk_mul_f32 v[68:69], v[26:27], s[16:17]
	s_nop 0
	v_pk_fma_f32 v[26:27], s[82:83], v[26:27], v[68:69] op_sel:[0,0,1] op_sel_hi:[0,1,0] neg_lo:[0,1,0] neg_hi:[0,1,0]
	v_pk_add_f32 v[68:69], v[8:9], v[26:27]
	v_pk_add_f32 v[8:9], v[8:9], v[26:27] neg_lo:[0,1] neg_hi:[0,1]
	v_pk_mul_f32 v[26:27], v[22:23], s[78:79]
	s_nop 0
	v_pk_fma_f32 v[22:23], s[0:1], v[22:23], v[26:27] op_sel:[0,0,1] op_sel_hi:[0,1,0] neg_lo:[0,1,0] neg_hi:[0,1,0]
	v_pk_add_f32 v[26:27], v[6:7], v[22:23]
	v_pk_add_f32 v[6:7], v[6:7], v[22:23] neg_lo:[0,1] neg_hi:[0,1]
	v_pk_mul_f32 v[22:23], v[24:25], s[80:81]
	s_nop 0
	v_pk_fma_f32 v[22:23], s[16:17], v[24:25], v[22:23] op_sel:[0,0,1] op_sel_hi:[0,1,0] neg_lo:[0,1,0] neg_hi:[0,1,0]
	v_pk_add_f32 v[24:25], v[4:5], v[22:23]
	v_pk_add_f32 v[4:5], v[4:5], v[22:23] neg_lo:[0,1] neg_hi:[0,1]
	v_pk_add_f32 v[22:23], v[28:29], v[44:45]
	v_pk_add_f32 v[28:29], v[28:29], v[44:45] neg_lo:[0,1] neg_hi:[0,1]
	v_pk_mul_f32 v[44:45], v[64:65], s[80:81]
	s_nop 0
	v_pk_fma_f32 v[44:45], s[16:17], v[64:65], v[44:45] op_sel:[0,0,1] op_sel_hi:[0,1,0]
	v_pk_add_f32 v[64:65], v[52:53], v[44:45]
	v_pk_add_f32 v[44:45], v[52:53], v[44:45] neg_lo:[0,1] neg_hi:[0,1]
	v_pk_mul_f32 v[52:53], v[62:63], s[78:79]
	s_nop 0
	v_pk_fma_f32 v[52:53], s[0:1], v[62:63], v[52:53] op_sel:[0,0,1] op_sel_hi:[0,1,0]
	v_pk_add_f32 v[62:63], v[46:47], v[52:53]
	v_pk_add_f32 v[46:47], v[46:47], v[52:53] neg_lo:[0,1] neg_hi:[0,1]
	v_pk_mul_f32 v[52:53], v[60:61], s[16:17]
	s_nop 0
	v_pk_fma_f32 v[52:53], s[82:83], v[60:61], v[52:53] op_sel:[0,0,1] op_sel_hi:[0,1,0]
	v_pk_add_f32 v[60:61], v[48:49], v[52:53]
	v_pk_add_f32 v[48:49], v[48:49], v[52:53] neg_lo:[0,1] neg_hi:[0,1]
	v_xor_b32_e32 v52, 0x80000000, v51
	v_mov_b32_e32 v53, v50
	v_pk_add_f32 v[50:51], v[34:35], v[52:53]
	v_pk_add_f32 v[34:35], v[34:35], v[52:53] neg_lo:[0,1] neg_hi:[0,1]
	v_pk_mul_f32 v[52:53], v[58:59], s[16:17]
	s_nop 0
	v_pk_fma_f32 v[52:53], s[82:83], v[58:59], v[52:53] op_sel:[0,0,1] op_sel_hi:[0,1,0] neg_lo:[0,1,0] neg_hi:[0,1,0]
	v_pk_add_f32 v[58:59], v[42:43], v[52:53]
	v_pk_add_f32 v[42:43], v[42:43], v[52:53] neg_lo:[0,1] neg_hi:[0,1]
	v_pk_mul_f32 v[52:53], v[54:55], s[78:79]
	s_nop 0
	v_pk_fma_f32 v[52:53], s[0:1], v[54:55], v[52:53] op_sel:[0,0,1] op_sel_hi:[0,1,0] neg_lo:[0,1,0] neg_hi:[0,1,0]
	v_pk_add_f32 v[54:55], v[38:39], v[52:53]
	v_pk_add_f32 v[38:39], v[38:39], v[52:53] neg_lo:[0,1] neg_hi:[0,1]
	v_pk_mul_f32 v[52:53], v[40:41], s[80:81]
	s_nop 0
	v_pk_fma_f32 v[40:41], s[16:17], v[40:41], v[52:53] op_sel:[0,0,1] op_sel_hi:[0,1,0] neg_lo:[0,1,0] neg_hi:[0,1,0]
	v_pk_add_f32 v[52:53], v[16:17], v[40:41]
	v_pk_add_f32 v[16:17], v[16:17], v[40:41] neg_lo:[0,1] neg_hi:[0,1]
	v_pk_add_f32 v[40:41], v[56:57], v[22:23]
	v_pk_add_f32 v[22:23], v[56:57], v[22:23] neg_lo:[0,1] neg_hi:[0,1]
	v_pk_mul_f32 v[56:57], v[64:65], s[88:89]
	s_nop 0
	v_pk_fma_f32 v[56:57], v[64:65], s[8:9], v[56:57] op_sel:[0,0,1] op_sel_hi:[1,0,0]
	s_mov_b32 s9, s42
	v_pk_add_f32 v[64:65], v[66:67], v[56:57]
	v_pk_add_f32 v[56:57], v[66:67], v[56:57] neg_lo:[0,1] neg_hi:[0,1]
	v_pk_mul_f32 v[66:67], v[62:63], s[80:81]
	s_nop 0
	v_pk_fma_f32 v[62:63], s[16:17], v[62:63], v[66:67] op_sel:[0,0,1] op_sel_hi:[0,1,0]
	v_pk_add_f32 v[66:67], v[70:71], v[62:63]
	v_pk_add_f32 v[62:63], v[70:71], v[62:63] neg_lo:[0,1] neg_hi:[0,1]
	v_pk_mul_f32 v[70:71], v[60:61], s[62:63]
	s_nop 0
	v_pk_fma_f32 v[60:61], v[60:61], s[24:25], v[70:71] op_sel:[0,0,1] op_sel_hi:[1,0,0]
	s_mov_b32 s25, s38
	v_pk_add_f32 v[70:71], v[32:33], v[60:61]
	v_pk_add_f32 v[32:33], v[32:33], v[60:61] neg_lo:[0,1] neg_hi:[0,1]
	v_pk_mul_f32 v[60:61], v[50:51], s[78:79]
	s_nop 0
	v_pk_fma_f32 v[50:51], s[0:1], v[50:51], v[60:61] op_sel:[0,0,1] op_sel_hi:[0,1,0]
	v_pk_add_f32 v[60:61], v[14:15], v[50:51]
	v_pk_add_f32 v[14:15], v[14:15], v[50:51] neg_lo:[0,1] neg_hi:[0,1]
	v_pk_mul_f32 v[50:51], v[58:59], s[24:25]
	s_nop 0
	v_pk_fma_f32 v[50:51], s[84:85], v[58:59], v[50:51] op_sel:[0,0,1] op_sel_hi:[0,1,0]
	v_pk_add_f32 v[58:59], v[68:69], v[50:51]
	v_pk_add_f32 v[50:51], v[68:69], v[50:51] neg_lo:[0,1] neg_hi:[0,1]
	v_pk_mul_f32 v[68:69], v[54:55], s[16:17]
	s_nop 0
	v_pk_fma_f32 v[54:55], s[82:83], v[54:55], v[68:69] op_sel:[0,0,1] op_sel_hi:[0,1,0]
	v_pk_add_f32 v[68:69], v[26:27], v[54:55]
	v_pk_add_f32 v[26:27], v[26:27], v[54:55] neg_lo:[0,1] neg_hi:[0,1]
	v_pk_mul_f32 v[54:55], v[52:53], s[8:9]
	s_nop 0
	v_pk_fma_f32 v[52:53], s[86:87], v[52:53], v[54:55] op_sel:[0,0,1] op_sel_hi:[0,1,0]
	v_pk_add_f32 v[54:55], v[24:25], v[52:53]
	v_pk_add_f32 v[24:25], v[24:25], v[52:53] neg_lo:[0,1] neg_hi:[0,1]
	v_xor_b32_e32 v52, 0x80000000, v29
	v_mov_b32_e32 v53, v28
	v_pk_add_f32 v[28:29], v[12:13], v[52:53]
	v_pk_add_f32 v[12:13], v[12:13], v[52:53] neg_lo:[0,1] neg_hi:[0,1]
	v_pk_mul_f32 v[52:53], v[44:45], s[8:9]
	s_nop 0
	v_pk_fma_f32 v[44:45], s[86:87], v[44:45], v[52:53] op_sel:[0,0,1] op_sel_hi:[0,1,0] neg_lo:[0,1,0] neg_hi:[0,1,0]
	v_pk_add_f32 v[52:53], v[36:37], v[44:45]
	v_pk_add_f32 v[36:37], v[36:37], v[44:45] neg_lo:[0,1] neg_hi:[0,1]
	v_pk_mul_f32 v[44:45], v[46:47], s[16:17]
	s_nop 0
	v_pk_fma_f32 v[44:45], s[82:83], v[46:47], v[44:45] op_sel:[0,0,1] op_sel_hi:[0,1,0] neg_lo:[0,1,0] neg_hi:[0,1,0]
	v_pk_add_f32 v[46:47], v[10:11], v[44:45]
	v_pk_add_f32 v[10:11], v[10:11], v[44:45] neg_lo:[0,1] neg_hi:[0,1]
	v_pk_mul_f32 v[44:45], v[48:49], s[24:25]
	s_nop 0
	v_pk_fma_f32 v[44:45], s[84:85], v[48:49], v[44:45] op_sel:[0,0,1] op_sel_hi:[0,1,0] neg_lo:[0,1,0] neg_hi:[0,1,0]
	v_pk_add_f32 v[48:49], v[20:21], v[44:45]
	v_pk_add_f32 v[20:21], v[20:21], v[44:45] neg_lo:[0,1] neg_hi:[0,1]
	v_pk_mul_f32 v[44:45], v[34:35], s[78:79]
	s_nop 0
	v_pk_fma_f32 v[34:35], v[34:35], s[0:1], v[44:45] op_sel:[0,0,1] op_sel_hi:[1,0,0] neg_lo:[1,0,0] neg_hi:[1,0,0]
	s_lshl_b64 s[0:1], s[72:73], 2
	v_pk_add_f32 v[44:45], v[30:31], v[34:35]
	v_pk_add_f32 v[30:31], v[30:31], v[34:35] neg_lo:[0,1] neg_hi:[0,1]
	v_pk_mul_f32 v[34:35], v[42:43], s[62:63]
	s_add_u32 s0, s49, s0
	v_pk_fma_f32 v[34:35], v[42:43], s[24:25], v[34:35] op_sel:[0,0,1] op_sel_hi:[1,0,0] neg_lo:[1,0,0] neg_hi:[1,0,0]
	s_addc_u32 s1, s60, s1
	v_pk_add_f32 v[42:43], v[8:9], v[34:35]
	v_pk_add_f32 v[8:9], v[8:9], v[34:35] neg_lo:[0,1] neg_hi:[0,1]
	v_pk_mul_f32 v[34:35], v[38:39], s[80:81]
	s_lshl_b64 s[62:63], s[76:77], 2
	v_pk_fma_f32 v[34:35], v[38:39], s[16:17], v[34:35] op_sel:[0,0,1] op_sel_hi:[1,0,0] neg_lo:[1,0,0] neg_hi:[1,0,0]
	s_add_u32 s62, s22, s62
	v_pk_add_f32 v[38:39], v[6:7], v[34:35]
	v_pk_add_f32 v[6:7], v[6:7], v[34:35] neg_lo:[0,1] neg_hi:[0,1]
	v_pk_mul_f32 v[34:35], v[16:17], s[88:89]
	s_addc_u32 s63, s23, s63
	v_pk_fma_f32 v[16:17], s[8:9], v[16:17], v[34:35] op_sel:[0,0,1] op_sel_hi:[0,1,0] neg_lo:[0,1,0] neg_hi:[0,1,0]
	v_pk_add_f32 v[34:35], v[4:5], v[16:17]
	v_pk_add_f32 v[4:5], v[4:5], v[16:17] neg_lo:[0,1] neg_hi:[0,1]
	ds_write2_b64 v2, v[40:41], v[64:65] offset1:16
	ds_write2_b64 v2, v[66:67], v[70:71] offset0:33 offset1:49
	ds_write2_b64 v2, v[60:61], v[58:59] offset0:66 offset1:82
	ds_write2_b64 v2, v[68:69], v[54:55] offset0:99 offset1:115
	ds_write2_b64 v2, v[28:29], v[52:53] offset0:132 offset1:148
	ds_write2_b64 v2, v[46:47], v[48:49] offset0:165 offset1:181
	ds_write2_b64 v2, v[44:45], v[42:43] offset0:198 offset1:214
	ds_write2_b64 v2, v[38:39], v[34:35] offset0:231 offset1:247
	ds_write2_b64 v3, v[22:23], v[56:57] offset0:8 offset1:24
	ds_write2_b64 v3, v[62:63], v[32:33] offset0:41 offset1:57
	ds_write2_b64 v3, v[14:15], v[50:51] offset0:74 offset1:90
	ds_write2_b64 v3, v[26:27], v[24:25] offset0:107 offset1:123
	ds_write2_b64 v3, v[12:13], v[36:37] offset0:140 offset1:156
	ds_write2_b64 v3, v[10:11], v[20:21] offset0:173 offset1:189
	ds_write2_b64 v3, v[30:31], v[8:9] offset0:206 offset1:222
	ds_write2_b64 v3, v[6:7], v[4:5] offset0:239 offset1:255
	s_waitcnt lgkmcnt(0)
	s_barrier
	global_load_dword v30, v206, s[0:1]
	global_load_dword v20, v207, s[0:1]
	v_ashrrev_i32_e32 v2, 31, v210
	v_lshrrev_b32_e32 v2, 22, v2
	v_add_u32_e32 v2, v210, v2
	v_ashrrev_i32_e32 v2, 10, v2
	v_mul_i32_i24_e32 v3, 0x400, v2
	global_load_dword v31, v205, s[0:1]
	global_load_dword v24, v205, s[62:63]
	s_add_u32 s0, s87, s74
	v_sub_u32_e32 v21, v210, v3
	v_lshlrev_b32_e32 v36, 14, v2
	s_addc_u32 s1, s90, s75
	v_ashrrev_i32_e32 v37, 31, v36
	v_lshlrev_b32_e32 v32, 4, v21
	v_lshl_add_u64 v[2:3], v[36:37], 1, s[0:1]
	v_ashrrev_i32_e32 v33, 31, v32
	v_lshl_add_u64 v[2:3], v[32:33], 1, v[2:3]
	global_load_dwordx4 v[10:13], v[2:3], off offset:16 nt
	global_load_dwordx4 v[14:17], v[2:3], off nt
	v_cmp_lt_i32_e32 vcc, 0, v21
	v_mov_b32_e32 v39, 0
	v_mov_b32_e32 v41, 0
	s_and_saveexec_b64 s[72:73], vcc
	s_cbranch_execz .LBB0_505
	global_load_ushort v41, v[2:3], off offset:-2

.LBB0_511:
	s_or_b64 exec, exec, s[0:1]
	v_mov_b32_e32 v25, v210
	s_mov_b32 s72, s37
	v_and_b32_e32 v28, 0x1ff, v25
	v_cvt_f32_u32_e32 v34, v28
	v_lshlrev_b32_e32 v25, 5, v25
	v_and_or_b32 v25, v25, s94, v28
	v_ashrrev_i32_e32 v28, 5, v25
	v_mul_f32_e32 v34, 0x38800000, v34
	v_sin_f32_e32 v43, v34
	v_cos_f32_e32 v42, v34
	v_lshlrev_b32_e32 v25, 3, v25
	v_lshlrev_b32_e32 v28, 3, v28
	v_xor_b32_e32 v44, 0x80000000, v43
	v_mov_b32_e32 v45, v43
	v_pk_mul_f32 v[46:47], v[42:43], v[44:45] op_sel:[1,0] op_sel_hi:[0,1]
	v_pk_fma_f32 v[46:47], v[42:43], v[42:43], v[46:47] op_sel_hi:[1,0,1]
	v_add3_u32 v25, 0, v25, v28
	v_xor_b32_e32 v50, 0x80000000, v47
	v_mov_b32_e32 v51, v47
	v_pk_mul_f32 v[52:53], v[46:47], v[50:51] op_sel:[1,0] op_sel_hi:[0,1]
	v_pk_fma_f32 v[52:53], v[46:47], v[46:47], v[52:53] op_sel_hi:[1,0,1]
	v_add_u32_e32 v28, 0x10800, v25
	v_xor_b32_e32 v54, 0x80000000, v53
	v_mov_b32_e32 v55, v53
	v_pk_mul_f32 v[70:71], v[52:53], v[54:55] op_sel:[1,0] op_sel_hi:[0,1]
	v_pk_fma_f32 v[70:71], v[52:53], v[52:53], v[70:71] op_sel_hi:[1,0,1]
	v_pk_mul_f32 v[48:49], v[44:45], v[46:47] op_sel:[0,1] op_sel_hi:[1,0]
	v_pk_mul_f32 v[86:87], v[54:55], v[70:71] op_sel:[0,1] op_sel_hi:[1,0]
	ds_read_b64 v[168:169], v25
	ds_read_b64 v[170:171], v25 offset:4224
	ds_read_b64 v[172:173], v25 offset:8448
	ds_read_b64 v[174:175], v25 offset:12672
	ds_read_b64 v[176:177], v25 offset:16896
	ds_read_b64 v[178:179], v25 offset:21120
	ds_read_b64 v[180:181], v25 offset:25344
	ds_read_b64 v[182:183], v25 offset:29568
	ds_read_b64 v[184:185], v25 offset:33792
	ds_read_b64 v[186:187], v25 offset:38016
	ds_read_b64 v[188:189], v25 offset:42240
	ds_read_b64 v[190:191], v25 offset:46464
	ds_read_b64 v[192:193], v25 offset:50688
	ds_read_b64 v[194:195], v25 offset:54912
	ds_read_b64 v[196:197], v25 offset:59136
	ds_read_b64 v[198:199], v25 offset:63360
	v_pk_fma_f32 v[86:87], v[52:53], v[70:71], v[86:87] op_sel_hi:[0,1,1]
	v_pk_mul_f32 v[102:103], v[54:55], v[86:87] op_sel:[0,1] op_sel_hi:[1,0]
	v_add_u32_e32 v34, 0x11880, v25
	v_pk_fma_f32 v[102:103], v[52:53], v[86:87], v[102:103] op_sel_hi:[0,1,1]
	v_pk_mul_f32 v[118:119], v[54:55], v[102:103] op_sel:[0,1] op_sel_hi:[1,0]
	v_add_u32_e32 v38, 0x12900, v25
	v_pk_fma_f32 v[118:119], v[52:53], v[102:103], v[118:119] op_sel_hi:[0,1,1]
	v_pk_mul_f32 v[134:135], v[54:55], v[118:119] op_sel:[0,1] op_sel_hi:[1,0]
	v_add_u32_e32 v40, 0x13980, v25
	v_pk_fma_f32 v[134:135], v[52:53], v[118:119], v[134:135] op_sel_hi:[0,1,1]
	v_pk_mul_f32 v[152:153], v[54:55], v[134:135] op_sel:[0,1] op_sel_hi:[1,0]
	ds_read_b64 v[212:213], v28
	ds_read_b64 v[214:215], v34
	ds_read_b64 v[216:217], v38
	ds_read_b64 v[218:219], v40
	v_add_u32_e32 v28, 0x14a00, v25
	v_pk_fma_f32 v[48:49], v[42:43], v[46:47], v[48:49] op_sel_hi:[0,1,1]
	v_pk_fma_f32 v[152:153], v[52:53], v[134:135], v[152:153] op_sel_hi:[0,1,1]
	v_add_u32_e32 v34, 0x15a80, v25
	v_add_u32_e32 v38, 0x16b00, v25
	v_add_u32_e32 v40, 0x17b80, v25
	ds_read_b64 v[220:221], v28
	ds_read_b64 v[222:223], v34
	ds_read_b64 v[224:225], v38
	ds_read_b64 v[226:227], v40
	v_add_u32_e32 v28, 0x18c00, v25
	v_xor_b32_e32 v56, 0x80000000, v49
	v_mov_b32_e32 v57, v49
	v_pk_mul_f32 v[58:59], v[44:45], v[52:53] op_sel:[0,1] op_sel_hi:[1,0]
	v_pk_mul_f32 v[74:75], v[44:45], v[70:71] op_sel:[0,1] op_sel_hi:[1,0]
	v_pk_mul_f32 v[90:91], v[44:45], v[86:87] op_sel:[0,1] op_sel_hi:[1,0]
	v_pk_mul_f32 v[106:107], v[44:45], v[102:103] op_sel:[0,1] op_sel_hi:[1,0]
	v_pk_mul_f32 v[122:123], v[44:45], v[118:119] op_sel:[0,1] op_sel_hi:[1,0]
	v_pk_mul_f32 v[138:139], v[44:45], v[134:135] op_sel:[0,1] op_sel_hi:[1,0]
	v_pk_mul_f32 v[156:157], v[44:45], v[152:153] op_sel:[0,1] op_sel_hi:[1,0]
	v_add_u32_e32 v34, 0x19c80, v25
	v_add_u32_e32 v38, 0x1ad00, v25
	v_add_u32_e32 v40, 0x1bd80, v25
	ds_read_b64 v[228:229], v28
	ds_read_b64 v[230:231], v34
	ds_read_b64 v[232:233], v38
	ds_read_b64 v[234:235], v40
	v_add_u32_e32 v28, 0x1ce00, v25
	s_waitcnt lgkmcnt(11)
	v_pk_mul_f32 v[44:45], v[44:45], v[212:213] op_sel:[0,1] op_sel_hi:[1,0]
	v_pk_fma_f32 v[58:59], v[42:43], v[52:53], v[58:59] op_sel_hi:[0,1,1]
	v_pk_mul_f32 v[62:63], v[50:51], v[52:53] op_sel:[0,1] op_sel_hi:[1,0]
	v_pk_mul_f32 v[66:67], v[52:53], v[56:57] op_sel:[1,0] op_sel_hi:[0,1]
	v_pk_fma_f32 v[74:75], v[42:43], v[70:71], v[74:75] op_sel_hi:[0,1,1]
	v_pk_mul_f32 v[78:79], v[50:51], v[70:71] op_sel:[0,1] op_sel_hi:[1,0]
	v_pk_fma_f32 v[90:91], v[42:43], v[86:87], v[90:91] op_sel_hi:[0,1,1]
	v_pk_mul_f32 v[94:95], v[50:51], v[86:87] op_sel:[0,1] op_sel_hi:[1,0]
	v_pk_fma_f32 v[106:107], v[42:43], v[102:103], v[106:107] op_sel_hi:[0,1,1]
	v_pk_mul_f32 v[110:111], v[50:51], v[102:103] op_sel:[0,1] op_sel_hi:[1,0]
	v_pk_fma_f32 v[122:123], v[42:43], v[118:119], v[122:123] op_sel_hi:[0,1,1]
	v_pk_mul_f32 v[126:127], v[50:51], v[118:119] op_sel:[0,1] op_sel_hi:[1,0]
	v_pk_fma_f32 v[138:139], v[42:43], v[134:135], v[138:139] op_sel_hi:[0,1,1]
	v_pk_mul_f32 v[142:143], v[50:51], v[134:135] op_sel:[0,1] op_sel_hi:[1,0]
	v_pk_fma_f32 v[156:157], v[42:43], v[152:153], v[156:157] op_sel_hi:[0,1,1]
	v_pk_mul_f32 v[160:161], v[50:51], v[152:153] op_sel:[0,1] op_sel_hi:[1,0]
	v_add_u32_e32 v34, 0x1de80, v25
	v_add_u32_e32 v38, 0x1ef00, v25
	v_add_u32_e32 v40, 0x1ff80, v25
	ds_read_b64 v[236:237], v28
	ds_read_b64 v[238:239], v34
	ds_read_b64 v[240:241], v38
	ds_read_b64 v[242:243], v40
	v_pk_fma_f32 v[42:43], v[42:43], v[212:213], v[44:45] op_sel_hi:[0,1,1]
	v_pk_mul_f32 v[44:45], v[184:185], v[50:51] op_sel:[1,0] op_sel_hi:[0,1]
	v_pk_fma_f32 v[62:63], v[46:47], v[52:53], v[62:63] op_sel_hi:[0,1,1]
	v_pk_fma_f32 v[66:67], v[52:53], v[48:49], v[66:67] op_sel_hi:[1,0,1]
	v_pk_fma_f32 v[78:79], v[46:47], v[70:71], v[78:79] op_sel_hi:[0,1,1]
	v_pk_mul_f32 v[82:83], v[56:57], v[70:71] op_sel:[0,1] op_sel_hi:[1,0]
	v_pk_fma_f32 v[94:95], v[46:47], v[86:87], v[94:95] op_sel_hi:[0,1,1]
	v_pk_mul_f32 v[98:99], v[56:57], v[86:87] op_sel:[0,1] op_sel_hi:[1,0]
	v_pk_fma_f32 v[110:111], v[46:47], v[102:103], v[110:111] op_sel_hi:[0,1,1]
	v_pk_mul_f32 v[114:115], v[56:57], v[102:103] op_sel:[0,1] op_sel_hi:[1,0]
	v_pk_fma_f32 v[126:127], v[46:47], v[118:119], v[126:127] op_sel_hi:[0,1,1]
	v_pk_mul_f32 v[130:131], v[56:57], v[118:119] op_sel:[0,1] op_sel_hi:[1,0]
	v_pk_fma_f32 v[142:143], v[46:47], v[134:135], v[142:143] op_sel_hi:[0,1,1]
	v_pk_mul_f32 v[148:149], v[56:57], v[134:135] op_sel:[0,1] op_sel_hi:[1,0]
	v_pk_fma_f32 v[160:161], v[46:47], v[152:153], v[160:161] op_sel_hi:[0,1,1]
	v_pk_mul_f32 v[164:165], v[56:57], v[152:153] op_sel:[0,1] op_sel_hi:[1,0]
	v_pk_fma_f32 v[44:45], v[184:185], v[46:47], v[44:45] op_sel_hi:[1,0,1]
	s_waitcnt lgkmcnt(7)
	v_pk_mul_f32 v[46:47], v[56:57], v[228:229] op_sel:[0,1] op_sel_hi:[1,0]
	v_xor_b32_e32 v60, 0x80000000, v59
	v_xor_b32_e32 v64, 0x80000000, v63
	v_xor_b32_e32 v68, 0x80000000, v67
	v_xor_b32_e32 v72, 0x80000000, v71
	v_pk_fma_f32 v[82:83], v[48:49], v[70:71], v[82:83] op_sel_hi:[0,1,1]
	v_pk_fma_f32 v[98:99], v[48:49], v[86:87], v[98:99] op_sel_hi:[0,1,1]
	v_pk_fma_f32 v[114:115], v[48:49], v[102:103], v[114:115] op_sel_hi:[0,1,1]
	v_pk_fma_f32 v[130:131], v[48:49], v[118:119], v[130:131] op_sel_hi:[0,1,1]
	v_pk_fma_f32 v[148:149], v[48:49], v[134:135], v[148:149] op_sel_hi:[0,1,1]
	v_pk_fma_f32 v[164:165], v[48:49], v[152:153], v[164:165] op_sel_hi:[0,1,1]
	v_mov_b32_e32 v61, v59
	v_mov_b32_e32 v65, v63
	v_mov_b32_e32 v69, v67
	v_mov_b32_e32 v73, v71
	v_pk_fma_f32 v[46:47], v[48:49], v[228:229], v[46:47] op_sel_hi:[0,1,1]
	v_pk_mul_f32 v[48:49], v[176:177], v[54:55] op_sel:[1,0] op_sel_hi:[0,1]
	v_xor_b32_e32 v76, 0x80000000, v75
	v_xor_b32_e32 v80, 0x80000000, v79
	v_xor_b32_e32 v84, 0x80000000, v83
	v_xor_b32_e32 v88, 0x80000000, v87
	v_xor_b32_e32 v92, 0x80000000, v91
	v_xor_b32_e32 v96, 0x80000000, v95
	v_xor_b32_e32 v100, 0x80000000, v99
	v_xor_b32_e32 v104, 0x80000000, v103
	v_xor_b32_e32 v136, 0x80000000, v135
	v_mov_b32_e32 v77, v75
	v_mov_b32_e32 v81, v79
	v_mov_b32_e32 v85, v83
	v_mov_b32_e32 v89, v87
	v_mov_b32_e32 v93, v91
	v_mov_b32_e32 v97, v95
	v_mov_b32_e32 v101, v99
	v_mov_b32_e32 v105, v103
	v_mov_b32_e32 v137, v135
	v_pk_fma_f32 v[48:49], v[176:177], v[52:53], v[48:49] op_sel_hi:[1,0,1]
	v_pk_mul_f32 v[50:51], v[60:61], v[220:221] op_sel:[0,1] op_sel_hi:[1,0]
	v_pk_mul_f32 v[52:53], v[192:193], v[64:65] op_sel:[1,0] op_sel_hi:[0,1]
	s_waitcnt lgkmcnt(3)
	v_pk_mul_f32 v[54:55], v[68:69], v[236:237] op_sel:[0,1] op_sel_hi:[1,0]
	v_pk_mul_f32 v[56:57], v[172:173], v[72:73] op_sel:[1,0] op_sel_hi:[0,1]
	v_xor_b32_e32 v108, 0x80000000, v107
	v_xor_b32_e32 v112, 0x80000000, v111
	v_xor_b32_e32 v116, 0x80000000, v115
	v_xor_b32_e32 v120, 0x80000000, v119
	v_xor_b32_e32 v124, 0x80000000, v123
	v_xor_b32_e32 v128, 0x80000000, v127
	v_xor_b32_e32 v132, 0x80000000, v131
	v_xor_b32_e32 v140, 0x80000000, v139
	v_xor_b32_e32 v144, 0x80000000, v143
	v_xor_b32_e32 v150, 0x80000000, v149
	v_xor_b32_e32 v154, 0x80000000, v153
	v_xor_b32_e32 v158, 0x80000000, v157
	v_xor_b32_e32 v162, 0x80000000, v161
	v_xor_b32_e32 v166, 0x80000000, v165
	v_mov_b32_e32 v109, v107
	v_mov_b32_e32 v113, v111
	v_mov_b32_e32 v117, v115
	v_mov_b32_e32 v121, v119
	v_mov_b32_e32 v125, v123
	v_mov_b32_e32 v129, v127
	v_mov_b32_e32 v133, v131
	v_mov_b32_e32 v141, v139
	v_mov_b32_e32 v145, v143
	v_mov_b32_e32 v151, v149
	v_mov_b32_e32 v155, v153
	v_mov_b32_e32 v159, v157
	v_mov_b32_e32 v163, v161
	v_mov_b32_e32 v167, v165
	v_pk_fma_f32 v[50:51], v[58:59], v[220:221], v[50:51] op_sel_hi:[0,1,1]
	v_pk_fma_f32 v[52:53], v[192:193], v[62:63], v[52:53] op_sel_hi:[1,0,1]
	v_pk_fma_f32 v[54:55], v[66:67], v[236:237], v[54:55] op_sel_hi:[0,1,1]
	v_pk_fma_f32 v[56:57], v[172:173], v[70:71], v[56:57] op_sel_hi:[1,0,1]
	v_pk_mul_f32 v[58:59], v[216:217], v[76:77] op_sel:[1,0] op_sel_hi:[0,1]
	v_pk_mul_f32 v[60:61], v[188:189], v[80:81] op_sel:[1,0] op_sel_hi:[0,1]
	v_pk_mul_f32 v[62:63], v[84:85], v[232:233] op_sel:[0,1] op_sel_hi:[1,0]
	v_pk_mul_f32 v[64:65], v[180:181], v[88:89] op_sel:[1,0] op_sel_hi:[0,1]
	v_pk_mul_f32 v[66:67], v[224:225], v[92:93] op_sel:[1,0] op_sel_hi:[0,1]
	v_pk_mul_f32 v[68:69], v[196:197], v[96:97] op_sel:[1,0] op_sel_hi:[0,1]
	s_waitcnt lgkmcnt(1)
	v_pk_mul_f32 v[70:71], v[100:101], v[240:241] op_sel:[0,1] op_sel_hi:[1,0]
	v_pk_mul_f32 v[72:73], v[170:171], v[104:105] op_sel:[1,0] op_sel_hi:[0,1]
	v_pk_mul_f32 v[88:89], v[174:175], v[136:137] op_sel:[1,0] op_sel_hi:[0,1]
	v_pk_fma_f32 v[58:59], v[216:217], v[74:75], v[58:59] op_sel_hi:[1,0,1]
	v_pk_fma_f32 v[60:61], v[188:189], v[78:79], v[60:61] op_sel_hi:[1,0,1]
	v_pk_fma_f32 v[62:63], v[82:83], v[232:233], v[62:63] op_sel_hi:[0,1,1]
	v_pk_fma_f32 v[64:65], v[180:181], v[86:87], v[64:65] op_sel_hi:[1,0,1]
	v_pk_fma_f32 v[66:67], v[224:225], v[90:91], v[66:67] op_sel_hi:[1,0,1]
	v_pk_fma_f32 v[68:69], v[196:197], v[94:95], v[68:69] op_sel_hi:[1,0,1]
	v_pk_fma_f32 v[70:71], v[98:99], v[240:241], v[70:71] op_sel_hi:[0,1,1]
	v_pk_fma_f32 v[72:73], v[170:171], v[102:103], v[72:73] op_sel_hi:[1,0,1]
	v_pk_mul_f32 v[74:75], v[214:215], v[108:109] op_sel:[1,0] op_sel_hi:[0,1]
	v_pk_mul_f32 v[76:77], v[186:187], v[112:113] op_sel:[1,0] op_sel_hi:[0,1]
	v_pk_mul_f32 v[78:79], v[230:231], v[116:117] op_sel:[1,0] op_sel_hi:[0,1]
	v_pk_mul_f32 v[80:81], v[178:179], v[120:121] op_sel:[1,0] op_sel_hi:[0,1]
	v_pk_mul_f32 v[82:83], v[222:223], v[124:125] op_sel:[1,0] op_sel_hi:[0,1]
	v_pk_mul_f32 v[84:85], v[194:195], v[128:129] op_sel:[1,0] op_sel_hi:[0,1]
	v_pk_mul_f32 v[86:87], v[132:133], v[238:239] op_sel:[0,1] op_sel_hi:[1,0]
	v_pk_fma_f32 v[88:89], v[174:175], v[134:135], v[88:89] op_sel_hi:[1,0,1]
	v_pk_mul_f32 v[90:91], v[218:219], v[140:141] op_sel:[1,0] op_sel_hi:[0,1]
	v_pk_mul_f32 v[92:93], v[190:191], v[144:145] op_sel:[1,0] op_sel_hi:[0,1]
	v_pk_mul_f32 v[94:95], v[234:235], v[150:151] op_sel:[1,0] op_sel_hi:[0,1]
	v_pk_mul_f32 v[96:97], v[182:183], v[154:155] op_sel:[1,0] op_sel_hi:[0,1]
	v_pk_mul_f32 v[98:99], v[226:227], v[158:159] op_sel:[1,0] op_sel_hi:[0,1]
	v_pk_mul_f32 v[100:101], v[198:199], v[162:163] op_sel:[1,0] op_sel_hi:[0,1]
	s_waitcnt lgkmcnt(0)
	v_pk_mul_f32 v[102:103], v[242:243], v[166:167] op_sel:[1,0] op_sel_hi:[0,1]
	v_pk_fma_f32 v[74:75], v[214:215], v[106:107], v[74:75] op_sel_hi:[1,0,1]
	v_pk_fma_f32 v[76:77], v[186:187], v[110:111], v[76:77] op_sel_hi:[1,0,1]
	v_pk_fma_f32 v[78:79], v[230:231], v[114:115], v[78:79] op_sel_hi:[1,0,1]
	v_pk_fma_f32 v[80:81], v[178:179], v[118:119], v[80:81] op_sel_hi:[1,0,1]
	v_pk_fma_f32 v[82:83], v[222:223], v[122:123], v[82:83] op_sel_hi:[1,0,1]
	v_pk_fma_f32 v[84:85], v[194:195], v[126:127], v[84:85] op_sel_hi:[1,0,1]
	v_pk_fma_f32 v[86:87], v[130:131], v[238:239], v[86:87] op_sel_hi:[0,1,1]
	v_pk_fma_f32 v[90:91], v[218:219], v[138:139], v[90:91] op_sel_hi:[1,0,1]
	v_pk_fma_f32 v[92:93], v[190:191], v[142:143], v[92:93] op_sel_hi:[1,0,1]
	v_pk_fma_f32 v[94:95], v[234:235], v[148:149], v[94:95] op_sel_hi:[1,0,1]
	v_pk_fma_f32 v[96:97], v[182:183], v[152:153], v[96:97] op_sel_hi:[1,0,1]
	v_pk_fma_f32 v[98:99], v[226:227], v[156:157], v[98:99] op_sel_hi:[1,0,1]
	v_pk_fma_f32 v[100:101], v[198:199], v[160:161], v[100:101] op_sel_hi:[1,0,1]
	v_pk_fma_f32 v[102:103], v[242:243], v[164:165], v[102:103] op_sel_hi:[1,0,1]
	v_pk_add_f32 v[104:105], v[168:169], v[72:73]
	v_pk_add_f32 v[106:107], v[56:57], v[88:89]
	v_pk_add_f32 v[246:247], v[56:57], v[88:89] neg_lo:[0,1] neg_hi:[0,1]
	v_pk_add_f32 v[72:73], v[168:169], v[72:73] neg_lo:[0,1] neg_hi:[0,1]
	v_pk_add_f32 v[88:89], v[48:49], v[80:81]
	v_pk_add_f32 v[48:49], v[48:49], v[80:81] neg_lo:[0,1] neg_hi:[0,1]
	v_pk_add_f32 v[80:81], v[64:65], v[96:97]
	v_pk_add_f32 v[64:65], v[64:65], v[96:97] neg_lo:[0,1] neg_hi:[0,1]
	v_pk_add_f32 v[96:97], v[44:45], v[76:77]
	v_pk_add_f32 v[44:45], v[44:45], v[76:77] neg_lo:[0,1] neg_hi:[0,1]
	v_pk_add_f32 v[76:77], v[60:61], v[92:93]
	v_pk_add_f32 v[60:61], v[60:61], v[92:93] neg_lo:[0,1] neg_hi:[0,1]
	v_pk_add_f32 v[92:93], v[52:53], v[84:85]
	v_pk_add_f32 v[52:53], v[52:53], v[84:85] neg_lo:[0,1] neg_hi:[0,1]
	v_pk_add_f32 v[84:85], v[68:69], v[100:101]
	v_pk_add_f32 v[68:69], v[68:69], v[100:101] neg_lo:[0,1] neg_hi:[0,1]
	v_pk_add_f32 v[100:101], v[42:43], v[74:75]
	v_pk_add_f32 v[42:43], v[42:43], v[74:75] neg_lo:[0,1] neg_hi:[0,1]
	v_pk_add_f32 v[74:75], v[58:59], v[90:91]
	v_pk_add_f32 v[58:59], v[58:59], v[90:91] neg_lo:[0,1] neg_hi:[0,1]
	v_pk_add_f32 v[90:91], v[50:51], v[82:83]
	v_pk_add_f32 v[50:51], v[50:51], v[82:83] neg_lo:[0,1] neg_hi:[0,1]
	v_pk_add_f32 v[82:83], v[66:67], v[98:99]
	v_pk_add_f32 v[66:67], v[66:67], v[98:99] neg_lo:[0,1] neg_hi:[0,1]
	v_pk_add_f32 v[98:99], v[46:47], v[78:79]
	v_pk_add_f32 v[46:47], v[46:47], v[78:79] neg_lo:[0,1] neg_hi:[0,1]
	v_pk_add_f32 v[78:79], v[62:63], v[94:95]
	v_pk_add_f32 v[62:63], v[62:63], v[94:95] neg_lo:[0,1] neg_hi:[0,1]
	v_pk_add_f32 v[94:95], v[54:55], v[86:87]
	v_pk_add_f32 v[54:55], v[54:55], v[86:87] neg_lo:[0,1] neg_hi:[0,1]
	v_pk_add_f32 v[86:87], v[70:71], v[102:103]
	v_pk_add_f32 v[70:71], v[70:71], v[102:103] neg_lo:[0,1] neg_hi:[0,1]
	v_pk_add_f32 v[102:103], v[104:105], v[106:107]
	v_pk_add_f32 v[104:105], v[104:105], v[106:107] neg_lo:[0,1] neg_hi:[0,1]
	v_pk_add_f32 v[56:57], v[72:73], v[246:247] op_sel:[0,1] op_sel_hi:[1,0] neg_lo:[0,1]
	v_pk_add_f32 v[72:73], v[72:73], v[246:247] op_sel:[0,1] op_sel_hi:[1,0] neg_hi:[0,1]
	v_pk_add_f32 v[106:107], v[88:89], v[80:81]
	v_pk_add_f32 v[80:81], v[88:89], v[80:81] neg_lo:[0,1] neg_hi:[0,1]
	v_xor_b32_e32 v88, 0x80000000, v65
	v_mov_b32_e32 v89, v64
	v_pk_add_f32 v[64:65], v[48:49], v[88:89]
	v_pk_add_f32 v[48:49], v[48:49], v[88:89] neg_lo:[0,1] neg_hi:[0,1]
	v_pk_add_f32 v[88:89], v[96:97], v[76:77]
	v_pk_add_f32 v[76:77], v[96:97], v[76:77] neg_lo:[0,1] neg_hi:[0,1]
	v_xor_b32_e32 v96, 0x80000000, v61
	v_mov_b32_e32 v97, v60
	v_pk_add_f32 v[60:61], v[44:45], v[96:97]
	v_pk_add_f32 v[44:45], v[44:45], v[96:97] neg_lo:[0,1] neg_hi:[0,1]
	v_pk_add_f32 v[96:97], v[92:93], v[84:85]
	v_pk_add_f32 v[84:85], v[92:93], v[84:85] neg_lo:[0,1] neg_hi:[0,1]
	v_xor_b32_e32 v92, 0x80000000, v69
	v_mov_b32_e32 v93, v68
	v_pk_add_f32 v[68:69], v[52:53], v[92:93]
	v_pk_add_f32 v[52:53], v[52:53], v[92:93] neg_lo:[0,1] neg_hi:[0,1]
	v_pk_add_f32 v[92:93], v[100:101], v[74:75]
	v_pk_add_f32 v[74:75], v[100:101], v[74:75] neg_lo:[0,1] neg_hi:[0,1]
	v_xor_b32_e32 v100, 0x80000000, v59
	v_mov_b32_e32 v101, v58
	v_pk_add_f32 v[58:59], v[42:43], v[100:101]
	v_pk_add_f32 v[42:43], v[42:43], v[100:101] neg_lo:[0,1] neg_hi:[0,1]
	v_pk_add_f32 v[100:101], v[90:91], v[82:83]
	v_pk_add_f32 v[82:83], v[90:91], v[82:83] neg_lo:[0,1] neg_hi:[0,1]
	v_xor_b32_e32 v90, 0x80000000, v67
	v_mov_b32_e32 v91, v66
	v_pk_add_f32 v[66:67], v[50:51], v[90:91]
	v_pk_add_f32 v[50:51], v[50:51], v[90:91] neg_lo:[0,1] neg_hi:[0,1]
	v_pk_add_f32 v[90:91], v[98:99], v[78:79]
	v_pk_add_f32 v[78:79], v[98:99], v[78:79] neg_lo:[0,1] neg_hi:[0,1]
	v_xor_b32_e32 v98, 0x80000000, v63
	v_mov_b32_e32 v99, v62
	v_pk_add_f32 v[62:63], v[46:47], v[98:99]
	v_pk_add_f32 v[46:47], v[46:47], v[98:99] neg_lo:[0,1] neg_hi:[0,1]
	v_pk_add_f32 v[98:99], v[94:95], v[86:87]
	v_pk_add_f32 v[86:87], v[94:95], v[86:87] neg_lo:[0,1] neg_hi:[0,1]
	v_xor_b32_e32 v94, 0x80000000, v71
	v_mov_b32_e32 v95, v70
	s_mov_b32 s73, s36
	v_pk_add_f32 v[70:71], v[54:55], v[94:95]
	v_pk_add_f32 v[54:55], v[54:55], v[94:95] neg_lo:[0,1] neg_hi:[0,1]
	v_pk_add_f32 v[94:95], v[102:103], v[106:107]
	v_pk_add_f32 v[102:103], v[102:103], v[106:107] neg_lo:[0,1] neg_hi:[0,1]
	s_mov_b32 s0, s37
	v_pk_mul_f32 v[106:107], v[64:65], s[72:73]
	s_mov_b32 s74, s19
	v_pk_fma_f32 v[64:65], v[64:65], s[0:1], v[106:107] op_sel:[0,0,1] op_sel_hi:[1,0,0]
	s_mov_b32 s75, s18
	v_pk_add_f32 v[106:107], v[56:57], v[64:65]
	v_pk_add_f32 v[56:57], v[56:57], v[64:65] neg_lo:[0,1] neg_hi:[0,1]
	v_xor_b32_e32 v64, 0x80000000, v81
	v_mov_b32_e32 v65, v80
	v_pk_add_f32 v[80:81], v[104:105], v[64:65]
	v_pk_add_f32 v[64:65], v[104:105], v[64:65] neg_lo:[0,1] neg_hi:[0,1]
	v_pk_mul_f32 v[104:105], v[48:49], s[72:73]
	s_mov_b32 s76, s19
	v_pk_fma_f32 v[48:49], v[48:49], s[0:1], v[104:105] op_sel:[0,0,1] op_sel_hi:[1,0,0] neg_lo:[1,0,0] neg_hi:[1,0,0]
	s_mov_b32 s62, s11
	v_pk_add_f32 v[104:105], v[72:73], v[48:49]
	v_pk_add_f32 v[48:49], v[72:73], v[48:49] neg_lo:[0,1] neg_hi:[0,1]
	v_pk_add_f32 v[72:73], v[88:89], v[96:97]
	v_pk_add_f32 v[246:247], v[88:89], v[96:97] neg_lo:[0,1] neg_hi:[0,1]
	v_pk_mul_f32 v[96:97], v[68:69], s[72:73]
	s_mov_b32 s63, s10
	v_pk_fma_f32 v[68:69], v[68:69], s[0:1], v[96:97] op_sel:[0,0,1] op_sel_hi:[1,0,0]
	s_mov_b32 s78, s27
	v_pk_add_f32 v[96:97], v[60:61], v[68:69]
	v_pk_add_f32 v[60:61], v[60:61], v[68:69] neg_lo:[0,1] neg_hi:[0,1]
	v_xor_b32_e32 v68, 0x80000000, v85
	v_mov_b32_e32 v69, v84
	v_pk_add_f32 v[84:85], v[76:77], v[68:69]
	v_pk_add_f32 v[68:69], v[76:77], v[68:69] neg_lo:[0,1] neg_hi:[0,1]
	v_pk_mul_f32 v[76:77], v[52:53], s[72:73]
	v_pk_mul_f32 v[108:109], v[96:97], s[74:75]
	v_pk_fma_f32 v[52:53], v[52:53], s[0:1], v[76:77] op_sel:[0,0,1] op_sel_hi:[1,0,0] neg_lo:[1,0,0] neg_hi:[1,0,0]
	v_pk_fma_f32 v[96:97], v[96:97], s[16:17], v[108:109] op_sel:[0,0,1] op_sel_hi:[1,0,0]
	v_pk_add_f32 v[76:77], v[44:45], v[52:53]
	v_pk_add_f32 v[44:45], v[44:45], v[52:53] neg_lo:[0,1] neg_hi:[0,1]
	v_pk_add_f32 v[52:53], v[92:93], v[100:101]
	v_pk_add_f32 v[92:93], v[92:93], v[100:101] neg_lo:[0,1] neg_hi:[0,1]
	v_pk_mul_f32 v[100:101], v[66:67], s[72:73]
	s_mov_b32 s17, s40
	v_pk_fma_f32 v[66:67], v[66:67], s[0:1], v[100:101] op_sel:[0,0,1] op_sel_hi:[1,0,0]
	v_pk_add_f32 v[108:109], v[106:107], v[96:97]
	v_pk_add_f32 v[100:101], v[58:59], v[66:67]
	v_pk_add_f32 v[58:59], v[58:59], v[66:67] neg_lo:[0,1] neg_hi:[0,1]
	v_xor_b32_e32 v66, 0x80000000, v83
	v_mov_b32_e32 v67, v82
	v_pk_add_f32 v[82:83], v[74:75], v[66:67]
	v_pk_add_f32 v[66:67], v[74:75], v[66:67] neg_lo:[0,1] neg_hi:[0,1]
	v_pk_mul_f32 v[74:75], v[50:51], s[72:73]
	v_pk_add_f32 v[96:97], v[106:107], v[96:97] neg_lo:[0,1] neg_hi:[0,1]
	v_pk_fma_f32 v[50:51], v[50:51], s[0:1], v[74:75] op_sel:[0,0,1] op_sel_hi:[1,0,0] neg_lo:[1,0,0] neg_hi:[1,0,0]
	v_pk_mul_f32 v[106:107], v[84:85], s[72:73]
	v_pk_add_f32 v[74:75], v[42:43], v[50:51]
	v_pk_add_f32 v[42:43], v[42:43], v[50:51] neg_lo:[0,1] neg_hi:[0,1]
	v_pk_add_f32 v[50:51], v[90:91], v[98:99]
	v_pk_add_f32 v[90:91], v[90:91], v[98:99] neg_lo:[0,1] neg_hi:[0,1]
	v_pk_mul_f32 v[98:99], v[70:71], s[72:73]
	v_pk_fma_f32 v[84:85], v[84:85], s[0:1], v[106:107] op_sel:[0,0,1] op_sel_hi:[1,0,0]
	v_pk_fma_f32 v[70:71], v[70:71], s[0:1], v[98:99] op_sel:[0,0,1] op_sel_hi:[1,0,0]
	v_pk_add_f32 v[106:107], v[80:81], v[84:85]
	v_pk_add_f32 v[98:99], v[62:63], v[70:71]
	v_pk_add_f32 v[62:63], v[62:63], v[70:71] neg_lo:[0,1] neg_hi:[0,1]
	v_xor_b32_e32 v70, 0x80000000, v87
	v_mov_b32_e32 v71, v86
	v_pk_mul_f32 v[110:111], v[98:99], s[74:75]
	v_pk_add_f32 v[86:87], v[78:79], v[70:71]
	v_pk_add_f32 v[70:71], v[78:79], v[70:71] neg_lo:[0,1] neg_hi:[0,1]
	v_pk_mul_f32 v[78:79], v[54:55], s[72:73]
	v_pk_fma_f32 v[98:99], v[98:99], s[16:17], v[110:111] op_sel:[0,0,1] op_sel_hi:[1,0,0]
	v_pk_fma_f32 v[54:55], v[54:55], s[0:1], v[78:79] op_sel:[0,0,1] op_sel_hi:[1,0,0] neg_lo:[1,0,0] neg_hi:[1,0,0]
	v_pk_add_f32 v[110:111], v[100:101], v[98:99]
	v_pk_add_f32 v[98:99], v[100:101], v[98:99] neg_lo:[0,1] neg_hi:[0,1]
	v_pk_mul_f32 v[100:101], v[86:87], s[72:73]
	v_pk_add_f32 v[78:79], v[46:47], v[54:55]
	v_pk_fma_f32 v[86:87], v[86:87], s[0:1], v[100:101] op_sel:[0,0,1] op_sel_hi:[1,0,0]
	v_pk_add_f32 v[46:47], v[46:47], v[54:55] neg_lo:[0,1] neg_hi:[0,1]
	v_pk_add_f32 v[100:101], v[82:83], v[86:87]
	v_pk_add_f32 v[82:83], v[82:83], v[86:87] neg_lo:[0,1] neg_hi:[0,1]
	v_pk_mul_f32 v[86:87], v[78:79], s[16:17]
	v_pk_add_f32 v[80:81], v[80:81], v[84:85] neg_lo:[0,1] neg_hi:[0,1]
	v_pk_fma_f32 v[78:79], v[78:79], s[76:77], v[86:87] op_sel:[0,0,1] op_sel_hi:[1,0,0]
	v_pk_mul_f32 v[84:85], v[76:77], s[16:17]
	v_pk_add_f32 v[86:87], v[74:75], v[78:79]
	v_pk_add_f32 v[74:75], v[74:75], v[78:79] neg_lo:[0,1] neg_hi:[0,1]
	v_xor_b32_e32 v78, 0x80000000, v91
	v_mov_b32_e32 v79, v90
	v_pk_add_f32 v[90:91], v[92:93], v[78:79]
	v_pk_add_f32 v[78:79], v[92:93], v[78:79] neg_lo:[0,1] neg_hi:[0,1]
	v_pk_mul_f32 v[92:93], v[62:63], s[16:17]
	v_pk_fma_f32 v[76:77], v[76:77], s[76:77], v[84:85] op_sel:[0,0,1] op_sel_hi:[1,0,0]
	v_pk_fma_f32 v[62:63], v[62:63], s[76:77], v[92:93] op_sel:[0,0,1] op_sel_hi:[1,0,0] neg_lo:[1,0,0] neg_hi:[1,0,0]
	v_pk_add_f32 v[84:85], v[104:105], v[76:77]
	v_pk_add_f32 v[92:93], v[58:59], v[62:63]
	v_pk_add_f32 v[58:59], v[58:59], v[62:63] neg_lo:[0,1] neg_hi:[0,1]
	v_pk_mul_f32 v[62:63], v[70:71], s[72:73]
	v_pk_add_f32 v[76:77], v[104:105], v[76:77] neg_lo:[0,1] neg_hi:[0,1]
	v_pk_fma_f32 v[62:63], s[0:1], v[70:71], v[62:63] op_sel:[0,0,1] op_sel_hi:[0,1,0] neg_lo:[0,1,0] neg_hi:[0,1,0]
	v_pk_add_f32 v[70:71], v[66:67], v[62:63]
	v_pk_add_f32 v[62:63], v[66:67], v[62:63] neg_lo:[0,1] neg_hi:[0,1]
	v_pk_mul_f32 v[66:67], v[46:47], s[74:75]
	s_nop 0
	v_pk_fma_f32 v[46:47], v[46:47], s[16:17], v[66:67] op_sel:[0,0,1] op_sel_hi:[1,0,0] neg_lo:[1,0,0] neg_hi:[1,0,0]
	s_mov_b32 s79, s26
	v_pk_add_f32 v[66:67], v[42:43], v[46:47]
	v_pk_add_f32 v[42:43], v[42:43], v[46:47] neg_lo:[0,1] neg_hi:[0,1]
	v_pk_mul_f32 v[46:47], v[110:111], s[62:63]
	v_pk_add_f32 v[88:89], v[102:103], v[246:247] op_sel:[0,1] op_sel_hi:[1,0] neg_lo:[0,1]
	v_pk_fma_f32 v[46:47], v[110:111], s[8:9], v[46:47] op_sel:[0,0,1] op_sel_hi:[1,0,0]
	v_pk_add_f32 v[102:103], v[102:103], v[246:247] op_sel:[0,1] op_sel_hi:[1,0] neg_hi:[0,1]
	v_pk_add_f32 v[46:47], v[108:109], v[46:47]
	v_pk_mul_f32 v[108:109], v[100:101], s[74:75]
	v_pk_mul_f32 v[104:105], v[60:61], s[16:17]
	v_pk_fma_f32 v[100:101], v[100:101], s[16:17], v[108:109] op_sel:[0,0,1] op_sel_hi:[1,0,0]
	v_pk_fma_f32 v[60:61], v[60:61], s[76:77], v[104:105] op_sel:[0,0,1] op_sel_hi:[1,0,0] neg_lo:[1,0,0] neg_hi:[1,0,0]
	v_pk_add_f32 v[100:101], v[106:107], v[100:101]
	v_pk_mul_f32 v[106:107], v[86:87], s[78:79]
	v_pk_add_f32 v[104:105], v[56:57], v[60:61]
	v_pk_fma_f32 v[86:87], v[86:87], s[24:25], v[106:107] op_sel:[0,0,1] op_sel_hi:[1,0,0]
	v_pk_add_f32 v[56:57], v[56:57], v[60:61] neg_lo:[0,1] neg_hi:[0,1]
	v_pk_mul_f32 v[60:61], v[68:69], s[72:73]
	v_pk_add_f32 v[84:85], v[84:85], v[86:87]
	v_pk_mul_f32 v[86:87], v[90:91], s[72:73]
	v_pk_fma_f32 v[60:61], v[68:69], s[0:1], v[60:61] op_sel:[0,0,1] op_sel_hi:[1,0,0] neg_lo:[1,0,0] neg_hi:[1,0,0]
	v_pk_fma_f32 v[86:87], v[90:91], s[0:1], v[86:87] op_sel:[0,0,1] op_sel_hi:[1,0,0]
	v_pk_mul_f32 v[90:91], v[70:71], s[16:17]
	v_pk_add_f32 v[68:69], v[64:65], v[60:61]
	v_pk_fma_f32 v[70:71], v[70:71], s[76:77], v[90:91] op_sel:[0,0,1] op_sel_hi:[1,0,0]
	s_mov_b32 s9, s42
	s_mov_b32 s25, s38
	v_pk_add_f32 v[68:69], v[68:69], v[70:71]
	s_mov_b32 s82, s11
	v_pk_mul_f32 v[70:71], v[66:67], s[8:9]
	s_mov_b32 s80, s27
	v_pk_fma_f32 v[66:67], v[66:67], s[82:83], v[70:71] op_sel:[0,0,1] op_sel_hi:[1,0,0]
	v_pk_mul_f32 v[70:71], v[74:75], s[24:25]
	v_pk_add_f32 v[60:61], v[64:65], v[60:61] neg_lo:[0,1] neg_hi:[0,1]
	v_pk_fma_f32 v[70:71], v[74:75], s[80:81], v[70:71] op_sel:[0,0,1] op_sel_hi:[1,0,0] neg_lo:[1,0,0] neg_hi:[1,0,0]
	v_pk_mul_f32 v[64:65], v[44:45], s[74:75]
	v_pk_add_f32 v[70:71], v[76:77], v[70:71]
	v_pk_mul_f32 v[76:77], v[58:59], s[78:79]
	v_pk_fma_f32 v[44:45], v[44:45], s[16:17], v[64:65] op_sel:[0,0,1] op_sel_hi:[1,0,0] neg_lo:[1,0,0] neg_hi:[1,0,0]
	v_pk_fma_f32 v[58:59], v[58:59], s[24:25], v[76:77] op_sel:[0,0,1] op_sel_hi:[1,0,0] neg_lo:[1,0,0] neg_hi:[1,0,0]
	v_pk_add_f32 v[64:65], v[48:49], v[44:45]
	v_pk_add_f32 v[56:57], v[56:57], v[58:59]
	v_pk_mul_f32 v[58:59], v[62:63], s[74:75]
	v_pk_add_f32 v[44:45], v[48:49], v[44:45] neg_lo:[0,1] neg_hi:[0,1]
	v_pk_fma_f32 v[58:59], s[16:17], v[62:63], v[58:59] op_sel:[0,0,1] op_sel_hi:[0,1,0] neg_lo:[0,1,0] neg_hi:[0,1,0]
	v_pk_add_f32 v[58:59], v[60:61], v[58:59]
	v_pk_mul_f32 v[60:61], v[42:43], s[62:63]
	v_pk_add_f32 v[54:55], v[94:95], v[72:73] neg_lo:[0,1] neg_hi:[0,1]
	v_pk_add_f32 v[64:65], v[64:65], v[66:67]
	v_pk_add_f32 v[66:67], v[52:53], v[50:51] neg_lo:[0,1] neg_hi:[0,1]
	v_pk_fma_f32 v[42:43], v[42:43], s[8:9], v[60:61] op_sel:[0,0,1] op_sel_hi:[1,0,0] neg_lo:[1,0,0] neg_hi:[1,0,0]
	v_pk_add_f32 v[86:87], v[88:89], v[86:87]
	v_pk_mul_f32 v[88:89], v[92:93], s[24:25]
	v_pk_add_f32 v[48:49], v[54:55], v[66:67] op_sel:[0,1] op_sel_hi:[1,0] neg_lo:[0,1]
	v_pk_mul_f32 v[54:55], v[98:99], s[8:9]
	v_pk_mul_f32 v[66:67], v[82:83], s[16:17]
	v_pk_mul_f32 v[74:75], v[78:79], s[72:73]
	v_pk_add_f32 v[42:43], v[44:45], v[42:43]
	v_pk_add_f32 v[44:45], v[94:95], v[72:73]
	v_pk_add_f32 v[50:51], v[52:53], v[50:51]
	v_pk_fma_f32 v[88:89], v[92:93], s[80:81], v[88:89] op_sel:[0,0,1] op_sel_hi:[1,0,0]
	v_pk_fma_f32 v[54:55], v[98:99], s[82:83], v[54:55] op_sel:[0,0,1] op_sel_hi:[1,0,0] neg_lo:[1,0,0] neg_hi:[1,0,0]
	v_pk_fma_f32 v[66:67], v[82:83], s[76:77], v[66:67] op_sel:[0,0,1] op_sel_hi:[1,0,0] neg_lo:[1,0,0] neg_hi:[1,0,0]
	v_pk_fma_f32 v[74:75], v[78:79], s[0:1], v[74:75] op_sel:[0,0,1] op_sel_hi:[1,0,0] neg_lo:[1,0,0] neg_hi:[1,0,0]
	v_pk_add_f32 v[44:45], v[44:45], v[50:51]
	v_lshl_add_u32 v21, v21, 3, v36
	v_pk_add_f32 v[88:89], v[104:105], v[88:89]
	v_pk_add_f32 v[54:55], v[96:97], v[54:55]
	v_pk_add_f32 v[66:67], v[80:81], v[66:67]
	v_pk_add_f32 v[74:75], v[102:103], v[74:75]
	ds_write_b64 v25, v[44:45]
	ds_write_b64 v25, v[46:47] offset:4224
	ds_write_b64 v25, v[100:101] offset:8448
	ds_write_b64 v25, v[84:85] offset:12672
	ds_write_b64 v25, v[86:87] offset:16896
	ds_write_b64 v25, v[88:89] offset:21120
	ds_write_b64 v25, v[68:69] offset:25344
	ds_write_b64 v25, v[64:65] offset:29568
	ds_write_b64 v25, v[48:49] offset:33792
	ds_write_b64 v25, v[54:55] offset:38016
	ds_write_b64 v25, v[66:67] offset:42240
	ds_write_b64 v25, v[70:71] offset:46464
	ds_write_b64 v25, v[74:75] offset:50688
	ds_write_b64 v25, v[56:57] offset:54912
	ds_write_b64 v25, v[58:59] offset:59136
	ds_write_b64 v25, v[42:43] offset:63360
	v_ashrrev_i32_e32 v25, 5, v21
	v_lshlrev_b32_e32 v21, 3, v21
	v_lshlrev_b32_e32 v25, 3, v25
	s_waitcnt vmcnt(0)
	v_lshlrev_b32_e32 v41, 16, v41
	v_lshlrev_b32_e32 v39, 16, v39
	v_lshlrev_b32_e32 v35, 16, v35
	v_lshlrev_b32_e32 v29, 16, v29
	v_and_b32_e32 v48, 0xffff0000, v14
	v_add3_u32 v21, 0, v21, v25
	v_mov_b32_e32 v40, v48
	s_waitcnt lgkmcnt(0)
	s_barrier
	v_pk_mul_f32 v[44:45], v[30:31], v[40:41]
	ds_read2_b64 v[40:43], v21 offset1:1
	v_lshlrev_b32_e32 v28, 16, v14
	v_lshlrev_b32_e32 v49, 16, v15
	v_pk_fma_f32 v[44:45], v[30:31], v[28:29], v[44:45] op_sel:[0,0,1] op_sel_hi:[1,0,0]
	v_mov_b32_e32 v28, v31
	v_pk_fma_f32 v[44:45], v[20:21], v[48:49], v[44:45] op_sel_hi:[0,1,1]
	v_pk_add_f32 v[50:51], v[24:25], v[44:45] op_sel_hi:[0,1]
	ds_read2_b64 v[44:47], v21 offset0:2 offset1:3
	s_waitcnt lgkmcnt(1)
	v_pk_mul_f32 v[40:41], v[50:51], v[40:41]
	v_and_b32_e32 v51, 16, v16
	v_and_b32_e32 v50, 0xffff0000, v15
	v_pk_mov_b32 v[14:15], v[48:49], v[50:51] op_sel:[1,0]
	v_lshlrev_b32_e32 v53, 16, v16
	v_pk_mul_f32 v[14:15], v[30:31], v[14:15] op_sel_hi:[0,1]
	v_mov_b32_e32 v52, v50
	v_pk_fma_f32 v[14:15], v[28:29], v[48:49], v[14:15] op_sel_hi:[0,1,1]
	v_pk_fma_f32 v[14:15], v[20:21], v[52:53], v[14:15] op_sel_hi:[0,1,1]
	v_pk_add_f32 v[14:15], v[24:25], v[14:15] op_sel_hi:[0,1]
	v_pk_mul_f32 v[14:15], v[14:15], v[42:43]
	v_and_b32_e32 v43, 16, v17
	v_and_b32_e32 v42, 0xffff0000, v16
	v_lshlrev_b32_e32 v49, 16, v17
	v_mov_b32_e32 v48, v42
	v_pk_mov_b32 v[42:43], v[52:53], v[42:43] op_sel:[1,0]
	v_pk_mov_b32 v[16:17], v[16:17], v[10:11] op_sel:[1,0]
	v_pk_mul_f32 v[42:43], v[30:31], v[42:43] op_sel_hi:[0,1]
	v_and_b32_e32 v17, 16, v17
	v_and_b32_e32 v16, 0xffff0000, v16
	v_pk_fma_f32 v[42:43], v[28:29], v[52:53], v[42:43] op_sel_hi:[0,1,1]
	v_mov_b32_e32 v50, v16
	v_pk_mov_b32 v[16:17], v[48:49], v[16:17] op_sel:[1,0]
	v_pk_fma_f32 v[42:43], v[20:21], v[48:49], v[42:43] op_sel_hi:[0,1,1]
	v_pk_mul_f32 v[16:17], v[30:31], v[16:17] op_sel_hi:[0,1]
	v_pk_add_f32 v[42:43], v[24:25], v[42:43] op_sel_hi:[0,1]
	v_lshlrev_b32_e32 v51, 16, v10
	v_pk_fma_f32 v[16:17], v[28:29], v[48:49], v[16:17] op_sel_hi:[0,1,1]
	s_waitcnt lgkmcnt(0)
	v_pk_mul_f32 v[42:43], v[42:43], v[44:45]
	v_pk_fma_f32 v[16:17], v[20:21], v[50:51], v[16:17] op_sel_hi:[0,1,1]
	v_and_b32_e32 v45, 16, v11
	v_and_b32_e32 v44, 0xffff0000, v10
	v_pk_add_f32 v[16:17], v[24:25], v[16:17] op_sel_hi:[0,1]
	v_mov_b32_e32 v52, v44
	v_pk_mov_b32 v[44:45], v[50:51], v[44:45] op_sel:[1,0]
	v_pk_mul_f32 v[16:17], v[16:17], v[46:47]
	v_pk_mul_f32 v[48:49], v[30:31], v[44:45] op_sel_hi:[0,1]
	ds_read2_b64 v[44:47], v21 offset0:4 offset1:5
	v_lshlrev_b32_e32 v53, 16, v11
	v_pk_fma_f32 v[48:49], v[28:29], v[50:51], v[48:49] op_sel_hi:[0,1,1]
	v_pk_fma_f32 v[48:49], v[20:21], v[52:53], v[48:49] op_sel_hi:[0,1,1]
	v_pk_add_f32 v[54:55], v[24:25], v[48:49] op_sel_hi:[0,1]
	ds_read2_b64 v[48:51], v21 offset0:6 offset1:7
	s_waitcnt lgkmcnt(1)
	v_pk_mul_f32 v[44:45], v[54:55], v[44:45]
	v_and_b32_e32 v55, 16, v12
	v_and_b32_e32 v54, 0xffff0000, v11
	v_pk_mov_b32 v[10:11], v[52:53], v[54:55] op_sel:[1,0]
	v_lshlrev_b32_e32 v57, 16, v12
	v_pk_mul_f32 v[10:11], v[30:31], v[10:11] op_sel_hi:[0,1]
	v_mov_b32_e32 v56, v54
	v_pk_fma_f32 v[10:11], v[28:29], v[52:53], v[10:11] op_sel_hi:[0,1,1]
	v_pk_fma_f32 v[10:11], v[20:21], v[56:57], v[10:11] op_sel_hi:[0,1,1]
	v_pk_add_f32 v[10:11], v[24:25], v[10:11] op_sel_hi:[0,1]
	v_and_b32_e32 v38, 0xffff0000, v13
	v_pk_mul_f32 v[10:11], v[10:11], v[46:47]
	v_and_b32_e32 v47, 16, v13
	v_and_b32_e32 v46, 0xffff0000, v12
	v_lshlrev_b32_e32 v53, 16, v13
	v_mov_b32_e32 v52, v46
	v_pk_mov_b32 v[12:13], v[56:57], v[46:47] op_sel:[1,0]
	v_mov_b32_e32 v46, v53
	v_mov_b32_e32 v47, v38
	v_pk_mul_f32 v[12:13], v[30:31], v[12:13] op_sel_hi:[0,1]
	v_pk_mul_f32 v[46:47], v[30:31], v[46:47] op_sel_hi:[0,1]
	v_pk_fma_f32 v[12:13], v[28:29], v[56:57], v[12:13] op_sel_hi:[0,1,1]
	v_pk_fma_f32 v[46:47], v[28:29], v[52:53], v[46:47] op_sel_hi:[0,1,1]
	v_pk_fma_f32 v[12:13], v[20:21], v[52:53], v[12:13] op_sel_hi:[0,1,1]
	v_pk_fma_f32 v[38:39], v[20:21], v[38:39], v[46:47] op_sel_hi:[0,1,1]
	s_xor_b64 s[70:71], s[70:71], -1
	v_pk_add_f32 v[12:13], v[24:25], v[12:13] op_sel_hi:[0,1]
	v_pk_add_f32 v[38:39], v[24:25], v[38:39] op_sel_hi:[0,1]
	s_waitcnt lgkmcnt(0)
	v_pk_mul_f32 v[12:13], v[12:13], v[48:49]
	v_pk_mul_f32 v[38:39], v[38:39], v[50:51]
	s_mov_b64 s[0:1], -1
	s_and_b64 vcc, exec, s[70:71]
	s_cbranch_vccz .LBB0_513
	v_bfe_u32 v46, v15, 16, 1
	v_add3_u32 v47, v15, v46, s4
	v_bfe_u32 v46, v14, 16, 1
	v_bfe_u32 v48, v16, 16, 1
	v_bfe_u32 v50, v42, 16, 1
	v_bfe_u32 v34, v17, 16, 1
	v_bfe_u32 v49, v40, 16, 1
	v_add3_u32 v50, v42, v50, s4
	v_add3_u32 v48, v16, v48, s4
	v_add3_u32 v46, v14, v46, s4
	v_bfe_u32 v25, v43, 16, 1
	v_bfe_u32 v28, v41, 16, 1
	v_add3_u32 v34, v17, v34, s4
	v_add3_u32 v49, v40, v49, s4
	v_lshrrev_b32_e32 v51, 16, v46
	v_lshrrev_b32_e32 v52, 16, v48
	v_lshrrev_b32_e32 v48, 16, v50
	v_bfe_u32 v50, v11, 16, 1
	v_add3_u32 v28, v41, v28, s4
	v_add3_u32 v25, v43, v25, s4
	v_lshrrev_b32_e32 v46, 16, v49
	v_and_or_b32 v49, v34, s91, v52
	v_and_or_b32 v47, v47, s91, v51
	v_add3_u32 v51, v11, v50, s4
	v_bfe_u32 v50, v10, 16, 1
	v_bfe_u32 v52, v38, 16, 1
	v_bfe_u32 v53, v44, 16, 1
	v_bfe_u32 v54, v12, 16, 1
	v_lshl_add_u64 v[36:37], v[36:37], 1, s[50:51]
	v_and_or_b32 v48, v25, s91, v48
	v_and_or_b32 v46, v28, s91, v46
	v_bfe_u32 v25, v13, 16, 1
	v_bfe_u32 v28, v45, 16, 1
	v_bfe_u32 v34, v39, 16, 1
	v_add3_u32 v54, v12, v54, s4
	v_add3_u32 v53, v44, v53, s4
	v_add3_u32 v52, v38, v52, s4
	v_add3_u32 v50, v10, v50, s4
	v_add3_u32 v34, v39, v34, s4
	v_add3_u32 v28, v45, v28, s4
	v_add3_u32 v25, v13, v25, s4
	v_lshrrev_b32_e32 v55, 16, v50
	v_lshrrev_b32_e32 v56, 16, v52
	v_lshrrev_b32_e32 v50, 16, v53
	v_lshrrev_b32_e32 v52, 16, v54
	v_lshl_add_u64 v[32:33], v[32:33], 1, v[36:37]
	v_and_or_b32 v52, v25, s91, v52
	v_and_or_b32 v50, v28, s91, v50
	v_and_or_b32 v53, v34, s91, v56
	v_and_or_b32 v51, v51, s91, v55
	global_store_dwordx4 v[32:33], v[46:49], off
	global_store_dwordx4 v[32:33], v[50:53], off offset:16
	s_mov_b64 s[0:1], 0

.LBB0_534:
	v_mov_b32_e32 v2, v210
	s_mov_b32 s43, s8
	v_and_b32_e32 v3, 0xff, v2
	v_lshlrev_b32_e32 v4, 5, v2
	v_and_or_b32 v3, v4, s33, v3
	v_ashrrev_i32_e32 v4, 5, v3
	v_lshlrev_b32_e32 v3, 3, v3
	v_lshlrev_b32_e32 v4, 3, v4
	v_add3_u32 v18, 0, v3, v4
	ds_read_b64 v[128:129], v18
	ds_read_b64 v[132:133], v18 offset:2112
	ds_read_b64 v[134:135], v18 offset:4224
	ds_read_b64 v[136:137], v18 offset:6336
	ds_read_b64 v[138:139], v18 offset:8448
	ds_read_b64 v[140:141], v18 offset:10560
	ds_read_b64 v[142:143], v18 offset:12672
	ds_read_b64 v[130:131], v18 offset:14784
	ds_read_b64 v[144:145], v18 offset:16896
	ds_read_b64 v[148:149], v18 offset:19008
	ds_read_b64 v[150:151], v18 offset:21120
	ds_read_b64 v[152:153], v18 offset:23232
	s_waitcnt lgkmcnt(10)
	v_pk_mul_f32 v[162:163], v[132:133], s[10:11]
	s_mov_b32 s64, s11
	v_pk_fma_f32 v[162:163], v[132:133], s[8:9], v[162:163] op_sel:[0,0,1] op_sel_hi:[1,0,0]
	s_waitcnt lgkmcnt(2)
	v_pk_mul_f32 v[178:179], v[148:149], s[42:43]
	v_pk_add_f32 v[194:195], v[132:133], v[148:149]
	v_pk_add_f32 v[132:133], v[132:133], v[148:149] neg_lo:[0,1] neg_hi:[0,1]
	v_pk_mul_f32 v[164:165], v[134:135], s[18:19]
	s_mov_b32 s41, s16
	v_pk_fma_f32 v[178:179], v[148:149], s[64:65], v[178:179] op_sel:[0,0,1] op_sel_hi:[1,0,0] neg_lo:[1,0,0] neg_hi:[1,0,0]
	v_pk_mul_f32 v[148:149], v[132:133], s[18:19]
	v_pk_fma_f32 v[164:165], v[134:135], s[16:17], v[164:165] op_sel:[0,0,1] op_sel_hi:[1,0,0]
	s_mov_b32 s68, s19
	s_waitcnt lgkmcnt(1)
	v_pk_mul_f32 v[180:181], v[150:151], s[40:41]
	v_pk_fma_f32 v[132:133], v[132:133], s[16:17], v[148:149] op_sel:[0,0,1] op_sel_hi:[1,0,0]
	v_pk_add_f32 v[148:149], v[134:135], v[150:151]
	v_pk_add_f32 v[134:135], v[134:135], v[150:151] neg_lo:[0,1] neg_hi:[0,1]
	v_pk_mul_f32 v[166:167], v[136:137], s[26:27]
	s_mov_b32 s66, s37
	s_mov_b32 s39, s24
	v_pk_fma_f32 v[180:181], v[150:151], s[68:69], v[180:181] op_sel:[0,0,1] op_sel_hi:[1,0,0] neg_lo:[1,0,0] neg_hi:[1,0,0]
	v_pk_mul_f32 v[150:151], v[134:135], s[36:37]
	ds_read_b64 v[154:155], v18 offset:25344
	ds_read_b64 v[156:157], v18 offset:27456
	ds_read_b64 v[158:159], v18 offset:29568
	ds_read_b64 v[160:161], v18 offset:31680
	v_pk_fma_f32 v[166:167], v[136:137], s[24:25], v[166:167] op_sel:[0,0,1] op_sel_hi:[1,0,0]
	s_mov_b32 s0, s27
	s_waitcnt lgkmcnt(4)
	v_pk_mul_f32 v[182:183], v[152:153], s[38:39]
	v_pk_fma_f32 v[134:135], v[134:135], s[66:67], v[150:151] op_sel:[0,0,1] op_sel_hi:[1,0,0]
	v_pk_add_f32 v[150:151], v[136:137], v[152:153]
	v_pk_add_f32 v[136:137], v[136:137], v[152:153] neg_lo:[0,1] neg_hi:[0,1]
	v_pk_mul_f32 v[168:169], v[138:139], s[36:37]
	v_pk_fma_f32 v[182:183], v[152:153], s[0:1], v[182:183] op_sel:[0,0,1] op_sel_hi:[1,0,0] neg_lo:[1,0,0] neg_hi:[1,0,0]
	v_pk_mul_f32 v[152:153], v[136:137], s[40:41]
	v_pk_fma_f32 v[168:169], v[138:139], s[66:67], v[168:169] op_sel:[0,0,1] op_sel_hi:[1,0,0]
	v_pk_mul_f32 v[170:171], v[140:141], s[38:39]
	s_waitcnt lgkmcnt(3)
	v_pk_mul_f32 v[184:185], v[154:155], s[36:37]
	v_pk_fma_f32 v[136:137], v[136:137], s[68:69], v[152:153] op_sel:[0,0,1] op_sel_hi:[1,0,0]
	v_pk_add_f32 v[152:153], v[138:139], v[154:155]
	v_pk_add_f32 v[246:247], v[138:139], v[154:155] neg_lo:[0,1] neg_hi:[0,1]
	v_pk_fma_f32 v[170:171], v[140:141], s[0:1], v[170:171] op_sel:[0,0,1] op_sel_hi:[1,0,0]
	v_pk_fma_f32 v[184:185], v[154:155], s[66:67], v[184:185] op_sel:[0,0,1] op_sel_hi:[1,0,0] neg_lo:[1,0,0] neg_hi:[1,0,0]
	s_waitcnt lgkmcnt(2)
	v_pk_mul_f32 v[186:187], v[156:157], s[26:27]
	v_pk_add_f32 v[138:139], v[140:141], v[156:157]
	v_pk_add_f32 v[140:141], v[140:141], v[156:157] neg_lo:[0,1] neg_hi:[0,1]
	v_pk_mul_f32 v[172:173], v[142:143], s[40:41]
	v_pk_fma_f32 v[186:187], v[156:157], s[24:25], v[186:187] op_sel:[0,0,1] op_sel_hi:[1,0,0] neg_lo:[1,0,0] neg_hi:[1,0,0]
	v_pk_mul_f32 v[156:157], v[140:141], s[40:41]
	v_pk_fma_f32 v[172:173], v[142:143], s[68:69], v[172:173] op_sel:[0,0,1] op_sel_hi:[1,0,0]
	s_waitcnt lgkmcnt(1)
	v_pk_mul_f32 v[188:189], v[158:159], s[18:19]
	v_pk_fma_f32 v[140:141], v[140:141], s[68:69], v[156:157] op_sel:[0,0,1] op_sel_hi:[1,0,0] neg_lo:[1,0,0] neg_hi:[1,0,0]
	v_pk_add_f32 v[156:157], v[142:143], v[158:159]
	v_pk_add_f32 v[142:143], v[142:143], v[158:159] neg_lo:[0,1] neg_hi:[0,1]
	v_pk_mul_f32 v[174:175], v[130:131], s[42:43]
	v_pk_fma_f32 v[188:189], v[158:159], s[16:17], v[188:189] op_sel:[0,0,1] op_sel_hi:[1,0,0] neg_lo:[1,0,0] neg_hi:[1,0,0]
	v_pk_mul_f32 v[158:159], v[142:143], s[36:37]
	v_pk_fma_f32 v[174:175], v[130:131], s[64:65], v[174:175] op_sel:[0,0,1] op_sel_hi:[1,0,0]
	s_waitcnt lgkmcnt(0)
	v_pk_mul_f32 v[190:191], v[160:161], s[10:11]
	v_pk_fma_f32 v[142:143], v[142:143], s[66:67], v[158:159] op_sel:[0,0,1] op_sel_hi:[1,0,0] neg_lo:[1,0,0] neg_hi:[1,0,0]
	v_pk_add_f32 v[158:159], v[130:131], v[160:161]
	v_pk_add_f32 v[130:131], v[130:131], v[160:161] neg_lo:[0,1] neg_hi:[0,1]
	v_xor_b32_e32 v177, 0x80000000, v144
	v_mov_b32_e32 v176, v145
	v_pk_fma_f32 v[190:191], v[160:161], s[8:9], v[190:191] op_sel:[0,0,1] op_sel_hi:[1,0,0] neg_lo:[1,0,0] neg_hi:[1,0,0]
	v_pk_mul_f32 v[160:161], v[130:131], s[18:19]
	v_pk_add_f32 v[192:193], v[128:129], v[144:145]
	v_pk_add_f32 v[144:145], v[128:129], v[144:145] neg_lo:[0,1] neg_hi:[0,1]
	v_pk_fma_f32 v[130:131], v[130:131], s[16:17], v[160:161] op_sel:[0,0,1] op_sel_hi:[1,0,0] neg_lo:[1,0,0] neg_hi:[1,0,0]
	v_pk_add_f32 v[160:161], v[128:129], v[176:177]
	v_pk_add_f32 v[128:129], v[128:129], v[176:177] neg_lo:[0,1] neg_hi:[0,1]
	v_pk_add_f32 v[176:177], v[162:163], v[178:179]
	v_pk_add_f32 v[162:163], v[162:163], v[178:179] neg_lo:[0,1] neg_hi:[0,1]
	v_cvt_f32_ubyte0_e32 v2, v2
	v_pk_mul_f32 v[178:179], v[162:163], s[18:19]
	v_mul_f32_e32 v2, 0x39000000, v2
	v_pk_fma_f32 v[162:163], v[162:163], s[16:17], v[178:179] op_sel:[0,0,1] op_sel_hi:[1,0,0]
	v_pk_add_f32 v[178:179], v[164:165], v[180:181]
	v_pk_add_f32 v[164:165], v[164:165], v[180:181] neg_lo:[0,1] neg_hi:[0,1]
	v_sin_f32_e32 v34, v2
	v_pk_mul_f32 v[180:181], v[164:165], s[36:37]
	v_cos_f32_e32 v30, v2
	v_pk_fma_f32 v[164:165], v[164:165], s[66:67], v[180:181] op_sel:[0,0,1] op_sel_hi:[1,0,0]
	v_pk_add_f32 v[180:181], v[166:167], v[182:183]
	v_pk_add_f32 v[166:167], v[166:167], v[182:183] neg_lo:[0,1] neg_hi:[0,1]
	v_xor_b32_e32 v31, 0x80000000, v34
	v_pk_mul_f32 v[182:183], v[166:167], s[40:41]
	v_mov_b32_e32 v35, v31
	v_pk_fma_f32 v[166:167], v[166:167], s[68:69], v[182:183] op_sel:[0,0,1] op_sel_hi:[1,0,0]
	v_pk_add_f32 v[182:183], v[168:169], v[184:185]
	v_pk_add_f32 v[184:185], v[168:169], v[184:185] neg_lo:[0,1] neg_hi:[0,1]
	v_pk_mul_f32 v[2:3], v[30:31], v[34:35] op_sel:[1,0] op_sel_hi:[0,1]
	v_pk_add_f32 v[168:169], v[170:171], v[186:187]
	v_pk_add_f32 v[170:171], v[170:171], v[186:187] neg_lo:[0,1] neg_hi:[0,1]
	v_pk_fma_f32 v[44:45], v[30:31], v[30:31], v[2:3] op_sel_hi:[1,0,1]
	v_pk_mul_f32 v[186:187], v[170:171], s[40:41]
	v_pk_mul_f32 v[2:3], v[34:35], v[44:45] op_sel:[0,1] op_sel_hi:[1,0]
	v_pk_fma_f32 v[170:171], v[170:171], s[68:69], v[186:187] op_sel:[0,0,1] op_sel_hi:[1,0,0] neg_lo:[1,0,0] neg_hi:[1,0,0]
	v_pk_add_f32 v[186:187], v[172:173], v[188:189]
	v_pk_add_f32 v[172:173], v[172:173], v[188:189] neg_lo:[0,1] neg_hi:[0,1]
	v_xor_b32_e32 v54, 0x80000000, v45
	v_pk_mul_f32 v[188:189], v[172:173], s[36:37]
	v_mov_b32_e32 v55, v45
	v_pk_fma_f32 v[172:173], v[172:173], s[66:67], v[188:189] op_sel:[0,0,1] op_sel_hi:[1,0,0] neg_lo:[1,0,0] neg_hi:[1,0,0]
	v_pk_add_f32 v[188:189], v[174:175], v[190:191]
	v_pk_add_f32 v[174:175], v[174:175], v[190:191] neg_lo:[0,1] neg_hi:[0,1]
	v_pk_fma_f32 v[46:47], v[30:31], v[44:45], v[2:3] op_sel_hi:[0,1,1]
	v_pk_mul_f32 v[190:191], v[174:175], s[18:19]
	v_pk_mul_f32 v[2:3], v[44:45], v[54:55] op_sel:[1,0] op_sel_hi:[0,1]
	v_pk_fma_f32 v[174:175], v[174:175], s[16:17], v[190:191] op_sel:[0,0,1] op_sel_hi:[1,0,0] neg_lo:[1,0,0] neg_hi:[1,0,0]
	v_pk_add_f32 v[190:191], v[192:193], v[152:153]
	v_pk_add_f32 v[152:153], v[192:193], v[152:153] neg_lo:[0,1] neg_hi:[0,1]
	v_pk_add_f32 v[192:193], v[194:195], v[138:139]
	v_pk_add_f32 v[138:139], v[194:195], v[138:139] neg_lo:[0,1] neg_hi:[0,1]
	v_pk_fma_f32 v[52:53], v[44:45], v[44:45], v[2:3] op_sel_hi:[1,0,1]
	v_pk_mul_f32 v[194:195], v[138:139], s[36:37]
	v_xor_b32_e32 v58, 0x80000000, v53
	v_pk_fma_f32 v[138:139], v[138:139], s[66:67], v[194:195] op_sel:[0,0,1] op_sel_hi:[1,0,0]
	v_pk_add_f32 v[194:195], v[148:149], v[156:157]
	v_pk_add_f32 v[156:157], v[148:149], v[156:157] neg_lo:[0,1] neg_hi:[0,1]
	v_mov_b32_e32 v59, v53
	v_pk_add_f32 v[148:149], v[150:151], v[158:159]
	v_pk_add_f32 v[150:151], v[150:151], v[158:159] neg_lo:[0,1] neg_hi:[0,1]
	v_pk_mul_f32 v[2:3], v[52:53], v[58:59] op_sel:[1,0] op_sel_hi:[0,1]
	v_pk_mul_f32 v[158:159], v[150:151], s[36:37]
	v_pk_fma_f32 v[48:49], v[52:53], v[52:53], v[2:3] op_sel_hi:[1,0,1]
	v_pk_fma_f32 v[150:151], v[150:151], s[66:67], v[158:159] op_sel:[0,0,1] op_sel_hi:[1,0,0] neg_lo:[1,0,0] neg_hi:[1,0,0]
	v_pk_add_f32 v[158:159], v[144:145], v[246:247] op_sel:[0,1] op_sel_hi:[1,0] neg_hi:[0,1]
	v_pk_add_f32 v[144:145], v[144:145], v[246:247] op_sel:[0,1] op_sel_hi:[1,0] neg_lo:[0,1]
	v_pk_add_f32 v[154:155], v[132:133], v[140:141]
	v_pk_add_f32 v[132:133], v[132:133], v[140:141] neg_lo:[0,1] neg_hi:[0,1]
	v_pk_mul_f32 v[2:3], v[58:59], v[48:49] op_sel:[0,1] op_sel_hi:[1,0]
	v_pk_mul_f32 v[140:141], v[132:133], s[36:37]
	v_pk_fma_f32 v[36:37], v[52:53], v[48:49], v[2:3] op_sel_hi:[0,1,1]
	v_pk_fma_f32 v[132:133], v[132:133], s[66:67], v[140:141] op_sel:[0,0,1] op_sel_hi:[1,0,0]
	v_pk_add_f32 v[140:141], v[134:135], v[142:143]
	v_pk_add_f32 v[142:143], v[134:135], v[142:143] neg_lo:[0,1] neg_hi:[0,1]
	v_pk_mul_f32 v[2:3], v[58:59], v[36:37] op_sel:[0,1] op_sel_hi:[1,0]
	v_pk_add_f32 v[134:135], v[136:137], v[130:131]
	v_pk_add_f32 v[130:131], v[136:137], v[130:131] neg_lo:[0,1] neg_hi:[0,1]
	v_pk_fma_f32 v[26:27], v[52:53], v[36:37], v[2:3] op_sel_hi:[0,1,1]
	v_pk_mul_f32 v[136:137], v[130:131], s[36:37]
	v_pk_mul_f32 v[2:3], v[58:59], v[26:27] op_sel:[0,1] op_sel_hi:[1,0]
	v_pk_fma_f32 v[130:131], v[130:131], s[66:67], v[136:137] op_sel:[0,0,1] op_sel_hi:[1,0,0] neg_lo:[1,0,0] neg_hi:[1,0,0]
	v_pk_add_f32 v[136:137], v[160:161], v[182:183]
	v_pk_add_f32 v[160:161], v[160:161], v[182:183] neg_lo:[0,1] neg_hi:[0,1]
	v_pk_add_f32 v[182:183], v[176:177], v[168:169]
	v_pk_add_f32 v[168:169], v[176:177], v[168:169] neg_lo:[0,1] neg_hi:[0,1]
	v_pk_fma_f32 v[20:21], v[52:53], v[26:27], v[2:3] op_sel_hi:[0,1,1]
	v_pk_mul_f32 v[176:177], v[168:169], s[36:37]
	v_pk_mul_f32 v[2:3], v[58:59], v[20:21] op_sel:[0,1] op_sel_hi:[1,0]
	v_pk_fma_f32 v[168:169], v[168:169], s[66:67], v[176:177] op_sel:[0,0,1] op_sel_hi:[1,0,0]
	v_pk_add_f32 v[176:177], v[178:179], v[186:187]
	v_pk_add_f32 v[186:187], v[178:179], v[186:187] neg_lo:[0,1] neg_hi:[0,1]
	v_pk_fma_f32 v[10:11], v[52:53], v[20:21], v[2:3] op_sel_hi:[0,1,1]
	v_pk_add_f32 v[178:179], v[180:181], v[188:189]
	v_pk_add_f32 v[180:181], v[180:181], v[188:189] neg_lo:[0,1] neg_hi:[0,1]
	v_pk_mul_f32 v[2:3], v[58:59], v[10:11] op_sel:[0,1] op_sel_hi:[1,0]
	v_pk_mul_f32 v[188:189], v[180:181], s[36:37]
	v_pk_fma_f32 v[4:5], v[52:53], v[10:11], v[2:3] op_sel_hi:[0,1,1]
	v_pk_fma_f32 v[180:181], v[180:181], s[66:67], v[188:189] op_sel:[0,0,1] op_sel_hi:[1,0,0] neg_lo:[1,0,0] neg_hi:[1,0,0]
	v_pk_add_f32 v[188:189], v[128:129], v[184:185] op_sel:[0,1] op_sel_hi:[1,0] neg_hi:[0,1]
	v_pk_add_f32 v[128:129], v[128:129], v[184:185] op_sel:[0,1] op_sel_hi:[1,0] neg_lo:[0,1]
	v_pk_add_f32 v[184:185], v[162:163], v[170:171]
	v_pk_add_f32 v[162:163], v[162:163], v[170:171] neg_lo:[0,1] neg_hi:[0,1]
	v_xor_b32_e32 v72, 0x80000000, v47
	v_pk_mul_f32 v[170:171], v[162:163], s[36:37]
	v_mov_b32_e32 v73, v47
	v_pk_fma_f32 v[162:163], v[162:163], s[66:67], v[170:171] op_sel:[0,0,1] op_sel_hi:[1,0,0]
	v_pk_add_f32 v[170:171], v[164:165], v[172:173]
	v_pk_add_f32 v[172:173], v[164:165], v[172:173] neg_lo:[0,1] neg_hi:[0,1]
	v_pk_mul_f32 v[2:3], v[72:73], v[4:5] op_sel:[0,1] op_sel_hi:[1,0]
	v_pk_add_f32 v[164:165], v[166:167], v[174:175]
	v_pk_add_f32 v[166:167], v[166:167], v[174:175] neg_lo:[0,1] neg_hi:[0,1]
	v_pk_mul_f32 v[14:15], v[34:35], v[4:5] op_sel:[0,1] op_sel_hi:[1,0]
	v_pk_mul_f32 v[174:175], v[166:167], s[36:37]
	v_pk_mul_f32 v[40:41], v[34:35], v[10:11] op_sel:[0,1] op_sel_hi:[1,0]
	v_pk_fma_f32 v[166:167], v[166:167], s[66:67], v[174:175] op_sel:[0,0,1] op_sel_hi:[1,0,0] neg_lo:[1,0,0] neg_hi:[1,0,0]
	v_pk_add_f32 v[174:175], v[190:191], v[194:195]
	v_pk_add_f32 v[190:191], v[190:191], v[194:195] neg_lo:[0,1] neg_hi:[0,1]
	v_pk_add_f32 v[194:195], v[192:193], v[148:149]
	v_pk_add_f32 v[192:193], v[192:193], v[148:149] neg_lo:[0,1] neg_hi:[0,1]
	v_pk_mul_f32 v[66:67], v[34:35], v[20:21] op_sel:[0,1] op_sel_hi:[1,0]
	v_pk_add_f32 v[148:149], v[152:153], v[156:157] op_sel:[0,1] op_sel_hi:[1,0] neg_hi:[0,1]
	v_pk_add_f32 v[152:153], v[152:153], v[156:157] op_sel:[0,1] op_sel_hi:[1,0] neg_lo:[0,1]
	v_pk_add_f32 v[156:157], v[138:139], v[150:151]
	v_pk_add_f32 v[150:151], v[138:139], v[150:151] neg_lo:[0,1] neg_hi:[0,1]
	v_pk_mul_f32 v[82:83], v[34:35], v[26:27] op_sel:[0,1] op_sel_hi:[1,0]
	v_pk_add_f32 v[138:139], v[158:159], v[140:141]
	v_pk_add_f32 v[140:141], v[158:159], v[140:141] neg_lo:[0,1] neg_hi:[0,1]
	v_pk_add_f32 v[158:159], v[154:155], v[134:135]
	v_pk_add_f32 v[154:155], v[154:155], v[134:135] neg_lo:[0,1] neg_hi:[0,1]
	v_pk_mul_f32 v[96:97], v[34:35], v[36:37] op_sel:[0,1] op_sel_hi:[1,0]
	v_pk_add_f32 v[134:135], v[144:145], v[142:143] op_sel:[0,1] op_sel_hi:[1,0] neg_hi:[0,1]
	v_pk_add_f32 v[142:143], v[144:145], v[142:143] op_sel:[0,1] op_sel_hi:[1,0] neg_lo:[0,1]
	v_pk_add_f32 v[144:145], v[132:133], v[130:131]
	v_pk_add_f32 v[132:133], v[132:133], v[130:131] neg_lo:[0,1] neg_hi:[0,1]
	v_pk_mul_f32 v[110:111], v[34:35], v[48:49] op_sel:[0,1] op_sel_hi:[1,0]
	v_pk_add_f32 v[130:131], v[136:137], v[176:177]
	v_pk_add_f32 v[136:137], v[136:137], v[176:177] neg_lo:[0,1] neg_hi:[0,1]
	v_pk_add_f32 v[176:177], v[182:183], v[178:179]
	v_pk_add_f32 v[182:183], v[182:183], v[178:179] neg_lo:[0,1] neg_hi:[0,1]
	v_pk_mul_f32 v[124:125], v[34:35], v[52:53] op_sel:[0,1] op_sel_hi:[1,0]
	v_pk_add_f32 v[178:179], v[160:161], v[186:187] op_sel:[0,1] op_sel_hi:[1,0] neg_hi:[0,1]
	v_pk_add_f32 v[160:161], v[160:161], v[186:187] op_sel:[0,1] op_sel_hi:[1,0] neg_lo:[0,1]
	v_pk_add_f32 v[186:187], v[168:169], v[180:181]
	v_pk_add_f32 v[180:181], v[168:169], v[180:181] neg_lo:[0,1] neg_hi:[0,1]
	v_pk_fma_f32 v[2:3], v[46:47], v[4:5], v[2:3] op_sel_hi:[0,1,1]
	v_pk_add_f32 v[168:169], v[188:189], v[170:171]
	v_pk_add_f32 v[170:171], v[188:189], v[170:171] neg_lo:[0,1] neg_hi:[0,1]
	v_pk_add_f32 v[188:189], v[184:185], v[164:165]
	v_pk_add_f32 v[184:185], v[184:185], v[164:165] neg_lo:[0,1] neg_hi:[0,1]
	v_pk_mul_f32 v[8:9], v[54:55], v[4:5] op_sel:[0,1] op_sel_hi:[1,0]
	v_pk_add_f32 v[164:165], v[128:129], v[172:173] op_sel:[0,1] op_sel_hi:[1,0] neg_hi:[0,1]
	v_pk_add_f32 v[128:129], v[128:129], v[172:173] op_sel:[0,1] op_sel_hi:[1,0] neg_lo:[0,1]
	v_pk_add_f32 v[172:173], v[162:163], v[166:167]
	v_pk_add_f32 v[166:167], v[162:163], v[166:167] neg_lo:[0,1] neg_hi:[0,1]
	v_pk_fma_f32 v[14:15], v[30:31], v[4:5], v[14:15] op_sel_hi:[0,1,1]
	v_pk_add_f32 v[162:163], v[174:175], v[194:195]
	v_pk_add_f32 v[174:175], v[174:175], v[194:195] neg_lo:[0,1] neg_hi:[0,1]
	v_pk_add_f32 v[194:195], v[190:191], v[192:193] op_sel:[0,1] op_sel_hi:[1,0] neg_hi:[0,1]
	v_pk_add_f32 v[190:191], v[190:191], v[192:193] op_sel:[0,1] op_sel_hi:[1,0] neg_lo:[0,1]
	v_pk_add_f32 v[192:193], v[148:149], v[156:157]
	v_pk_add_f32 v[148:149], v[148:149], v[156:157] neg_lo:[0,1] neg_hi:[0,1]
	v_pk_add_f32 v[156:157], v[152:153], v[150:151] op_sel:[0,1] op_sel_hi:[1,0] neg_hi:[0,1]
	v_pk_add_f32 v[150:151], v[152:153], v[150:151] op_sel:[0,1] op_sel_hi:[1,0] neg_lo:[0,1]
	v_pk_add_f32 v[152:153], v[138:139], v[158:159]
	v_pk_add_f32 v[138:139], v[138:139], v[158:159] neg_lo:[0,1] neg_hi:[0,1]
	v_pk_add_f32 v[158:159], v[140:141], v[154:155] op_sel:[0,1] op_sel_hi:[1,0] neg_hi:[0,1]
	v_pk_add_f32 v[140:141], v[140:141], v[154:155] op_sel:[0,1] op_sel_hi:[1,0] neg_lo:[0,1]
	v_pk_add_f32 v[154:155], v[134:135], v[144:145]
	v_pk_add_f32 v[134:135], v[134:135], v[144:145] neg_lo:[0,1] neg_hi:[0,1]
	v_pk_add_f32 v[144:145], v[142:143], v[132:133] op_sel:[0,1] op_sel_hi:[1,0] neg_hi:[0,1]
	v_pk_add_f32 v[132:133], v[142:143], v[132:133] op_sel:[0,1] op_sel_hi:[1,0] neg_lo:[0,1]
	v_pk_add_f32 v[142:143], v[130:131], v[176:177]
	v_pk_mul_f32 v[24:25], v[72:73], v[10:11] op_sel:[0,1] op_sel_hi:[1,0]
	v_pk_mul_f32 v[34:35], v[34:35], v[142:143] op_sel:[0,1] op_sel_hi:[1,0]
	v_pk_mul_f32 v[32:33], v[54:55], v[10:11] op_sel:[0,1] op_sel_hi:[1,0]
	v_pk_fma_f32 v[40:41], v[30:31], v[10:11], v[40:41] op_sel_hi:[0,1,1]
	v_pk_mul_f32 v[56:57], v[72:73], v[20:21] op_sel:[0,1] op_sel_hi:[1,0]
	v_pk_mul_f32 v[62:63], v[54:55], v[20:21] op_sel:[0,1] op_sel_hi:[1,0]
	v_pk_fma_f32 v[66:67], v[30:31], v[20:21], v[66:67] op_sel_hi:[0,1,1]
	v_pk_mul_f32 v[74:75], v[72:73], v[26:27] op_sel:[0,1] op_sel_hi:[1,0]
	v_pk_mul_f32 v[78:79], v[54:55], v[26:27] op_sel:[0,1] op_sel_hi:[1,0]
	v_pk_fma_f32 v[82:83], v[30:31], v[26:27], v[82:83] op_sel_hi:[0,1,1]
	v_pk_mul_f32 v[88:89], v[72:73], v[36:37] op_sel:[0,1] op_sel_hi:[1,0]
	v_pk_mul_f32 v[92:93], v[54:55], v[36:37] op_sel:[0,1] op_sel_hi:[1,0]
	v_pk_fma_f32 v[96:97], v[30:31], v[36:37], v[96:97] op_sel_hi:[0,1,1]
	v_pk_mul_f32 v[102:103], v[72:73], v[48:49] op_sel:[0,1] op_sel_hi:[1,0]
	v_pk_mul_f32 v[106:107], v[54:55], v[48:49] op_sel:[0,1] op_sel_hi:[1,0]
	v_pk_fma_f32 v[110:111], v[30:31], v[48:49], v[110:111] op_sel_hi:[0,1,1]
	v_pk_mul_f32 v[116:117], v[52:53], v[72:73] op_sel:[1,0] op_sel_hi:[0,1]
	v_pk_mul_f32 v[120:121], v[54:55], v[52:53] op_sel:[0,1] op_sel_hi:[1,0]
	v_pk_fma_f32 v[124:125], v[30:31], v[52:53], v[124:125] op_sel_hi:[0,1,1]
	v_pk_add_f32 v[130:131], v[130:131], v[176:177] neg_lo:[0,1] neg_hi:[0,1]
	v_pk_add_f32 v[176:177], v[136:137], v[182:183] op_sel:[0,1] op_sel_hi:[1,0] neg_hi:[0,1]
	v_pk_add_f32 v[136:137], v[136:137], v[182:183] op_sel:[0,1] op_sel_hi:[1,0] neg_lo:[0,1]
	v_pk_add_f32 v[182:183], v[178:179], v[186:187]
	v_pk_add_f32 v[178:179], v[178:179], v[186:187] neg_lo:[0,1] neg_hi:[0,1]
	v_pk_add_f32 v[186:187], v[160:161], v[180:181] op_sel:[0,1] op_sel_hi:[1,0] neg_hi:[0,1]
	v_pk_add_f32 v[160:161], v[160:161], v[180:181] op_sel:[0,1] op_sel_hi:[1,0] neg_lo:[0,1]
	v_pk_add_f32 v[180:181], v[168:169], v[188:189]
	v_pk_fma_f32 v[30:31], v[30:31], v[142:143], v[34:35] op_sel_hi:[0,1,1]
	v_pk_mul_f32 v[34:35], v[54:55], v[152:153] op_sel:[0,1] op_sel_hi:[1,0]
	v_xor_b32_e32 v6, 0x80000000, v3
	v_pk_fma_f32 v[8:9], v[44:45], v[4:5], v[8:9] op_sel_hi:[0,1,1]
	v_pk_fma_f32 v[24:25], v[46:47], v[10:11], v[24:25] op_sel_hi:[0,1,1]
	v_pk_fma_f32 v[32:33], v[44:45], v[10:11], v[32:33] op_sel_hi:[0,1,1]
	v_pk_fma_f32 v[56:57], v[46:47], v[20:21], v[56:57] op_sel_hi:[0,1,1]
	v_pk_fma_f32 v[62:63], v[44:45], v[20:21], v[62:63] op_sel_hi:[0,1,1]
	v_pk_fma_f32 v[74:75], v[46:47], v[26:27], v[74:75] op_sel_hi:[0,1,1]
	v_pk_fma_f32 v[78:79], v[44:45], v[26:27], v[78:79] op_sel_hi:[0,1,1]
	v_pk_fma_f32 v[88:89], v[46:47], v[36:37], v[88:89] op_sel_hi:[0,1,1]
	v_pk_fma_f32 v[92:93], v[44:45], v[36:37], v[92:93] op_sel_hi:[0,1,1]
	v_pk_fma_f32 v[102:103], v[46:47], v[48:49], v[102:103] op_sel_hi:[0,1,1]
	v_pk_fma_f32 v[106:107], v[44:45], v[48:49], v[106:107] op_sel_hi:[0,1,1]
	v_xor_b32_e32 v114, 0x80000000, v49
	v_pk_fma_f32 v[116:117], v[52:53], v[46:47], v[116:117] op_sel_hi:[1,0,1]
	v_pk_fma_f32 v[120:121], v[44:45], v[52:53], v[120:121] op_sel_hi:[0,1,1]
	v_mov_b32_e32 v115, v49
	v_mov_b32_e32 v7, v3
	v_pk_add_f32 v[168:169], v[168:169], v[188:189] neg_lo:[0,1] neg_hi:[0,1]
	v_pk_add_f32 v[188:189], v[170:171], v[184:185] op_sel:[0,1] op_sel_hi:[1,0] neg_hi:[0,1]
	v_pk_add_f32 v[170:171], v[170:171], v[184:185] op_sel:[0,1] op_sel_hi:[1,0] neg_lo:[0,1]
	v_pk_add_f32 v[184:185], v[164:165], v[172:173]
	v_pk_add_f32 v[164:165], v[164:165], v[172:173] neg_lo:[0,1] neg_hi:[0,1]
	v_pk_add_f32 v[172:173], v[128:129], v[166:167] op_sel:[0,1] op_sel_hi:[1,0] neg_hi:[0,1]
	v_pk_add_f32 v[128:129], v[128:129], v[166:167] op_sel:[0,1] op_sel_hi:[1,0] neg_lo:[0,1]
	v_pk_fma_f32 v[34:35], v[44:45], v[152:153], v[34:35] op_sel_hi:[0,1,1]
	v_pk_mul_f32 v[44:45], v[72:73], v[180:181] op_sel:[0,1] op_sel_hi:[1,0]
	v_xor_b32_e32 v12, 0x80000000, v9
	v_xor_b32_e32 v16, 0x80000000, v15
	v_xor_b32_e32 v22, 0x80000000, v5
	v_xor_b32_e32 v28, 0x80000000, v25
	v_xor_b32_e32 v38, 0x80000000, v33
	v_xor_b32_e32 v42, 0x80000000, v41
	v_xor_b32_e32 v50, 0x80000000, v11
	v_xor_b32_e32 v60, 0x80000000, v57
	v_xor_b32_e32 v64, 0x80000000, v63
	v_xor_b32_e32 v68, 0x80000000, v67
	v_xor_b32_e32 v70, 0x80000000, v21
	v_xor_b32_e32 v76, 0x80000000, v75
	v_xor_b32_e32 v80, 0x80000000, v79
	v_xor_b32_e32 v84, 0x80000000, v83
	v_xor_b32_e32 v86, 0x80000000, v27
	v_xor_b32_e32 v90, 0x80000000, v89
	v_xor_b32_e32 v94, 0x80000000, v93
	v_xor_b32_e32 v98, 0x80000000, v97
	v_xor_b32_e32 v100, 0x80000000, v37
	v_xor_b32_e32 v104, 0x80000000, v103
	v_xor_b32_e32 v108, 0x80000000, v107
	v_xor_b32_e32 v112, 0x80000000, v111
	v_xor_b32_e32 v118, 0x80000000, v117
	v_xor_b32_e32 v122, 0x80000000, v121
	v_xor_b32_e32 v126, 0x80000000, v125
	v_mov_b32_e32 v127, v125
	v_mov_b32_e32 v123, v121
	v_mov_b32_e32 v119, v117
	v_mov_b32_e32 v113, v111
	v_mov_b32_e32 v109, v107
	v_mov_b32_e32 v105, v103
	v_mov_b32_e32 v101, v37
	v_mov_b32_e32 v99, v97
	v_mov_b32_e32 v95, v93
	v_mov_b32_e32 v91, v89
	v_mov_b32_e32 v87, v27
	v_mov_b32_e32 v85, v83
	v_mov_b32_e32 v81, v79
	v_mov_b32_e32 v77, v75
	v_mov_b32_e32 v71, v21
	v_mov_b32_e32 v69, v67
	v_mov_b32_e32 v65, v63
	v_mov_b32_e32 v61, v57
	v_mov_b32_e32 v51, v11
	v_mov_b32_e32 v43, v41
	v_mov_b32_e32 v39, v33
	v_mov_b32_e32 v29, v25
	v_mov_b32_e32 v23, v5
	v_mov_b32_e32 v17, v15
	v_mov_b32_e32 v13, v9
	v_pk_fma_f32 v[44:45], v[46:47], v[180:181], v[44:45] op_sel_hi:[0,1,1]
	v_pk_mul_f32 v[46:47], v[58:59], v[192:193] op_sel:[0,1] op_sel_hi:[1,0]
	v_pk_mul_f32 v[72:73], v[114:115], v[194:195] op_sel:[0,1] op_sel_hi:[1,0]
	v_pk_mul_f32 v[6:7], v[128:129], v[6:7] op_sel:[1,0] op_sel_hi:[0,1]
	v_pk_fma_f32 v[46:47], v[52:53], v[192:193], v[46:47] op_sel_hi:[0,1,1]
	v_pk_mul_f32 v[52:53], v[126:127], v[182:183] op_sel:[0,1] op_sel_hi:[1,0]
	v_pk_mul_f32 v[54:55], v[122:123], v[154:155] op_sel:[0,1] op_sel_hi:[1,0]
	v_pk_mul_f32 v[58:59], v[118:119], v[184:185] op_sel:[0,1] op_sel_hi:[1,0]
	v_pk_fma_f32 v[48:49], v[48:49], v[194:195], v[72:73] op_sel_hi:[0,1,1]
	v_pk_mul_f32 v[72:73], v[112:113], v[176:177] op_sel:[0,1] op_sel_hi:[1,0]
	v_pk_mul_f32 v[108:109], v[108:109], v[158:159] op_sel:[0,1] op_sel_hi:[1,0]
	v_pk_mul_f32 v[104:105], v[104:105], v[188:189] op_sel:[0,1] op_sel_hi:[1,0]
	v_pk_mul_f32 v[100:101], v[100:101], v[156:157] op_sel:[0,1] op_sel_hi:[1,0]
	v_pk_mul_f32 v[98:99], v[98:99], v[186:187] op_sel:[0,1] op_sel_hi:[1,0]
	v_pk_mul_f32 v[94:95], v[94:95], v[144:145] op_sel:[0,1] op_sel_hi:[1,0]
	v_pk_mul_f32 v[90:91], v[90:91], v[172:173] op_sel:[0,1] op_sel_hi:[1,0]
	v_pk_mul_f32 v[86:87], v[174:175], v[86:87] op_sel:[1,0] op_sel_hi:[0,1]
	v_pk_mul_f32 v[84:85], v[130:131], v[84:85] op_sel:[1,0] op_sel_hi:[0,1]
	v_pk_mul_f32 v[80:81], v[138:139], v[80:81] op_sel:[1,0] op_sel_hi:[0,1]
	v_pk_mul_f32 v[76:77], v[168:169], v[76:77] op_sel:[1,0] op_sel_hi:[0,1]
	v_pk_mul_f32 v[70:71], v[148:149], v[70:71] op_sel:[1,0] op_sel_hi:[0,1]
	v_pk_mul_f32 v[68:69], v[178:179], v[68:69] op_sel:[1,0] op_sel_hi:[0,1]
	v_pk_mul_f32 v[64:65], v[134:135], v[64:65] op_sel:[1,0] op_sel_hi:[0,1]
	v_pk_mul_f32 v[60:61], v[164:165], v[60:61] op_sel:[1,0] op_sel_hi:[0,1]
	v_pk_mul_f32 v[50:51], v[190:191], v[50:51] op_sel:[1,0] op_sel_hi:[0,1]
	v_pk_mul_f32 v[42:43], v[136:137], v[42:43] op_sel:[1,0] op_sel_hi:[0,1]
	v_pk_mul_f32 v[38:39], v[140:141], v[38:39] op_sel:[1,0] op_sel_hi:[0,1]
	v_pk_mul_f32 v[28:29], v[170:171], v[28:29] op_sel:[1,0] op_sel_hi:[0,1]
	v_pk_mul_f32 v[22:23], v[150:151], v[22:23] op_sel:[1,0] op_sel_hi:[0,1]
	v_pk_mul_f32 v[16:17], v[160:161], v[16:17] op_sel:[1,0] op_sel_hi:[0,1]
	v_pk_mul_f32 v[12:13], v[132:133], v[12:13] op_sel:[1,0] op_sel_hi:[0,1]
	v_pk_fma_f32 v[2:3], v[128:129], v[2:3], v[6:7] op_sel_hi:[1,0,1]
	v_pk_fma_f32 v[52:53], v[124:125], v[182:183], v[52:53] op_sel_hi:[0,1,1]
	v_pk_fma_f32 v[54:55], v[120:121], v[154:155], v[54:55] op_sel_hi:[0,1,1]
	v_pk_fma_f32 v[58:59], v[116:117], v[184:185], v[58:59] op_sel_hi:[0,1,1]
	v_pk_fma_f32 v[72:73], v[110:111], v[176:177], v[72:73] op_sel_hi:[0,1,1]
	v_pk_fma_f32 v[106:107], v[106:107], v[158:159], v[108:109] op_sel_hi:[0,1,1]
	v_pk_fma_f32 v[102:103], v[102:103], v[188:189], v[104:105] op_sel_hi:[0,1,1]
	v_pk_fma_f32 v[36:37], v[36:37], v[156:157], v[100:101] op_sel_hi:[0,1,1]
	v_pk_fma_f32 v[96:97], v[96:97], v[186:187], v[98:99] op_sel_hi:[0,1,1]
	v_pk_fma_f32 v[92:93], v[92:93], v[144:145], v[94:95] op_sel_hi:[0,1,1]
	v_pk_fma_f32 v[88:89], v[88:89], v[172:173], v[90:91] op_sel_hi:[0,1,1]
	v_pk_fma_f32 v[26:27], v[174:175], v[26:27], v[86:87] op_sel_hi:[1,0,1]
	v_pk_fma_f32 v[82:83], v[130:131], v[82:83], v[84:85] op_sel_hi:[1,0,1]
	v_pk_fma_f32 v[78:79], v[138:139], v[78:79], v[80:81] op_sel_hi:[1,0,1]
	v_pk_fma_f32 v[74:75], v[168:169], v[74:75], v[76:77] op_sel_hi:[1,0,1]
	v_pk_fma_f32 v[20:21], v[148:149], v[20:21], v[70:71] op_sel_hi:[1,0,1]
	v_pk_fma_f32 v[66:67], v[178:179], v[66:67], v[68:69] op_sel_hi:[1,0,1]
	v_pk_fma_f32 v[62:63], v[134:135], v[62:63], v[64:65] op_sel_hi:[1,0,1]
	v_pk_fma_f32 v[56:57], v[164:165], v[56:57], v[60:61] op_sel_hi:[1,0,1]
	v_pk_fma_f32 v[10:11], v[190:191], v[10:11], v[50:51] op_sel_hi:[1,0,1]
	v_pk_fma_f32 v[40:41], v[136:137], v[40:41], v[42:43] op_sel_hi:[1,0,1]
	v_pk_fma_f32 v[32:33], v[140:141], v[32:33], v[38:39] op_sel_hi:[1,0,1]
	v_pk_fma_f32 v[24:25], v[170:171], v[24:25], v[28:29] op_sel_hi:[1,0,1]
	v_pk_fma_f32 v[4:5], v[150:151], v[4:5], v[22:23] op_sel_hi:[1,0,1]
	v_pk_fma_f32 v[14:15], v[160:161], v[14:15], v[16:17] op_sel_hi:[1,0,1]
	v_pk_fma_f32 v[8:9], v[132:133], v[8:9], v[12:13] op_sel_hi:[1,0,1]
	ds_write_b64 v18, v[162:163]
	ds_write_b64 v18, v[26:27] offset:2112
	ds_write_b64 v18, v[48:49] offset:4224
	ds_write_b64 v18, v[10:11] offset:6336
	ds_write_b64 v18, v[46:47] offset:8448
	ds_write_b64 v18, v[20:21] offset:10560
	ds_write_b64 v18, v[36:37] offset:12672
	ds_write_b64 v18, v[4:5] offset:14784
	ds_write_b64 v18, v[34:35] offset:16896
	ds_write_b64 v18, v[78:79] offset:19008
	ds_write_b64 v18, v[106:107] offset:21120
	ds_write_b64 v18, v[32:33] offset:23232
	ds_write_b64 v18, v[54:55] offset:25344
	ds_write_b64 v18, v[62:63] offset:27456
	ds_write_b64 v18, v[92:93] offset:29568
	ds_write_b64 v18, v[8:9] offset:31680
	ds_write_b64 v18, v[30:31] offset:33792
	ds_write_b64 v18, v[82:83] offset:35904
	ds_write_b64 v18, v[72:73] offset:38016
	ds_write_b64 v18, v[40:41] offset:40128
	ds_write_b64 v18, v[52:53] offset:42240
	ds_write_b64 v18, v[66:67] offset:44352
	ds_write_b64 v18, v[96:97] offset:46464
	ds_write_b64 v18, v[14:15] offset:48576
	ds_write_b64 v18, v[44:45] offset:50688
	ds_write_b64 v18, v[74:75] offset:52800
	ds_write_b64 v18, v[102:103] offset:54912
	ds_write_b64 v18, v[24:25] offset:57024
	ds_write_b64 v18, v[58:59] offset:59136
	ds_write_b64 v18, v[56:57] offset:61248
	ds_write_b64 v18, v[88:89] offset:63360
	ds_write_b64 v18, v[2:3] offset:65472
	v_mov_b32_e32 v3, v210
	s_waitcnt lgkmcnt(0)
	s_barrier
	s_add_i32 s64, s62, s48
	v_and_b32_e32 v5, 15, v3
	v_cvt_f32_ubyte0_e32 v2, v5
	v_mul_f32_e32 v4, 0x3b800000, v2
	v_sin_f32_e32 v2, v4
	v_cos_f32_e32 v4, v4
	v_lshlrev_b32_e32 v64, 3, v5
	v_lshlrev_b32_e32 v18, 4, v3
	v_xor_b32_e32 v5, 0x80000000, v2
	v_mov_b32_e32 v3, v5
	v_pk_mul_f32 v[6:7], v[4:5], v[2:3] op_sel:[1,0] op_sel_hi:[0,1]
	v_pk_fma_f32 v[6:7], v[4:5], v[4:5], v[6:7] op_sel_hi:[1,0,1]
	s_ashr_i32 s65, s64, 31
	v_xor_b32_e32 v12, 0x80000000, v7
	v_mov_b32_e32 v13, v7
	v_pk_mul_f32 v[10:11], v[6:7], v[12:13] op_sel:[1,0] op_sel_hi:[0,1]
	v_pk_fma_f32 v[10:11], v[6:7], v[6:7], v[10:11] op_sel_hi:[1,0,1]
	v_pk_mul_f32 v[8:9], v[2:3], v[6:7] op_sel:[0,1] op_sel_hi:[1,0]
	v_xor_b32_e32 v14, 0x80000000, v11
	v_mov_b32_e32 v15, v11
	v_pk_mul_f32 v[32:33], v[10:11], v[14:15] op_sel:[1,0] op_sel_hi:[0,1]
	v_pk_fma_f32 v[32:33], v[10:11], v[10:11], v[32:33] op_sel_hi:[1,0,1]
	v_pk_mul_f32 v[16:17], v[2:3], v[10:11] op_sel:[0,1] op_sel_hi:[1,0]
	v_pk_mul_f32 v[48:49], v[14:15], v[32:33] op_sel:[0,1] op_sel_hi:[1,0]
	v_pk_mul_f32 v[36:37], v[2:3], v[32:33] op_sel:[0,1] op_sel_hi:[1,0]
	v_pk_fma_f32 v[48:49], v[10:11], v[32:33], v[48:49] op_sel_hi:[0,1,1]
	v_pk_mul_f32 v[52:53], v[2:3], v[48:49] op_sel:[0,1] op_sel_hi:[1,0]
	v_pk_fma_f32 v[8:9], v[4:5], v[6:7], v[8:9] op_sel_hi:[0,1,1]
	v_pk_fma_f32 v[16:17], v[4:5], v[10:11], v[16:17] op_sel_hi:[0,1,1]
	v_pk_fma_f32 v[36:37], v[4:5], v[32:33], v[36:37] op_sel_hi:[0,1,1]
	v_pk_fma_f32 v[52:53], v[4:5], v[48:49], v[52:53] op_sel_hi:[0,1,1]
	v_and_b32_e32 v5, 0xffffff00, v18
	v_lshlrev_b32_e32 v18, 3, v5
	v_add3_u32 v18, 0, v64, v18
	v_ashrrev_i32_e32 v64, 2, v5
	v_add_u32_e32 v106, v18, v64
	ds_read2_b64 v[64:67], v106 offset1:16
	ds_read2_b64 v[68:71], v106 offset0:33 offset1:49
	ds_read2_b64 v[72:75], v106 offset0:66 offset1:82
	ds_read2_b64 v[76:79], v106 offset0:132 offset1:148
	ds_read2_b64 v[80:83], v106 offset0:99 offset1:115
	ds_read2_b64 v[84:87], v106 offset0:165 offset1:181
	ds_read2_b64 v[88:91], v106 offset0:198 offset1:214
	ds_read2_b64 v[92:95], v106 offset0:231 offset1:247
	s_waitcnt lgkmcnt(4)
	v_pk_add_f32 v[96:97], v[64:65], v[76:77]
	v_pk_add_f32 v[64:65], v[64:65], v[76:77] neg_lo:[0,1] neg_hi:[0,1]
	v_pk_add_f32 v[76:77], v[66:67], v[78:79]
	v_pk_add_f32 v[66:67], v[66:67], v[78:79] neg_lo:[0,1] neg_hi:[0,1]
	s_waitcnt lgkmcnt(1)
	v_pk_add_f32 v[98:99], v[74:75], v[90:91]
	v_pk_mul_f32 v[78:79], v[66:67], s[18:19]
	v_pk_add_f32 v[74:75], v[74:75], v[90:91] neg_lo:[0,1] neg_hi:[0,1]
	v_pk_fma_f32 v[66:67], v[66:67], s[16:17], v[78:79] op_sel:[0,0,1] op_sel_hi:[1,0,0]
	v_pk_add_f32 v[78:79], v[68:69], v[84:85]
	v_pk_add_f32 v[68:69], v[68:69], v[84:85] neg_lo:[0,1] neg_hi:[0,1]
	v_pk_mul_f32 v[90:91], v[74:75], s[40:41]
	v_pk_mul_f32 v[84:85], v[68:69], s[36:37]
	v_pk_fma_f32 v[74:75], v[74:75], s[68:69], v[90:91] op_sel:[0,0,1] op_sel_hi:[1,0,0] neg_lo:[1,0,0] neg_hi:[1,0,0]
	v_pk_fma_f32 v[68:69], v[68:69], s[66:67], v[84:85] op_sel:[0,0,1] op_sel_hi:[1,0,0]
	v_pk_add_f32 v[84:85], v[70:71], v[86:87]
	v_pk_add_f32 v[70:71], v[70:71], v[86:87] neg_lo:[0,1] neg_hi:[0,1]
	s_waitcnt lgkmcnt(0)
	v_pk_add_f32 v[90:91], v[80:81], v[92:93]
	v_pk_add_f32 v[80:81], v[80:81], v[92:93] neg_lo:[0,1] neg_hi:[0,1]
	v_pk_mul_f32 v[86:87], v[70:71], s[40:41]
	v_pk_mul_f32 v[92:93], v[80:81], s[36:37]
	v_pk_fma_f32 v[70:71], v[70:71], s[68:69], v[86:87] op_sel:[0,0,1] op_sel_hi:[1,0,0]
	v_pk_add_f32 v[86:87], v[72:73], v[88:89]
	v_pk_add_f32 v[88:89], v[72:73], v[88:89] neg_lo:[0,1] neg_hi:[0,1]
	v_pk_fma_f32 v[80:81], v[80:81], s[66:67], v[92:93] op_sel:[0,0,1] op_sel_hi:[1,0,0] neg_lo:[1,0,0] neg_hi:[1,0,0]
	v_pk_add_f32 v[92:93], v[82:83], v[94:95]
	v_pk_add_f32 v[82:83], v[82:83], v[94:95] neg_lo:[0,1] neg_hi:[0,1]
	s_nop 0
	v_pk_mul_f32 v[94:95], v[82:83], s[18:19]
	s_nop 0
	v_pk_fma_f32 v[82:83], v[82:83], s[16:17], v[94:95] op_sel:[0,0,1] op_sel_hi:[1,0,0] neg_lo:[1,0,0] neg_hi:[1,0,0]
	v_pk_add_f32 v[94:95], v[96:97], v[86:87]
	v_pk_add_f32 v[86:87], v[96:97], v[86:87] neg_lo:[0,1] neg_hi:[0,1]
	v_pk_add_f32 v[96:97], v[76:77], v[98:99]
	v_pk_add_f32 v[76:77], v[76:77], v[98:99] neg_lo:[0,1] neg_hi:[0,1]
	v_pk_add_f32 v[100:101], v[84:85], v[92:93]
	v_pk_add_f32 v[84:85], v[84:85], v[92:93] neg_lo:[0,1] neg_hi:[0,1]
	v_pk_add_f32 v[72:73], v[64:65], v[88:89] op_sel:[0,1] op_sel_hi:[1,0] neg_hi:[0,1]
	v_pk_add_f32 v[64:65], v[64:65], v[88:89] op_sel:[0,1] op_sel_hi:[1,0] neg_lo:[0,1]
	v_pk_add_f32 v[88:89], v[66:67], v[74:75]
	v_pk_add_f32 v[66:67], v[66:67], v[74:75] neg_lo:[0,1] neg_hi:[0,1]
	v_pk_mul_f32 v[98:99], v[76:77], s[36:37]
	v_pk_mul_f32 v[92:93], v[84:85], s[36:37]
	v_pk_mul_f32 v[74:75], v[66:67], s[36:37]
	v_pk_fma_f32 v[76:77], v[76:77], s[66:67], v[98:99] op_sel:[0,0,1] op_sel_hi:[1,0,0]
	v_pk_add_f32 v[98:99], v[78:79], v[90:91]
	v_pk_add_f32 v[90:91], v[78:79], v[90:91] neg_lo:[0,1] neg_hi:[0,1]
	v_pk_fma_f32 v[84:85], v[84:85], s[66:67], v[92:93] op_sel:[0,0,1] op_sel_hi:[1,0,0] neg_lo:[1,0,0] neg_hi:[1,0,0]
	v_pk_fma_f32 v[66:67], v[66:67], s[66:67], v[74:75] op_sel:[0,0,1] op_sel_hi:[1,0,0]
	v_pk_add_f32 v[74:75], v[68:69], v[80:81]
	v_pk_add_f32 v[92:93], v[70:71], v[82:83]
	v_pk_add_f32 v[70:71], v[70:71], v[82:83] neg_lo:[0,1] neg_hi:[0,1]
	v_pk_add_f32 v[80:81], v[68:69], v[80:81] neg_lo:[0,1] neg_hi:[0,1]
	v_pk_mul_f32 v[82:83], v[70:71], s[36:37]
	v_pk_add_f32 v[102:103], v[72:73], v[74:75]
	v_pk_add_f32 v[72:73], v[72:73], v[74:75] neg_lo:[0,1] neg_hi:[0,1]
	v_pk_add_f32 v[74:75], v[88:89], v[92:93]
	v_pk_add_f32 v[92:93], v[88:89], v[92:93] neg_lo:[0,1] neg_hi:[0,1]
	v_xor_b32_e32 v20, 0x80000000, v9
	v_mov_b32_e32 v21, v9
	v_pk_mul_f32 v[24:25], v[12:13], v[10:11] op_sel:[0,1] op_sel_hi:[1,0]
	v_pk_fma_f32 v[70:71], v[70:71], s[66:67], v[82:83] op_sel:[0,0,1] op_sel_hi:[1,0,0] neg_lo:[1,0,0] neg_hi:[1,0,0]
	v_pk_add_f32 v[78:79], v[86:87], v[90:91] op_sel:[0,1] op_sel_hi:[1,0] neg_hi:[0,1]
	v_pk_add_f32 v[86:87], v[86:87], v[90:91] op_sel:[0,1] op_sel_hi:[1,0] neg_lo:[0,1]
	v_pk_add_f32 v[90:91], v[76:77], v[84:85]
	v_pk_add_f32 v[84:85], v[76:77], v[84:85] neg_lo:[0,1] neg_hi:[0,1]
	v_xor_b32_e32 v22, 0x80000000, v17
	v_mov_b32_e32 v23, v17
	v_pk_fma_f32 v[24:25], v[6:7], v[10:11], v[24:25] op_sel_hi:[0,1,1]
	v_pk_mul_f32 v[28:29], v[10:11], v[20:21] op_sel:[1,0] op_sel_hi:[0,1]
	v_pk_add_f32 v[68:69], v[64:65], v[80:81] op_sel:[0,1] op_sel_hi:[1,0] neg_hi:[0,1]
	v_pk_add_f32 v[64:65], v[64:65], v[80:81] op_sel:[0,1] op_sel_hi:[1,0] neg_lo:[0,1]
	v_pk_add_f32 v[80:81], v[66:67], v[70:71]
	v_pk_add_f32 v[70:71], v[66:67], v[70:71] neg_lo:[0,1] neg_hi:[0,1]
	v_pk_add_f32 v[88:89], v[72:73], v[92:93] op_sel:[0,1] op_sel_hi:[1,0] neg_hi:[0,1]
	v_xor_b32_e32 v26, 0x80000000, v25
	v_mov_b32_e32 v27, v25
	v_pk_fma_f32 v[28:29], v[10:11], v[8:9], v[28:29] op_sel_hi:[1,0,1]
	v_pk_add_f32 v[76:77], v[86:87], v[84:85] op_sel:[0,1] op_sel_hi:[1,0] neg_hi:[0,1]
	v_pk_add_f32 v[72:73], v[72:73], v[92:93] op_sel:[0,1] op_sel_hi:[1,0] neg_lo:[0,1]
	v_pk_mul_f32 v[92:93], v[22:23], v[88:89] op_sel:[0,1] op_sel_hi:[1,0]
	v_xor_b32_e32 v30, 0x80000000, v29
	v_mov_b32_e32 v31, v29
	v_pk_add_f32 v[82:83], v[94:95], v[98:99]
	v_pk_add_f32 v[94:95], v[94:95], v[98:99] neg_lo:[0,1] neg_hi:[0,1]
	v_pk_add_f32 v[98:99], v[96:97], v[100:101]
	v_pk_add_f32 v[66:67], v[64:65], v[70:71] op_sel:[0,1] op_sel_hi:[1,0] neg_hi:[0,1]
	v_pk_fma_f32 v[88:89], v[16:17], v[88:89], v[92:93] op_sel_hi:[0,1,1]
	v_pk_mul_f32 v[92:93], v[26:27], v[76:77] op_sel:[0,1] op_sel_hi:[1,0]
	v_xor_b32_e32 v34, 0x80000000, v33
	v_mov_b32_e32 v35, v33
	v_pk_mul_f32 v[40:41], v[12:13], v[32:33] op_sel:[0,1] op_sel_hi:[1,0]
	v_pk_add_f32 v[104:105], v[82:83], v[98:99]
	v_pk_add_f32 v[82:83], v[82:83], v[98:99] neg_lo:[0,1] neg_hi:[0,1]
	v_pk_fma_f32 v[76:77], v[24:25], v[76:77], v[92:93] op_sel_hi:[0,1,1]
	v_pk_mul_f32 v[92:93], v[30:31], v[66:67] op_sel:[0,1] op_sel_hi:[1,0]
	v_xor_b32_e32 v38, 0x80000000, v37
	v_mov_b32_e32 v39, v37
	v_pk_fma_f32 v[40:41], v[6:7], v[32:33], v[40:41] op_sel_hi:[0,1,1]
	v_pk_mul_f32 v[44:45], v[20:21], v[32:33] op_sel:[0,1] op_sel_hi:[1,0]
	v_pk_add_f32 v[84:85], v[86:87], v[84:85] op_sel:[0,1] op_sel_hi:[1,0] neg_lo:[0,1]
	v_pk_add_f32 v[86:87], v[102:103], v[74:75]
	v_pk_add_f32 v[74:75], v[102:103], v[74:75] neg_lo:[0,1] neg_hi:[0,1]
	v_pk_fma_f32 v[66:67], v[28:29], v[66:67], v[92:93] op_sel_hi:[0,1,1]
	v_pk_mul_f32 v[92:93], v[34:35], v[82:83] op_sel:[0,1] op_sel_hi:[1,0]
	v_xor_b32_e32 v42, 0x80000000, v41
	v_mov_b32_e32 v43, v41
	v_pk_fma_f32 v[44:45], v[8:9], v[32:33], v[44:45] op_sel_hi:[0,1,1]
	v_pk_add_f32 v[100:101], v[96:97], v[100:101] neg_lo:[0,1] neg_hi:[0,1]
	v_pk_add_f32 v[98:99], v[78:79], v[90:91]
	v_pk_add_f32 v[78:79], v[78:79], v[90:91] neg_lo:[0,1] neg_hi:[0,1]
	v_pk_fma_f32 v[82:83], v[32:33], v[82:83], v[92:93] op_sel_hi:[0,1,1]
	v_pk_mul_f32 v[92:93], v[38:39], v[74:75] op_sel:[0,1] op_sel_hi:[1,0]
	v_xor_b32_e32 v46, 0x80000000, v45
	v_mov_b32_e32 v47, v45
	v_pk_add_f32 v[90:91], v[68:69], v[80:81]
	v_pk_add_f32 v[68:69], v[68:69], v[80:81] neg_lo:[0,1] neg_hi:[0,1]
	v_pk_fma_f32 v[74:75], v[36:37], v[74:75], v[92:93] op_sel_hi:[0,1,1]
	v_pk_mul_f32 v[92:93], v[42:43], v[78:79] op_sel:[0,1] op_sel_hi:[1,0]
	v_xor_b32_e32 v50, 0x80000000, v49
	v_mov_b32_e32 v51, v49
	v_pk_mul_f32 v[56:57], v[12:13], v[48:49] op_sel:[0,1] op_sel_hi:[1,0]
	v_pk_add_f32 v[96:97], v[94:95], v[100:101] op_sel:[0,1] op_sel_hi:[1,0] neg_hi:[0,1]
	v_pk_add_f32 v[94:95], v[94:95], v[100:101] op_sel:[0,1] op_sel_hi:[1,0] neg_lo:[0,1]
	v_pk_fma_f32 v[78:79], v[40:41], v[78:79], v[92:93] op_sel_hi:[0,1,1]
	v_pk_mul_f32 v[92:93], v[46:47], v[68:69] op_sel:[0,1] op_sel_hi:[1,0]
	v_xor_b32_e32 v54, 0x80000000, v53
	v_mov_b32_e32 v55, v53
	v_pk_fma_f32 v[56:57], v[6:7], v[48:49], v[56:57] op_sel_hi:[0,1,1]
	v_pk_mul_f32 v[60:61], v[20:21], v[48:49] op_sel:[0,1] op_sel_hi:[1,0]
	v_pk_fma_f32 v[68:69], v[44:45], v[68:69], v[92:93] op_sel_hi:[0,1,1]
	v_pk_mul_f32 v[92:93], v[50:51], v[94:95] op_sel:[0,1] op_sel_hi:[1,0]
	v_xor_b32_e32 v58, 0x80000000, v57
	v_mov_b32_e32 v59, v57
	v_pk_fma_f32 v[60:61], v[8:9], v[48:49], v[60:61] op_sel_hi:[0,1,1]
	v_pk_add_f32 v[64:65], v[64:65], v[70:71] op_sel:[0,1] op_sel_hi:[1,0] neg_lo:[0,1]
	v_pk_mul_f32 v[70:71], v[2:3], v[86:87] op_sel:[0,1] op_sel_hi:[1,0]
	v_pk_fma_f32 v[92:93], v[48:49], v[94:95], v[92:93] op_sel_hi:[0,1,1]
	v_pk_mul_f32 v[94:95], v[54:55], v[72:73] op_sel:[0,1] op_sel_hi:[1,0]
	v_xor_b32_e32 v62, 0x80000000, v61
	v_mov_b32_e32 v63, v61
	v_pk_fma_f32 v[70:71], v[4:5], v[86:87], v[70:71] op_sel_hi:[0,1,1]
	v_pk_mul_f32 v[86:87], v[20:21], v[90:91] op_sel:[0,1] op_sel_hi:[1,0]
	v_pk_fma_f32 v[72:73], v[52:53], v[72:73], v[94:95] op_sel_hi:[0,1,1]
	v_pk_mul_f32 v[94:95], v[58:59], v[84:85] op_sel:[0,1] op_sel_hi:[1,0]
	v_add_u32_e32 v5, 0x2000, v5
	v_pk_mul_f32 v[80:81], v[12:13], v[98:99] op_sel:[0,1] op_sel_hi:[1,0]
	v_pk_fma_f32 v[86:87], v[8:9], v[90:91], v[86:87] op_sel_hi:[0,1,1]
	v_pk_mul_f32 v[90:91], v[14:15], v[96:97] op_sel:[0,1] op_sel_hi:[1,0]
	v_pk_fma_f32 v[84:85], v[56:57], v[84:85], v[94:95] op_sel_hi:[0,1,1]
	v_pk_mul_f32 v[94:95], v[62:63], v[64:65] op_sel:[0,1] op_sel_hi:[1,0]
	v_ashrrev_i32_e32 v5, 2, v5
	v_pk_fma_f32 v[80:81], v[6:7], v[98:99], v[80:81] op_sel_hi:[0,1,1]
	v_pk_fma_f32 v[90:91], v[10:11], v[96:97], v[90:91] op_sel_hi:[0,1,1]
	v_pk_fma_f32 v[64:65], v[60:61], v[64:65], v[94:95] op_sel_hi:[0,1,1]
	ds_write2_b64 v106, v[104:105], v[82:83] offset1:16
	ds_write2_b64 v106, v[90:91], v[92:93] offset0:33 offset1:49
	ds_write2_b64 v106, v[80:81], v[78:79] offset0:66 offset1:82
	ds_write2_b64 v106, v[76:77], v[84:85] offset0:99 offset1:115
	ds_write2_b64 v106, v[70:71], v[74:75] offset0:132 offset1:148
	ds_write2_b64 v106, v[88:89], v[72:73] offset0:165 offset1:181
	ds_write2_b64 v106, v[86:87], v[68:69] offset0:198 offset1:214
	ds_write2_b64 v106, v[66:67], v[64:65] offset0:231 offset1:247
	v_add3_u32 v18, v18, v5, s5
	ds_read2_b64 v[64:67], v18 offset1:16
	ds_read2_b64 v[68:71], v18 offset0:33 offset1:49
	ds_read2_b64 v[72:75], v18 offset0:66 offset1:82
	ds_read2_b64 v[76:79], v18 offset0:132 offset1:148
	ds_read2_b64 v[80:83], v18 offset0:99 offset1:115
	ds_read2_b64 v[84:87], v18 offset0:165 offset1:181
	ds_read2_b64 v[88:91], v18 offset0:198 offset1:214
	ds_read2_b64 v[92:95], v18 offset0:231 offset1:247
	s_waitcnt lgkmcnt(4)
	v_pk_add_f32 v[96:97], v[64:65], v[76:77]
	v_pk_add_f32 v[64:65], v[64:65], v[76:77] neg_lo:[0,1] neg_hi:[0,1]
	v_pk_add_f32 v[76:77], v[66:67], v[78:79]
	v_pk_add_f32 v[66:67], v[66:67], v[78:79] neg_lo:[0,1] neg_hi:[0,1]
	s_waitcnt lgkmcnt(1)
	v_pk_add_f32 v[98:99], v[74:75], v[90:91]
	v_pk_mul_f32 v[78:79], v[66:67], s[18:19]
	v_pk_add_f32 v[74:75], v[74:75], v[90:91] neg_lo:[0,1] neg_hi:[0,1]
	v_pk_fma_f32 v[66:67], v[66:67], s[16:17], v[78:79] op_sel:[0,0,1] op_sel_hi:[1,0,0]
	v_pk_add_f32 v[78:79], v[68:69], v[84:85]
	v_pk_add_f32 v[68:69], v[68:69], v[84:85] neg_lo:[0,1] neg_hi:[0,1]
	v_pk_mul_f32 v[90:91], v[74:75], s[40:41]
	v_pk_mul_f32 v[84:85], v[68:69], s[36:37]
	v_pk_fma_f32 v[74:75], v[74:75], s[68:69], v[90:91] op_sel:[0,0,1] op_sel_hi:[1,0,0] neg_lo:[1,0,0] neg_hi:[1,0,0]
	s_waitcnt lgkmcnt(0)
	v_pk_add_f32 v[90:91], v[80:81], v[92:93]
	v_pk_add_f32 v[80:81], v[80:81], v[92:93] neg_lo:[0,1] neg_hi:[0,1]
	v_pk_fma_f32 v[68:69], v[68:69], s[66:67], v[84:85] op_sel:[0,0,1] op_sel_hi:[1,0,0]
	v_pk_add_f32 v[84:85], v[70:71], v[86:87]
	v_pk_add_f32 v[70:71], v[70:71], v[86:87] neg_lo:[0,1] neg_hi:[0,1]
	v_pk_mul_f32 v[92:93], v[80:81], s[36:37]
	v_pk_mul_f32 v[86:87], v[70:71], s[40:41]
	v_pk_fma_f32 v[80:81], v[80:81], s[66:67], v[92:93] op_sel:[0,0,1] op_sel_hi:[1,0,0] neg_lo:[1,0,0] neg_hi:[1,0,0]
	v_pk_add_f32 v[92:93], v[82:83], v[94:95]
	v_pk_add_f32 v[82:83], v[82:83], v[94:95] neg_lo:[0,1] neg_hi:[0,1]
	v_pk_fma_f32 v[70:71], v[70:71], s[68:69], v[86:87] op_sel:[0,0,1] op_sel_hi:[1,0,0]
	v_pk_add_f32 v[86:87], v[72:73], v[88:89]
	v_pk_mul_f32 v[94:95], v[82:83], s[18:19]
	v_pk_add_f32 v[88:89], v[72:73], v[88:89] neg_lo:[0,1] neg_hi:[0,1]
	v_pk_fma_f32 v[82:83], v[82:83], s[16:17], v[94:95] op_sel:[0,0,1] op_sel_hi:[1,0,0] neg_lo:[1,0,0] neg_hi:[1,0,0]
	v_pk_add_f32 v[94:95], v[96:97], v[86:87]
	v_pk_add_f32 v[86:87], v[96:97], v[86:87] neg_lo:[0,1] neg_hi:[0,1]
	v_pk_add_f32 v[96:97], v[76:77], v[98:99]
	v_pk_add_f32 v[76:77], v[76:77], v[98:99] neg_lo:[0,1] neg_hi:[0,1]
	s_nop 0
	v_pk_mul_f32 v[98:99], v[76:77], s[36:37]
	v_pk_add_f32 v[100:101], v[84:85], v[92:93]
	v_pk_add_f32 v[84:85], v[84:85], v[92:93] neg_lo:[0,1] neg_hi:[0,1]
	v_pk_fma_f32 v[76:77], v[76:77], s[66:67], v[98:99] op_sel:[0,0,1] op_sel_hi:[1,0,0]
	v_pk_add_f32 v[98:99], v[78:79], v[90:91]
	v_pk_add_f32 v[90:91], v[78:79], v[90:91] neg_lo:[0,1] neg_hi:[0,1]
	v_pk_mul_f32 v[92:93], v[84:85], s[36:37]
	v_pk_add_f32 v[72:73], v[64:65], v[88:89] op_sel:[0,1] op_sel_hi:[1,0] neg_hi:[0,1]
	v_pk_add_f32 v[64:65], v[64:65], v[88:89] op_sel:[0,1] op_sel_hi:[1,0] neg_lo:[0,1]
	v_pk_add_f32 v[88:89], v[66:67], v[74:75]
	v_pk_add_f32 v[66:67], v[66:67], v[74:75] neg_lo:[0,1] neg_hi:[0,1]
	v_pk_fma_f32 v[84:85], v[84:85], s[66:67], v[92:93] op_sel:[0,0,1] op_sel_hi:[1,0,0] neg_lo:[1,0,0] neg_hi:[1,0,0]
	v_pk_mul_f32 v[74:75], v[66:67], s[36:37]
	s_nop 0
	v_pk_fma_f32 v[66:67], v[66:67], s[66:67], v[74:75] op_sel:[0,0,1] op_sel_hi:[1,0,0]
	v_pk_add_f32 v[74:75], v[68:69], v[80:81]
	v_pk_add_f32 v[92:93], v[70:71], v[82:83]
	v_pk_add_f32 v[70:71], v[70:71], v[82:83] neg_lo:[0,1] neg_hi:[0,1]
	v_pk_add_f32 v[78:79], v[86:87], v[90:91] op_sel:[0,1] op_sel_hi:[1,0] neg_hi:[0,1]
	v_pk_add_f32 v[86:87], v[86:87], v[90:91] op_sel:[0,1] op_sel_hi:[1,0] neg_lo:[0,1]
	v_pk_add_f32 v[90:91], v[76:77], v[84:85]
	v_pk_add_f32 v[84:85], v[76:77], v[84:85] neg_lo:[0,1] neg_hi:[0,1]
	v_pk_add_f32 v[80:81], v[68:69], v[80:81] neg_lo:[0,1] neg_hi:[0,1]
	v_pk_mul_f32 v[82:83], v[70:71], s[36:37]
	v_pk_add_f32 v[102:103], v[72:73], v[74:75]
	v_pk_add_f32 v[72:73], v[72:73], v[74:75] neg_lo:[0,1] neg_hi:[0,1]
	v_pk_add_f32 v[74:75], v[88:89], v[92:93]
	v_pk_fma_f32 v[70:71], v[70:71], s[66:67], v[82:83] op_sel:[0,0,1] op_sel_hi:[1,0,0] neg_lo:[1,0,0] neg_hi:[1,0,0]
	v_pk_add_f32 v[82:83], v[94:95], v[98:99]
	v_pk_add_f32 v[94:95], v[94:95], v[98:99] neg_lo:[0,1] neg_hi:[0,1]
	v_pk_add_f32 v[98:99], v[96:97], v[100:101]
	v_pk_add_f32 v[76:77], v[86:87], v[84:85] op_sel:[0,1] op_sel_hi:[1,0] neg_hi:[0,1]
	v_pk_add_f32 v[84:85], v[86:87], v[84:85] op_sel:[0,1] op_sel_hi:[1,0] neg_lo:[0,1]
	v_pk_add_f32 v[86:87], v[102:103], v[74:75]
	v_pk_add_f32 v[100:101], v[96:97], v[100:101] neg_lo:[0,1] neg_hi:[0,1]
	v_pk_add_f32 v[68:69], v[64:65], v[80:81] op_sel:[0,1] op_sel_hi:[1,0] neg_hi:[0,1]
	v_pk_add_f32 v[64:65], v[64:65], v[80:81] op_sel:[0,1] op_sel_hi:[1,0] neg_lo:[0,1]
	v_pk_add_f32 v[80:81], v[66:67], v[70:71]
	v_pk_add_f32 v[104:105], v[82:83], v[98:99]
	v_pk_add_f32 v[82:83], v[82:83], v[98:99] neg_lo:[0,1] neg_hi:[0,1]
	v_pk_add_f32 v[98:99], v[78:79], v[90:91]
	v_pk_mul_f32 v[2:3], v[2:3], v[86:87] op_sel:[0,1] op_sel_hi:[1,0]
	v_pk_add_f32 v[92:93], v[88:89], v[92:93] neg_lo:[0,1] neg_hi:[0,1]
	v_pk_add_f32 v[78:79], v[78:79], v[90:91] neg_lo:[0,1] neg_hi:[0,1]
	v_pk_add_f32 v[90:91], v[68:69], v[80:81]
	v_pk_fma_f32 v[2:3], v[4:5], v[86:87], v[2:3] op_sel_hi:[0,1,1]
	v_pk_mul_f32 v[4:5], v[12:13], v[98:99] op_sel:[0,1] op_sel_hi:[1,0]
	v_pk_add_f32 v[70:71], v[66:67], v[70:71] neg_lo:[0,1] neg_hi:[0,1]
	v_pk_add_f32 v[96:97], v[94:95], v[100:101] op_sel:[0,1] op_sel_hi:[1,0] neg_hi:[0,1]
	v_pk_fma_f32 v[4:5], v[6:7], v[98:99], v[4:5] op_sel_hi:[0,1,1]
	v_pk_mul_f32 v[6:7], v[20:21], v[90:91] op_sel:[0,1] op_sel_hi:[1,0]
	v_pk_add_f32 v[88:89], v[72:73], v[92:93] op_sel:[0,1] op_sel_hi:[1,0] neg_hi:[0,1]
	v_pk_fma_f32 v[6:7], v[8:9], v[90:91], v[6:7] op_sel_hi:[0,1,1]
	v_pk_mul_f32 v[8:9], v[14:15], v[96:97] op_sel:[0,1] op_sel_hi:[1,0]
	v_pk_add_f32 v[66:67], v[64:65], v[70:71] op_sel:[0,1] op_sel_hi:[1,0] neg_hi:[0,1]
	v_pk_fma_f32 v[8:9], v[10:11], v[96:97], v[8:9] op_sel_hi:[0,1,1]
	v_pk_mul_f32 v[10:11], v[22:23], v[88:89] op_sel:[0,1] op_sel_hi:[1,0]
	v_pk_add_f32 v[94:95], v[94:95], v[100:101] op_sel:[0,1] op_sel_hi:[1,0] neg_lo:[0,1]
	v_pk_add_f32 v[74:75], v[102:103], v[74:75] neg_lo:[0,1] neg_hi:[0,1]
	v_pk_add_f32 v[72:73], v[72:73], v[92:93] op_sel:[0,1] op_sel_hi:[1,0] neg_lo:[0,1]
	v_pk_add_f32 v[68:69], v[68:69], v[80:81] neg_lo:[0,1] neg_hi:[0,1]
	v_pk_add_f32 v[64:65], v[64:65], v[70:71] op_sel:[0,1] op_sel_hi:[1,0] neg_lo:[0,1]
	v_pk_fma_f32 v[10:11], v[16:17], v[88:89], v[10:11] op_sel_hi:[0,1,1]
	v_pk_mul_f32 v[12:13], v[26:27], v[76:77] op_sel:[0,1] op_sel_hi:[1,0]
	v_pk_mul_f32 v[14:15], v[30:31], v[66:67] op_sel:[0,1] op_sel_hi:[1,0]
	v_pk_mul_f32 v[16:17], v[34:35], v[82:83] op_sel:[0,1] op_sel_hi:[1,0]
	v_pk_fma_f32 v[12:13], v[24:25], v[76:77], v[12:13] op_sel_hi:[0,1,1]
	v_pk_fma_f32 v[14:15], v[28:29], v[66:67], v[14:15] op_sel_hi:[0,1,1]
	v_pk_fma_f32 v[16:17], v[32:33], v[82:83], v[16:17] op_sel_hi:[0,1,1]
	v_pk_mul_f32 v[20:21], v[38:39], v[74:75] op_sel:[0,1] op_sel_hi:[1,0]
	v_pk_mul_f32 v[22:23], v[42:43], v[78:79] op_sel:[0,1] op_sel_hi:[1,0]
	v_pk_mul_f32 v[24:25], v[46:47], v[68:69] op_sel:[0,1] op_sel_hi:[1,0]
	v_pk_mul_f32 v[26:27], v[50:51], v[94:95] op_sel:[0,1] op_sel_hi:[1,0]
	v_pk_mul_f32 v[28:29], v[54:55], v[72:73] op_sel:[0,1] op_sel_hi:[1,0]
	v_pk_mul_f32 v[30:31], v[58:59], v[84:85] op_sel:[0,1] op_sel_hi:[1,0]
	v_pk_mul_f32 v[32:33], v[62:63], v[64:65] op_sel:[0,1] op_sel_hi:[1,0]
	v_pk_fma_f32 v[20:21], v[36:37], v[74:75], v[20:21] op_sel_hi:[0,1,1]
	v_pk_fma_f32 v[22:23], v[40:41], v[78:79], v[22:23] op_sel_hi:[0,1,1]
	v_pk_fma_f32 v[24:25], v[44:45], v[68:69], v[24:25] op_sel_hi:[0,1,1]
	v_pk_fma_f32 v[26:27], v[48:49], v[94:95], v[26:27] op_sel_hi:[0,1,1]
	v_pk_fma_f32 v[28:29], v[52:53], v[72:73], v[28:29] op_sel_hi:[0,1,1]
	v_pk_fma_f32 v[30:31], v[56:57], v[84:85], v[30:31] op_sel_hi:[0,1,1]
	v_pk_fma_f32 v[32:33], v[60:61], v[64:65], v[32:33] op_sel_hi:[0,1,1]
	ds_write2_b64 v18, v[104:105], v[16:17] offset1:16
	ds_write2_b64 v18, v[8:9], v[26:27] offset0:33 offset1:49
	ds_write2_b64 v18, v[4:5], v[22:23] offset0:66 offset1:82
	ds_write2_b64 v18, v[12:13], v[30:31] offset0:99 offset1:115
	ds_write2_b64 v18, v[2:3], v[20:21] offset0:132 offset1:148
	ds_write2_b64 v18, v[10:11], v[28:29] offset0:165 offset1:181
	ds_write2_b64 v18, v[6:7], v[24:25] offset0:198 offset1:214
	ds_write2_b64 v18, v[14:15], v[32:33] offset0:231 offset1:247
	v_ashrrev_i32_e32 v2, 31, v210
	v_add_u32_sdwa v2, v210, v2 dst_sel:DWORD dst_unused:UNUSED_PAD src0_sel:DWORD src1_sel:BYTE_3
	s_lshl_b64 s[0:1], s[64:65], 15
	v_and_b32_e32 v2, 0xffffff00, v2
	s_add_u32 s0, s29, s0
	v_sub_u32_e32 v2, v210, v2
	s_addc_u32 s1, s85, s1
	v_ashrrev_i32_e32 v3, 31, v2
	v_lshl_add_u64 v[14:15], v[2:3], 3, s[0:1]
	s_movk_i32 s0, 0x1000
	v_add_co_u32_e32 v16, vcc, s0, v14
	s_movk_i32 s0, 0x3000
	s_nop 0
	v_addc_co_u32_e32 v17, vcc, 0, v15, vcc
	v_add_co_u32_e32 v2, vcc, s92, v14
	s_waitcnt lgkmcnt(0)
	s_nop 0
	v_addc_co_u32_e32 v3, vcc, 0, v15, vcc
	v_add_co_u32_e32 v22, vcc, s0, v14
	s_movk_i32 s0, 0x5000
	s_nop 0
	v_addc_co_u32_e32 v23, vcc, 0, v15, vcc
	v_add_co_u32_e32 v8, vcc, s95, v14
	s_barrier
	s_nop 0
	v_addc_co_u32_e32 v9, vcc, 0, v15, vcc
	v_add_co_u32_e32 v26, vcc, s0, v14
	s_nop 1
	v_addc_co_u32_e32 v27, vcc, 0, v15, vcc
	v_add_co_u32_e32 v10, vcc, s96, v14
	global_load_dwordx2 v[12:13], v[2:3], off nt
	global_load_dwordx2 v[6:7], v[2:3], off offset:2048 nt
	global_load_dwordx2 v[4:5], v[8:9], off offset:-4096 nt
	global_load_dwordx2 v[122:123], v[8:9], off nt
	v_addc_co_u32_e32 v11, vcc, 0, v15, vcc
	v_add_co_u32_e32 v28, vcc, s97, v14
	global_load_dwordx2 v[46:47], v[8:9], off offset:2048 nt
	global_load_dwordx2 v[38:39], v[10:11], off offset:-4096 nt
	global_load_dwordx2 v[20:21], v[10:11], off nt
	s_nop 0
	global_load_dwordx2 v[10:11], v[10:11], off offset:2048 nt
	v_addc_co_u32_e32 v29, vcc, 0, v15, vcc
	global_load_dwordx2 v[24:25], v[2:3], off offset:-4096 nt
	s_nop 0
	global_load_dwordx2 v[26:27], v[26:27], off offset:2048 nt
	s_nop 0
	global_load_dwordx2 v[8:9], v[28:29], off nt
	global_load_dwordx2 v[2:3], v[28:29], off offset:2048 nt
	global_load_dwordx2 v[30:31], v[14:15], off offset:2048 nt
	s_nop 0
	global_load_dwordx2 v[28:29], v[16:17], off offset:2048 nt
	s_nop 0
	global_load_dwordx2 v[16:17], v[22:23], off offset:2048 nt
	global_load_dwordx2 v[32:33], v[14:15], off nt
	v_mov_b32_e32 v14, v210
	s_waitcnt vmcnt(15)
	v_cvt_f32_f16_sdwa v164, v12 dst_sel:DWORD dst_unused:UNUSED_PAD src0_sel:WORD_1
	v_ashrrev_i32_e32 v15, 31, v14
	v_add_u32_sdwa v15, v14, v15 dst_sel:DWORD dst_unused:UNUSED_PAD src0_sel:DWORD src1_sel:BYTE_3
	v_ashrrev_i32_e32 v15, 8, v15
	v_mul_i32_i24_e32 v18, 0x100, v15
	v_sub_u32_e32 v18, v14, v18
	v_lshlrev_b32_e32 v14, 13, v15
	v_lshlrev_b32_e32 v15, 1, v18
	v_bfrev_b32_e32 v15, v15
	v_lshrrev_b32_e32 v15, 23, v15
	v_sub_u32_e32 v15, 0x200, v15
	v_bfrev_b32_e32 v15, v15
	v_lshrrev_b32_e32 v15, 19, v15
	v_and_b32_e32 v15, 0x1ff0, v15
	v_cmp_eq_u32_e64 s[0:1], 0, v18
	v_lshl_add_u32 v22, v18, 5, v14
	v_lshl_add_u32 v23, v22, 3, 0
	v_cndmask_b32_e64 v15, v15, 16, s[0:1]
	v_or_b32_e32 v14, v15, v14
	v_ashrrev_i32_e32 v22, 2, v22
	v_ashrrev_i32_e32 v15, 5, v14
	v_add_u32_e32 v211, v23, v22
	v_lshlrev_b32_e32 v14, 3, v14
	v_lshlrev_b32_e32 v15, 3, v15
	v_add3_u32 v212, 0, v14, v15
	ds_read2_b64 v[34:37], v211 offset1:1
	ds_read2_b64 v[40:43], v211 offset0:2 offset1:3
	ds_read2_b64 v[48:51], v212 offset1:1
	ds_read2_b64 v[52:55], v212 offset0:2 offset1:3
	ds_read2_b64 v[56:59], v211 offset0:4 offset1:5
	ds_read2_b64 v[60:63], v211 offset0:6 offset1:7
	ds_read2_b64 v[68:71], v212 offset0:4 offset1:5
	ds_read2_b64 v[72:75], v212 offset0:6 offset1:7
	ds_read2_b64 v[64:67], v211 offset0:8 offset1:9
	ds_read2_b64 v[76:79], v211 offset0:10 offset1:11
	ds_read2_b64 v[80:83], v212 offset0:8 offset1:9
	ds_read2_b64 v[98:101], v212 offset0:10 offset1:11
	ds_read2_b64 v[84:87], v211 offset0:12 offset1:13
	ds_read2_b64 v[88:91], v211 offset0:14 offset1:15
	ds_read2_b64 v[102:105], v212 offset0:12 offset1:13
	ds_read2_b64 v[106:109], v212 offset0:14 offset1:15
	s_waitcnt lgkmcnt(7)
	v_pk_add_f32 v[14:15], v[34:35], v[64:65]
	v_pk_add_f32 v[22:23], v[34:35], v[64:65] neg_lo:[0,1] neg_hi:[0,1]
	v_pk_add_f32 v[34:35], v[36:37], v[66:67]
	v_pk_add_f32 v[36:37], v[36:37], v[66:67] neg_lo:[0,1] neg_hi:[0,1]
	v_cmp_ne_u32_e32 vcc, 0, v18
	v_pk_mul_f32 v[44:45], v[36:37], s[18:19]
	v_bfrev_b32_e32 v18, v18
	v_pk_fma_f32 v[36:37], v[36:37], s[16:17], v[44:45] op_sel:[0,0,1] op_sel_hi:[1,0,0]
	s_waitcnt lgkmcnt(6)
	v_pk_add_f32 v[44:45], v[40:41], v[76:77]
	v_pk_add_f32 v[40:41], v[40:41], v[76:77] neg_lo:[0,1] neg_hi:[0,1]
	v_cvt_f32_ubyte3_e32 v18, v18
	v_pk_mul_f32 v[64:65], v[40:41], s[36:37]
	v_mul_f32_e32 v18, 0x38800000, v18
	v_pk_fma_f32 v[40:41], v[40:41], s[66:67], v[64:65] op_sel:[0,0,1] op_sel_hi:[1,0,0]
	v_pk_add_f32 v[64:65], v[42:43], v[78:79]
	v_pk_add_f32 v[42:43], v[42:43], v[78:79] neg_lo:[0,1] neg_hi:[0,1]
	s_waitcnt lgkmcnt(3)
	v_pk_add_f32 v[78:79], v[58:59], v[86:87]
	v_pk_mul_f32 v[66:67], v[42:43], s[40:41]
	v_pk_add_f32 v[58:59], v[58:59], v[86:87] neg_lo:[0,1] neg_hi:[0,1]
	v_pk_fma_f32 v[42:43], v[42:43], s[68:69], v[66:67] op_sel:[0,0,1] op_sel_hi:[1,0,0]
	v_pk_add_f32 v[66:67], v[56:57], v[84:85]
	v_pk_add_f32 v[76:77], v[56:57], v[84:85] neg_lo:[0,1] neg_hi:[0,1]
	v_pk_mul_f32 v[84:85], v[58:59], s[40:41]
	s_nop 0
	v_pk_fma_f32 v[58:59], v[58:59], s[68:69], v[84:85] op_sel:[0,0,1] op_sel_hi:[1,0,0] neg_lo:[1,0,0] neg_hi:[1,0,0]
	s_waitcnt lgkmcnt(2)
	v_pk_add_f32 v[84:85], v[60:61], v[88:89]
	v_pk_add_f32 v[60:61], v[60:61], v[88:89] neg_lo:[0,1] neg_hi:[0,1]
	s_nop 0
	v_pk_mul_f32 v[86:87], v[60:61], s[36:37]
	v_pk_add_f32 v[56:57], v[22:23], v[76:77] op_sel:[0,1] op_sel_hi:[1,0] neg_hi:[0,1]
	v_pk_fma_f32 v[60:61], v[60:61], s[66:67], v[86:87] op_sel:[0,0,1] op_sel_hi:[1,0,0] neg_lo:[1,0,0] neg_hi:[1,0,0]
	v_pk_add_f32 v[86:87], v[62:63], v[90:91]
	v_pk_add_f32 v[62:63], v[62:63], v[90:91] neg_lo:[0,1] neg_hi:[0,1]
	v_pk_add_f32 v[90:91], v[64:65], v[86:87]
	v_pk_mul_f32 v[88:89], v[62:63], s[18:19]
	v_pk_add_f32 v[64:65], v[64:65], v[86:87] neg_lo:[0,1] neg_hi:[0,1]
	v_pk_fma_f32 v[62:63], v[62:63], s[16:17], v[88:89] op_sel:[0,0,1] op_sel_hi:[1,0,0] neg_lo:[1,0,0] neg_hi:[1,0,0]
	v_pk_add_f32 v[88:89], v[14:15], v[66:67]
	v_pk_add_f32 v[14:15], v[14:15], v[66:67] neg_lo:[0,1] neg_hi:[0,1]
	v_pk_add_f32 v[66:67], v[34:35], v[78:79]
	v_pk_add_f32 v[34:35], v[34:35], v[78:79] neg_lo:[0,1] neg_hi:[0,1]
	v_pk_add_f32 v[22:23], v[22:23], v[76:77] op_sel:[0,1] op_sel_hi:[1,0] neg_lo:[0,1]
	v_pk_mul_f32 v[78:79], v[34:35], s[36:37]
	v_pk_add_f32 v[76:77], v[36:37], v[58:59]
	v_pk_add_f32 v[36:37], v[36:37], v[58:59] neg_lo:[0,1] neg_hi:[0,1]
	v_pk_fma_f32 v[34:35], v[34:35], s[66:67], v[78:79] op_sel:[0,0,1] op_sel_hi:[1,0,0]
	v_pk_add_f32 v[78:79], v[44:45], v[84:85]
	v_pk_add_f32 v[84:85], v[44:45], v[84:85] neg_lo:[0,1] neg_hi:[0,1]
	v_pk_mul_f32 v[86:87], v[64:65], s[36:37]
	v_pk_mul_f32 v[58:59], v[36:37], s[36:37]
	v_pk_fma_f32 v[64:65], v[64:65], s[66:67], v[86:87] op_sel:[0,0,1] op_sel_hi:[1,0,0] neg_lo:[1,0,0] neg_hi:[1,0,0]
	v_pk_fma_f32 v[36:37], v[36:37], s[66:67], v[58:59] op_sel:[0,0,1] op_sel_hi:[1,0,0]
	v_pk_add_f32 v[58:59], v[40:41], v[60:61]
	v_pk_add_f32 v[86:87], v[42:43], v[62:63]
	v_pk_add_f32 v[42:43], v[42:43], v[62:63] neg_lo:[0,1] neg_hi:[0,1]
	s_nop 0
	v_pk_mul_f32 v[62:63], v[42:43], s[36:37]
	v_pk_add_f32 v[44:45], v[14:15], v[84:85] op_sel:[0,1] op_sel_hi:[1,0] neg_hi:[0,1]
	v_pk_add_f32 v[14:15], v[14:15], v[84:85] op_sel:[0,1] op_sel_hi:[1,0] neg_lo:[0,1]
	v_pk_add_f32 v[84:85], v[34:35], v[64:65]
	v_pk_add_f32 v[64:65], v[34:35], v[64:65] neg_lo:[0,1] neg_hi:[0,1]
	v_pk_add_f32 v[94:95], v[56:57], v[58:59]
	v_pk_add_f32 v[56:57], v[56:57], v[58:59] neg_lo:[0,1] neg_hi:[0,1]
	v_pk_add_f32 v[58:59], v[76:77], v[86:87]
	v_pk_fma_f32 v[42:43], v[42:43], s[66:67], v[62:63] op_sel:[0,0,1] op_sel_hi:[1,0,0] neg_lo:[1,0,0] neg_hi:[1,0,0]
	v_pk_add_f32 v[62:63], v[88:89], v[78:79]
	v_pk_add_f32 v[78:79], v[88:89], v[78:79] neg_lo:[0,1] neg_hi:[0,1]
	v_pk_add_f32 v[88:89], v[66:67], v[90:91]
	v_pk_add_f32 v[110:111], v[76:77], v[86:87] neg_lo:[0,1] neg_hi:[0,1]
	v_pk_add_f32 v[86:87], v[94:95], v[58:59]
	v_pk_add_f32 v[34:35], v[94:95], v[58:59] neg_lo:[0,1] neg_hi:[0,1]
	v_pk_add_f32 v[58:59], v[50:51], v[82:83]
	v_pk_add_f32 v[50:51], v[50:51], v[82:83] neg_lo:[0,1] neg_hi:[0,1]
	v_pk_add_f32 v[60:61], v[40:41], v[60:61] neg_lo:[0,1] neg_hi:[0,1]
	v_pk_add_f32 v[148:149], v[62:63], v[88:89]
	v_pk_add_f32 v[138:139], v[62:63], v[88:89] neg_lo:[0,1] neg_hi:[0,1]
	v_pk_mul_f32 v[62:63], v[50:51], s[18:19]
	v_pk_add_f32 v[90:91], v[66:67], v[90:91] neg_lo:[0,1] neg_hi:[0,1]
	v_pk_fma_f32 v[50:51], v[50:51], s[16:17], v[62:63] op_sel:[0,0,1] op_sel_hi:[1,0,0]
	v_pk_add_f32 v[62:63], v[52:53], v[98:99]
	v_pk_add_f32 v[52:53], v[52:53], v[98:99] neg_lo:[0,1] neg_hi:[0,1]
	v_pk_add_f32 v[112:113], v[22:23], v[60:61] op_sel:[0,1] op_sel_hi:[1,0] neg_hi:[0,1]
	v_pk_add_f32 v[114:115], v[22:23], v[60:61] op_sel:[0,1] op_sel_hi:[1,0] neg_lo:[0,1]
	v_pk_add_f32 v[96:97], v[44:45], v[84:85]
	v_pk_add_f32 v[66:67], v[44:45], v[84:85] neg_lo:[0,1] neg_hi:[0,1]
	v_pk_add_f32 v[60:61], v[14:15], v[64:65] op_sel:[0,1] op_sel_hi:[1,0] neg_hi:[0,1]
	v_pk_add_f32 v[84:85], v[14:15], v[64:65] op_sel:[0,1] op_sel_hi:[1,0] neg_lo:[0,1]
	v_pk_mul_f32 v[64:65], v[52:53], s[36:37]
	s_nop 0
	v_pk_fma_f32 v[52:53], v[52:53], s[66:67], v[64:65] op_sel:[0,0,1] op_sel_hi:[1,0,0]
	v_pk_add_f32 v[64:65], v[54:55], v[100:101]
	v_pk_add_f32 v[54:55], v[54:55], v[100:101] neg_lo:[0,1] neg_hi:[0,1]
	s_nop 0
	v_pk_mul_f32 v[76:77], v[54:55], s[40:41]
	v_pk_add_f32 v[92:93], v[78:79], v[90:91] op_sel:[0,1] op_sel_hi:[1,0] neg_hi:[0,1]
	v_pk_fma_f32 v[54:55], v[54:55], s[68:69], v[76:77] op_sel:[0,0,1] op_sel_hi:[1,0,0]
	s_waitcnt lgkmcnt(1)
	v_pk_add_f32 v[76:77], v[68:69], v[102:103]
	v_pk_add_f32 v[88:89], v[78:79], v[90:91] op_sel:[0,1] op_sel_hi:[1,0] neg_lo:[0,1]
	v_pk_add_f32 v[78:79], v[68:69], v[102:103] neg_lo:[0,1] neg_hi:[0,1]
	v_pk_add_f32 v[68:69], v[70:71], v[104:105]
	v_pk_add_f32 v[70:71], v[70:71], v[104:105] neg_lo:[0,1] neg_hi:[0,1]
	v_pk_add_f32 v[40:41], v[56:57], v[110:111] op_sel:[0,1] op_sel_hi:[1,0] neg_hi:[0,1]
	v_pk_add_f32 v[44:45], v[56:57], v[110:111] op_sel:[0,1] op_sel_hi:[1,0] neg_lo:[0,1]
	v_pk_add_f32 v[56:57], v[48:49], v[80:81]
	v_pk_add_f32 v[48:49], v[48:49], v[80:81] neg_lo:[0,1] neg_hi:[0,1]
	v_pk_mul_f32 v[80:81], v[70:71], s[40:41]
	v_cndmask_b32_e64 v18, v18, v208, s[0:1]
	v_pk_fma_f32 v[70:71], v[70:71], s[68:69], v[80:81] op_sel:[0,0,1] op_sel_hi:[1,0,0] neg_lo:[1,0,0] neg_hi:[1,0,0]
	s_waitcnt lgkmcnt(0)
	v_pk_add_f32 v[80:81], v[72:73], v[106:107]
	v_pk_add_f32 v[72:73], v[72:73], v[106:107] neg_lo:[0,1] neg_hi:[0,1]
	v_pk_add_f32 v[22:23], v[36:37], v[42:43]
	v_pk_mul_f32 v[82:83], v[72:73], s[36:37]
	v_pk_add_f32 v[116:117], v[36:37], v[42:43] neg_lo:[0,1] neg_hi:[0,1]
	v_pk_fma_f32 v[72:73], v[72:73], s[66:67], v[82:83] op_sel:[0,0,1] op_sel_hi:[1,0,0] neg_lo:[1,0,0] neg_hi:[1,0,0]
	v_pk_add_f32 v[82:83], v[74:75], v[108:109]
	v_pk_add_f32 v[74:75], v[74:75], v[108:109] neg_lo:[0,1] neg_hi:[0,1]
	s_nop 0
	v_pk_mul_f32 v[90:91], v[74:75], s[18:19]
	s_nop 0
	v_pk_fma_f32 v[74:75], v[74:75], s[16:17], v[90:91] op_sel:[0,0,1] op_sel_hi:[1,0,0] neg_lo:[1,0,0] neg_hi:[1,0,0]
	v_pk_add_f32 v[90:91], v[56:57], v[76:77]
	v_pk_add_f32 v[56:57], v[56:57], v[76:77] neg_lo:[0,1] neg_hi:[0,1]
	v_pk_add_f32 v[76:77], v[58:59], v[68:69]
	v_pk_add_f32 v[58:59], v[58:59], v[68:69] neg_lo:[0,1] neg_hi:[0,1]
	v_pk_add_f32 v[14:15], v[114:115], v[116:117] op_sel:[0,1] op_sel_hi:[1,0] neg_hi:[0,1]
	v_pk_mul_f32 v[68:69], v[58:59], s[36:37]
	v_pk_add_f32 v[36:37], v[114:115], v[116:117] op_sel:[0,1] op_sel_hi:[1,0] neg_lo:[0,1]
	v_pk_fma_f32 v[58:59], v[58:59], s[66:67], v[68:69] op_sel:[0,0,1] op_sel_hi:[1,0,0]
	v_pk_add_f32 v[68:69], v[62:63], v[80:81]
	v_pk_add_f32 v[80:81], v[62:63], v[80:81] neg_lo:[0,1] neg_hi:[0,1]
	s_waitcnt vmcnt(0)
	v_cvt_f32_f16_e32 v193, v33
	s_nop 0
	s_nop 0
	v_pk_add_f32 v[62:63], v[64:65], v[82:83]
	v_pk_add_f32 v[64:65], v[64:65], v[82:83] neg_lo:[0,1] neg_hi:[0,1]
	v_cvt_f32_f16_sdwa v192, v32 dst_sel:DWORD dst_unused:UNUSED_PAD src0_sel:WORD_1
	v_pk_mul_f32 v[82:83], v[64:65], s[36:37]
	v_cvt_f32_f16_e32 v194, v32
	v_pk_fma_f32 v[64:65], v[64:65], s[66:67], v[82:83] op_sel:[0,0,1] op_sel_hi:[1,0,0] neg_lo:[1,0,0] neg_hi:[1,0,0]
	v_pk_add_f32 v[82:83], v[48:49], v[78:79] op_sel:[0,1] op_sel_hi:[1,0] neg_hi:[0,1]
	v_pk_add_f32 v[48:49], v[48:49], v[78:79] op_sel:[0,1] op_sel_hi:[1,0] neg_lo:[0,1]
	v_pk_add_f32 v[78:79], v[50:51], v[70:71]
	v_pk_add_f32 v[50:51], v[50:51], v[70:71] neg_lo:[0,1] neg_hi:[0,1]
	v_cvt_f32_f16_sdwa v195, v33 dst_sel:DWORD dst_unused:UNUSED_PAD src0_sel:WORD_1
	v_pk_mul_f32 v[70:71], v[50:51], s[36:37]
	v_cvt_f32_f16_sdwa v170, v30 dst_sel:DWORD dst_unused:UNUSED_PAD src0_sel:WORD_1
	v_pk_fma_f32 v[50:51], v[50:51], s[66:67], v[70:71] op_sel:[0,0,1] op_sel_hi:[1,0,0]
	v_pk_add_f32 v[70:71], v[52:53], v[72:73]
	v_pk_add_f32 v[72:73], v[52:53], v[72:73] neg_lo:[0,1] neg_hi:[0,1]
	v_cvt_f32_f16_e32 v171, v31
	s_nop 0
	s_nop 0
	v_pk_add_f32 v[52:53], v[54:55], v[74:75]
	v_pk_add_f32 v[54:55], v[54:55], v[74:75] neg_lo:[0,1] neg_hi:[0,1]
	v_cvt_f32_f16_sdwa v185, v31 dst_sel:DWORD dst_unused:UNUSED_PAD src0_sel:WORD_1
	v_pk_mul_f32 v[74:75], v[54:55], s[36:37]
	v_cvt_f32_f16_e32 v184, v30
	v_pk_fma_f32 v[54:55], v[54:55], s[66:67], v[74:75] op_sel:[0,0,1] op_sel_hi:[1,0,0] neg_lo:[1,0,0] neg_hi:[1,0,0]
	v_pk_add_f32 v[74:75], v[90:91], v[68:69]
	v_pk_add_f32 v[68:69], v[90:91], v[68:69] neg_lo:[0,1] neg_hi:[0,1]
	v_pk_add_f32 v[90:91], v[76:77], v[62:63]
	v_pk_add_f32 v[62:63], v[76:77], v[62:63] neg_lo:[0,1] neg_hi:[0,1]
	v_cvt_f32_f16_sdwa v172, v24 dst_sel:DWORD dst_unused:UNUSED_PAD src0_sel:WORD_1
	v_xor_b32_e32 v77, 0x80000000, v62
	v_mov_b32_e32 v76, v63
	v_pk_add_f32 v[62:63], v[56:57], v[80:81] op_sel:[0,1] op_sel_hi:[1,0] neg_hi:[0,1]
	v_pk_add_f32 v[56:57], v[56:57], v[80:81] op_sel:[0,1] op_sel_hi:[1,0] neg_lo:[0,1]
	v_pk_add_f32 v[80:81], v[58:59], v[64:65]
	v_pk_add_f32 v[58:59], v[58:59], v[64:65] neg_lo:[0,1] neg_hi:[0,1]
	v_cvt_f32_f16_e32 v173, v25
	v_xor_b32_e32 v65, 0x80000000, v58
	v_mov_b32_e32 v64, v59
	v_pk_add_f32 v[58:59], v[82:83], v[70:71]
	v_pk_add_f32 v[70:71], v[82:83], v[70:71] neg_lo:[0,1] neg_hi:[0,1]
	v_pk_add_f32 v[82:83], v[78:79], v[52:53]
	v_pk_add_f32 v[52:53], v[78:79], v[52:53] neg_lo:[0,1] neg_hi:[0,1]
	v_pk_add_f32 v[118:119], v[58:59], v[82:83]
	v_pk_add_f32 v[134:135], v[58:59], v[82:83] neg_lo:[0,1] neg_hi:[0,1]
	v_cos_f32_e32 v83, v18
	v_sin_f32_e32 v82, v18
	v_cvt_f32_f16_sdwa v181, v25 dst_sel:DWORD dst_unused:UNUSED_PAD src0_sel:WORD_1
	v_cvt_f32_f16_e32 v180, v24
	v_cvt_f32_f16_sdwa v174, v28 dst_sel:DWORD dst_unused:UNUSED_PAD src0_sel:WORD_1
	v_cvt_f32_f16_e32 v175, v29
	v_cvt_f32_f16_sdwa v179, v29 dst_sel:DWORD dst_unused:UNUSED_PAD src0_sel:WORD_1
	v_cvt_f32_f16_e32 v178, v28
	v_cvt_f32_f16_e32 v165, v13
	v_cvt_f32_f16_sdwa v167, v13 dst_sel:DWORD dst_unused:UNUSED_PAD src0_sel:WORD_1
	v_cvt_f32_f16_e32 v166, v12
	v_cvt_f32_f16_e32 v154, v6
	v_cvt_f32_f16_e32 v155, v7
	v_cvt_f32_f16_sdwa v157, v7 dst_sel:DWORD dst_unused:UNUSED_PAD src0_sel:WORD_1
	v_cvt_f32_f16_sdwa v156, v6 dst_sel:DWORD dst_unused:UNUSED_PAD src0_sel:WORD_1
	v_cvt_f32_f16_sdwa v140, v4 dst_sel:DWORD dst_unused:UNUSED_PAD src0_sel:WORD_1
	v_cvt_f32_f16_e32 v141, v5
	v_cvt_f32_f16_sdwa v143, v5 dst_sel:DWORD dst_unused:UNUSED_PAD src0_sel:WORD_1
	v_cvt_f32_f16_e32 v142, v4
	v_cvt_f32_f16_e32 v124, v16
	v_cvt_f32_f16_e32 v125, v17
	v_cvt_f32_f16_sdwa v127, v17 dst_sel:DWORD dst_unused:UNUSED_PAD src0_sel:WORD_1
	v_cvt_f32_f16_sdwa v126, v16 dst_sel:DWORD dst_unused:UNUSED_PAD src0_sel:WORD_1
	v_cvt_f32_f16_sdwa v114, v122 dst_sel:DWORD dst_unused:UNUSED_PAD src0_sel:WORD_1
	v_cvt_f32_f16_e32 v115, v123
	v_cvt_f32_f16_sdwa v117, v123 dst_sel:DWORD dst_unused:UNUSED_PAD src0_sel:WORD_1
	v_cvt_f32_f16_e32 v116, v122
	v_xor_b32_e32 v79, 0x80000000, v52
	v_mov_b32_e32 v78, v53
	v_pk_add_f32 v[52:53], v[48:49], v[72:73] op_sel:[0,1] op_sel_hi:[1,0] neg_hi:[0,1]
	v_pk_add_f32 v[48:49], v[48:49], v[72:73] op_sel:[0,1] op_sel_hi:[1,0] neg_lo:[0,1]
	v_pk_add_f32 v[72:73], v[50:51], v[54:55]
	v_pk_add_f32 v[50:51], v[50:51], v[54:55] neg_lo:[0,1] neg_hi:[0,1]
	v_pk_fma_f32 v[160:161], v[82:83], 0, v[82:83] op_sel:[0,0,1] op_sel_hi:[1,0,0] neg_lo:[1,0,0] neg_hi:[1,0,0]
	v_xor_b32_e32 v55, 0x80000000, v50
	v_mov_b32_e32 v54, v51
	v_pk_fma_f32 v[198:199], v[82:83], 0, v[82:83] op_sel:[0,0,1] op_sel_hi:[1,0,0]
	v_pk_add_f32 v[42:43], v[112:113], v[22:23]
	v_pk_add_f32 v[22:23], v[112:113], v[22:23] neg_lo:[0,1] neg_hi:[0,1]
	v_pk_add_f32 v[98:99], v[74:75], v[90:91]
	v_pk_add_f32 v[100:101], v[74:75], v[90:91] neg_lo:[0,1] neg_hi:[0,1]
	v_pk_add_f32 v[102:103], v[68:69], v[76:77]
	v_pk_add_f32 v[106:107], v[68:69], v[76:77] neg_lo:[0,1] neg_hi:[0,1]
	v_pk_add_f32 v[104:105], v[62:63], v[80:81]
	v_pk_add_f32 v[108:109], v[62:63], v[80:81] neg_lo:[0,1] neg_hi:[0,1]
	v_pk_add_f32 v[110:111], v[56:57], v[64:65]
	v_pk_add_f32 v[112:113], v[56:57], v[64:65] neg_lo:[0,1] neg_hi:[0,1]
	v_pk_add_f32 v[152:153], v[70:71], v[78:79]
	v_pk_add_f32 v[162:163], v[70:71], v[78:79] neg_lo:[0,1] neg_hi:[0,1]
	v_pk_add_f32 v[176:177], v[52:53], v[72:73]
	v_pk_add_f32 v[182:183], v[52:53], v[72:73] neg_lo:[0,1] neg_hi:[0,1]
	v_pk_add_f32 v[188:189], v[48:49], v[54:55]
	v_pk_add_f32 v[196:197], v[48:49], v[54:55] neg_lo:[0,1] neg_hi:[0,1]
	v_pk_mul_f32 v[186:187], v[82:83], 0 op_sel_hi:[1,0]
	v_mov_b32_e32 v190, v160
	v_mov_b32_e32 v191, v199
	v_mul_f32_e32 v18, 0x3f3504f3, v83
	v_mul_f32_e32 v158, 0xbec3ef15, v83
	v_mul_f32_e32 v132, 0xbf6c835e, v83
	s_and_saveexec_b64 s[0:1], vcc
	s_xor_b64 s[0:1], exec, s[0:1]
	s_cbranch_execz .LBB0_536
	v_pk_add_f32 v[4:5], v[148:149], v[196:197]
	v_pk_add_f32 v[6:7], v[148:149], v[196:197] neg_lo:[0,1] neg_hi:[0,1]
	v_mul_f32_e32 v4, 0.5, v4
	v_mul_f32_e32 v12, 0.5, v7
	v_mov_b32_e32 v7, v5
	v_pk_mul_f32 v[6:7], v[6:7], s[44:45]
	v_pk_mov_b32 v[16:17], v[198:199], v[160:161] op_sel:[1,0]
	v_pk_mul_f32 v[24:25], v[190:191], v[6:7] op_sel:[0,1] op_sel_hi:[1,0]
	v_pk_mul_f32 v[6:7], v[190:191], v[6:7]
	v_pk_add_f32 v[24:25], v[24:25], v[24:25] op_sel:[0,1] op_sel_hi:[0,1]
	v_pk_add_f32 v[28:29], v[4:5], v[24:25] op_sel_hi:[0,1] neg_hi:[0,1]
	v_pk_add_f32 v[4:5], v[6:7], v[6:7] op_sel:[0,1] op_sel_hi:[0,1] neg_lo:[0,1] neg_hi:[0,1]
	v_pk_add_f32 v[6:7], v[12:13], v[4:5] op_sel_hi:[0,1] neg_hi:[0,1]
	v_pk_mul_f32 v[4:5], v[6:7], v[194:195]
	v_pk_mul_f32 v[6:7], v[6:7], v[192:193]
	v_pk_fma_f32 v[4:5], v[28:29], v[192:193], v[4:5]
	v_pk_fma_f32 v[6:7], v[28:29], v[194:195], v[6:7] neg_lo:[0,0,1] neg_hi:[0,0,1]
	s_mov_b32 s66, s19
	v_pk_add_f32 v[12:13], v[6:7], v[4:5] op_sel:[0,1] op_sel_hi:[1,0] neg_lo:[0,1]
	v_pk_add_f32 v[28:29], v[6:7], v[4:5] op_sel:[0,1] op_sel_hi:[1,0]
	v_pk_add_f32 v[4:5], v[4:5], v[6:7] op_sel:[1,0] op_sel_hi:[0,1] neg_lo:[0,1] neg_hi:[0,1]
	s_nop 0
	v_pk_mul_f32 v[12:13], v[12:13], 0.5 op_sel_hi:[1,0]
	v_mov_b32_e32 v29, v5
	v_mul_f32_e32 v24, v190, v12
	v_pk_fma_f32 v[30:31], v[190:191], v[12:13], v[24:25] op_sel_hi:[1,1,0] neg_lo:[1,0,0] neg_hi:[1,0,0]
	v_mul_f32_e32 v24, v160, v13
	v_pk_fma_f32 v[12:13], v[16:17], v[12:13], v[24:25] op_sel_hi:[1,1,0]
	v_mov_b32_e32 v16, v83
	v_mov_b32_e32 v30, v12
	v_pk_fma_f32 v[4:5], v[28:29], 0.5, v[12:13] op_sel_hi:[1,0,1] neg_lo:[0,0,1] neg_hi:[0,0,1]
	v_pk_fma_f32 v[122:123], v[28:29], 0.5, v[30:31] op_sel_hi:[1,0,1]
	v_pk_fma_f32 v[6:7], v[28:29], 0.5, v[30:31] op_sel_hi:[1,0,1] neg_lo:[1,0,0] neg_hi:[1,0,0]
	v_mov_b32_e32 v5, v123
	v_pk_mul_f32 v[24:25], v[4:5], s[46:47] op_sel_hi:[1,0]
	v_pk_add_f32 v[4:5], v[138:139], v[188:189]
	v_pk_add_f32 v[12:13], v[138:139], v[188:189] neg_lo:[0,1] neg_hi:[0,1]
	v_mov_b32_e32 v17, v82
	v_mul_f32_e32 v6, 0.5, v13
	v_pk_add_f32 v[28:29], v[186:187], v[16:17] neg_lo:[0,1] neg_hi:[0,1]
	v_pk_add_f32 v[30:31], v[186:187], v[16:17]
	v_mov_b32_e32 v13, v5
	v_pk_mov_b32 v[32:33], v[28:29], v[30:31] op_sel:[1,0]
	v_pk_mul_f32 v[12:13], v[12:13], s[44:45]
	v_mul_f32_e32 v4, 0.5, v4
	v_pk_mul_f32 v[48:49], v[32:33], v[12:13] op_sel:[0,1] op_sel_hi:[1,0]
	v_pk_mul_f32 v[12:13], v[32:33], v[12:13]
	v_pk_add_f32 v[48:49], v[48:49], v[48:49] op_sel:[0,1] op_sel_hi:[0,1]
	v_pk_add_f32 v[50:51], v[4:5], v[48:49] op_sel_hi:[0,1] neg_hi:[0,1]
	v_pk_add_f32 v[4:5], v[12:13], v[12:13] op_sel:[0,1] op_sel_hi:[0,1] neg_lo:[0,1] neg_hi:[0,1]
	v_pk_add_f32 v[12:13], v[6:7], v[4:5] op_sel_hi:[0,1] neg_hi:[0,1]
	v_pk_mul_f32 v[4:5], v[12:13], v[184:185]
	v_pk_mul_f32 v[12:13], v[12:13], v[170:171]
	v_pk_fma_f32 v[4:5], v[50:51], v[170:171], v[4:5]
	v_pk_fma_f32 v[12:13], v[50:51], v[184:185], v[12:13] neg_lo:[0,0,1] neg_hi:[0,0,1]
	v_mov_b32_e32 v31, v29
	v_pk_add_f32 v[48:49], v[12:13], v[4:5] op_sel:[0,1] op_sel_hi:[1,0] neg_lo:[0,1]
	v_pk_add_f32 v[50:51], v[12:13], v[4:5] op_sel:[0,1] op_sel_hi:[1,0]
	v_pk_add_f32 v[4:5], v[4:5], v[12:13] op_sel:[1,0] op_sel_hi:[0,1] neg_lo:[0,1] neg_hi:[0,1]
	v_pk_mul_f32 v[48:49], v[48:49], 0.5 op_sel_hi:[1,0]
	v_mov_b32_e32 v51, v5
	v_mul_f32_e32 v6, v29, v48
	v_pk_fma_f32 v[32:33], v[32:33], v[48:49], v[6:7] op_sel_hi:[1,1,0] neg_lo:[1,0,0] neg_hi:[1,0,0]
	v_mul_f32_e32 v6, v29, v49
	v_pk_fma_f32 v[28:29], v[30:31], v[48:49], v[6:7] op_sel_hi:[1,1,0]
	v_pk_mul_f32 v[12:13], v[16:17], s[36:37]
	v_mov_b32_e32 v32, v28
	v_pk_fma_f32 v[4:5], v[50:51], 0.5, v[28:29] op_sel_hi:[1,0,1] neg_lo:[0,0,1] neg_hi:[0,0,1]
	v_pk_fma_f32 v[138:139], v[50:51], 0.5, v[32:33] op_sel_hi:[1,0,1]
	v_pk_add_f32 v[16:17], v[92:93], v[182:183]
	v_mov_b32_e32 v5, v139
	v_pk_add_f32 v[28:29], v[92:93], v[182:183] neg_lo:[0,1] neg_hi:[0,1]
	v_pk_mul_f32 v[30:31], v[4:5], s[46:47] op_sel_hi:[1,0]
	v_pk_fma_f32 v[4:5], v[50:51], 0.5, v[32:33] op_sel_hi:[1,0,1] neg_lo:[1,0,0] neg_hi:[1,0,0]
	v_mul_f32_e32 v6, 0.5, v29
	v_pk_add_f32 v[32:33], v[18:19], v[12:13] op_sel:[0,1] op_sel_hi:[0,1] neg_lo:[0,1] neg_hi:[0,1]
	v_pk_add_f32 v[48:49], v[18:19], v[12:13] op_sel:[0,1] op_sel_hi:[0,1]
	v_mov_b32_e32 v29, v17
	v_mul_f32_e32 v4, 0.5, v16
	v_mov_b32_e32 v50, v32
	v_mov_b32_e32 v51, v49
	v_pk_mul_f32 v[16:17], v[28:29], s[44:45]
	v_pk_mov_b32 v[48:49], v[48:49], v[32:33] op_sel:[1,0]
	v_pk_mul_f32 v[28:29], v[50:51], v[16:17] op_sel:[0,1] op_sel_hi:[1,0]
	v_pk_mul_f32 v[16:17], v[50:51], v[16:17]
	v_pk_add_f32 v[28:29], v[28:29], v[28:29] op_sel:[0,1] op_sel_hi:[0,1]
	v_pk_add_f32 v[52:53], v[4:5], v[28:29] op_sel_hi:[0,1] neg_hi:[0,1]
	v_pk_add_f32 v[16:17], v[16:17], v[16:17] op_sel:[0,1] op_sel_hi:[0,1] neg_lo:[0,1] neg_hi:[0,1]
	v_pk_add_f32 v[28:29], v[6:7], v[16:17] op_sel_hi:[0,1] neg_hi:[0,1]
	v_pk_mul_f32 v[16:17], v[28:29], v[180:181]
	v_pk_mul_f32 v[28:29], v[28:29], v[172:173]
	v_pk_fma_f32 v[16:17], v[52:53], v[172:173], v[16:17]
	v_pk_fma_f32 v[28:29], v[52:53], v[180:181], v[28:29] neg_lo:[0,0,1] neg_hi:[0,0,1]
	v_sub_f32_e32 v6, v89, v177
	v_pk_add_f32 v[52:53], v[28:29], v[16:17] op_sel:[0,1] op_sel_hi:[1,0] neg_lo:[0,1]
	v_pk_add_f32 v[54:55], v[28:29], v[16:17] op_sel:[0,1] op_sel_hi:[1,0]
	v_pk_add_f32 v[16:17], v[16:17], v[28:29] op_sel:[1,0] op_sel_hi:[0,1] neg_lo:[0,1] neg_hi:[0,1]
	v_pk_mul_f32 v[52:53], v[52:53], 0.5 op_sel_hi:[1,0]
	v_mov_b32_e32 v55, v17
	v_mul_f32_e32 v4, v32, v52
	v_pk_fma_f32 v[56:57], v[50:51], v[52:53], v[4:5] op_sel_hi:[1,1,0] neg_lo:[1,0,0] neg_hi:[1,0,0]
	v_mul_f32_e32 v4, v32, v53
	v_pk_fma_f32 v[48:49], v[48:49], v[52:53], v[4:5] op_sel_hi:[1,1,0]
	v_pk_add_f32 v[28:29], v[88:89], v[176:177]
	v_mov_b32_e32 v56, v48
	v_pk_fma_f32 v[16:17], v[54:55], 0.5, v[48:49] op_sel_hi:[1,0,1] neg_lo:[0,0,1] neg_hi:[0,0,1]
	v_mov_b32_e32 v48, v12
	v_mov_b32_e32 v49, v88
	v_pk_mov_b32 v[12:13], v[12:13], v[176:177] op_sel:[1,0]
	v_mul_f32_e32 v18, 0.5, v29
	v_pk_add_f32 v[12:13], v[48:49], v[12:13] neg_lo:[0,1] neg_hi:[0,1]
	v_mul_f32_e32 v4, 0.5, v28
	v_pk_mul_f32 v[48:49], v[12:13], v[18:19]
	v_mov_b32_e32 v13, v32
	v_pk_fma_f32 v[50:51], v[50:51], v[48:49], v[48:49] op_sel:[0,1,0] op_sel_hi:[1,0,1]
	v_mov_b32_e32 v48, v49
	v_mov_b32_e32 v49, v18
	v_pk_mul_f32 v[48:49], v[12:13], v[48:49]
	v_pk_add_f32 v[52:53], v[4:5], v[50:51]
	v_mul_f32_e32 v6, 0.5, v6
	v_fma_f32 v53, v28, 0.5, -v50
	v_pk_add_f32 v[28:29], v[48:49], v[48:49] op_sel:[0,1] op_sel_hi:[0,1] neg_lo:[0,1] neg_hi:[0,1]
	v_pk_add_f32 v[48:49], v[6:7], v[28:29] op_sel_hi:[0,1] neg_hi:[0,1]
	v_pk_mul_f32 v[28:29], v[48:49], v[178:179]
	v_pk_mul_f32 v[48:49], v[48:49], v[174:175]
	v_pk_fma_f32 v[28:29], v[52:53], v[174:175], v[28:29]
	v_pk_fma_f32 v[48:49], v[52:53], v[178:179], v[48:49] neg_lo:[0,0,1] neg_hi:[0,0,1]
	v_pk_fma_f32 v[92:93], v[54:55], 0.5, v[56:57] op_sel_hi:[1,0,1]
	v_pk_add_f32 v[50:51], v[48:49], v[28:29] op_sel:[0,1] op_sel_hi:[1,0] neg_lo:[0,1]
	v_pk_add_f32 v[52:53], v[48:49], v[28:29] op_sel:[0,1] op_sel_hi:[1,0]
	v_mov_b32_e32 v17, v93
	v_pk_mul_f32 v[50:51], v[50:51], 0.5 op_sel_hi:[1,0]
	v_pk_mul_f32 v[64:65], v[16:17], s[46:47] op_sel_hi:[1,0]
	v_mul_f32_e32 v4, v12, v50
	v_pk_fma_f32 v[16:17], v[54:55], 0.5, v[56:57] op_sel_hi:[1,0,1] neg_lo:[1,0,0] neg_hi:[1,0,0]
	v_pk_fma_f32 v[54:55], v[12:13], v[50:51], v[4:5] op_sel_hi:[1,1,0] neg_lo:[1,0,0] neg_hi:[1,0,0]
	v_mov_b32_e32 v33, v12
	v_mul_f32_e32 v4, v12, v51
	v_pk_fma_f32 v[12:13], v[32:33], v[50:51], v[4:5] op_sel_hi:[1,1,0]
	v_pk_add_f32 v[28:29], v[28:29], v[48:49] op_sel:[1,0] op_sel_hi:[0,1] neg_lo:[0,1] neg_hi:[0,1]
	v_mov_b32_e32 v53, v29
	v_mov_b32_e32 v54, v12
	v_pk_fma_f32 v[12:13], v[52:53], 0.5, v[12:13] op_sel_hi:[1,0,1] neg_lo:[0,0,1] neg_hi:[0,0,1]
	v_pk_fma_f32 v[88:89], v[52:53], 0.5, v[54:55] op_sel_hi:[1,0,1]
	s_mov_b32 s67, s16
	v_mov_b32_e32 v13, v89
	v_pk_mul_f32 v[68:69], v[12:13], s[46:47] op_sel_hi:[1,0]
	v_pk_fma_f32 v[12:13], v[52:53], 0.5, v[54:55] op_sel_hi:[1,0,1] neg_lo:[1,0,0] neg_hi:[1,0,0]
	v_mov_b32_e32 v4, v83
	s_mov_b32 s17, s19
	v_pk_mul_f32 v[48:49], v[82:83], s[66:67] op_sel_hi:[0,1]
	v_pk_add_f32 v[28:29], v[96:97], v[162:163]
	v_pk_add_f32 v[32:33], v[96:97], v[162:163] neg_lo:[0,1] neg_hi:[0,1]
	v_pk_fma_f32 v[52:53], v[4:5], s[16:17], v[48:49] op_sel_hi:[0,1,1] neg_lo:[0,0,1] neg_hi:[0,0,1]
	v_mul_f32_e32 v12, 0.5, v33
	v_pk_fma_f32 v[50:51], v[4:5], s[16:17], v[48:49] op_sel_hi:[0,1,1]
	v_mov_b32_e32 v33, v29
	v_mul_f32_e32 v6, 0.5, v28
	v_mov_b32_e32 v54, v52
	v_mov_b32_e32 v55, v51
	v_pk_mul_f32 v[28:29], v[32:33], s[44:45]
	v_pk_mov_b32 v[56:57], v[50:51], v[52:53] op_sel:[1,0]
	v_pk_mul_f32 v[32:33], v[54:55], v[28:29] op_sel:[0,1] op_sel_hi:[1,0]
	v_pk_mul_f32 v[28:29], v[54:55], v[28:29]
	v_pk_add_f32 v[32:33], v[32:33], v[32:33] op_sel:[0,1] op_sel_hi:[0,1]
	v_pk_add_f32 v[58:59], v[6:7], v[32:33] op_sel_hi:[0,1] neg_hi:[0,1]
	v_pk_add_f32 v[28:29], v[28:29], v[28:29] op_sel:[0,1] op_sel_hi:[0,1] neg_lo:[0,1] neg_hi:[0,1]
	v_pk_add_f32 v[32:33], v[12:13], v[28:29] op_sel_hi:[0,1] neg_hi:[0,1]
	v_pk_mul_f32 v[28:29], v[32:33], v[166:167]
	v_pk_mul_f32 v[32:33], v[32:33], v[164:165]
	v_pk_fma_f32 v[28:29], v[58:59], v[164:165], v[28:29]
	v_pk_fma_f32 v[32:33], v[58:59], v[166:167], v[32:33] neg_lo:[0,0,1] neg_hi:[0,0,1]
	v_mov_b32_e32 v159, v66
	v_pk_add_f32 v[58:59], v[32:33], v[28:29] op_sel:[0,1] op_sel_hi:[1,0] neg_lo:[0,1]
	v_pk_add_f32 v[70:71], v[32:33], v[28:29] op_sel:[0,1] op_sel_hi:[1,0]
	v_pk_add_f32 v[28:29], v[28:29], v[32:33] op_sel:[1,0] op_sel_hi:[0,1] neg_lo:[0,1] neg_hi:[0,1]
	v_pk_mul_f32 v[58:59], v[58:59], 0.5 op_sel_hi:[1,0]
	v_mov_b32_e32 v71, v29
	v_mul_f32_e32 v6, v52, v58
	v_pk_fma_f32 v[72:73], v[54:55], v[58:59], v[6:7] op_sel_hi:[1,1,0] neg_lo:[1,0,0] neg_hi:[1,0,0]
	v_mul_f32_e32 v6, v52, v59
	v_pk_fma_f32 v[56:57], v[56:57], v[58:59], v[6:7] op_sel_hi:[1,1,0]
	v_sub_f32_e32 v12, v67, v153
	v_mov_b32_e32 v72, v56
	v_pk_fma_f32 v[28:29], v[70:71], 0.5, v[56:57] op_sel_hi:[1,0,1] neg_lo:[0,0,1] neg_hi:[0,0,1]
	v_pk_fma_f32 v[96:97], v[70:71], 0.5, v[72:73] op_sel_hi:[1,0,1]
	v_pk_mov_b32 v[56:57], v[48:49], v[152:153] op_sel:[1,0]
	v_mov_b32_e32 v29, v97
	v_pk_mul_f32 v[62:63], v[28:29], s[46:47] op_sel_hi:[1,0]
	v_pk_add_f32 v[28:29], v[66:67], v[152:153]
	v_pk_add_f32 v[56:57], v[158:159], v[56:57] neg_lo:[0,1] neg_hi:[0,1]
	v_mul_f32_e32 v18, 0.5, v29
	v_pk_mul_f32 v[58:59], v[56:57], v[18:19]
	v_mul_f32_e32 v6, 0.5, v28
	v_pk_fma_f32 v[54:55], v[54:55], v[58:59], v[58:59] op_sel:[0,1,0] op_sel_hi:[1,0,1]
	v_mov_b32_e32 v66, v56
	v_mov_b32_e32 v67, v52
	v_mov_b32_e32 v58, v59
	v_mov_b32_e32 v59, v18
	v_pk_mul_f32 v[58:59], v[66:67], v[58:59]
	v_pk_add_f32 v[66:67], v[6:7], v[54:55]
	v_mul_f32_e32 v12, 0.5, v12
	v_fma_f32 v67, v28, 0.5, -v54
	v_pk_add_f32 v[28:29], v[58:59], v[58:59] op_sel:[0,1] op_sel_hi:[0,1] neg_lo:[0,1] neg_hi:[0,1]
	v_pk_add_f32 v[54:55], v[12:13], v[28:29] op_sel_hi:[0,1] neg_hi:[0,1]
	v_pk_mul_f32 v[28:29], v[54:55], v[156:157]
	v_pk_mul_f32 v[54:55], v[54:55], v[154:155]
	v_pk_fma_f32 v[32:33], v[70:71], 0.5, v[72:73] op_sel_hi:[1,0,1] neg_lo:[1,0,0] neg_hi:[1,0,0]
	v_pk_fma_f32 v[58:59], v[66:67], v[154:155], v[28:29] neg_lo:[0,0,1] neg_hi:[0,0,1]
	v_pk_fma_f32 v[28:29], v[66:67], v[154:155], v[28:29]
	v_pk_fma_f32 v[70:71], v[66:67], v[156:157], v[54:55]
	v_pk_fma_f32 v[54:55], v[66:67], v[156:157], v[54:55] neg_lo:[0,0,1] neg_hi:[0,0,1]
	v_pk_add_f32 v[72:73], v[58:59], v[28:29] op_sel:[0,1] op_sel_hi:[1,0]
	v_pk_add_f32 v[66:67], v[70:71], v[54:55] op_sel_hi:[0,1] neg_lo:[0,1] neg_hi:[0,1]
	v_pk_add_f32 v[28:29], v[58:59], v[28:29] op_sel_hi:[0,1] neg_lo:[0,1] neg_hi:[0,1]
	v_pk_add_f32 v[54:55], v[70:71], v[54:55] op_sel:[0,1] op_sel_hi:[1,0]
	v_mov_b32_e32 v73, v67
	v_mov_b32_e32 v55, v29
	v_pk_mul_f32 v[28:29], v[54:55], 0.5 op_sel_hi:[1,0]
	v_mov_b32_e32 v133, v84
	v_pk_mul_f32 v[54:55], v[52:53], v[28:29] op_sel:[0,1] op_sel_hi:[0,0]
	v_pk_fma_f32 v[58:59], v[56:57], v[28:29], v[54:55] op_sel_hi:[0,1,1]
	v_pk_fma_f32 v[28:29], v[56:57], v[28:29], v[54:55] op_sel_hi:[0,1,1] neg_hi:[0,0,1]
	v_pk_fma_f32 v[54:55], v[72:73], 0.5, v[58:59] op_sel_hi:[1,0,1] neg_lo:[0,0,1] neg_hi:[0,0,1]
	v_pk_fma_f32 v[66:67], v[72:73], 0.5, v[28:29] op_sel_hi:[1,0,1]
	v_pk_add_f32 v[56:57], v[60:61], v[134:135] neg_lo:[0,1] neg_hi:[0,1]
	v_mov_b32_e32 v55, v67
	v_pk_mul_f32 v[90:91], v[54:55], s[46:47] op_sel_hi:[1,0]
	v_pk_add_f32 v[54:55], v[134:135], v[60:61]
	v_mul_f32_e32 v12, 0.5, v57
	v_mov_b32_e32 v57, v55
	v_mul_f32_e32 v6, 0.5, v54
	v_pk_mov_b32 v[58:59], v[52:53], v[50:51] op_sel:[1,0]
	v_pk_mul_f32 v[54:55], v[56:57], s[44:45]
	v_pk_fma_f32 v[28:29], v[72:73], 0.5, v[28:29] op_sel_hi:[1,0,1] neg_lo:[1,0,0] neg_hi:[1,0,0]
	v_pk_mul_f32 v[56:57], v[58:59], v[54:55] op_sel:[0,1] op_sel_hi:[1,0]
	v_pk_mul_f32 v[54:55], v[58:59], v[54:55]
	v_pk_add_f32 v[56:57], v[56:57], v[56:57] op_sel:[0,1] op_sel_hi:[0,1]
	v_pk_add_f32 v[60:61], v[6:7], v[56:57] op_sel_hi:[0,1] neg_hi:[0,1]
	v_pk_add_f32 v[54:55], v[54:55], v[54:55] op_sel:[0,1] op_sel_hi:[0,1] neg_lo:[0,1] neg_hi:[0,1]
	v_pk_add_f32 v[56:57], v[12:13], v[54:55] op_sel_hi:[0,1] neg_hi:[0,1]
	v_pk_mul_f32 v[54:55], v[56:57], v[142:143]
	v_pk_mul_f32 v[56:57], v[56:57], v[140:141]
	v_pk_fma_f32 v[54:55], v[60:61], v[140:141], v[54:55]
	v_pk_fma_f32 v[56:57], v[60:61], v[142:143], v[56:57] neg_lo:[0,0,1] neg_hi:[0,0,1]
	v_mov_b32_e32 v51, v53
	v_pk_add_f32 v[60:61], v[56:57], v[54:55] op_sel:[0,1] op_sel_hi:[1,0] neg_lo:[0,1]
	v_pk_add_f32 v[70:71], v[56:57], v[54:55] op_sel:[0,1] op_sel_hi:[1,0]
	v_pk_add_f32 v[54:55], v[54:55], v[56:57] op_sel:[1,0] op_sel_hi:[0,1] neg_lo:[0,1] neg_hi:[0,1]
	v_pk_mul_f32 v[60:61], v[60:61], 0.5 op_sel_hi:[1,0]
	v_mov_b32_e32 v71, v55
	v_mul_f32_e32 v6, v53, v60
	v_pk_fma_f32 v[72:73], v[58:59], v[60:61], v[6:7] op_sel_hi:[1,1,0] neg_lo:[1,0,0] neg_hi:[1,0,0]
	v_mul_f32_e32 v6, v53, v61
	v_pk_fma_f32 v[50:51], v[50:51], v[60:61], v[6:7] op_sel_hi:[1,1,0]
	v_pk_add_f32 v[54:55], v[118:119], v[84:85]
	v_mov_b32_e32 v72, v50
	v_mov_b32_e32 v49, v118
	v_pk_fma_f32 v[50:51], v[70:71], 0.5, v[50:51] op_sel_hi:[1,0,1] neg_lo:[0,0,1] neg_hi:[0,0,1]
	v_pk_fma_f32 v[60:61], v[70:71], 0.5, v[72:73] op_sel_hi:[1,0,1]
	v_mul_f32_e32 v18, 0.5, v55
	v_pk_add_f32 v[48:49], v[132:133], v[48:49] neg_lo:[0,1] neg_hi:[0,1]
	v_mov_b32_e32 v51, v61
	v_pk_mul_f32 v[56:57], v[48:49], v[18:19]
	v_pk_mul_f32 v[94:95], v[50:51], s[46:47] op_sel_hi:[1,0]
	v_pk_fma_f32 v[50:51], v[70:71], 0.5, v[72:73] op_sel_hi:[1,0,1] neg_lo:[1,0,0] neg_hi:[1,0,0]
	v_mul_f32_e32 v6, 0.5, v54
	v_pk_fma_f32 v[58:59], v[58:59], v[56:57], v[56:57] op_sel:[0,1,0] op_sel_hi:[1,0,1]
	v_mov_b32_e32 v70, v48
	v_mov_b32_e32 v71, v53
	v_mov_b32_e32 v56, v57
	v_mov_b32_e32 v57, v18
	v_sub_f32_e32 v12, v85, v119
	v_pk_mul_f32 v[56:57], v[70:71], v[56:57]
	v_pk_add_f32 v[70:71], v[6:7], v[58:59]
	v_mul_f32_e32 v12, 0.5, v12
	v_fma_f32 v71, v54, 0.5, -v58
	v_pk_add_f32 v[54:55], v[56:57], v[56:57] op_sel:[0,1] op_sel_hi:[0,1] neg_lo:[0,1] neg_hi:[0,1]
	v_pk_add_f32 v[56:57], v[12:13], v[54:55] op_sel_hi:[0,1] neg_hi:[0,1]
	v_pk_mul_f32 v[54:55], v[56:57], v[126:127]
	v_pk_mul_f32 v[56:57], v[56:57], v[124:125]
	v_pk_fma_f32 v[58:59], v[70:71], v[124:125], v[54:55] neg_lo:[0,0,1] neg_hi:[0,0,1]
	v_pk_fma_f32 v[54:55], v[70:71], v[124:125], v[54:55]
	v_pk_fma_f32 v[72:73], v[70:71], v[126:127], v[56:57]
	v_pk_fma_f32 v[56:57], v[70:71], v[126:127], v[56:57] neg_lo:[0,0,1] neg_hi:[0,0,1]
	v_pk_add_f32 v[70:71], v[58:59], v[54:55] op_sel:[0,1] op_sel_hi:[1,0]
	v_pk_add_f32 v[74:75], v[72:73], v[56:57] op_sel_hi:[0,1] neg_lo:[0,1] neg_hi:[0,1]
	v_pk_add_f32 v[54:55], v[58:59], v[54:55] op_sel_hi:[0,1] neg_lo:[0,1] neg_hi:[0,1]
	v_pk_add_f32 v[56:57], v[72:73], v[56:57] op_sel:[0,1] op_sel_hi:[1,0]
	v_mov_b32_e32 v71, v75
	v_mov_b32_e32 v57, v55
	v_pk_mul_f32 v[54:55], v[56:57], 0.5 op_sel_hi:[1,0]
	s_mov_b32 s66, s11
	v_pk_mul_f32 v[52:53], v[52:53], v[54:55] op_sel:[1,1] op_sel_hi:[1,0]
	s_mov_b32 s67, s8
	v_pk_fma_f32 v[56:57], v[48:49], v[54:55], v[52:53] op_sel_hi:[0,1,1]
	v_pk_fma_f32 v[48:49], v[48:49], v[54:55], v[52:53] op_sel_hi:[0,1,1] neg_hi:[0,0,1]
	s_nop 0
	v_pk_fma_f32 v[52:53], v[70:71], 0.5, v[56:57] op_sel_hi:[1,0,1] neg_lo:[0,0,1] neg_hi:[0,0,1]
	v_pk_fma_f32 v[84:85], v[70:71], 0.5, v[48:49] op_sel_hi:[1,0,1]
	s_mov_b32 s9, s11
	v_mov_b32_e32 v53, v85
	v_pk_mul_f32 v[80:81], v[52:53], s[46:47] op_sel_hi:[1,0]
	v_pk_mul_f32 v[118:119], v[82:83], s[66:67] op_sel_hi:[0,1]
	v_pk_add_f32 v[52:53], v[86:87], v[112:113]
	v_pk_add_f32 v[54:55], v[86:87], v[112:113] neg_lo:[0,1] neg_hi:[0,1]
	v_pk_fma_f32 v[58:59], v[4:5], s[8:9], v[118:119] op_sel_hi:[0,1,1] neg_lo:[0,0,1] neg_hi:[0,0,1]
	v_mul_f32_e32 v12, 0.5, v55
	v_pk_fma_f32 v[72:73], v[4:5], s[8:9], v[118:119] op_sel_hi:[0,1,1]
	v_mov_b32_e32 v55, v53
	v_mul_f32_e32 v6, 0.5, v52
	v_mov_b32_e32 v56, v58
	v_mov_b32_e32 v57, v73
	v_pk_mul_f32 v[52:53], v[54:55], s[44:45]
	v_pk_fma_f32 v[48:49], v[70:71], 0.5, v[48:49] op_sel_hi:[1,0,1] neg_lo:[1,0,0] neg_hi:[1,0,0]
	v_pk_mul_f32 v[54:55], v[56:57], v[52:53] op_sel:[0,1] op_sel_hi:[1,0]
	v_pk_mul_f32 v[52:53], v[56:57], v[52:53]
	v_pk_add_f32 v[54:55], v[54:55], v[54:55] op_sel:[0,1] op_sel_hi:[0,1]
	v_pk_add_f32 v[74:75], v[6:7], v[54:55] op_sel_hi:[0,1] neg_hi:[0,1]
	v_pk_add_f32 v[52:53], v[52:53], v[52:53] op_sel:[0,1] op_sel_hi:[0,1] neg_lo:[0,1] neg_hi:[0,1]
	v_pk_add_f32 v[54:55], v[12:13], v[52:53] op_sel_hi:[0,1] neg_hi:[0,1]
	v_pk_mul_f32 v[52:53], v[54:55], v[116:117]
	v_pk_mul_f32 v[54:55], v[54:55], v[114:115]
	v_pk_fma_f32 v[52:53], v[74:75], v[114:115], v[52:53]
	v_pk_fma_f32 v[54:55], v[74:75], v[116:117], v[54:55] neg_lo:[0,0,1] neg_hi:[0,0,1]
	v_pk_mov_b32 v[70:71], v[72:73], v[58:59] op_sel:[1,0]
	v_pk_add_f32 v[74:75], v[54:55], v[52:53] op_sel:[0,1] op_sel_hi:[1,0] neg_lo:[0,1]
	v_pk_add_f32 v[76:77], v[54:55], v[52:53] op_sel:[0,1] op_sel_hi:[1,0]
	v_pk_add_f32 v[52:53], v[52:53], v[54:55] op_sel:[1,0] op_sel_hi:[0,1] neg_lo:[0,1] neg_hi:[0,1]
	v_pk_mul_f32 v[74:75], v[74:75], 0.5 op_sel_hi:[1,0]
	v_mov_b32_e32 v77, v53
	v_mul_f32_e32 v6, v58, v74
	v_pk_fma_f32 v[112:113], v[56:57], v[74:75], v[6:7] op_sel_hi:[1,1,0] neg_lo:[1,0,0] neg_hi:[1,0,0]
	v_mul_f32_e32 v6, v58, v75
	v_pk_fma_f32 v[70:71], v[70:71], v[74:75], v[6:7] op_sel_hi:[1,1,0]
	v_pk_add_f32 v[54:55], v[34:35], v[110:111]
	v_mov_b32_e32 v112, v70
	v_pk_fma_f32 v[52:53], v[76:77], 0.5, v[70:71] op_sel_hi:[1,0,1] neg_lo:[0,0,1] neg_hi:[0,0,1]
	v_pk_fma_f32 v[86:87], v[76:77], 0.5, v[112:113] op_sel_hi:[1,0,1]
	v_sub_f32_e32 v12, v35, v111
	v_mov_b32_e32 v53, v87
	v_pk_mul_f32 v[78:79], v[52:53], s[46:47] op_sel_hi:[1,0]
	v_mul_f32_e32 v52, 0xbe47c5c2, v83
	v_mov_b32_e32 v53, v34
	v_pk_mov_b32 v[34:35], v[118:119], v[110:111] op_sel:[1,0]
	v_mul_f32_e32 v18, 0.5, v55
	v_pk_add_f32 v[34:35], v[52:53], v[34:35] neg_lo:[0,1] neg_hi:[0,1]
	v_mov_b32_e32 v71, v58
	v_pk_mul_f32 v[52:53], v[34:35], v[18:19]
	v_mov_b32_e32 v70, v34
	v_pk_fma_f32 v[56:57], v[56:57], v[52:53], v[52:53] op_sel:[0,1,0] op_sel_hi:[1,0,1]
	v_mov_b32_e32 v52, v53
	v_mov_b32_e32 v53, v18
	v_mul_f32_e32 v6, 0.5, v54
	v_pk_mul_f32 v[52:53], v[70:71], v[52:53]
	v_cvt_f32_f16_e32 v70, v46
	v_cvt_f32_f16_e32 v71, v47
	v_cvt_f32_f16_sdwa v47, v47 dst_sel:DWORD dst_unused:UNUSED_PAD src0_sel:WORD_1
	v_cvt_f32_f16_sdwa v46, v46 dst_sel:DWORD dst_unused:UNUSED_PAD src0_sel:WORD_1
	v_pk_fma_f32 v[74:75], v[76:77], 0.5, v[112:113] op_sel_hi:[1,0,1] neg_lo:[1,0,0] neg_hi:[1,0,0]
	v_mul_f32_e32 v12, 0.5, v12
	v_pk_add_f32 v[76:77], v[6:7], v[56:57]
	v_pk_add_f32 v[52:53], v[52:53], v[52:53] op_sel:[0,1] op_sel_hi:[0,1] neg_lo:[0,1] neg_hi:[0,1]
	v_fma_f32 v77, v54, 0.5, -v56
	v_pk_add_f32 v[54:55], v[12:13], v[52:53] op_sel_hi:[0,1] neg_hi:[0,1]
	v_pk_mul_f32 v[52:53], v[54:55], v[46:47]
	v_pk_mul_f32 v[54:55], v[54:55], v[70:71]
	v_pk_fma_f32 v[56:57], v[76:77], v[70:71], v[52:53] neg_lo:[0,0,1] neg_hi:[0,0,1]
	v_pk_fma_f32 v[52:53], v[76:77], v[70:71], v[52:53]
	v_pk_fma_f32 v[70:71], v[76:77], v[46:47], v[54:55]
	v_pk_fma_f32 v[46:47], v[76:77], v[46:47], v[54:55] neg_lo:[0,0,1] neg_hi:[0,0,1]
	v_pk_add_f32 v[54:55], v[56:57], v[52:53] op_sel:[0,1] op_sel_hi:[1,0]
	v_pk_add_f32 v[76:77], v[70:71], v[46:47] op_sel_hi:[0,1] neg_lo:[0,1] neg_hi:[0,1]
	v_pk_add_f32 v[52:53], v[56:57], v[52:53] op_sel_hi:[0,1] neg_lo:[0,1] neg_hi:[0,1]
	v_pk_add_f32 v[46:47], v[70:71], v[46:47] op_sel:[0,1] op_sel_hi:[1,0]
	v_mov_b32_e32 v55, v77
	v_mov_b32_e32 v47, v53
	v_pk_mul_f32 v[46:47], v[46:47], 0.5 op_sel_hi:[1,0]
	s_mov_b32 s25, s27
	v_pk_mul_f32 v[52:53], v[58:59], v[46:47] op_sel:[0,1] op_sel_hi:[0,0]
	v_pk_fma_f32 v[56:57], v[34:35], v[46:47], v[52:53] op_sel_hi:[0,1,1]
	v_pk_fma_f32 v[46:47], v[34:35], v[46:47], v[52:53] op_sel_hi:[0,1,1] neg_hi:[0,0,1]
	s_nop 0
	v_pk_fma_f32 v[52:53], v[54:55], 0.5, v[56:57] op_sel_hi:[1,0,1] neg_lo:[0,0,1] neg_hi:[0,0,1]
	v_pk_fma_f32 v[34:35], v[54:55], 0.5, v[46:47] op_sel_hi:[1,0,1]
	s_mov_b32 s66, s27
	v_mov_b32_e32 v53, v35
	v_pk_mul_f32 v[136:137], v[52:53], s[46:47] op_sel_hi:[1,0]
	v_pk_fma_f32 v[52:53], v[54:55], 0.5, v[46:47] op_sel_hi:[1,0,1] neg_lo:[1,0,0] neg_hi:[1,0,0]
	s_mov_b32 s67, s24
	v_pk_mul_f32 v[46:47], v[82:83], s[24:25] op_sel_hi:[0,1]
	v_pk_add_f32 v[54:55], v[108:109], v[40:41]
	v_pk_add_f32 v[40:41], v[40:41], v[108:109] neg_lo:[0,1] neg_hi:[0,1]
	v_pk_fma_f32 v[108:109], v[4:5], s[66:67], v[46:47] op_sel_hi:[0,1,1] neg_lo:[0,0,1] neg_hi:[0,0,1]
	v_mul_f32_e32 v12, 0.5, v41
	v_pk_fma_f32 v[70:71], v[4:5], s[66:67], v[46:47] op_sel_hi:[0,1,1]
	v_mov_b32_e32 v41, v55
	v_mov_b32_e32 v56, v108
	v_mov_b32_e32 v57, v71
	v_pk_mul_f32 v[40:41], v[40:41], s[44:45]
	v_mul_f32_e32 v6, 0.5, v54
	v_pk_mul_f32 v[54:55], v[56:57], v[40:41] op_sel:[0,1] op_sel_hi:[1,0]
	v_cvt_f32_f16_sdwa v76, v38 dst_sel:DWORD dst_unused:UNUSED_PAD src0_sel:WORD_1
	v_cvt_f32_f16_e32 v77, v39
	v_cvt_f32_f16_sdwa v39, v39 dst_sel:DWORD dst_unused:UNUSED_PAD src0_sel:WORD_1
	v_cvt_f32_f16_e32 v38, v38
	v_pk_mul_f32 v[40:41], v[56:57], v[40:41]
	v_pk_add_f32 v[54:55], v[54:55], v[54:55] op_sel:[0,1] op_sel_hi:[0,1]
	v_pk_add_f32 v[112:113], v[6:7], v[54:55] op_sel_hi:[0,1] neg_hi:[0,1]
	s_nop 0
	v_pk_add_f32 v[40:41], v[40:41], v[40:41] op_sel:[0,1] op_sel_hi:[0,1] neg_lo:[0,1] neg_hi:[0,1]
	v_pk_add_f32 v[54:55], v[12:13], v[40:41] op_sel_hi:[0,1] neg_hi:[0,1]
	v_pk_mul_f32 v[40:41], v[54:55], v[38:39]
	v_pk_mul_f32 v[54:55], v[54:55], v[76:77]
	v_pk_fma_f32 v[40:41], v[112:113], v[76:77], v[40:41]
	v_pk_fma_f32 v[38:39], v[112:113], v[38:39], v[54:55] neg_lo:[0,0,1] neg_hi:[0,0,1]
	v_pk_mov_b32 v[110:111], v[70:71], v[108:109] op_sel:[1,0]
	v_pk_add_f32 v[54:55], v[38:39], v[40:41] op_sel:[0,1] op_sel_hi:[1,0] neg_lo:[0,1]
	v_pk_add_f32 v[76:77], v[38:39], v[40:41] op_sel:[0,1] op_sel_hi:[1,0]
	v_pk_add_f32 v[38:39], v[40:41], v[38:39] op_sel:[1,0] op_sel_hi:[0,1] neg_lo:[0,1] neg_hi:[0,1]
	v_pk_mul_f32 v[54:55], v[54:55], 0.5 op_sel_hi:[1,0]
	v_mov_b32_e32 v77, v39
	v_mul_f32_e32 v4, v108, v54
	v_pk_fma_f32 v[112:113], v[56:57], v[54:55], v[4:5] op_sel_hi:[1,1,0] neg_lo:[1,0,0] neg_hi:[1,0,0]
	v_mul_f32_e32 v4, v108, v55
	v_pk_fma_f32 v[54:55], v[110:111], v[54:55], v[4:5] op_sel_hi:[1,1,0]
	v_sub_f32_e32 v6, v45, v105
	v_mov_b32_e32 v112, v54
	v_pk_fma_f32 v[40:41], v[76:77], 0.5, v[54:55] op_sel_hi:[1,0,1] neg_lo:[0,0,1] neg_hi:[0,0,1]
	v_pk_fma_f32 v[38:39], v[76:77], 0.5, v[112:113] op_sel_hi:[1,0,1]
	v_pk_add_f32 v[54:55], v[104:105], v[44:45]
	v_mov_b32_e32 v41, v39
	v_pk_mul_f32 v[130:131], v[40:41], s[46:47] op_sel_hi:[1,0]
	v_mul_f32_e32 v40, 0xbf54db31, v83
	v_mov_b32_e32 v41, v44
	v_pk_mov_b32 v[44:45], v[46:47], v[104:105] op_sel:[1,0]
	v_mul_f32_e32 v18, 0.5, v55
	v_pk_add_f32 v[40:41], v[40:41], v[44:45] neg_lo:[0,1] neg_hi:[0,1]
	v_mov_b32_e32 v105, v108
	v_pk_mul_f32 v[44:45], v[40:41], v[18:19]
	v_mov_b32_e32 v104, v40
	v_pk_fma_f32 v[56:57], v[56:57], v[44:45], v[44:45] op_sel:[0,1,0] op_sel_hi:[1,0,1]
	v_mov_b32_e32 v44, v45
	v_mov_b32_e32 v45, v18
	v_mul_f32_e32 v4, 0.5, v54
	v_pk_mul_f32 v[44:45], v[104:105], v[44:45]
	v_cvt_f32_f16_e32 v104, v26
	v_cvt_f32_f16_e32 v105, v27
	v_cvt_f32_f16_sdwa v27, v27 dst_sel:DWORD dst_unused:UNUSED_PAD src0_sel:WORD_1
	v_cvt_f32_f16_sdwa v26, v26 dst_sel:DWORD dst_unused:UNUSED_PAD src0_sel:WORD_1
	v_mul_f32_e32 v6, 0.5, v6
	v_pk_add_f32 v[110:111], v[4:5], v[56:57]
	v_pk_add_f32 v[44:45], v[44:45], v[44:45] op_sel:[0,1] op_sel_hi:[0,1] neg_lo:[0,1] neg_hi:[0,1]
	v_fma_f32 v111, v54, 0.5, -v56
	v_pk_add_f32 v[54:55], v[6:7], v[44:45] op_sel_hi:[0,1] neg_hi:[0,1]
	v_pk_mul_f32 v[44:45], v[54:55], v[26:27]
	v_pk_mul_f32 v[54:55], v[54:55], v[104:105]
	v_pk_fma_f32 v[56:57], v[110:111], v[104:105], v[44:45] neg_lo:[0,0,1] neg_hi:[0,0,1]
	v_pk_fma_f32 v[44:45], v[110:111], v[104:105], v[44:45]
	v_pk_fma_f32 v[104:105], v[110:111], v[26:27], v[54:55]
	v_pk_fma_f32 v[26:27], v[110:111], v[26:27], v[54:55] neg_lo:[0,0,1] neg_hi:[0,0,1]
	v_pk_add_f32 v[54:55], v[56:57], v[44:45] op_sel:[0,1] op_sel_hi:[1,0]
	v_pk_add_f32 v[110:111], v[104:105], v[26:27] op_sel_hi:[0,1] neg_lo:[0,1] neg_hi:[0,1]
	v_pk_add_f32 v[44:45], v[56:57], v[44:45] op_sel_hi:[0,1] neg_lo:[0,1] neg_hi:[0,1]
	v_pk_add_f32 v[26:27], v[104:105], v[26:27] op_sel:[0,1] op_sel_hi:[1,0]
	v_mov_b32_e32 v55, v111
	v_mov_b32_e32 v27, v45
	v_pk_mul_f32 v[26:27], v[26:27], 0.5 op_sel_hi:[1,0]
	v_mov_b32_e32 v47, v102
	v_pk_mul_f32 v[44:45], v[108:109], v[26:27] op_sel:[0,1] op_sel_hi:[0,0]
	v_pk_fma_f32 v[56:57], v[40:41], v[26:27], v[44:45] op_sel_hi:[0,1,1]
	v_pk_fma_f32 v[40:41], v[40:41], v[26:27], v[44:45] op_sel_hi:[0,1,1] neg_hi:[0,0,1]
	v_pk_fma_f32 v[44:45], v[54:55], 0.5, v[56:57] op_sel_hi:[1,0,1] neg_lo:[0,0,1] neg_hi:[0,0,1]
	v_pk_fma_f32 v[26:27], v[54:55], 0.5, v[40:41] op_sel_hi:[1,0,1]
	v_pk_fma_f32 v[56:57], v[54:55], 0.5, v[40:41] op_sel_hi:[1,0,1] neg_lo:[1,0,0] neg_hi:[1,0,0]
	v_pk_add_f32 v[40:41], v[106:107], v[42:43]
	v_pk_add_f32 v[42:43], v[42:43], v[106:107] neg_lo:[0,1] neg_hi:[0,1]
	v_mov_b32_e32 v45, v27
	v_mul_f32_e32 v6, 0.5, v43
	v_mov_b32_e32 v43, v41
	v_pk_mul_f32 v[120:121], v[44:45], s[46:47] op_sel_hi:[1,0]
	v_mul_f32_e32 v4, 0.5, v40
	v_pk_mov_b32 v[44:45], v[108:109], v[70:71] op_sel:[1,0]
	v_pk_mul_f32 v[40:41], v[42:43], s[44:45]
	v_cvt_f32_f16_sdwa v54, v20 dst_sel:DWORD dst_unused:UNUSED_PAD src0_sel:WORD_1
	v_pk_mul_f32 v[42:43], v[44:45], v[40:41] op_sel:[0,1] op_sel_hi:[1,0]
	v_cvt_f32_f16_e32 v55, v21
	v_cvt_f32_f16_sdwa v21, v21 dst_sel:DWORD dst_unused:UNUSED_PAD src0_sel:WORD_1
	v_cvt_f32_f16_e32 v20, v20
	v_pk_mul_f32 v[40:41], v[44:45], v[40:41]
	v_pk_add_f32 v[42:43], v[42:43], v[42:43] op_sel:[0,1] op_sel_hi:[0,1]
	v_pk_add_f32 v[104:105], v[4:5], v[42:43] op_sel_hi:[0,1] neg_hi:[0,1]
	s_nop 0
	v_pk_add_f32 v[40:41], v[40:41], v[40:41] op_sel:[0,1] op_sel_hi:[0,1] neg_lo:[0,1] neg_hi:[0,1]
	v_pk_add_f32 v[42:43], v[6:7], v[40:41] op_sel_hi:[0,1] neg_hi:[0,1]
	v_pk_mul_f32 v[40:41], v[42:43], v[20:21]
	v_pk_mul_f32 v[42:43], v[42:43], v[54:55]
	v_pk_fma_f32 v[40:41], v[104:105], v[54:55], v[40:41]
	v_pk_fma_f32 v[20:21], v[104:105], v[20:21], v[42:43] neg_lo:[0,0,1] neg_hi:[0,0,1]
	v_mov_b32_e32 v71, v109
	v_pk_add_f32 v[42:43], v[20:21], v[40:41] op_sel:[0,1] op_sel_hi:[1,0] neg_lo:[0,1]
	v_pk_add_f32 v[54:55], v[20:21], v[40:41] op_sel:[0,1] op_sel_hi:[1,0]
	v_pk_add_f32 v[20:21], v[40:41], v[20:21] op_sel:[1,0] op_sel_hi:[0,1] neg_lo:[0,1] neg_hi:[0,1]
	v_pk_mul_f32 v[42:43], v[42:43], 0.5 op_sel_hi:[1,0]
	v_mov_b32_e32 v55, v21
	v_mul_f32_e32 v4, v109, v42
	v_pk_fma_f32 v[104:105], v[44:45], v[42:43], v[4:5] op_sel_hi:[1,1,0] neg_lo:[1,0,0] neg_hi:[1,0,0]
	v_mul_f32_e32 v4, v109, v43
	v_pk_fma_f32 v[42:43], v[70:71], v[42:43], v[4:5] op_sel_hi:[1,1,0]
	v_sub_f32_e32 v6, v23, v103
	v_mov_b32_e32 v104, v42
	v_pk_fma_f32 v[40:41], v[54:55], 0.5, v[42:43] op_sel_hi:[1,0,1] neg_lo:[0,0,1] neg_hi:[0,0,1]
	v_pk_fma_f32 v[20:21], v[54:55], 0.5, v[104:105] op_sel_hi:[1,0,1]
	v_pk_add_f32 v[42:43], v[102:103], v[22:23]
	v_mov_b32_e32 v41, v21
	v_pk_mul_f32 v[128:129], v[40:41], s[46:47] op_sel_hi:[1,0]
	v_mul_f32_e32 v40, 0xbf0e39da, v83
	v_mov_b32_e32 v41, v22
	v_mul_f32_e32 v18, 0.5, v43
	v_pk_add_f32 v[22:23], v[40:41], v[46:47] neg_lo:[0,1] neg_hi:[0,1]
	v_mov_b32_e32 v47, v109
	v_pk_mul_f32 v[40:41], v[22:23], v[18:19]
	v_mov_b32_e32 v46, v22
	v_pk_fma_f32 v[44:45], v[44:45], v[40:41], v[40:41] op_sel:[0,1,0] op_sel_hi:[1,0,1]
	v_mov_b32_e32 v40, v41
	v_mov_b32_e32 v41, v18
	v_mul_f32_e32 v4, 0.5, v42
	v_pk_mul_f32 v[40:41], v[46:47], v[40:41]
	v_cvt_f32_f16_e32 v46, v10
	v_cvt_f32_f16_e32 v47, v11
	v_cvt_f32_f16_sdwa v11, v11 dst_sel:DWORD dst_unused:UNUSED_PAD src0_sel:WORD_1
	v_cvt_f32_f16_sdwa v10, v10 dst_sel:DWORD dst_unused:UNUSED_PAD src0_sel:WORD_1
	v_pk_fma_f32 v[70:71], v[54:55], 0.5, v[104:105] op_sel_hi:[1,0,1] neg_lo:[1,0,0] neg_hi:[1,0,0]
	v_mul_f32_e32 v6, 0.5, v6
	v_pk_add_f32 v[54:55], v[4:5], v[44:45]
	v_pk_add_f32 v[40:41], v[40:41], v[40:41] op_sel:[0,1] op_sel_hi:[0,1] neg_lo:[0,1] neg_hi:[0,1]
	v_fma_f32 v55, v42, 0.5, -v44
	v_pk_add_f32 v[42:43], v[6:7], v[40:41] op_sel_hi:[0,1] neg_hi:[0,1]
	v_pk_mul_f32 v[40:41], v[42:43], v[10:11]
	v_pk_mul_f32 v[42:43], v[42:43], v[46:47]
	v_pk_fma_f32 v[44:45], v[54:55], v[46:47], v[40:41] neg_lo:[0,0,1] neg_hi:[0,0,1]
	v_pk_fma_f32 v[40:41], v[54:55], v[46:47], v[40:41]
	v_pk_fma_f32 v[46:47], v[54:55], v[10:11], v[42:43]
	v_pk_fma_f32 v[10:11], v[54:55], v[10:11], v[42:43] neg_lo:[0,0,1] neg_hi:[0,0,1]
	v_pk_add_f32 v[42:43], v[44:45], v[40:41] op_sel:[0,1] op_sel_hi:[1,0]
	v_pk_add_f32 v[54:55], v[46:47], v[10:11] op_sel_hi:[0,1] neg_lo:[0,1] neg_hi:[0,1]
	v_pk_add_f32 v[40:41], v[44:45], v[40:41] op_sel_hi:[0,1] neg_lo:[0,1] neg_hi:[0,1]
	v_pk_add_f32 v[10:11], v[46:47], v[10:11] op_sel:[0,1] op_sel_hi:[1,0]
	v_mov_b32_e32 v43, v55
	v_mov_b32_e32 v11, v41
	v_pk_mul_f32 v[10:11], v[10:11], 0.5 op_sel_hi:[1,0]
	v_mov_b32_e32 v119, v98
	v_pk_mul_f32 v[40:41], v[108:109], v[10:11] op_sel:[1,1] op_sel_hi:[1,0]
	v_pk_fma_f32 v[76:77], v[76:77], 0.5, v[112:113] op_sel_hi:[1,0,1] neg_lo:[1,0,0] neg_hi:[1,0,0]
	v_pk_fma_f32 v[44:45], v[22:23], v[10:11], v[40:41] op_sel_hi:[0,1,1]
	v_pk_fma_f32 v[10:11], v[22:23], v[10:11], v[40:41] op_sel_hi:[0,1,1] neg_hi:[0,0,1]
	v_pk_fma_f32 v[22:23], v[42:43], 0.5, v[44:45] op_sel_hi:[1,0,1] neg_lo:[0,0,1] neg_hi:[0,0,1]
	v_pk_fma_f32 v[40:41], v[42:43], 0.5, v[10:11] op_sel_hi:[1,0,1]
	v_pk_fma_f32 v[54:55], v[42:43], 0.5, v[10:11] op_sel_hi:[1,0,1] neg_lo:[1,0,0] neg_hi:[1,0,0]
	v_pk_add_f32 v[10:11], v[100:101], v[14:15]
	v_pk_add_f32 v[14:15], v[14:15], v[100:101] neg_lo:[0,1] neg_hi:[0,1]
	v_mov_b32_e32 v23, v41
	v_mul_f32_e32 v6, 0.5, v15
	v_mov_b32_e32 v15, v11
	v_pk_mul_f32 v[150:151], v[22:23], s[46:47] op_sel_hi:[1,0]
	v_mul_f32_e32 v4, 0.5, v10
	v_pk_mov_b32 v[22:23], v[58:59], v[72:73] op_sel:[1,0]
	v_pk_mul_f32 v[10:11], v[14:15], s[44:45]
	v_cvt_f32_f16_sdwa v42, v8 dst_sel:DWORD dst_unused:UNUSED_PAD src0_sel:WORD_1
	v_pk_mul_f32 v[14:15], v[22:23], v[10:11] op_sel:[0,1] op_sel_hi:[1,0]
	v_cvt_f32_f16_e32 v43, v9
	v_cvt_f32_f16_sdwa v9, v9 dst_sel:DWORD dst_unused:UNUSED_PAD src0_sel:WORD_1
	v_cvt_f32_f16_e32 v8, v8
	v_pk_mul_f32 v[10:11], v[22:23], v[10:11]
	v_pk_add_f32 v[14:15], v[14:15], v[14:15] op_sel:[0,1] op_sel_hi:[0,1]
	v_pk_add_f32 v[44:45], v[4:5], v[14:15] op_sel_hi:[0,1] neg_hi:[0,1]
	s_nop 0
	v_pk_add_f32 v[10:11], v[10:11], v[10:11] op_sel:[0,1] op_sel_hi:[0,1] neg_lo:[0,1] neg_hi:[0,1]
	v_pk_add_f32 v[14:15], v[6:7], v[10:11] op_sel_hi:[0,1] neg_hi:[0,1]
	v_pk_mul_f32 v[10:11], v[14:15], v[8:9]
	v_pk_mul_f32 v[14:15], v[14:15], v[42:43]
	v_pk_fma_f32 v[10:11], v[44:45], v[42:43], v[10:11]
	v_pk_fma_f32 v[8:9], v[44:45], v[8:9], v[14:15] neg_lo:[0,0,1] neg_hi:[0,0,1]
	v_mov_b32_e32 v73, v59
	v_pk_add_f32 v[14:15], v[8:9], v[10:11] op_sel:[0,1] op_sel_hi:[1,0] neg_lo:[0,1]
	v_pk_add_f32 v[42:43], v[8:9], v[10:11] op_sel:[0,1] op_sel_hi:[1,0]
	v_pk_add_f32 v[8:9], v[10:11], v[8:9] op_sel:[1,0] op_sel_hi:[0,1] neg_lo:[0,1] neg_hi:[0,1]
	v_pk_mul_f32 v[14:15], v[14:15], 0.5 op_sel_hi:[1,0]
	v_mov_b32_e32 v43, v9
	v_mul_f32_e32 v4, v59, v14
	v_pk_fma_f32 v[44:45], v[22:23], v[14:15], v[4:5] op_sel_hi:[1,1,0] neg_lo:[1,0,0] neg_hi:[1,0,0]
	v_mul_f32_e32 v4, v59, v15
	v_pk_fma_f32 v[14:15], v[72:73], v[14:15], v[4:5] op_sel_hi:[1,1,0]
	v_sub_f32_e32 v6, v37, v99
	v_mov_b32_e32 v44, v14
	v_pk_fma_f32 v[8:9], v[42:43], 0.5, v[14:15] op_sel_hi:[1,0,1] neg_lo:[0,0,1] neg_hi:[0,0,1]
	v_pk_fma_f32 v[10:11], v[42:43], 0.5, v[44:45] op_sel_hi:[1,0,1]
	v_pk_add_f32 v[14:15], v[98:99], v[36:37]
	v_mov_b32_e32 v9, v11
	v_pk_mul_f32 v[168:169], v[8:9], s[46:47] op_sel_hi:[1,0]
	v_mul_f32_e32 v8, 0xbf7b14be, v83
	v_mov_b32_e32 v9, v36
	v_mul_f32_e32 v18, 0.5, v15
	v_pk_add_f32 v[8:9], v[8:9], v[118:119] neg_lo:[0,1] neg_hi:[0,1]
	v_pk_fma_f32 v[72:73], v[42:43], 0.5, v[44:45] op_sel_hi:[1,0,1] neg_lo:[1,0,0] neg_hi:[1,0,0]
	v_pk_mul_f32 v[36:37], v[8:9], v[18:19]
	v_mov_b32_e32 v42, v8
	v_pk_fma_f32 v[22:23], v[22:23], v[36:37], v[36:37] op_sel:[0,1,0] op_sel_hi:[1,0,1]
	v_mov_b32_e32 v43, v59
	v_mov_b32_e32 v36, v37
	v_mov_b32_e32 v37, v18
	v_mul_f32_e32 v4, 0.5, v14
	v_pk_mul_f32 v[36:37], v[42:43], v[36:37]
	v_cvt_f32_f16_e32 v44, v2
	v_cvt_f32_f16_e32 v45, v3
	v_cvt_f32_f16_sdwa v3, v3 dst_sel:DWORD dst_unused:UNUSED_PAD src0_sel:WORD_1
	v_cvt_f32_f16_sdwa v2, v2 dst_sel:DWORD dst_unused:UNUSED_PAD src0_sel:WORD_1
	v_mul_f32_e32 v6, 0.5, v6
	v_pk_add_f32 v[46:47], v[4:5], v[22:23]
	v_fma_f32 v4, v14, 0.5, -v22
	v_pk_add_f32 v[22:23], v[36:37], v[36:37] op_sel:[0,1] op_sel_hi:[0,1] neg_lo:[0,1] neg_hi:[0,1]
	v_pk_add_f32 v[36:37], v[6:7], v[22:23] op_sel_hi:[0,1] neg_hi:[0,1]
	v_mov_b32_e32 v14, v46
	v_mov_b32_e32 v15, v4
	v_pk_mul_f32 v[22:23], v[4:5], v[44:45] op_sel_hi:[0,1]
	v_pk_mul_f32 v[82:83], v[36:37], v[2:3]
	v_pk_mul_f32 v[46:47], v[46:47], v[2:3]
	v_pk_mul_f32 v[36:37], v[36:37], v[44:45]
	v_pk_fma_f32 v[98:99], v[14:15], v[44:45], v[82:83] neg_lo:[0,0,1] neg_hi:[0,0,1]
	v_pk_fma_f32 v[2:3], v[14:15], v[2:3], v[36:37] neg_lo:[0,0,1] neg_hi:[0,0,1]
	v_add_f32_e32 v4, v23, v83
	v_add_f32_e32 v6, v46, v36
	v_pk_add_f32 v[22:23], v[6:7], v[2:3] op_sel_hi:[0,1] neg_lo:[0,1] neg_hi:[0,1]
	v_pk_add_f32 v[36:37], v[98:99], v[4:5] op_sel_hi:[1,0] neg_lo:[0,1] neg_hi:[0,1]
	v_pk_add_f32 v[2:3], v[6:7], v[2:3] op_sel_hi:[0,1]
	v_mov_b32_e32 v37, v3
	v_pk_mul_f32 v[2:3], v[36:37], 0.5 op_sel_hi:[1,0]
	v_pk_add_f32 v[14:15], v[98:99], v[4:5] op_sel_hi:[1,0]
	v_mul_f32_e32 v4, v59, v3
	v_pk_fma_f32 v[36:37], v[42:43], v[2:3], v[4:5] op_sel_hi:[1,1,0] neg_lo:[0,0,1] neg_hi:[0,0,1]
	v_pk_mov_b32 v[42:43], v[58:59], v[8:9] op_sel:[1,0]
	v_mul_f32_e32 v4, v8, v3
	v_pk_fma_f32 v[2:3], v[42:43], v[2:3], v[4:5] op_sel_hi:[1,1,0]
	v_mov_b32_e32 v15, v23
	v_pk_fma_f32 v[8:9], v[14:15], 0.5, v[2:3] op_sel_hi:[1,0,1] neg_lo:[0,0,1] neg_hi:[0,0,1]
	v_pk_fma_f32 v[42:43], v[14:15], 0.5, v[36:37] op_sel_hi:[1,0,0]
	v_pk_fma_f32 v[2:3], v[14:15], 0.5, v[2:3] op_sel_hi:[1,0,1]
	v_mov_b32_e32 v9, v43
	v_pk_fma_f32 v[58:59], v[22:23], 0.5, v[36:37] op_sel_hi:[1,0,0] neg_lo:[1,0,0] neg_hi:[1,0,0]
	v_pk_mul_f32 v[144:145], v[8:9], s[46:47] op_sel_hi:[1,0]
	v_mov_b32_e32 v58, v2
	v_mov_b32_e32 v72, v10
	v_mov_b32_e32 v54, v40
	v_mov_b32_e32 v70, v20
	v_mov_b32_e32 v56, v26
	v_mov_b32_e32 v76, v38
	v_mov_b32_e32 v52, v34
	v_mov_b32_e32 v74, v86
	v_mov_b32_e32 v48, v84
	v_mov_b32_e32 v50, v60
	v_mov_b32_e32 v28, v66
	v_mov_b32_e32 v32, v96
	v_mov_b32_e32 v12, v88
	v_mov_b32_e32 v16, v92
	v_mov_b32_e32 v4, v138
	v_mov_b32_e32 v6, v122

.LBB0_538:
	s_or_b64 exec, exec, s[0:1]
	v_pk_mul_f32 v[22:23], v[32:33], s[46:47] op_sel_hi:[1,0]
	v_pk_add_f32 v[26:27], v[24:25], v[30:31]
	v_pk_add_f32 v[24:25], v[24:25], v[30:31] neg_lo:[0,1] neg_hi:[0,1]
	v_pk_add_f32 v[30:31], v[64:65], v[68:69]
	v_pk_add_f32 v[246:247], v[64:65], v[68:69] neg_lo:[0,1] neg_hi:[0,1]
	v_pk_add_f32 v[34:35], v[62:63], v[90:91]
	v_pk_add_f32 v[38:39], v[94:95], v[80:81]
	v_pk_add_f32 v[68:69], v[26:27], v[30:31]
	v_pk_add_f32 v[26:27], v[26:27], v[30:31] neg_lo:[0,1] neg_hi:[0,1]
	v_pk_mul_f32 v[20:21], v[50:51], s[46:47] op_sel_hi:[1,0]
	v_pk_add_f32 v[36:37], v[62:63], v[90:91] neg_lo:[0,1] neg_hi:[0,1]
	v_pk_add_f32 v[42:43], v[78:79], v[136:137]
	v_pk_add_f32 v[46:47], v[130:131], v[120:121]
	v_pk_add_f32 v[32:33], v[24:25], v[246:247] op_sel:[0,1] op_sel_hi:[1,0] neg_lo:[0,1]
	v_pk_add_f32 v[24:25], v[24:25], v[246:247] op_sel:[0,1] op_sel_hi:[1,0] neg_hi:[0,1]
	v_pk_add_f32 v[30:31], v[34:35], v[38:39]
	v_pk_add_f32 v[34:35], v[34:35], v[38:39] neg_lo:[0,1] neg_hi:[0,1]
	v_pk_add_f32 v[38:39], v[94:95], v[80:81] neg_lo:[0,1] neg_hi:[0,1]
	v_pk_add_f32 v[44:45], v[78:79], v[136:137] neg_lo:[0,1] neg_hi:[0,1]
	v_pk_add_f32 v[60:61], v[128:129], v[150:151]
	v_pk_add_f32 v[64:65], v[168:169], v[144:145]
	v_pk_add_f32 v[40:41], v[36:37], v[38:39] op_sel:[0,1] op_sel_hi:[1,0] neg_lo:[0,1]
	v_pk_add_f32 v[36:37], v[36:37], v[38:39] op_sel:[0,1] op_sel_hi:[1,0] neg_hi:[0,1]
	v_pk_add_f32 v[38:39], v[42:43], v[46:47]
	v_pk_add_f32 v[42:43], v[42:43], v[46:47] neg_lo:[0,1] neg_hi:[0,1]
	v_pk_add_f32 v[46:47], v[130:131], v[120:121] neg_lo:[0,1] neg_hi:[0,1]
	v_pk_add_f32 v[62:63], v[128:129], v[150:151] neg_lo:[0,1] neg_hi:[0,1]
	v_pk_add_f32 v[50:51], v[44:45], v[46:47] op_sel:[0,1] op_sel_hi:[1,0] neg_lo:[0,1]
	v_pk_add_f32 v[44:45], v[44:45], v[46:47] op_sel:[0,1] op_sel_hi:[1,0] neg_hi:[0,1]
	v_pk_add_f32 v[46:47], v[60:61], v[64:65]
	v_pk_add_f32 v[246:247], v[60:61], v[64:65] neg_lo:[0,1] neg_hi:[0,1]
	v_pk_add_f32 v[64:65], v[168:169], v[144:145] neg_lo:[0,1] neg_hi:[0,1]
	s_mov_b32 s66, s37
	s_mov_b32 s67, s36
	v_pk_add_f32 v[66:67], v[62:63], v[64:65] op_sel:[0,1] op_sel_hi:[1,0] neg_lo:[0,1]
	v_pk_add_f32 v[62:63], v[62:63], v[64:65] op_sel:[0,1] op_sel_hi:[1,0] neg_hi:[0,1]
	v_pk_add_f32 v[64:65], v[68:69], v[30:31]
	v_pk_add_f32 v[30:31], v[68:69], v[30:31] neg_lo:[0,1] neg_hi:[0,1]
	s_mov_b32 s0, s37
	v_pk_mul_f32 v[68:69], v[40:41], s[66:67]
	s_mov_b32 s68, s19
	v_pk_fma_f32 v[40:41], v[40:41], s[0:1], v[68:69] op_sel:[0,0,1] op_sel_hi:[1,0,0]
	s_mov_b32 s69, s18
	v_pk_add_f32 v[68:69], v[32:33], v[40:41]
	v_pk_add_f32 v[32:33], v[32:33], v[40:41] neg_lo:[0,1] neg_hi:[0,1]
	v_xor_b32_e32 v40, 0x80000000, v35
	v_mov_b32_e32 v41, v34
	v_pk_add_f32 v[34:35], v[26:27], v[40:41]
	v_pk_add_f32 v[26:27], v[26:27], v[40:41] neg_lo:[0,1] neg_hi:[0,1]
	v_pk_mul_f32 v[40:41], v[36:37], s[66:67]
	s_mov_b32 s72, s19
	v_pk_fma_f32 v[36:37], v[36:37], s[0:1], v[40:41] op_sel:[0,0,1] op_sel_hi:[1,0,0] neg_lo:[1,0,0] neg_hi:[1,0,0]
	v_pk_mul_f32 v[2:3], v[72:73], s[46:47] op_sel_hi:[1,0]
	v_pk_add_f32 v[40:41], v[24:25], v[36:37]
	v_pk_add_f32 v[24:25], v[24:25], v[36:37] neg_lo:[0,1] neg_hi:[0,1]
	v_pk_add_f32 v[36:37], v[38:39], v[46:47]
	v_pk_add_f32 v[38:39], v[38:39], v[46:47] neg_lo:[0,1] neg_hi:[0,1]
	v_pk_mul_f32 v[46:47], v[66:67], s[66:67]
	v_pk_mul_f32 v[8:9], v[70:71], s[46:47] op_sel_hi:[1,0]
	v_pk_fma_f32 v[46:47], v[66:67], s[0:1], v[46:47] op_sel:[0,0,1] op_sel_hi:[1,0,0]
	v_pk_mul_f32 v[10:11], v[76:77], s[46:47] op_sel_hi:[1,0]
	v_pk_add_f32 v[66:67], v[50:51], v[46:47]
	v_pk_add_f32 v[46:47], v[50:51], v[46:47] neg_lo:[0,1] neg_hi:[0,1]
	v_pk_add_f32 v[60:61], v[42:43], v[246:247] op_sel:[0,1] op_sel_hi:[1,0] neg_lo:[0,1]
	v_pk_add_f32 v[42:43], v[42:43], v[246:247] op_sel:[0,1] op_sel_hi:[1,0] neg_hi:[0,1]
	v_pk_mul_f32 v[50:51], v[62:63], s[66:67]
	v_pk_mul_f32 v[14:15], v[74:75], s[46:47] op_sel_hi:[1,0]
	v_pk_fma_f32 v[50:51], v[62:63], s[0:1], v[50:51] op_sel:[0,0,1] op_sel_hi:[1,0,0] neg_lo:[1,0,0] neg_hi:[1,0,0]
	v_pk_mul_f32 v[16:17], v[16:17], s[46:47] op_sel_hi:[1,0]
	v_pk_add_f32 v[62:63], v[44:45], v[50:51]
	v_pk_add_f32 v[44:45], v[44:45], v[50:51] neg_lo:[0,1] neg_hi:[0,1]
	v_pk_add_f32 v[50:51], v[64:65], v[36:37]
	v_pk_add_f32 v[36:37], v[64:65], v[36:37] neg_lo:[0,1] neg_hi:[0,1]
	v_pk_mul_f32 v[64:65], v[66:67], s[68:69]
	v_pk_mul_f32 v[6:7], v[6:7], s[46:47] op_sel_hi:[1,0]
	v_pk_fma_f32 v[64:65], v[66:67], s[16:17], v[64:65] op_sel:[0,0,1] op_sel_hi:[1,0,0]
	s_mov_b32 s17, s40
	v_pk_add_f32 v[66:67], v[68:69], v[64:65]
	v_pk_add_f32 v[64:65], v[68:69], v[64:65] neg_lo:[0,1] neg_hi:[0,1]
	v_pk_mul_f32 v[68:69], v[60:61], s[66:67]
	s_ashr_i32 s63, s62, 31
	v_pk_fma_f32 v[60:61], s[0:1], v[60:61], v[68:69] op_sel:[0,0,1] op_sel_hi:[0,1,0]
	v_pk_add_f32 v[68:69], v[34:35], v[60:61]
	v_pk_add_f32 v[34:35], v[34:35], v[60:61] neg_lo:[0,1] neg_hi:[0,1]
	v_pk_mul_f32 v[60:61], v[62:63], s[16:17]
	s_nop 0
	v_pk_fma_f32 v[60:61], s[72:73], v[62:63], v[60:61] op_sel:[0,0,1] op_sel_hi:[0,1,0]
	v_pk_add_f32 v[62:63], v[40:41], v[60:61]
	v_pk_add_f32 v[40:41], v[40:41], v[60:61] neg_lo:[0,1] neg_hi:[0,1]
	v_xor_b32_e32 v60, 0x80000000, v39
	v_mov_b32_e32 v61, v38
	v_pk_add_f32 v[38:39], v[30:31], v[60:61]
	v_pk_add_f32 v[30:31], v[30:31], v[60:61] neg_lo:[0,1] neg_hi:[0,1]
	v_pk_mul_f32 v[60:61], v[46:47], s[16:17]
	s_nop 0
	v_pk_fma_f32 v[46:47], s[72:73], v[46:47], v[60:61] op_sel:[0,0,1] op_sel_hi:[0,1,0] neg_lo:[0,1,0] neg_hi:[0,1,0]
	v_pk_add_f32 v[60:61], v[32:33], v[46:47]
	v_pk_add_f32 v[32:33], v[32:33], v[46:47] neg_lo:[0,1] neg_hi:[0,1]
	v_pk_mul_f32 v[46:47], v[42:43], s[66:67]
	s_nop 0
	v_pk_fma_f32 v[42:43], s[0:1], v[42:43], v[46:47] op_sel:[0,0,1] op_sel_hi:[0,1,0] neg_lo:[0,1,0] neg_hi:[0,1,0]
	v_pk_add_f32 v[46:47], v[26:27], v[42:43]
	v_pk_add_f32 v[26:27], v[26:27], v[42:43] neg_lo:[0,1] neg_hi:[0,1]
	v_pk_mul_f32 v[42:43], v[44:45], s[68:69]
	s_nop 0
	v_pk_fma_f32 v[42:43], s[16:17], v[44:45], v[42:43] op_sel:[0,0,1] op_sel_hi:[0,1,0] neg_lo:[0,1,0] neg_hi:[0,1,0]
	v_pk_add_f32 v[44:45], v[24:25], v[42:43]
	v_pk_add_f32 v[24:25], v[24:25], v[42:43] neg_lo:[0,1] neg_hi:[0,1]
	v_pk_fma_f32 v[42:43], v[58:59], s[46:47], v[2:3] op_sel_hi:[1,0,1]
	v_pk_fma_f32 v[2:3], v[58:59], s[46:47], v[2:3] op_sel_hi:[1,0,1] neg_lo:[0,0,1] neg_hi:[0,0,1]
	v_pk_fma_f32 v[58:59], v[54:55], s[46:47], v[8:9] op_sel_hi:[1,0,1]
	v_pk_fma_f32 v[246:247], v[54:55], s[46:47], v[8:9] op_sel_hi:[1,0,1] neg_lo:[0,0,1] neg_hi:[0,0,1]
	v_pk_fma_f32 v[54:55], v[56:57], s[46:47], v[10:11] op_sel_hi:[1,0,1]
	v_pk_fma_f32 v[10:11], v[56:57], s[46:47], v[10:11] op_sel_hi:[1,0,1] neg_lo:[0,0,1] neg_hi:[0,0,1]
	v_pk_fma_f32 v[56:57], v[52:53], s[46:47], v[14:15] op_sel_hi:[1,0,1]
	v_pk_fma_f32 v[14:15], v[52:53], s[46:47], v[14:15] op_sel_hi:[1,0,1] neg_lo:[0,0,1] neg_hi:[0,0,1]
	v_pk_fma_f32 v[52:53], v[48:49], s[46:47], v[20:21] op_sel_hi:[1,0,1]
	v_pk_fma_f32 v[20:21], v[48:49], s[46:47], v[20:21] op_sel_hi:[1,0,1] neg_lo:[0,0,1] neg_hi:[0,0,1]
	v_pk_fma_f32 v[48:49], v[28:29], s[46:47], v[22:23] op_sel_hi:[1,0,1]
	v_pk_fma_f32 v[22:23], v[28:29], s[46:47], v[22:23] op_sel_hi:[1,0,1] neg_lo:[0,0,1] neg_hi:[0,0,1]
	v_pk_fma_f32 v[28:29], v[12:13], s[46:47], v[16:17] op_sel_hi:[1,0,1]
	v_pk_fma_f32 v[12:13], v[12:13], s[46:47], v[16:17] op_sel_hi:[1,0,1] neg_lo:[0,0,1] neg_hi:[0,0,1]
	v_pk_fma_f32 v[16:17], v[4:5], s[46:47], v[6:7] op_sel_hi:[1,0,1]
	v_pk_fma_f32 v[4:5], v[4:5], s[46:47], v[6:7] op_sel_hi:[1,0,1] neg_lo:[0,0,1] neg_hi:[0,0,1]
	v_pk_add_f32 v[6:7], v[58:59], v[42:43]
	v_pk_add_f32 v[42:43], v[42:43], v[58:59] neg_lo:[0,1] neg_hi:[0,1]
	v_pk_add_f32 v[8:9], v[2:3], v[246:247] op_sel:[0,1] op_sel_hi:[1,0] neg_lo:[0,1]
	v_pk_add_f32 v[2:3], v[2:3], v[246:247] op_sel:[0,1] op_sel_hi:[1,0] neg_hi:[0,1]
	v_pk_add_f32 v[58:59], v[56:57], v[54:55]
	v_pk_add_f32 v[54:55], v[54:55], v[56:57] neg_lo:[0,1] neg_hi:[0,1]
	v_xor_b32_e32 v56, 0x80000000, v15
	v_mov_b32_e32 v57, v14
	v_pk_add_f32 v[14:15], v[10:11], v[56:57]
	v_pk_add_f32 v[10:11], v[10:11], v[56:57] neg_lo:[0,1] neg_hi:[0,1]
	v_pk_add_f32 v[56:57], v[48:49], v[52:53]
	v_pk_add_f32 v[48:49], v[52:53], v[48:49] neg_lo:[0,1] neg_hi:[0,1]
	v_xor_b32_e32 v52, 0x80000000, v23
	v_mov_b32_e32 v53, v22
	v_pk_add_f32 v[22:23], v[20:21], v[52:53]
	v_pk_add_f32 v[20:21], v[20:21], v[52:53] neg_lo:[0,1] neg_hi:[0,1]
	v_pk_add_f32 v[52:53], v[16:17], v[28:29]
	v_pk_add_f32 v[246:247], v[28:29], v[16:17] neg_lo:[0,1] neg_hi:[0,1]
	v_xor_b32_e32 v28, 0x80000000, v5
	v_mov_b32_e32 v29, v4
	v_pk_add_f32 v[4:5], v[12:13], v[28:29]
	v_pk_add_f32 v[12:13], v[12:13], v[28:29] neg_lo:[0,1] neg_hi:[0,1]
	v_pk_add_f32 v[28:29], v[58:59], v[6:7]
	v_pk_add_f32 v[6:7], v[6:7], v[58:59] neg_lo:[0,1] neg_hi:[0,1]
	v_pk_mul_f32 v[58:59], v[14:15], s[66:67]
	s_nop 0
	v_pk_fma_f32 v[14:15], s[0:1], v[14:15], v[58:59] op_sel:[0,0,1] op_sel_hi:[0,1,0]
	v_pk_add_f32 v[58:59], v[14:15], v[8:9]
	v_pk_add_f32 v[8:9], v[8:9], v[14:15] neg_lo:[0,1] neg_hi:[0,1]
	v_xor_b32_e32 v14, 0x80000000, v55
	v_mov_b32_e32 v15, v54
	v_pk_add_f32 v[54:55], v[14:15], v[42:43]
	v_pk_add_f32 v[14:15], v[42:43], v[14:15] neg_lo:[0,1] neg_hi:[0,1]
	v_pk_mul_f32 v[42:43], v[10:11], s[66:67]
	s_nop 0
	v_pk_fma_f32 v[10:11], s[0:1], v[10:11], v[42:43] op_sel:[0,0,1] op_sel_hi:[0,1,0] neg_lo:[0,1,0] neg_hi:[0,1,0]
	v_pk_add_f32 v[42:43], v[10:11], v[2:3]
	v_pk_add_f32 v[2:3], v[2:3], v[10:11] neg_lo:[0,1] neg_hi:[0,1]
	v_pk_add_f32 v[10:11], v[52:53], v[56:57]
	v_pk_add_f32 v[52:53], v[56:57], v[52:53] neg_lo:[0,1] neg_hi:[0,1]
	v_pk_mul_f32 v[56:57], v[4:5], s[66:67]
	s_nop 0
	v_pk_fma_f32 v[4:5], s[0:1], v[4:5], v[56:57] op_sel:[0,0,1] op_sel_hi:[0,1,0]
	v_pk_add_f32 v[56:57], v[4:5], v[22:23]
	v_pk_add_f32 v[4:5], v[22:23], v[4:5] neg_lo:[0,1] neg_hi:[0,1]
	v_pk_add_f32 v[16:17], v[246:247], v[48:49] op_sel:[1,0] op_sel_hi:[0,1] neg_lo:[1,0]
	v_pk_add_f32 v[22:23], v[48:49], v[246:247] op_sel:[0,1] op_sel_hi:[1,0] neg_hi:[0,1]
	v_pk_mul_f32 v[48:49], v[12:13], s[66:67]
	s_nop 0
	v_pk_fma_f32 v[12:13], s[0:1], v[12:13], v[48:49] op_sel:[0,0,1] op_sel_hi:[0,1,0] neg_lo:[0,1,0] neg_hi:[0,1,0]
	v_pk_add_f32 v[48:49], v[12:13], v[20:21]
	v_pk_add_f32 v[12:13], v[20:21], v[12:13] neg_lo:[0,1] neg_hi:[0,1]
	v_pk_add_f32 v[20:21], v[10:11], v[28:29]
	v_pk_add_f32 v[10:11], v[28:29], v[10:11] neg_lo:[0,1] neg_hi:[0,1]
	v_pk_mul_f32 v[28:29], v[56:57], s[68:69]
	s_nop 0
	v_pk_fma_f32 v[28:29], s[16:17], v[56:57], v[28:29] op_sel:[0,0,1] op_sel_hi:[0,1,0]
	v_pk_add_f32 v[56:57], v[28:29], v[58:59]
	v_pk_add_f32 v[28:29], v[58:59], v[28:29] neg_lo:[0,1] neg_hi:[0,1]
	v_pk_mul_f32 v[58:59], v[16:17], s[66:67]
	s_nop 0
	v_pk_fma_f32 v[16:17], s[0:1], v[16:17], v[58:59] op_sel:[0,0,1] op_sel_hi:[0,1,0]
	v_pk_add_f32 v[58:59], v[16:17], v[54:55]
	v_pk_add_f32 v[16:17], v[54:55], v[16:17] neg_lo:[0,1] neg_hi:[0,1]
	v_pk_mul_f32 v[54:55], v[48:49], s[16:17]
	s_nop 0
	v_pk_fma_f32 v[48:49], s[72:73], v[48:49], v[54:55] op_sel:[0,0,1] op_sel_hi:[0,1,0]
	v_pk_add_f32 v[54:55], v[48:49], v[42:43]
	v_pk_add_f32 v[42:43], v[42:43], v[48:49] neg_lo:[0,1] neg_hi:[0,1]
	v_xor_b32_e32 v48, 0x80000000, v53
	v_mov_b32_e32 v49, v52
	v_pk_add_f32 v[52:53], v[48:49], v[6:7]
	v_pk_add_f32 v[6:7], v[6:7], v[48:49] neg_lo:[0,1] neg_hi:[0,1]
	v_pk_mul_f32 v[48:49], v[4:5], s[16:17]
	s_nop 0
	v_pk_fma_f32 v[4:5], s[72:73], v[4:5], v[48:49] op_sel:[0,0,1] op_sel_hi:[0,1,0] neg_lo:[0,1,0] neg_hi:[0,1,0]
	v_pk_add_f32 v[48:49], v[4:5], v[8:9]
	v_pk_add_f32 v[4:5], v[8:9], v[4:5] neg_lo:[0,1] neg_hi:[0,1]
	v_pk_mul_f32 v[8:9], v[22:23], s[66:67]
	s_nop 0
	v_pk_fma_f32 v[8:9], s[0:1], v[22:23], v[8:9] op_sel:[0,0,1] op_sel_hi:[0,1,0] neg_lo:[0,1,0] neg_hi:[0,1,0]
	v_pk_add_f32 v[22:23], v[8:9], v[14:15]
	v_pk_add_f32 v[8:9], v[14:15], v[8:9] neg_lo:[0,1] neg_hi:[0,1]
	v_pk_mul_f32 v[14:15], v[12:13], s[68:69]
	s_nop 0
	v_pk_fma_f32 v[12:13], s[16:17], v[12:13], v[14:15] op_sel:[0,0,1] op_sel_hi:[0,1,0] neg_lo:[0,1,0] neg_hi:[0,1,0]
	v_pk_add_f32 v[14:15], v[12:13], v[2:3]
	v_pk_add_f32 v[2:3], v[2:3], v[12:13] neg_lo:[0,1] neg_hi:[0,1]
	ds_write_b64 v211, v[50:51]
	ds_write_b64 v212, v[20:21]
	ds_write_b64 v211, v[66:67] offset:8
	ds_write_b64 v212, v[56:57] offset:8
	ds_write_b64 v211, v[68:69] offset:16
	ds_write_b64 v212, v[58:59] offset:16
	ds_write_b64 v211, v[62:63] offset:24
	ds_write_b64 v212, v[54:55] offset:24
	ds_write_b64 v211, v[38:39] offset:32
	ds_write_b64 v212, v[52:53] offset:32
	ds_write_b64 v211, v[60:61] offset:40
	ds_write_b64 v212, v[48:49] offset:40
	ds_write_b64 v211, v[46:47] offset:48
	ds_write_b64 v212, v[22:23] offset:48
	ds_write_b64 v211, v[44:45] offset:56
	ds_write_b64 v212, v[14:15] offset:56
	ds_write_b64 v211, v[36:37] offset:64
	ds_write_b64 v212, v[10:11] offset:64
	ds_write_b64 v211, v[64:65] offset:72
	ds_write_b64 v212, v[28:29] offset:72
	ds_write_b64 v211, v[34:35] offset:80
	ds_write_b64 v212, v[16:17] offset:80
	ds_write_b64 v211, v[40:41] offset:88
	ds_write_b64 v212, v[42:43] offset:88
	ds_write_b64 v211, v[30:31] offset:96
	ds_write_b64 v212, v[6:7] offset:96
	ds_write_b64 v211, v[32:33] offset:104
	ds_write_b64 v212, v[4:5] offset:104
	ds_write_b64 v211, v[26:27] offset:112
	ds_write_b64 v212, v[8:9] offset:112
	ds_write_b64 v211, v[24:25] offset:120
	ds_write_b64 v212, v[2:3] offset:120
	v_mov_b32_e32 v2, v210
	s_waitcnt lgkmcnt(0)
	s_barrier
	s_nop 0
	v_and_b32_e32 v4, 15, v2
	v_cvt_f32_ubyte0_e32 v3, v4
	v_mul_f32_e32 v5, 0x3b800000, v3
	v_sin_f32_e32 v3, v5
	v_lshlrev_b32_e32 v6, 4, v2
	v_cos_f32_e32 v2, v5
	v_lshlrev_b32_e32 v7, 3, v4
	v_xor_b32_e32 v16, 0x80000000, v3
	v_mov_b32_e32 v17, v3
	v_pk_mul_f32 v[4:5], v[2:3], v[16:17] op_sel:[1,0] op_sel_hi:[0,1]
	v_pk_fma_f32 v[40:41], v[2:3], v[2:3], v[4:5] op_sel_hi:[0,1,1]
	v_pk_mul_f32 v[4:5], v[16:17], v[40:41] op_sel:[0,1] op_sel_hi:[1,0]
	v_xor_b32_e32 v44, 0x80000000, v41
	v_mov_b32_e32 v45, v41
	v_pk_fma_f32 v[42:43], v[2:3], v[40:41], v[4:5] op_sel_hi:[0,1,1]
	v_pk_mul_f32 v[4:5], v[40:41], v[44:45] op_sel:[1,0] op_sel_hi:[0,1]
	v_pk_fma_f32 v[46:47], v[40:41], v[40:41], v[4:5] op_sel_hi:[1,0,1]
	v_xor_b32_e32 v50, 0x80000000, v43
	v_pk_mul_f32 v[4:5], v[16:17], v[46:47] op_sel:[0,1] op_sel_hi:[1,0]
	v_mov_b32_e32 v51, v43
	v_pk_fma_f32 v[52:53], v[2:3], v[46:47], v[4:5] op_sel_hi:[0,1,1]
	v_pk_mul_f32 v[4:5], v[44:45], v[46:47] op_sel:[0,1] op_sel_hi:[1,0]
	v_xor_b32_e32 v48, 0x80000000, v47
	v_mov_b32_e32 v49, v47
	v_pk_fma_f32 v[56:57], v[40:41], v[46:47], v[4:5] op_sel_hi:[0,1,1]
	v_pk_mul_f32 v[4:5], v[46:47], v[50:51] op_sel:[1,0] op_sel_hi:[0,1]
	v_pk_fma_f32 v[60:61], v[46:47], v[42:43], v[4:5] op_sel_hi:[1,0,1]
	v_pk_mul_f32 v[4:5], v[46:47], v[48:49] op_sel:[1,0] op_sel_hi:[0,1]
	v_pk_fma_f32 v[64:65], v[46:47], v[46:47], v[4:5] op_sel_hi:[1,0,1]
	v_xor_b32_e32 v54, 0x80000000, v53
	v_pk_mul_f32 v[4:5], v[16:17], v[64:65] op_sel:[0,1] op_sel_hi:[1,0]
	v_mov_b32_e32 v55, v53
	v_pk_fma_f32 v[68:69], v[2:3], v[64:65], v[4:5] op_sel_hi:[0,1,1]
	v_pk_mul_f32 v[4:5], v[44:45], v[64:65] op_sel:[0,1] op_sel_hi:[1,0]
	v_xor_b32_e32 v58, 0x80000000, v57
	v_pk_fma_f32 v[72:73], v[40:41], v[64:65], v[4:5] op_sel_hi:[0,1,1]
	v_pk_mul_f32 v[4:5], v[50:51], v[64:65] op_sel:[0,1] op_sel_hi:[1,0]
	v_mov_b32_e32 v59, v57
	v_pk_fma_f32 v[76:77], v[42:43], v[64:65], v[4:5] op_sel_hi:[0,1,1]
	v_pk_mul_f32 v[4:5], v[48:49], v[64:65] op_sel:[0,1] op_sel_hi:[1,0]
	v_xor_b32_e32 v62, 0x80000000, v61
	v_pk_fma_f32 v[80:81], v[46:47], v[64:65], v[4:5] op_sel_hi:[0,1,1]
	v_pk_mul_f32 v[4:5], v[16:17], v[80:81] op_sel:[0,1] op_sel_hi:[1,0]
	v_mov_b32_e32 v63, v61
	v_pk_fma_f32 v[84:85], v[2:3], v[80:81], v[4:5] op_sel_hi:[0,1,1]
	v_pk_mul_f32 v[4:5], v[44:45], v[80:81] op_sel:[0,1] op_sel_hi:[1,0]
	v_and_b32_e32 v3, 0xffffff00, v6
	v_pk_fma_f32 v[88:89], v[40:41], v[80:81], v[4:5] op_sel_hi:[0,1,1]
	v_pk_mul_f32 v[4:5], v[50:51], v[80:81] op_sel:[0,1] op_sel_hi:[1,0]
	v_xor_b32_e32 v66, 0x80000000, v65
	v_pk_fma_f32 v[92:93], v[42:43], v[80:81], v[4:5] op_sel_hi:[0,1,1]
	v_lshlrev_b32_e32 v4, 3, v3
	v_add3_u32 v18, 0, v7, v4
	v_ashrrev_i32_e32 v4, 2, v3
	v_add_u32_e32 v98, v18, v4
	ds_read2_b64 v[4:7], v98 offset1:16
	ds_read2_b64 v[8:11], v98 offset0:33 offset1:49
	ds_read2_b64 v[12:15], v98 offset0:66 offset1:82
	ds_read2_b64 v[20:23], v98 offset0:132 offset1:148
	ds_read2_b64 v[24:27], v98 offset0:99 offset1:115
	ds_read2_b64 v[28:31], v98 offset0:165 offset1:181
	ds_read2_b64 v[32:35], v98 offset0:198 offset1:214
	ds_read2_b64 v[36:39], v98 offset0:231 offset1:247
	s_waitcnt lgkmcnt(4)
	v_pk_mul_f32 v[96:97], v[16:17], v[20:21] op_sel:[0,1] op_sel_hi:[1,0]
	v_mov_b32_e32 v67, v65
	v_pk_fma_f32 v[20:21], v[2:3], v[20:21], v[96:97] op_sel_hi:[0,1,1]
	v_pk_mul_f32 v[96:97], v[12:13], v[44:45] op_sel:[1,0] op_sel_hi:[0,1]
	v_pk_fma_f32 v[12:13], v[12:13], v[40:41], v[96:97] op_sel_hi:[1,0,1]
	s_waitcnt lgkmcnt(1)
	v_pk_mul_f32 v[96:97], v[50:51], v[32:33] op_sel:[0,1] op_sel_hi:[1,0]
	v_xor_b32_e32 v70, 0x80000000, v69
	v_pk_fma_f32 v[32:33], v[42:43], v[32:33], v[96:97] op_sel_hi:[0,1,1]
	v_pk_mul_f32 v[96:97], v[8:9], v[48:49] op_sel:[1,0] op_sel_hi:[0,1]
	v_pk_fma_f32 v[8:9], v[8:9], v[46:47], v[96:97] op_sel_hi:[1,0,1]
	v_pk_mul_f32 v[96:97], v[28:29], v[54:55] op_sel:[1,0] op_sel_hi:[0,1]
	v_pk_fma_f32 v[28:29], v[28:29], v[52:53], v[96:97] op_sel_hi:[1,0,1]
	v_pk_mul_f32 v[96:97], v[24:25], v[58:59] op_sel:[1,0] op_sel_hi:[0,1]
	v_pk_fma_f32 v[24:25], v[24:25], v[56:57], v[96:97] op_sel_hi:[1,0,1]
	s_waitcnt lgkmcnt(0)
	v_pk_mul_f32 v[96:97], v[36:37], v[62:63] op_sel:[1,0] op_sel_hi:[0,1]
	v_mov_b32_e32 v71, v69
	v_pk_fma_f32 v[36:37], v[36:37], v[60:61], v[96:97] op_sel_hi:[1,0,1]
	v_pk_mul_f32 v[96:97], v[6:7], v[66:67] op_sel:[1,0] op_sel_hi:[0,1]
	v_xor_b32_e32 v74, 0x80000000, v73
	v_mov_b32_e32 v75, v73
	v_pk_fma_f32 v[6:7], v[6:7], v[64:65], v[96:97] op_sel_hi:[1,0,1]
	v_pk_mul_f32 v[96:97], v[22:23], v[70:71] op_sel:[1,0] op_sel_hi:[0,1]
	v_xor_b32_e32 v78, 0x80000000, v77
	v_mov_b32_e32 v79, v77
	v_pk_fma_f32 v[22:23], v[22:23], v[68:69], v[96:97] op_sel_hi:[1,0,1]
	v_pk_mul_f32 v[96:97], v[14:15], v[74:75] op_sel:[1,0] op_sel_hi:[0,1]
	v_xor_b32_e32 v82, 0x80000000, v81
	v_mov_b32_e32 v83, v81
	v_pk_fma_f32 v[14:15], v[14:15], v[72:73], v[96:97] op_sel_hi:[1,0,1]
	v_pk_mul_f32 v[96:97], v[34:35], v[78:79] op_sel:[1,0] op_sel_hi:[0,1]
	v_xor_b32_e32 v86, 0x80000000, v85
	v_mov_b32_e32 v87, v85
	v_pk_fma_f32 v[34:35], v[34:35], v[76:77], v[96:97] op_sel_hi:[1,0,1]
	v_pk_mul_f32 v[96:97], v[10:11], v[82:83] op_sel:[1,0] op_sel_hi:[0,1]
	v_xor_b32_e32 v90, 0x80000000, v89
	v_mov_b32_e32 v91, v89
	v_pk_fma_f32 v[10:11], v[10:11], v[80:81], v[96:97] op_sel_hi:[1,0,1]
	v_pk_mul_f32 v[96:97], v[30:31], v[86:87] op_sel:[1,0] op_sel_hi:[0,1]
	v_xor_b32_e32 v94, 0x80000000, v93
	v_mov_b32_e32 v95, v93
	v_pk_fma_f32 v[30:31], v[30:31], v[84:85], v[96:97] op_sel_hi:[1,0,1]
	v_pk_mul_f32 v[96:97], v[26:27], v[90:91] op_sel:[1,0] op_sel_hi:[0,1]
	v_pk_fma_f32 v[26:27], v[26:27], v[88:89], v[96:97] op_sel_hi:[1,0,1]
	v_pk_mul_f32 v[96:97], v[38:39], v[94:95] op_sel:[1,0] op_sel_hi:[0,1]
	v_pk_fma_f32 v[38:39], v[38:39], v[92:93], v[96:97] op_sel_hi:[1,0,1]
	v_pk_add_f32 v[96:97], v[4:5], v[6:7]
	v_pk_add_f32 v[4:5], v[4:5], v[6:7] neg_lo:[0,1] neg_hi:[0,1]
	v_pk_add_f32 v[6:7], v[8:9], v[10:11]
	v_pk_add_f32 v[246:247], v[8:9], v[10:11] neg_lo:[0,1] neg_hi:[0,1]
	v_pk_add_f32 v[10:11], v[12:13], v[14:15]
	v_pk_add_f32 v[12:13], v[12:13], v[14:15] neg_lo:[0,1] neg_hi:[0,1]
	v_pk_add_f32 v[14:15], v[24:25], v[26:27]
	v_pk_add_f32 v[24:25], v[24:25], v[26:27] neg_lo:[0,1] neg_hi:[0,1]
	v_pk_add_f32 v[26:27], v[20:21], v[22:23]
	v_pk_add_f32 v[20:21], v[20:21], v[22:23] neg_lo:[0,1] neg_hi:[0,1]
	v_pk_add_f32 v[22:23], v[28:29], v[30:31]
	v_pk_add_f32 v[28:29], v[28:29], v[30:31] neg_lo:[0,1] neg_hi:[0,1]
	v_pk_add_f32 v[30:31], v[32:33], v[34:35]
	v_pk_add_f32 v[32:33], v[32:33], v[34:35] neg_lo:[0,1] neg_hi:[0,1]
	v_pk_add_f32 v[34:35], v[36:37], v[38:39]
	v_pk_add_f32 v[36:37], v[36:37], v[38:39] neg_lo:[0,1] neg_hi:[0,1]
	v_pk_add_f32 v[38:39], v[96:97], v[6:7]
	v_pk_add_f32 v[6:7], v[96:97], v[6:7] neg_lo:[0,1] neg_hi:[0,1]
	v_pk_add_f32 v[8:9], v[4:5], v[246:247] op_sel:[0,1] op_sel_hi:[1,0] neg_lo:[0,1]
	v_pk_add_f32 v[4:5], v[4:5], v[246:247] op_sel:[0,1] op_sel_hi:[1,0] neg_hi:[0,1]
	v_pk_add_f32 v[96:97], v[10:11], v[14:15]
	v_pk_add_f32 v[10:11], v[10:11], v[14:15] neg_lo:[0,1] neg_hi:[0,1]
	v_xor_b32_e32 v14, 0x80000000, v25
	v_mov_b32_e32 v15, v24
	v_pk_add_f32 v[24:25], v[12:13], v[14:15]
	v_pk_add_f32 v[12:13], v[12:13], v[14:15] neg_lo:[0,1] neg_hi:[0,1]
	v_pk_add_f32 v[14:15], v[26:27], v[22:23]
	v_pk_add_f32 v[22:23], v[26:27], v[22:23] neg_lo:[0,1] neg_hi:[0,1]
	v_xor_b32_e32 v26, 0x80000000, v29
	v_mov_b32_e32 v27, v28
	v_pk_add_f32 v[28:29], v[20:21], v[26:27]
	v_pk_add_f32 v[20:21], v[20:21], v[26:27] neg_lo:[0,1] neg_hi:[0,1]
	v_pk_add_f32 v[26:27], v[30:31], v[34:35]
	v_pk_add_f32 v[246:247], v[30:31], v[34:35] neg_lo:[0,1] neg_hi:[0,1]
	v_xor_b32_e32 v34, 0x80000000, v37
	v_mov_b32_e32 v35, v36
	v_pk_add_f32 v[36:37], v[32:33], v[34:35]
	v_pk_add_f32 v[32:33], v[32:33], v[34:35] neg_lo:[0,1] neg_hi:[0,1]
	v_pk_add_f32 v[34:35], v[38:39], v[96:97]
	v_pk_add_f32 v[38:39], v[38:39], v[96:97] neg_lo:[0,1] neg_hi:[0,1]
	v_pk_mul_f32 v[96:97], v[24:25], s[66:67]
	v_add_u32_e32 v3, 0x2000, v3
	v_pk_fma_f32 v[24:25], v[24:25], s[0:1], v[96:97] op_sel:[0,0,1] op_sel_hi:[1,0,0]
	v_ashrrev_i32_e32 v3, 2, v3
	v_pk_add_f32 v[96:97], v[8:9], v[24:25]
	v_pk_add_f32 v[8:9], v[8:9], v[24:25] neg_lo:[0,1] neg_hi:[0,1]
	v_xor_b32_e32 v24, 0x80000000, v11
	v_mov_b32_e32 v25, v10
	v_pk_add_f32 v[10:11], v[6:7], v[24:25]
	v_pk_add_f32 v[6:7], v[6:7], v[24:25] neg_lo:[0,1] neg_hi:[0,1]
	v_pk_mul_f32 v[24:25], v[12:13], s[66:67]
	v_add3_u32 v18, v18, v3, s5
	v_pk_fma_f32 v[12:13], s[0:1], v[12:13], v[24:25] op_sel:[0,0,1] op_sel_hi:[0,1,0] neg_lo:[0,1,0] neg_hi:[0,1,0]
	v_pk_add_f32 v[24:25], v[4:5], v[12:13]
	v_pk_add_f32 v[4:5], v[4:5], v[12:13] neg_lo:[0,1] neg_hi:[0,1]
	v_pk_add_f32 v[12:13], v[14:15], v[26:27]
	v_pk_add_f32 v[14:15], v[14:15], v[26:27] neg_lo:[0,1] neg_hi:[0,1]
	v_pk_mul_f32 v[26:27], v[36:37], s[66:67]
	s_nop 0
	v_pk_fma_f32 v[26:27], s[0:1], v[36:37], v[26:27] op_sel:[0,0,1] op_sel_hi:[0,1,0]
	v_pk_add_f32 v[36:37], v[28:29], v[26:27]
	v_pk_add_f32 v[26:27], v[28:29], v[26:27] neg_lo:[0,1] neg_hi:[0,1]
	v_pk_add_f32 v[30:31], v[22:23], v[246:247] op_sel:[0,1] op_sel_hi:[1,0] neg_lo:[0,1]
	v_pk_add_f32 v[22:23], v[22:23], v[246:247] op_sel:[0,1] op_sel_hi:[1,0] neg_hi:[0,1]
	v_pk_mul_f32 v[28:29], v[32:33], s[66:67]
	s_nop 0
	v_pk_fma_f32 v[28:29], s[0:1], v[32:33], v[28:29] op_sel:[0,0,1] op_sel_hi:[0,1,0] neg_lo:[0,1,0] neg_hi:[0,1,0]
	v_pk_add_f32 v[32:33], v[20:21], v[28:29]
	v_pk_add_f32 v[20:21], v[20:21], v[28:29] neg_lo:[0,1] neg_hi:[0,1]
	v_pk_add_f32 v[28:29], v[34:35], v[12:13]
	v_pk_add_f32 v[12:13], v[34:35], v[12:13] neg_lo:[0,1] neg_hi:[0,1]
	v_pk_mul_f32 v[34:35], v[36:37], s[68:69]
	s_nop 0
	v_pk_fma_f32 v[34:35], s[16:17], v[36:37], v[34:35] op_sel:[0,0,1] op_sel_hi:[0,1,0]
	v_pk_add_f32 v[36:37], v[96:97], v[34:35]
	v_pk_add_f32 v[34:35], v[96:97], v[34:35] neg_lo:[0,1] neg_hi:[0,1]
	v_pk_mul_f32 v[96:97], v[30:31], s[66:67]
	s_nop 0
	v_pk_fma_f32 v[30:31], s[0:1], v[30:31], v[96:97] op_sel:[0,0,1] op_sel_hi:[0,1,0]
	v_pk_add_f32 v[96:97], v[10:11], v[30:31]
	v_pk_add_f32 v[10:11], v[10:11], v[30:31] neg_lo:[0,1] neg_hi:[0,1]
	v_pk_mul_f32 v[30:31], v[32:33], s[16:17]
	s_nop 0
	v_pk_fma_f32 v[30:31], s[72:73], v[32:33], v[30:31] op_sel:[0,0,1] op_sel_hi:[0,1,0]
	v_pk_add_f32 v[32:33], v[24:25], v[30:31]
	v_pk_add_f32 v[24:25], v[24:25], v[30:31] neg_lo:[0,1] neg_hi:[0,1]
	v_xor_b32_e32 v30, 0x80000000, v15
	v_mov_b32_e32 v31, v14
	v_pk_add_f32 v[14:15], v[38:39], v[30:31]
	v_pk_add_f32 v[30:31], v[38:39], v[30:31] neg_lo:[0,1] neg_hi:[0,1]
	v_pk_mul_f32 v[38:39], v[26:27], s[16:17]
	s_nop 0
	v_pk_fma_f32 v[26:27], s[72:73], v[26:27], v[38:39] op_sel:[0,0,1] op_sel_hi:[0,1,0] neg_lo:[0,1,0] neg_hi:[0,1,0]
	v_pk_add_f32 v[38:39], v[8:9], v[26:27]
	v_pk_add_f32 v[8:9], v[8:9], v[26:27] neg_lo:[0,1] neg_hi:[0,1]
	v_pk_mul_f32 v[26:27], v[22:23], s[66:67]
	s_nop 0
	v_pk_fma_f32 v[22:23], s[0:1], v[22:23], v[26:27] op_sel:[0,0,1] op_sel_hi:[0,1,0] neg_lo:[0,1,0] neg_hi:[0,1,0]
	v_pk_add_f32 v[26:27], v[6:7], v[22:23]
	v_pk_add_f32 v[6:7], v[6:7], v[22:23] neg_lo:[0,1] neg_hi:[0,1]
	v_pk_mul_f32 v[22:23], v[20:21], s[68:69]
	s_nop 0
	v_pk_fma_f32 v[20:21], s[16:17], v[20:21], v[22:23] op_sel:[0,0,1] op_sel_hi:[0,1,0] neg_lo:[0,1,0] neg_hi:[0,1,0]
	v_pk_add_f32 v[22:23], v[4:5], v[20:21]
	v_pk_add_f32 v[4:5], v[4:5], v[20:21] neg_lo:[0,1] neg_hi:[0,1]
	ds_write2_b64 v98, v[28:29], v[36:37] offset1:16
	ds_write2_b64 v98, v[96:97], v[32:33] offset0:33 offset1:49
	ds_write2_b64 v98, v[14:15], v[38:39] offset0:66 offset1:82
	ds_write2_b64 v98, v[26:27], v[22:23] offset0:99 offset1:115
	ds_write2_b64 v98, v[12:13], v[34:35] offset0:132 offset1:148
	ds_write2_b64 v98, v[10:11], v[24:25] offset0:165 offset1:181
	ds_write2_b64 v98, v[30:31], v[8:9] offset0:198 offset1:214
	ds_write2_b64 v98, v[6:7], v[4:5] offset0:231 offset1:247
	ds_read2_b64 v[4:7], v18 offset1:16
	ds_read2_b64 v[8:11], v18 offset0:33 offset1:49
	ds_read2_b64 v[12:15], v18 offset0:66 offset1:82
	ds_read2_b64 v[20:23], v18 offset0:132 offset1:148
	ds_read2_b64 v[24:27], v18 offset0:99 offset1:115
	ds_read2_b64 v[28:31], v18 offset0:165 offset1:181
	ds_read2_b64 v[32:35], v18 offset0:198 offset1:214
	ds_read2_b64 v[36:39], v18 offset0:231 offset1:247
	s_waitcnt lgkmcnt(4)
	v_pk_mul_f32 v[16:17], v[20:21], v[16:17] op_sel:[1,0] op_sel_hi:[0,1]
	v_pk_fma_f32 v[2:3], v[2:3], v[20:21], v[16:17] op_sel_hi:[0,1,1]
	v_pk_mul_f32 v[16:17], v[44:45], v[12:13] op_sel:[0,1] op_sel_hi:[1,0]
	v_pk_mul_f32 v[20:21], v[48:49], v[8:9] op_sel:[0,1] op_sel_hi:[1,0]
	v_pk_fma_f32 v[12:13], v[40:41], v[12:13], v[16:17] op_sel_hi:[0,1,1]
	s_waitcnt lgkmcnt(1)
	v_pk_mul_f32 v[16:17], v[50:51], v[32:33] op_sel:[0,1] op_sel_hi:[1,0]
	v_pk_fma_f32 v[8:9], v[46:47], v[8:9], v[20:21] op_sel_hi:[0,1,1]
	v_pk_fma_f32 v[16:17], v[42:43], v[32:33], v[16:17] op_sel_hi:[0,1,1]
	v_pk_mul_f32 v[32:33], v[66:67], v[6:7] op_sel:[0,1] op_sel_hi:[1,0]
	v_pk_mul_f32 v[20:21], v[54:55], v[28:29] op_sel:[0,1] op_sel_hi:[1,0]
	v_pk_fma_f32 v[6:7], v[64:65], v[6:7], v[32:33] op_sel_hi:[0,1,1]
	v_pk_mul_f32 v[32:33], v[70:71], v[22:23] op_sel:[0,1] op_sel_hi:[1,0]
	v_pk_fma_f32 v[20:21], v[52:53], v[28:29], v[20:21] op_sel_hi:[0,1,1]
	v_pk_fma_f32 v[22:23], v[68:69], v[22:23], v[32:33] op_sel_hi:[0,1,1]
	v_pk_mul_f32 v[32:33], v[74:75], v[14:15] op_sel:[0,1] op_sel_hi:[1,0]
	v_pk_mul_f32 v[28:29], v[58:59], v[24:25] op_sel:[0,1] op_sel_hi:[1,0]
	v_pk_fma_f32 v[14:15], v[72:73], v[14:15], v[32:33] op_sel_hi:[0,1,1]
	v_pk_mul_f32 v[32:33], v[78:79], v[34:35] op_sel:[0,1] op_sel_hi:[1,0]
	v_pk_fma_f32 v[24:25], v[56:57], v[24:25], v[28:29] op_sel_hi:[0,1,1]
	v_pk_fma_f32 v[32:33], v[76:77], v[34:35], v[32:33] op_sel_hi:[0,1,1]
	v_pk_mul_f32 v[34:35], v[82:83], v[10:11] op_sel:[0,1] op_sel_hi:[1,0]
	s_waitcnt lgkmcnt(0)
	v_pk_mul_f32 v[28:29], v[62:63], v[36:37] op_sel:[0,1] op_sel_hi:[1,0]
	v_pk_fma_f32 v[10:11], v[80:81], v[10:11], v[34:35] op_sel_hi:[0,1,1]
	v_pk_mul_f32 v[34:35], v[86:87], v[30:31] op_sel:[0,1] op_sel_hi:[1,0]
	v_pk_fma_f32 v[28:29], v[60:61], v[36:37], v[28:29] op_sel_hi:[0,1,1]
	v_pk_fma_f32 v[30:31], v[84:85], v[30:31], v[34:35] op_sel_hi:[0,1,1]
	v_pk_mul_f32 v[34:35], v[90:91], v[26:27] op_sel:[0,1] op_sel_hi:[1,0]
	v_pk_add_f32 v[36:37], v[4:5], v[6:7]
	v_pk_fma_f32 v[26:27], v[88:89], v[26:27], v[34:35] op_sel_hi:[0,1,1]
	v_pk_mul_f32 v[34:35], v[94:95], v[38:39] op_sel:[0,1] op_sel_hi:[1,0]
	v_pk_add_f32 v[4:5], v[4:5], v[6:7] neg_lo:[0,1] neg_hi:[0,1]
	v_pk_fma_f32 v[34:35], v[92:93], v[38:39], v[34:35] op_sel_hi:[0,1,1]
	v_pk_add_f32 v[6:7], v[8:9], v[10:11]
	v_pk_add_f32 v[246:247], v[8:9], v[10:11] neg_lo:[0,1] neg_hi:[0,1]
	v_pk_add_f32 v[10:11], v[12:13], v[14:15]
	v_pk_add_f32 v[12:13], v[12:13], v[14:15] neg_lo:[0,1] neg_hi:[0,1]
	v_pk_add_f32 v[14:15], v[24:25], v[26:27]
	v_pk_add_f32 v[24:25], v[24:25], v[26:27] neg_lo:[0,1] neg_hi:[0,1]
	v_pk_add_f32 v[26:27], v[2:3], v[22:23]
	v_pk_add_f32 v[2:3], v[2:3], v[22:23] neg_lo:[0,1] neg_hi:[0,1]
	v_pk_add_f32 v[22:23], v[20:21], v[30:31]
	v_pk_add_f32 v[20:21], v[20:21], v[30:31] neg_lo:[0,1] neg_hi:[0,1]
	v_pk_add_f32 v[30:31], v[16:17], v[32:33]
	v_pk_add_f32 v[16:17], v[16:17], v[32:33] neg_lo:[0,1] neg_hi:[0,1]
	v_pk_add_f32 v[32:33], v[28:29], v[34:35]
	v_pk_add_f32 v[28:29], v[28:29], v[34:35] neg_lo:[0,1] neg_hi:[0,1]
	v_pk_add_f32 v[34:35], v[36:37], v[6:7]
	v_pk_add_f32 v[6:7], v[36:37], v[6:7] neg_lo:[0,1] neg_hi:[0,1]
	v_pk_add_f32 v[8:9], v[4:5], v[246:247] op_sel:[0,1] op_sel_hi:[1,0] neg_lo:[0,1]
	v_pk_add_f32 v[4:5], v[4:5], v[246:247] op_sel:[0,1] op_sel_hi:[1,0] neg_hi:[0,1]
	v_pk_add_f32 v[36:37], v[10:11], v[14:15]
	v_pk_add_f32 v[10:11], v[10:11], v[14:15] neg_lo:[0,1] neg_hi:[0,1]
	v_xor_b32_e32 v14, 0x80000000, v25
	v_mov_b32_e32 v15, v24
	v_pk_add_f32 v[24:25], v[12:13], v[14:15]
	v_pk_add_f32 v[12:13], v[12:13], v[14:15] neg_lo:[0,1] neg_hi:[0,1]
	v_pk_add_f32 v[14:15], v[26:27], v[22:23]
	v_pk_add_f32 v[22:23], v[26:27], v[22:23] neg_lo:[0,1] neg_hi:[0,1]
	v_xor_b32_e32 v26, 0x80000000, v21
	v_mov_b32_e32 v27, v20
	v_pk_add_f32 v[20:21], v[2:3], v[26:27]
	v_pk_add_f32 v[2:3], v[2:3], v[26:27] neg_lo:[0,1] neg_hi:[0,1]
	v_pk_add_f32 v[26:27], v[30:31], v[32:33]
	v_pk_add_f32 v[30:31], v[30:31], v[32:33] neg_lo:[0,1] neg_hi:[0,1]
	v_xor_b32_e32 v32, 0x80000000, v29
	v_mov_b32_e32 v33, v28
	v_pk_add_f32 v[28:29], v[16:17], v[32:33]
	v_pk_add_f32 v[16:17], v[16:17], v[32:33] neg_lo:[0,1] neg_hi:[0,1]
	v_pk_add_f32 v[32:33], v[34:35], v[36:37]
	v_pk_add_f32 v[34:35], v[34:35], v[36:37] neg_lo:[0,1] neg_hi:[0,1]
	v_pk_mul_f32 v[36:37], v[24:25], s[66:67]
	v_mov_b32_e32 v39, 0
	v_pk_fma_f32 v[24:25], v[24:25], s[0:1], v[36:37] op_sel:[0,0,1] op_sel_hi:[1,0,0]
	v_mov_b32_e32 v41, 0
	v_pk_add_f32 v[36:37], v[8:9], v[24:25]
	v_pk_add_f32 v[8:9], v[8:9], v[24:25] neg_lo:[0,1] neg_hi:[0,1]
	v_xor_b32_e32 v24, 0x80000000, v11
	v_mov_b32_e32 v25, v10
	v_pk_add_f32 v[10:11], v[6:7], v[24:25]
	v_pk_add_f32 v[6:7], v[6:7], v[24:25] neg_lo:[0,1] neg_hi:[0,1]
	v_pk_mul_f32 v[24:25], v[12:13], s[66:67]
	s_nop 0
	v_pk_fma_f32 v[12:13], s[0:1], v[12:13], v[24:25] op_sel:[0,0,1] op_sel_hi:[0,1,0] neg_lo:[0,1,0] neg_hi:[0,1,0]
	v_pk_add_f32 v[24:25], v[4:5], v[12:13]
	v_pk_add_f32 v[4:5], v[4:5], v[12:13] neg_lo:[0,1] neg_hi:[0,1]
	v_pk_add_f32 v[12:13], v[14:15], v[26:27]
	v_pk_add_f32 v[14:15], v[14:15], v[26:27] neg_lo:[0,1] neg_hi:[0,1]
	v_pk_mul_f32 v[26:27], v[28:29], s[66:67]
	s_nop 0
	v_pk_fma_f32 v[26:27], s[0:1], v[28:29], v[26:27] op_sel:[0,0,1] op_sel_hi:[0,1,0]
	v_pk_add_f32 v[28:29], v[20:21], v[26:27]
	v_pk_add_f32 v[20:21], v[20:21], v[26:27] neg_lo:[0,1] neg_hi:[0,1]
	v_xor_b32_e32 v26, 0x80000000, v31
	v_mov_b32_e32 v27, v30
	v_pk_add_f32 v[30:31], v[22:23], v[26:27]
	v_pk_add_f32 v[22:23], v[22:23], v[26:27] neg_lo:[0,1] neg_hi:[0,1]
	v_pk_mul_f32 v[26:27], v[16:17], s[66:67]
	s_nop 0
	v_pk_fma_f32 v[16:17], s[0:1], v[16:17], v[26:27] op_sel:[0,0,1] op_sel_hi:[0,1,0] neg_lo:[0,1,0] neg_hi:[0,1,0]
	v_pk_add_f32 v[26:27], v[2:3], v[16:17]
	v_pk_add_f32 v[2:3], v[2:3], v[16:17] neg_lo:[0,1] neg_hi:[0,1]
	v_pk_add_f32 v[16:17], v[32:33], v[12:13]
	v_pk_add_f32 v[12:13], v[32:33], v[12:13] neg_lo:[0,1] neg_hi:[0,1]
	v_pk_mul_f32 v[32:33], v[28:29], s[68:69]
	s_nop 0
	v_pk_fma_f32 v[28:29], s[16:17], v[28:29], v[32:33] op_sel:[0,0,1] op_sel_hi:[0,1,0]
	v_pk_add_f32 v[32:33], v[36:37], v[28:29]
	v_pk_add_f32 v[28:29], v[36:37], v[28:29] neg_lo:[0,1] neg_hi:[0,1]
	v_pk_mul_f32 v[36:37], v[30:31], s[66:67]
	s_nop 0
	v_pk_fma_f32 v[30:31], s[0:1], v[30:31], v[36:37] op_sel:[0,0,1] op_sel_hi:[0,1,0]
	v_pk_add_f32 v[36:37], v[10:11], v[30:31]
	v_pk_add_f32 v[10:11], v[10:11], v[30:31] neg_lo:[0,1] neg_hi:[0,1]
	v_pk_mul_f32 v[30:31], v[26:27], s[16:17]
	s_nop 0
	v_pk_fma_f32 v[26:27], s[72:73], v[26:27], v[30:31] op_sel:[0,0,1] op_sel_hi:[0,1,0]
	v_pk_add_f32 v[30:31], v[24:25], v[26:27]
	v_pk_add_f32 v[24:25], v[24:25], v[26:27] neg_lo:[0,1] neg_hi:[0,1]
	v_xor_b32_e32 v26, 0x80000000, v15
	v_mov_b32_e32 v27, v14
	v_pk_add_f32 v[14:15], v[34:35], v[26:27]
	v_pk_add_f32 v[26:27], v[34:35], v[26:27] neg_lo:[0,1] neg_hi:[0,1]
	v_pk_mul_f32 v[34:35], v[20:21], s[16:17]
	s_nop 0
	v_pk_fma_f32 v[20:21], s[72:73], v[20:21], v[34:35] op_sel:[0,0,1] op_sel_hi:[0,1,0] neg_lo:[0,1,0] neg_hi:[0,1,0]
	v_pk_add_f32 v[34:35], v[8:9], v[20:21]
	v_pk_add_f32 v[8:9], v[8:9], v[20:21] neg_lo:[0,1] neg_hi:[0,1]
	v_pk_mul_f32 v[20:21], v[22:23], s[66:67]
	s_nop 0
	v_pk_fma_f32 v[20:21], v[22:23], s[0:1], v[20:21] op_sel:[0,0,1] op_sel_hi:[1,0,0] neg_lo:[1,0,0] neg_hi:[1,0,0]
	s_lshl_b64 s[0:1], s[62:63], 2
	v_pk_add_f32 v[22:23], v[6:7], v[20:21]
	v_pk_add_f32 v[6:7], v[6:7], v[20:21] neg_lo:[0,1] neg_hi:[0,1]
	v_pk_mul_f32 v[20:21], v[2:3], s[68:69]
	s_add_u32 s0, s49, s0
	v_pk_fma_f32 v[2:3], v[2:3], s[16:17], v[20:21] op_sel:[0,0,1] op_sel_hi:[1,0,0] neg_lo:[1,0,0] neg_hi:[1,0,0]
	s_addc_u32 s1, s60, s1
	v_pk_add_f32 v[20:21], v[4:5], v[2:3]
	v_pk_add_f32 v[2:3], v[4:5], v[2:3] neg_lo:[0,1] neg_hi:[0,1]
	ds_write2_b64 v18, v[16:17], v[32:33] offset1:16
	ds_write2_b64 v18, v[36:37], v[30:31] offset0:33 offset1:49
	ds_write2_b64 v18, v[14:15], v[34:35] offset0:66 offset1:82
	ds_write2_b64 v18, v[22:23], v[20:21] offset0:99 offset1:115
	ds_write2_b64 v18, v[12:13], v[28:29] offset0:132 offset1:148
	ds_write2_b64 v18, v[10:11], v[24:25] offset0:165 offset1:181
	ds_write2_b64 v18, v[26:27], v[8:9] offset0:198 offset1:214
	ds_write2_b64 v18, v[6:7], v[2:3] offset0:231 offset1:247
	s_waitcnt lgkmcnt(0)
	s_barrier
	s_lshl_b64 s[62:63], s[64:65], 2
	v_ashrrev_i32_e32 v2, 31, v210
	s_add_u32 s62, s22, s62
	v_lshrrev_b32_e32 v2, 23, v2
	global_load_dword v30, v206, s[0:1]
	global_load_dword v20, v207, s[0:1]
	s_addc_u32 s63, s23, s63
	global_load_dword v31, v205, s[0:1]
	global_load_dword v24, v205, s[62:63]
	s_lshl_b64 s[0:1], s[64:65], 16
	v_add_u32_e32 v2, v210, v2
	s_add_u32 s0, s87, s0
	v_ashrrev_i32_e32 v2, 9, v2
	s_addc_u32 s1, s90, s1
	v_mul_i32_i24_e32 v3, 0x200, v2
	s_add_u32 s0, s0, 0x8000
	v_sub_u32_e32 v21, v210, v3
	v_lshlrev_b32_e32 v36, 13, v2
	s_addc_u32 s1, s1, 0
	v_ashrrev_i32_e32 v37, 31, v36
	v_lshlrev_b32_e32 v32, 4, v21
	v_lshl_add_u64 v[2:3], v[36:37], 1, s[0:1]
	v_ashrrev_i32_e32 v33, 31, v32
	v_lshl_add_u64 v[2:3], v[32:33], 1, v[2:3]
	global_load_dwordx4 v[10:13], v[2:3], off offset:16 nt
	global_load_dwordx4 v[14:17], v[2:3], off nt
	v_cmp_lt_i32_e32 vcc, 0, v21
	s_and_saveexec_b64 s[62:63], vcc
	s_cbranch_execz .LBB0_540
	global_load_ushort v41, v[2:3], off offset:-2

.LBB0_546:
	s_or_b64 exec, exec, s[0:1]
	v_mov_b32_e32 v25, v210
	s_mov_b32 s62, s37
	v_and_b32_e32 v28, 0xff, v25
	v_lshlrev_b32_e32 v34, 5, v25
	v_cvt_f32_ubyte0_e32 v25, v25
	v_mul_f32_e32 v25, 0x39000000, v25
	v_sin_f32_e32 v43, v25
	v_cos_f32_e32 v42, v25
	v_and_or_b32 v28, v34, s33, v28
	v_ashrrev_i32_e32 v34, 5, v28
	v_xor_b32_e32 v44, 0x80000000, v43
	v_mov_b32_e32 v45, v43
	v_pk_mul_f32 v[46:47], v[42:43], v[44:45] op_sel:[1,0] op_sel_hi:[0,1]
	v_pk_fma_f32 v[46:47], v[42:43], v[42:43], v[46:47] op_sel_hi:[1,0,1]
	v_lshlrev_b32_e32 v28, 3, v28
	v_xor_b32_e32 v50, 0x80000000, v47
	v_mov_b32_e32 v51, v47
	v_pk_mul_f32 v[52:53], v[46:47], v[50:51] op_sel:[1,0] op_sel_hi:[0,1]
	v_pk_fma_f32 v[52:53], v[46:47], v[46:47], v[52:53] op_sel_hi:[1,0,1]
	v_lshlrev_b32_e32 v34, 3, v34
	v_xor_b32_e32 v54, 0x80000000, v53
	v_mov_b32_e32 v55, v53
	v_pk_mul_f32 v[70:71], v[52:53], v[54:55] op_sel:[1,0] op_sel_hi:[0,1]
	v_pk_fma_f32 v[70:71], v[52:53], v[52:53], v[70:71] op_sel_hi:[1,0,1]
	v_pk_mul_f32 v[48:49], v[44:45], v[46:47] op_sel:[0,1] op_sel_hi:[1,0]
	v_pk_mul_f32 v[86:87], v[54:55], v[70:71] op_sel:[0,1] op_sel_hi:[1,0]
	v_add3_u32 v25, 0, v28, v34
	v_pk_fma_f32 v[86:87], v[52:53], v[70:71], v[86:87] op_sel_hi:[0,1,1]
	v_pk_mul_f32 v[102:103], v[54:55], v[86:87] op_sel:[0,1] op_sel_hi:[1,0]
	v_pk_fma_f32 v[48:49], v[42:43], v[46:47], v[48:49] op_sel_hi:[0,1,1]
	v_pk_fma_f32 v[102:103], v[52:53], v[86:87], v[102:103] op_sel_hi:[0,1,1]
	v_pk_mul_f32 v[118:119], v[54:55], v[102:103] op_sel:[0,1] op_sel_hi:[1,0]
	v_xor_b32_e32 v56, 0x80000000, v49
	v_pk_fma_f32 v[118:119], v[52:53], v[102:103], v[118:119] op_sel_hi:[0,1,1]
	v_pk_mul_f32 v[134:135], v[54:55], v[118:119] op_sel:[0,1] op_sel_hi:[1,0]
	v_mov_b32_e32 v57, v49
	v_pk_fma_f32 v[134:135], v[52:53], v[118:119], v[134:135] op_sel_hi:[0,1,1]
	v_pk_mul_f32 v[152:153], v[54:55], v[134:135] op_sel:[0,1] op_sel_hi:[1,0]
	v_pk_mul_f32 v[58:59], v[44:45], v[52:53] op_sel:[0,1] op_sel_hi:[1,0]
	v_pk_fma_f32 v[152:153], v[52:53], v[134:135], v[152:153] op_sel_hi:[0,1,1]
	v_pk_mul_f32 v[74:75], v[44:45], v[70:71] op_sel:[0,1] op_sel_hi:[1,0]
	v_pk_mul_f32 v[90:91], v[44:45], v[86:87] op_sel:[0,1] op_sel_hi:[1,0]
	v_pk_mul_f32 v[106:107], v[44:45], v[102:103] op_sel:[0,1] op_sel_hi:[1,0]
	v_pk_mul_f32 v[122:123], v[44:45], v[118:119] op_sel:[0,1] op_sel_hi:[1,0]
	v_pk_mul_f32 v[138:139], v[44:45], v[134:135] op_sel:[0,1] op_sel_hi:[1,0]
	v_pk_mul_f32 v[156:157], v[44:45], v[152:153] op_sel:[0,1] op_sel_hi:[1,0]
	ds_read_b64 v[168:169], v25
	ds_read_b64 v[170:171], v25 offset:2112
	ds_read_b64 v[172:173], v25 offset:4224
	ds_read_b64 v[174:175], v25 offset:6336
	ds_read_b64 v[176:177], v25 offset:8448
	ds_read_b64 v[178:179], v25 offset:10560
	ds_read_b64 v[180:181], v25 offset:12672
	ds_read_b64 v[182:183], v25 offset:14784
	ds_read_b64 v[184:185], v25 offset:16896
	ds_read_b64 v[186:187], v25 offset:19008
	ds_read_b64 v[188:189], v25 offset:21120
	ds_read_b64 v[190:191], v25 offset:23232
	ds_read_b64 v[192:193], v25 offset:25344
	ds_read_b64 v[194:195], v25 offset:27456
	ds_read_b64 v[196:197], v25 offset:29568
	ds_read_b64 v[198:199], v25 offset:31680
	ds_read_b64 v[212:213], v25 offset:33792
	ds_read_b64 v[214:215], v25 offset:35904
	ds_read_b64 v[216:217], v25 offset:38016
	ds_read_b64 v[218:219], v25 offset:40128
	ds_read_b64 v[220:221], v25 offset:42240
	ds_read_b64 v[222:223], v25 offset:44352
	ds_read_b64 v[224:225], v25 offset:46464
	ds_read_b64 v[226:227], v25 offset:48576
	ds_read_b64 v[228:229], v25 offset:50688
	ds_read_b64 v[230:231], v25 offset:52800
	ds_read_b64 v[232:233], v25 offset:54912
	ds_read_b64 v[234:235], v25 offset:57024
	ds_read_b64 v[236:237], v25 offset:59136
	ds_read_b64 v[238:239], v25 offset:61248
	ds_read_b64 v[240:241], v25 offset:63360
	ds_read_b64 v[242:243], v25 offset:65472
	s_waitcnt lgkmcnt(14)
	v_pk_mul_f32 v[44:45], v[44:45], v[212:213] op_sel:[0,1] op_sel_hi:[1,0]
	v_pk_fma_f32 v[58:59], v[42:43], v[52:53], v[58:59] op_sel_hi:[0,1,1]
	v_pk_mul_f32 v[62:63], v[50:51], v[52:53] op_sel:[0,1] op_sel_hi:[1,0]
	v_pk_mul_f32 v[66:67], v[52:53], v[56:57] op_sel:[1,0] op_sel_hi:[0,1]
	v_pk_fma_f32 v[74:75], v[42:43], v[70:71], v[74:75] op_sel_hi:[0,1,1]
	v_pk_mul_f32 v[78:79], v[50:51], v[70:71] op_sel:[0,1] op_sel_hi:[1,0]
	v_pk_fma_f32 v[90:91], v[42:43], v[86:87], v[90:91] op_sel_hi:[0,1,1]
	v_pk_mul_f32 v[94:95], v[50:51], v[86:87] op_sel:[0,1] op_sel_hi:[1,0]
	v_pk_fma_f32 v[106:107], v[42:43], v[102:103], v[106:107] op_sel_hi:[0,1,1]
	v_pk_mul_f32 v[110:111], v[50:51], v[102:103] op_sel:[0,1] op_sel_hi:[1,0]
	v_pk_fma_f32 v[122:123], v[42:43], v[118:119], v[122:123] op_sel_hi:[0,1,1]
	v_pk_mul_f32 v[126:127], v[50:51], v[118:119] op_sel:[0,1] op_sel_hi:[1,0]
	v_pk_fma_f32 v[138:139], v[42:43], v[134:135], v[138:139] op_sel_hi:[0,1,1]
	v_pk_mul_f32 v[142:143], v[50:51], v[134:135] op_sel:[0,1] op_sel_hi:[1,0]
	v_pk_fma_f32 v[156:157], v[42:43], v[152:153], v[156:157] op_sel_hi:[0,1,1]
	v_pk_mul_f32 v[160:161], v[50:51], v[152:153] op_sel:[0,1] op_sel_hi:[1,0]
	v_pk_fma_f32 v[42:43], v[42:43], v[212:213], v[44:45] op_sel_hi:[0,1,1]
	v_pk_mul_f32 v[44:45], v[184:185], v[50:51] op_sel:[1,0] op_sel_hi:[0,1]
	v_pk_fma_f32 v[62:63], v[46:47], v[52:53], v[62:63] op_sel_hi:[0,1,1]
	v_pk_fma_f32 v[66:67], v[52:53], v[48:49], v[66:67] op_sel_hi:[1,0,1]
	v_pk_fma_f32 v[78:79], v[46:47], v[70:71], v[78:79] op_sel_hi:[0,1,1]
	v_pk_mul_f32 v[82:83], v[56:57], v[70:71] op_sel:[0,1] op_sel_hi:[1,0]
	v_pk_fma_f32 v[94:95], v[46:47], v[86:87], v[94:95] op_sel_hi:[0,1,1]
	v_pk_mul_f32 v[98:99], v[56:57], v[86:87] op_sel:[0,1] op_sel_hi:[1,0]
	v_pk_fma_f32 v[110:111], v[46:47], v[102:103], v[110:111] op_sel_hi:[0,1,1]
	v_pk_mul_f32 v[114:115], v[56:57], v[102:103] op_sel:[0,1] op_sel_hi:[1,0]
	v_pk_fma_f32 v[126:127], v[46:47], v[118:119], v[126:127] op_sel_hi:[0,1,1]
	v_pk_mul_f32 v[130:131], v[56:57], v[118:119] op_sel:[0,1] op_sel_hi:[1,0]
	v_pk_fma_f32 v[142:143], v[46:47], v[134:135], v[142:143] op_sel_hi:[0,1,1]
	v_pk_mul_f32 v[148:149], v[56:57], v[134:135] op_sel:[0,1] op_sel_hi:[1,0]
	v_pk_fma_f32 v[160:161], v[46:47], v[152:153], v[160:161] op_sel_hi:[0,1,1]
	v_pk_mul_f32 v[164:165], v[56:57], v[152:153] op_sel:[0,1] op_sel_hi:[1,0]
	v_pk_fma_f32 v[44:45], v[184:185], v[46:47], v[44:45] op_sel_hi:[1,0,1]
	s_waitcnt lgkmcnt(7)
	v_pk_mul_f32 v[46:47], v[56:57], v[228:229] op_sel:[0,1] op_sel_hi:[1,0]
	v_xor_b32_e32 v60, 0x80000000, v59
	v_xor_b32_e32 v64, 0x80000000, v63
	v_xor_b32_e32 v68, 0x80000000, v67
	v_xor_b32_e32 v72, 0x80000000, v71
	v_pk_fma_f32 v[82:83], v[48:49], v[70:71], v[82:83] op_sel_hi:[0,1,1]
	v_pk_fma_f32 v[98:99], v[48:49], v[86:87], v[98:99] op_sel_hi:[0,1,1]
	v_pk_fma_f32 v[114:115], v[48:49], v[102:103], v[114:115] op_sel_hi:[0,1,1]
	v_pk_fma_f32 v[130:131], v[48:49], v[118:119], v[130:131] op_sel_hi:[0,1,1]
	v_pk_fma_f32 v[148:149], v[48:49], v[134:135], v[148:149] op_sel_hi:[0,1,1]
	v_pk_fma_f32 v[164:165], v[48:49], v[152:153], v[164:165] op_sel_hi:[0,1,1]
	v_mov_b32_e32 v61, v59
	v_mov_b32_e32 v65, v63
	v_mov_b32_e32 v69, v67
	v_mov_b32_e32 v73, v71
	v_pk_fma_f32 v[46:47], v[48:49], v[228:229], v[46:47] op_sel_hi:[0,1,1]
	v_pk_mul_f32 v[48:49], v[176:177], v[54:55] op_sel:[1,0] op_sel_hi:[0,1]
	v_xor_b32_e32 v76, 0x80000000, v75
	v_xor_b32_e32 v80, 0x80000000, v79
	v_xor_b32_e32 v84, 0x80000000, v83
	v_xor_b32_e32 v88, 0x80000000, v87
	v_xor_b32_e32 v92, 0x80000000, v91
	v_xor_b32_e32 v96, 0x80000000, v95
	v_xor_b32_e32 v100, 0x80000000, v99
	v_xor_b32_e32 v104, 0x80000000, v103
	v_xor_b32_e32 v136, 0x80000000, v135
	v_mov_b32_e32 v77, v75
	v_mov_b32_e32 v81, v79
	v_mov_b32_e32 v85, v83
	v_mov_b32_e32 v89, v87
	v_mov_b32_e32 v93, v91
	v_mov_b32_e32 v97, v95
	v_mov_b32_e32 v101, v99
	v_mov_b32_e32 v105, v103
	v_mov_b32_e32 v137, v135
	v_pk_fma_f32 v[48:49], v[176:177], v[52:53], v[48:49] op_sel_hi:[1,0,1]
	v_pk_mul_f32 v[50:51], v[60:61], v[220:221] op_sel:[0,1] op_sel_hi:[1,0]
	v_pk_mul_f32 v[52:53], v[192:193], v[64:65] op_sel:[1,0] op_sel_hi:[0,1]
	s_waitcnt lgkmcnt(3)
	v_pk_mul_f32 v[54:55], v[68:69], v[236:237] op_sel:[0,1] op_sel_hi:[1,0]
	v_pk_mul_f32 v[56:57], v[172:173], v[72:73] op_sel:[1,0] op_sel_hi:[0,1]
	v_xor_b32_e32 v108, 0x80000000, v107
	v_xor_b32_e32 v112, 0x80000000, v111
	v_xor_b32_e32 v116, 0x80000000, v115
	v_xor_b32_e32 v120, 0x80000000, v119
	v_xor_b32_e32 v124, 0x80000000, v123
	v_xor_b32_e32 v128, 0x80000000, v127
	v_xor_b32_e32 v132, 0x80000000, v131
	v_xor_b32_e32 v140, 0x80000000, v139
	v_xor_b32_e32 v144, 0x80000000, v143
	v_xor_b32_e32 v150, 0x80000000, v149
	v_xor_b32_e32 v154, 0x80000000, v153
	v_xor_b32_e32 v158, 0x80000000, v157
	v_xor_b32_e32 v162, 0x80000000, v161
	v_xor_b32_e32 v166, 0x80000000, v165
	v_mov_b32_e32 v109, v107
	v_mov_b32_e32 v113, v111
	v_mov_b32_e32 v117, v115
	v_mov_b32_e32 v121, v119
	v_mov_b32_e32 v125, v123
	v_mov_b32_e32 v129, v127
	v_mov_b32_e32 v133, v131
	v_mov_b32_e32 v141, v139
	v_mov_b32_e32 v145, v143
	v_mov_b32_e32 v151, v149
	v_mov_b32_e32 v155, v153
	v_mov_b32_e32 v159, v157
	v_mov_b32_e32 v163, v161
	v_mov_b32_e32 v167, v165
	v_pk_fma_f32 v[50:51], v[58:59], v[220:221], v[50:51] op_sel_hi:[0,1,1]
	v_pk_fma_f32 v[52:53], v[192:193], v[62:63], v[52:53] op_sel_hi:[1,0,1]
	v_pk_fma_f32 v[54:55], v[66:67], v[236:237], v[54:55] op_sel_hi:[0,1,1]
	v_pk_fma_f32 v[56:57], v[172:173], v[70:71], v[56:57] op_sel_hi:[1,0,1]
	v_pk_mul_f32 v[58:59], v[216:217], v[76:77] op_sel:[1,0] op_sel_hi:[0,1]
	v_pk_mul_f32 v[60:61], v[188:189], v[80:81] op_sel:[1,0] op_sel_hi:[0,1]
	v_pk_mul_f32 v[62:63], v[84:85], v[232:233] op_sel:[0,1] op_sel_hi:[1,0]
	v_pk_mul_f32 v[64:65], v[180:181], v[88:89] op_sel:[1,0] op_sel_hi:[0,1]
	v_pk_mul_f32 v[66:67], v[224:225], v[92:93] op_sel:[1,0] op_sel_hi:[0,1]
	v_pk_mul_f32 v[68:69], v[196:197], v[96:97] op_sel:[1,0] op_sel_hi:[0,1]
	s_waitcnt lgkmcnt(1)
	v_pk_mul_f32 v[70:71], v[100:101], v[240:241] op_sel:[0,1] op_sel_hi:[1,0]
	v_pk_mul_f32 v[72:73], v[170:171], v[104:105] op_sel:[1,0] op_sel_hi:[0,1]
	v_pk_mul_f32 v[88:89], v[174:175], v[136:137] op_sel:[1,0] op_sel_hi:[0,1]
	v_pk_fma_f32 v[58:59], v[216:217], v[74:75], v[58:59] op_sel_hi:[1,0,1]
	v_pk_fma_f32 v[60:61], v[188:189], v[78:79], v[60:61] op_sel_hi:[1,0,1]
	v_pk_fma_f32 v[62:63], v[82:83], v[232:233], v[62:63] op_sel_hi:[0,1,1]
	v_pk_fma_f32 v[64:65], v[180:181], v[86:87], v[64:65] op_sel_hi:[1,0,1]
	v_pk_fma_f32 v[66:67], v[224:225], v[90:91], v[66:67] op_sel_hi:[1,0,1]
	v_pk_fma_f32 v[68:69], v[196:197], v[94:95], v[68:69] op_sel_hi:[1,0,1]
	v_pk_fma_f32 v[70:71], v[98:99], v[240:241], v[70:71] op_sel_hi:[0,1,1]
	v_pk_fma_f32 v[72:73], v[170:171], v[102:103], v[72:73] op_sel_hi:[1,0,1]
	v_pk_mul_f32 v[74:75], v[214:215], v[108:109] op_sel:[1,0] op_sel_hi:[0,1]
	v_pk_mul_f32 v[76:77], v[186:187], v[112:113] op_sel:[1,0] op_sel_hi:[0,1]
	v_pk_mul_f32 v[78:79], v[230:231], v[116:117] op_sel:[1,0] op_sel_hi:[0,1]
	v_pk_mul_f32 v[80:81], v[178:179], v[120:121] op_sel:[1,0] op_sel_hi:[0,1]
	v_pk_mul_f32 v[82:83], v[222:223], v[124:125] op_sel:[1,0] op_sel_hi:[0,1]
	v_pk_mul_f32 v[84:85], v[194:195], v[128:129] op_sel:[1,0] op_sel_hi:[0,1]
	v_pk_mul_f32 v[86:87], v[132:133], v[238:239] op_sel:[0,1] op_sel_hi:[1,0]
	v_pk_fma_f32 v[88:89], v[174:175], v[134:135], v[88:89] op_sel_hi:[1,0,1]
	v_pk_mul_f32 v[90:91], v[218:219], v[140:141] op_sel:[1,0] op_sel_hi:[0,1]
	v_pk_mul_f32 v[92:93], v[190:191], v[144:145] op_sel:[1,0] op_sel_hi:[0,1]
	v_pk_mul_f32 v[94:95], v[234:235], v[150:151] op_sel:[1,0] op_sel_hi:[0,1]
	v_pk_mul_f32 v[96:97], v[182:183], v[154:155] op_sel:[1,0] op_sel_hi:[0,1]
	v_pk_mul_f32 v[98:99], v[226:227], v[158:159] op_sel:[1,0] op_sel_hi:[0,1]
	v_pk_mul_f32 v[100:101], v[198:199], v[162:163] op_sel:[1,0] op_sel_hi:[0,1]
	s_waitcnt lgkmcnt(0)
	v_pk_mul_f32 v[102:103], v[242:243], v[166:167] op_sel:[1,0] op_sel_hi:[0,1]
	v_pk_fma_f32 v[74:75], v[214:215], v[106:107], v[74:75] op_sel_hi:[1,0,1]
	v_pk_fma_f32 v[76:77], v[186:187], v[110:111], v[76:77] op_sel_hi:[1,0,1]
	v_pk_fma_f32 v[78:79], v[230:231], v[114:115], v[78:79] op_sel_hi:[1,0,1]
	v_pk_fma_f32 v[80:81], v[178:179], v[118:119], v[80:81] op_sel_hi:[1,0,1]
	v_pk_fma_f32 v[82:83], v[222:223], v[122:123], v[82:83] op_sel_hi:[1,0,1]
	v_pk_fma_f32 v[84:85], v[194:195], v[126:127], v[84:85] op_sel_hi:[1,0,1]
	v_pk_fma_f32 v[86:87], v[130:131], v[238:239], v[86:87] op_sel_hi:[0,1,1]
	v_pk_fma_f32 v[90:91], v[218:219], v[138:139], v[90:91] op_sel_hi:[1,0,1]
	v_pk_fma_f32 v[92:93], v[190:191], v[142:143], v[92:93] op_sel_hi:[1,0,1]
	v_pk_fma_f32 v[94:95], v[234:235], v[148:149], v[94:95] op_sel_hi:[1,0,1]
	v_pk_fma_f32 v[96:97], v[182:183], v[152:153], v[96:97] op_sel_hi:[1,0,1]
	v_pk_fma_f32 v[98:99], v[226:227], v[156:157], v[98:99] op_sel_hi:[1,0,1]
	v_pk_fma_f32 v[100:101], v[198:199], v[160:161], v[100:101] op_sel_hi:[1,0,1]
	v_pk_fma_f32 v[102:103], v[242:243], v[164:165], v[102:103] op_sel_hi:[1,0,1]
	v_pk_add_f32 v[104:105], v[168:169], v[72:73]
	v_pk_add_f32 v[106:107], v[56:57], v[88:89]
	v_pk_add_f32 v[246:247], v[56:57], v[88:89] neg_lo:[0,1] neg_hi:[0,1]
	v_pk_add_f32 v[72:73], v[168:169], v[72:73] neg_lo:[0,1] neg_hi:[0,1]
	v_pk_add_f32 v[88:89], v[48:49], v[80:81]
	v_pk_add_f32 v[48:49], v[48:49], v[80:81] neg_lo:[0,1] neg_hi:[0,1]
	v_pk_add_f32 v[80:81], v[64:65], v[96:97]
	v_pk_add_f32 v[64:65], v[64:65], v[96:97] neg_lo:[0,1] neg_hi:[0,1]
	v_pk_add_f32 v[96:97], v[44:45], v[76:77]
	v_pk_add_f32 v[44:45], v[44:45], v[76:77] neg_lo:[0,1] neg_hi:[0,1]
	v_pk_add_f32 v[76:77], v[60:61], v[92:93]
	v_pk_add_f32 v[60:61], v[60:61], v[92:93] neg_lo:[0,1] neg_hi:[0,1]
	v_pk_add_f32 v[92:93], v[52:53], v[84:85]
	v_pk_add_f32 v[52:53], v[52:53], v[84:85] neg_lo:[0,1] neg_hi:[0,1]
	v_pk_add_f32 v[84:85], v[68:69], v[100:101]
	v_pk_add_f32 v[68:69], v[68:69], v[100:101] neg_lo:[0,1] neg_hi:[0,1]
	v_pk_add_f32 v[100:101], v[42:43], v[74:75]
	v_pk_add_f32 v[42:43], v[42:43], v[74:75] neg_lo:[0,1] neg_hi:[0,1]
	v_pk_add_f32 v[74:75], v[58:59], v[90:91]
	v_pk_add_f32 v[58:59], v[58:59], v[90:91] neg_lo:[0,1] neg_hi:[0,1]
	v_pk_add_f32 v[90:91], v[50:51], v[82:83]
	v_pk_add_f32 v[50:51], v[50:51], v[82:83] neg_lo:[0,1] neg_hi:[0,1]
	v_pk_add_f32 v[82:83], v[66:67], v[98:99]
	v_pk_add_f32 v[66:67], v[66:67], v[98:99] neg_lo:[0,1] neg_hi:[0,1]
	v_pk_add_f32 v[98:99], v[46:47], v[78:79]
	v_pk_add_f32 v[46:47], v[46:47], v[78:79] neg_lo:[0,1] neg_hi:[0,1]
	v_pk_add_f32 v[78:79], v[62:63], v[94:95]
	v_pk_add_f32 v[62:63], v[62:63], v[94:95] neg_lo:[0,1] neg_hi:[0,1]
	v_pk_add_f32 v[94:95], v[54:55], v[86:87]
	v_pk_add_f32 v[54:55], v[54:55], v[86:87] neg_lo:[0,1] neg_hi:[0,1]
	v_pk_add_f32 v[86:87], v[70:71], v[102:103]
	v_pk_add_f32 v[70:71], v[70:71], v[102:103] neg_lo:[0,1] neg_hi:[0,1]
	v_pk_add_f32 v[102:103], v[104:105], v[106:107]
	v_pk_add_f32 v[104:105], v[104:105], v[106:107] neg_lo:[0,1] neg_hi:[0,1]
	v_pk_add_f32 v[56:57], v[72:73], v[246:247] op_sel:[0,1] op_sel_hi:[1,0] neg_lo:[0,1]
	v_pk_add_f32 v[72:73], v[72:73], v[246:247] op_sel:[0,1] op_sel_hi:[1,0] neg_hi:[0,1]
	v_pk_add_f32 v[106:107], v[88:89], v[80:81]
	v_pk_add_f32 v[80:81], v[88:89], v[80:81] neg_lo:[0,1] neg_hi:[0,1]
	v_xor_b32_e32 v88, 0x80000000, v65
	v_mov_b32_e32 v89, v64
	v_pk_add_f32 v[64:65], v[48:49], v[88:89]
	v_pk_add_f32 v[48:49], v[48:49], v[88:89] neg_lo:[0,1] neg_hi:[0,1]
	v_pk_add_f32 v[88:89], v[96:97], v[76:77]
	v_pk_add_f32 v[76:77], v[96:97], v[76:77] neg_lo:[0,1] neg_hi:[0,1]
	v_xor_b32_e32 v96, 0x80000000, v61
	v_mov_b32_e32 v97, v60
	v_pk_add_f32 v[60:61], v[44:45], v[96:97]
	v_pk_add_f32 v[44:45], v[44:45], v[96:97] neg_lo:[0,1] neg_hi:[0,1]
	v_pk_add_f32 v[96:97], v[92:93], v[84:85]
	v_pk_add_f32 v[84:85], v[92:93], v[84:85] neg_lo:[0,1] neg_hi:[0,1]
	v_xor_b32_e32 v92, 0x80000000, v69
	v_mov_b32_e32 v93, v68
	v_pk_add_f32 v[68:69], v[52:53], v[92:93]
	v_pk_add_f32 v[52:53], v[52:53], v[92:93] neg_lo:[0,1] neg_hi:[0,1]
	v_pk_add_f32 v[92:93], v[100:101], v[74:75]
	v_pk_add_f32 v[74:75], v[100:101], v[74:75] neg_lo:[0,1] neg_hi:[0,1]
	v_xor_b32_e32 v100, 0x80000000, v59
	v_mov_b32_e32 v101, v58
	v_pk_add_f32 v[58:59], v[42:43], v[100:101]
	v_pk_add_f32 v[42:43], v[42:43], v[100:101] neg_lo:[0,1] neg_hi:[0,1]
	v_pk_add_f32 v[100:101], v[90:91], v[82:83]
	v_pk_add_f32 v[82:83], v[90:91], v[82:83] neg_lo:[0,1] neg_hi:[0,1]
	v_xor_b32_e32 v90, 0x80000000, v67
	v_mov_b32_e32 v91, v66
	v_pk_add_f32 v[66:67], v[50:51], v[90:91]
	v_pk_add_f32 v[50:51], v[50:51], v[90:91] neg_lo:[0,1] neg_hi:[0,1]
	v_pk_add_f32 v[90:91], v[98:99], v[78:79]
	v_pk_add_f32 v[78:79], v[98:99], v[78:79] neg_lo:[0,1] neg_hi:[0,1]
	v_xor_b32_e32 v98, 0x80000000, v63
	v_mov_b32_e32 v99, v62
	v_pk_add_f32 v[62:63], v[46:47], v[98:99]
	v_pk_add_f32 v[46:47], v[46:47], v[98:99] neg_lo:[0,1] neg_hi:[0,1]
	v_pk_add_f32 v[98:99], v[94:95], v[86:87]
	v_pk_add_f32 v[86:87], v[94:95], v[86:87] neg_lo:[0,1] neg_hi:[0,1]
	v_xor_b32_e32 v94, 0x80000000, v71
	v_mov_b32_e32 v95, v70
	s_mov_b32 s63, s36
	v_pk_add_f32 v[70:71], v[54:55], v[94:95]
	v_pk_add_f32 v[54:55], v[54:55], v[94:95] neg_lo:[0,1] neg_hi:[0,1]
	v_pk_add_f32 v[94:95], v[102:103], v[106:107]
	v_pk_add_f32 v[102:103], v[102:103], v[106:107] neg_lo:[0,1] neg_hi:[0,1]
	s_mov_b32 s0, s37
	v_pk_mul_f32 v[106:107], v[64:65], s[62:63]
	s_mov_b32 s64, s19
	v_pk_fma_f32 v[64:65], v[64:65], s[0:1], v[106:107] op_sel:[0,0,1] op_sel_hi:[1,0,0]
	s_mov_b32 s65, s18
	v_pk_add_f32 v[106:107], v[56:57], v[64:65]
	v_pk_add_f32 v[56:57], v[56:57], v[64:65] neg_lo:[0,1] neg_hi:[0,1]
	v_xor_b32_e32 v64, 0x80000000, v81
	v_mov_b32_e32 v65, v80
	v_pk_add_f32 v[80:81], v[104:105], v[64:65]
	v_pk_add_f32 v[64:65], v[104:105], v[64:65] neg_lo:[0,1] neg_hi:[0,1]
	v_pk_mul_f32 v[104:105], v[48:49], s[62:63]
	s_mov_b32 s66, s19
	v_pk_fma_f32 v[48:49], v[48:49], s[0:1], v[104:105] op_sel:[0,0,1] op_sel_hi:[1,0,0] neg_lo:[1,0,0] neg_hi:[1,0,0]
	s_mov_b32 s68, s11
	v_pk_add_f32 v[104:105], v[72:73], v[48:49]
	v_pk_add_f32 v[48:49], v[72:73], v[48:49] neg_lo:[0,1] neg_hi:[0,1]
	v_pk_add_f32 v[72:73], v[88:89], v[96:97]
	v_pk_add_f32 v[246:247], v[88:89], v[96:97] neg_lo:[0,1] neg_hi:[0,1]
	v_pk_mul_f32 v[96:97], v[68:69], s[62:63]
	s_mov_b32 s69, s10
	v_pk_fma_f32 v[68:69], v[68:69], s[0:1], v[96:97] op_sel:[0,0,1] op_sel_hi:[1,0,0]
	s_mov_b32 s72, s27
	v_pk_add_f32 v[96:97], v[60:61], v[68:69]
	v_pk_add_f32 v[60:61], v[60:61], v[68:69] neg_lo:[0,1] neg_hi:[0,1]
	v_xor_b32_e32 v68, 0x80000000, v85
	v_mov_b32_e32 v69, v84
	v_pk_add_f32 v[84:85], v[76:77], v[68:69]
	v_pk_add_f32 v[68:69], v[76:77], v[68:69] neg_lo:[0,1] neg_hi:[0,1]
	v_pk_mul_f32 v[76:77], v[52:53], s[62:63]
	v_pk_mul_f32 v[108:109], v[96:97], s[64:65]
	v_pk_fma_f32 v[52:53], v[52:53], s[0:1], v[76:77] op_sel:[0,0,1] op_sel_hi:[1,0,0] neg_lo:[1,0,0] neg_hi:[1,0,0]
	v_pk_fma_f32 v[96:97], v[96:97], s[16:17], v[108:109] op_sel:[0,0,1] op_sel_hi:[1,0,0]
	v_pk_add_f32 v[76:77], v[44:45], v[52:53]
	v_pk_add_f32 v[44:45], v[44:45], v[52:53] neg_lo:[0,1] neg_hi:[0,1]
	v_pk_add_f32 v[52:53], v[92:93], v[100:101]
	v_pk_add_f32 v[92:93], v[92:93], v[100:101] neg_lo:[0,1] neg_hi:[0,1]
	v_pk_mul_f32 v[100:101], v[66:67], s[62:63]
	s_mov_b32 s17, s40
	v_pk_fma_f32 v[66:67], v[66:67], s[0:1], v[100:101] op_sel:[0,0,1] op_sel_hi:[1,0,0]
	v_pk_add_f32 v[108:109], v[106:107], v[96:97]
	v_pk_add_f32 v[100:101], v[58:59], v[66:67]
	v_pk_add_f32 v[58:59], v[58:59], v[66:67] neg_lo:[0,1] neg_hi:[0,1]
	v_xor_b32_e32 v66, 0x80000000, v83
	v_mov_b32_e32 v67, v82
	v_pk_add_f32 v[82:83], v[74:75], v[66:67]
	v_pk_add_f32 v[66:67], v[74:75], v[66:67] neg_lo:[0,1] neg_hi:[0,1]
	v_pk_mul_f32 v[74:75], v[50:51], s[62:63]
	v_pk_add_f32 v[96:97], v[106:107], v[96:97] neg_lo:[0,1] neg_hi:[0,1]
	v_pk_fma_f32 v[50:51], v[50:51], s[0:1], v[74:75] op_sel:[0,0,1] op_sel_hi:[1,0,0] neg_lo:[1,0,0] neg_hi:[1,0,0]
	v_pk_mul_f32 v[106:107], v[84:85], s[62:63]
	v_pk_add_f32 v[74:75], v[42:43], v[50:51]
	v_pk_add_f32 v[42:43], v[42:43], v[50:51] neg_lo:[0,1] neg_hi:[0,1]
	v_pk_add_f32 v[50:51], v[90:91], v[98:99]
	v_pk_add_f32 v[90:91], v[90:91], v[98:99] neg_lo:[0,1] neg_hi:[0,1]
	v_pk_mul_f32 v[98:99], v[70:71], s[62:63]
	v_pk_fma_f32 v[84:85], v[84:85], s[0:1], v[106:107] op_sel:[0,0,1] op_sel_hi:[1,0,0]
	v_pk_fma_f32 v[70:71], v[70:71], s[0:1], v[98:99] op_sel:[0,0,1] op_sel_hi:[1,0,0]
	v_pk_add_f32 v[106:107], v[80:81], v[84:85]
	v_pk_add_f32 v[98:99], v[62:63], v[70:71]
	v_pk_add_f32 v[62:63], v[62:63], v[70:71] neg_lo:[0,1] neg_hi:[0,1]
	v_xor_b32_e32 v70, 0x80000000, v87
	v_mov_b32_e32 v71, v86
	v_pk_mul_f32 v[110:111], v[98:99], s[64:65]
	v_pk_add_f32 v[86:87], v[78:79], v[70:71]
	v_pk_add_f32 v[70:71], v[78:79], v[70:71] neg_lo:[0,1] neg_hi:[0,1]
	v_pk_mul_f32 v[78:79], v[54:55], s[62:63]
	v_pk_fma_f32 v[98:99], v[98:99], s[16:17], v[110:111] op_sel:[0,0,1] op_sel_hi:[1,0,0]
	v_pk_fma_f32 v[54:55], v[54:55], s[0:1], v[78:79] op_sel:[0,0,1] op_sel_hi:[1,0,0] neg_lo:[1,0,0] neg_hi:[1,0,0]
	v_pk_add_f32 v[110:111], v[100:101], v[98:99]
	v_pk_add_f32 v[98:99], v[100:101], v[98:99] neg_lo:[0,1] neg_hi:[0,1]
	v_pk_mul_f32 v[100:101], v[86:87], s[62:63]
	v_pk_add_f32 v[78:79], v[46:47], v[54:55]
	v_pk_fma_f32 v[86:87], v[86:87], s[0:1], v[100:101] op_sel:[0,0,1] op_sel_hi:[1,0,0]
	v_pk_add_f32 v[46:47], v[46:47], v[54:55] neg_lo:[0,1] neg_hi:[0,1]
	v_pk_add_f32 v[100:101], v[82:83], v[86:87]
	v_pk_add_f32 v[82:83], v[82:83], v[86:87] neg_lo:[0,1] neg_hi:[0,1]
	v_pk_mul_f32 v[86:87], v[78:79], s[16:17]
	v_pk_add_f32 v[80:81], v[80:81], v[84:85] neg_lo:[0,1] neg_hi:[0,1]
	v_pk_fma_f32 v[78:79], v[78:79], s[66:67], v[86:87] op_sel:[0,0,1] op_sel_hi:[1,0,0]
	v_pk_mul_f32 v[84:85], v[76:77], s[16:17]
	v_pk_add_f32 v[86:87], v[74:75], v[78:79]
	v_pk_add_f32 v[74:75], v[74:75], v[78:79] neg_lo:[0,1] neg_hi:[0,1]
	v_xor_b32_e32 v78, 0x80000000, v91
	v_mov_b32_e32 v79, v90
	v_pk_add_f32 v[90:91], v[92:93], v[78:79]
	v_pk_add_f32 v[78:79], v[92:93], v[78:79] neg_lo:[0,1] neg_hi:[0,1]
	v_pk_mul_f32 v[92:93], v[62:63], s[16:17]
	v_pk_fma_f32 v[76:77], v[76:77], s[66:67], v[84:85] op_sel:[0,0,1] op_sel_hi:[1,0,0]
	v_pk_fma_f32 v[62:63], v[62:63], s[66:67], v[92:93] op_sel:[0,0,1] op_sel_hi:[1,0,0] neg_lo:[1,0,0] neg_hi:[1,0,0]
	v_pk_add_f32 v[84:85], v[104:105], v[76:77]
	v_pk_add_f32 v[92:93], v[58:59], v[62:63]
	v_pk_add_f32 v[58:59], v[58:59], v[62:63] neg_lo:[0,1] neg_hi:[0,1]
	v_pk_mul_f32 v[62:63], v[70:71], s[62:63]
	v_pk_add_f32 v[76:77], v[104:105], v[76:77] neg_lo:[0,1] neg_hi:[0,1]
	v_pk_fma_f32 v[62:63], s[0:1], v[70:71], v[62:63] op_sel:[0,0,1] op_sel_hi:[0,1,0] neg_lo:[0,1,0] neg_hi:[0,1,0]
	v_pk_add_f32 v[70:71], v[66:67], v[62:63]
	v_pk_add_f32 v[62:63], v[66:67], v[62:63] neg_lo:[0,1] neg_hi:[0,1]
	v_pk_mul_f32 v[66:67], v[46:47], s[64:65]
	s_nop 0
	v_pk_fma_f32 v[46:47], v[46:47], s[16:17], v[66:67] op_sel:[0,0,1] op_sel_hi:[1,0,0] neg_lo:[1,0,0] neg_hi:[1,0,0]
	s_mov_b32 s73, s26
	v_pk_add_f32 v[66:67], v[42:43], v[46:47]
	v_pk_add_f32 v[42:43], v[42:43], v[46:47] neg_lo:[0,1] neg_hi:[0,1]
	v_pk_mul_f32 v[46:47], v[110:111], s[68:69]
	v_pk_add_f32 v[88:89], v[102:103], v[246:247] op_sel:[0,1] op_sel_hi:[1,0] neg_lo:[0,1]
	v_pk_fma_f32 v[46:47], v[110:111], s[8:9], v[46:47] op_sel:[0,0,1] op_sel_hi:[1,0,0]
	v_pk_add_f32 v[102:103], v[102:103], v[246:247] op_sel:[0,1] op_sel_hi:[1,0] neg_hi:[0,1]
	v_pk_add_f32 v[46:47], v[108:109], v[46:47]
	v_pk_mul_f32 v[108:109], v[100:101], s[64:65]
	v_pk_mul_f32 v[104:105], v[60:61], s[16:17]
	v_pk_fma_f32 v[100:101], v[100:101], s[16:17], v[108:109] op_sel:[0,0,1] op_sel_hi:[1,0,0]
	v_pk_fma_f32 v[60:61], v[60:61], s[66:67], v[104:105] op_sel:[0,0,1] op_sel_hi:[1,0,0] neg_lo:[1,0,0] neg_hi:[1,0,0]
	v_pk_add_f32 v[100:101], v[106:107], v[100:101]
	v_pk_mul_f32 v[106:107], v[86:87], s[72:73]
	v_pk_add_f32 v[104:105], v[56:57], v[60:61]
	v_pk_fma_f32 v[86:87], v[86:87], s[24:25], v[106:107] op_sel:[0,0,1] op_sel_hi:[1,0,0]
	v_pk_add_f32 v[56:57], v[56:57], v[60:61] neg_lo:[0,1] neg_hi:[0,1]
	v_pk_mul_f32 v[60:61], v[68:69], s[62:63]
	v_pk_add_f32 v[84:85], v[84:85], v[86:87]
	v_pk_mul_f32 v[86:87], v[90:91], s[62:63]
	v_pk_fma_f32 v[60:61], v[68:69], s[0:1], v[60:61] op_sel:[0,0,1] op_sel_hi:[1,0,0] neg_lo:[1,0,0] neg_hi:[1,0,0]
	v_pk_fma_f32 v[86:87], v[90:91], s[0:1], v[86:87] op_sel:[0,0,1] op_sel_hi:[1,0,0]
	v_pk_mul_f32 v[90:91], v[70:71], s[16:17]
	v_pk_add_f32 v[68:69], v[64:65], v[60:61]
	v_pk_fma_f32 v[70:71], v[70:71], s[66:67], v[90:91] op_sel:[0,0,1] op_sel_hi:[1,0,0]
	s_mov_b32 s9, s42
	s_mov_b32 s25, s38
	v_pk_add_f32 v[68:69], v[68:69], v[70:71]
	s_mov_b32 s76, s11
	v_pk_mul_f32 v[70:71], v[66:67], s[8:9]
	s_mov_b32 s74, s27
	v_pk_fma_f32 v[66:67], v[66:67], s[76:77], v[70:71] op_sel:[0,0,1] op_sel_hi:[1,0,0]
	v_pk_mul_f32 v[70:71], v[74:75], s[24:25]
	v_pk_add_f32 v[60:61], v[64:65], v[60:61] neg_lo:[0,1] neg_hi:[0,1]
	v_pk_fma_f32 v[70:71], v[74:75], s[74:75], v[70:71] op_sel:[0,0,1] op_sel_hi:[1,0,0] neg_lo:[1,0,0] neg_hi:[1,0,0]
	v_pk_mul_f32 v[64:65], v[44:45], s[64:65]
	v_pk_add_f32 v[70:71], v[76:77], v[70:71]
	v_pk_mul_f32 v[76:77], v[58:59], s[72:73]
	v_pk_fma_f32 v[44:45], v[44:45], s[16:17], v[64:65] op_sel:[0,0,1] op_sel_hi:[1,0,0] neg_lo:[1,0,0] neg_hi:[1,0,0]
	v_pk_fma_f32 v[58:59], v[58:59], s[24:25], v[76:77] op_sel:[0,0,1] op_sel_hi:[1,0,0] neg_lo:[1,0,0] neg_hi:[1,0,0]
	v_pk_add_f32 v[64:65], v[48:49], v[44:45]
	v_pk_add_f32 v[56:57], v[56:57], v[58:59]
	v_pk_mul_f32 v[58:59], v[62:63], s[64:65]
	v_pk_add_f32 v[44:45], v[48:49], v[44:45] neg_lo:[0,1] neg_hi:[0,1]
	v_pk_fma_f32 v[58:59], s[16:17], v[62:63], v[58:59] op_sel:[0,0,1] op_sel_hi:[0,1,0] neg_lo:[0,1,0] neg_hi:[0,1,0]
	v_pk_add_f32 v[58:59], v[60:61], v[58:59]
	v_pk_mul_f32 v[60:61], v[42:43], s[68:69]
	v_pk_add_f32 v[54:55], v[94:95], v[72:73] neg_lo:[0,1] neg_hi:[0,1]
	v_pk_add_f32 v[64:65], v[64:65], v[66:67]
	v_pk_add_f32 v[66:67], v[52:53], v[50:51] neg_lo:[0,1] neg_hi:[0,1]
	v_pk_fma_f32 v[42:43], v[42:43], s[8:9], v[60:61] op_sel:[0,0,1] op_sel_hi:[1,0,0] neg_lo:[1,0,0] neg_hi:[1,0,0]
	v_pk_add_f32 v[86:87], v[88:89], v[86:87]
	v_pk_mul_f32 v[88:89], v[92:93], s[24:25]
	v_pk_add_f32 v[48:49], v[54:55], v[66:67] op_sel:[0,1] op_sel_hi:[1,0] neg_lo:[0,1]
	v_pk_mul_f32 v[54:55], v[98:99], s[8:9]
	v_pk_mul_f32 v[66:67], v[82:83], s[16:17]
	v_pk_mul_f32 v[74:75], v[78:79], s[62:63]
	v_pk_add_f32 v[42:43], v[44:45], v[42:43]
	v_pk_add_f32 v[44:45], v[94:95], v[72:73]
	v_pk_add_f32 v[50:51], v[52:53], v[50:51]
	v_pk_fma_f32 v[88:89], v[92:93], s[74:75], v[88:89] op_sel:[0,0,1] op_sel_hi:[1,0,0]
	v_pk_fma_f32 v[54:55], v[98:99], s[76:77], v[54:55] op_sel:[0,0,1] op_sel_hi:[1,0,0] neg_lo:[1,0,0] neg_hi:[1,0,0]
	v_pk_fma_f32 v[66:67], v[82:83], s[66:67], v[66:67] op_sel:[0,0,1] op_sel_hi:[1,0,0] neg_lo:[1,0,0] neg_hi:[1,0,0]
	v_pk_fma_f32 v[74:75], v[78:79], s[0:1], v[74:75] op_sel:[0,0,1] op_sel_hi:[1,0,0] neg_lo:[1,0,0] neg_hi:[1,0,0]
	v_pk_add_f32 v[44:45], v[44:45], v[50:51]
	v_lshl_add_u32 v21, v21, 3, v36
	v_pk_add_f32 v[88:89], v[104:105], v[88:89]
	v_pk_add_f32 v[54:55], v[96:97], v[54:55]
	v_pk_add_f32 v[66:67], v[80:81], v[66:67]
	v_pk_add_f32 v[74:75], v[102:103], v[74:75]
	ds_write_b64 v25, v[44:45]
	ds_write_b64 v25, v[46:47] offset:2112
	ds_write_b64 v25, v[100:101] offset:4224
	ds_write_b64 v25, v[84:85] offset:6336
	ds_write_b64 v25, v[86:87] offset:8448
	ds_write_b64 v25, v[88:89] offset:10560
	ds_write_b64 v25, v[68:69] offset:12672
	ds_write_b64 v25, v[64:65] offset:14784
	ds_write_b64 v25, v[48:49] offset:16896
	ds_write_b64 v25, v[54:55] offset:19008
	ds_write_b64 v25, v[66:67] offset:21120
	ds_write_b64 v25, v[70:71] offset:23232
	ds_write_b64 v25, v[74:75] offset:25344
	ds_write_b64 v25, v[56:57] offset:27456
	ds_write_b64 v25, v[58:59] offset:29568
	ds_write_b64 v25, v[42:43] offset:31680
	v_ashrrev_i32_e32 v25, 5, v21
	v_lshlrev_b32_e32 v21, 3, v21
	v_lshlrev_b32_e32 v25, 3, v25
	s_waitcnt vmcnt(0)
	v_lshlrev_b32_e32 v41, 16, v41
	v_lshlrev_b32_e32 v39, 16, v39
	v_lshlrev_b32_e32 v35, 16, v35
	v_lshlrev_b32_e32 v29, 16, v29
	v_and_b32_e32 v48, 0xffff0000, v14
	v_add3_u32 v21, 0, v21, v25
	v_mov_b32_e32 v40, v48
	s_waitcnt lgkmcnt(0)
	s_barrier
	v_pk_mul_f32 v[44:45], v[30:31], v[40:41]
	ds_read2_b64 v[40:43], v21 offset1:1
	v_lshlrev_b32_e32 v28, 16, v14
	v_lshlrev_b32_e32 v49, 16, v15
	v_pk_fma_f32 v[44:45], v[30:31], v[28:29], v[44:45] op_sel:[0,0,1] op_sel_hi:[1,0,0]
	v_mov_b32_e32 v28, v31
	v_pk_fma_f32 v[44:45], v[20:21], v[48:49], v[44:45] op_sel_hi:[0,1,1]
	v_pk_add_f32 v[50:51], v[24:25], v[44:45] op_sel_hi:[0,1]
	ds_read2_b64 v[44:47], v21 offset0:2 offset1:3
	s_waitcnt lgkmcnt(1)
	v_pk_mul_f32 v[40:41], v[50:51], v[40:41]
	v_and_b32_e32 v51, 16, v16
	v_and_b32_e32 v50, 0xffff0000, v15
	v_pk_mov_b32 v[14:15], v[48:49], v[50:51] op_sel:[1,0]
	v_lshlrev_b32_e32 v53, 16, v16
	v_pk_mul_f32 v[14:15], v[30:31], v[14:15] op_sel_hi:[0,1]
	v_mov_b32_e32 v52, v50
	v_pk_fma_f32 v[14:15], v[28:29], v[48:49], v[14:15] op_sel_hi:[0,1,1]
	v_pk_fma_f32 v[14:15], v[20:21], v[52:53], v[14:15] op_sel_hi:[0,1,1]
	v_pk_add_f32 v[14:15], v[24:25], v[14:15] op_sel_hi:[0,1]
	v_pk_mul_f32 v[14:15], v[14:15], v[42:43]
	v_and_b32_e32 v43, 16, v17
	v_and_b32_e32 v42, 0xffff0000, v16
	v_lshlrev_b32_e32 v49, 16, v17
	v_mov_b32_e32 v48, v42
	v_pk_mov_b32 v[42:43], v[52:53], v[42:43] op_sel:[1,0]
	v_pk_mov_b32 v[16:17], v[16:17], v[10:11] op_sel:[1,0]
	v_pk_mul_f32 v[42:43], v[30:31], v[42:43] op_sel_hi:[0,1]
	v_and_b32_e32 v17, 16, v17
	v_and_b32_e32 v16, 0xffff0000, v16
	v_pk_fma_f32 v[42:43], v[28:29], v[52:53], v[42:43] op_sel_hi:[0,1,1]
	v_mov_b32_e32 v50, v16
	v_pk_mov_b32 v[16:17], v[48:49], v[16:17] op_sel:[1,0]
	v_pk_fma_f32 v[42:43], v[20:21], v[48:49], v[42:43] op_sel_hi:[0,1,1]
	v_pk_mul_f32 v[16:17], v[30:31], v[16:17] op_sel_hi:[0,1]
	v_pk_add_f32 v[42:43], v[24:25], v[42:43] op_sel_hi:[0,1]
	v_lshlrev_b32_e32 v51, 16, v10
	v_pk_fma_f32 v[16:17], v[28:29], v[48:49], v[16:17] op_sel_hi:[0,1,1]
	s_waitcnt lgkmcnt(0)
	v_pk_mul_f32 v[42:43], v[42:43], v[44:45]
	v_pk_fma_f32 v[16:17], v[20:21], v[50:51], v[16:17] op_sel_hi:[0,1,1]
	v_and_b32_e32 v45, 16, v11
	v_and_b32_e32 v44, 0xffff0000, v10
	v_pk_add_f32 v[16:17], v[24:25], v[16:17] op_sel_hi:[0,1]
	v_mov_b32_e32 v52, v44
	v_pk_mov_b32 v[44:45], v[50:51], v[44:45] op_sel:[1,0]
	v_pk_mul_f32 v[16:17], v[16:17], v[46:47]
	v_pk_mul_f32 v[48:49], v[30:31], v[44:45] op_sel_hi:[0,1]
	ds_read2_b64 v[44:47], v21 offset0:4 offset1:5
	v_lshlrev_b32_e32 v53, 16, v11
	v_pk_fma_f32 v[48:49], v[28:29], v[50:51], v[48:49] op_sel_hi:[0,1,1]
	v_pk_fma_f32 v[48:49], v[20:21], v[52:53], v[48:49] op_sel_hi:[0,1,1]
	v_pk_add_f32 v[54:55], v[24:25], v[48:49] op_sel_hi:[0,1]
	ds_read2_b64 v[48:51], v21 offset0:6 offset1:7
	s_waitcnt lgkmcnt(1)
	v_pk_mul_f32 v[44:45], v[54:55], v[44:45]
	v_and_b32_e32 v55, 16, v12
	v_and_b32_e32 v54, 0xffff0000, v11
	v_pk_mov_b32 v[10:11], v[52:53], v[54:55] op_sel:[1,0]
	v_lshlrev_b32_e32 v57, 16, v12
	v_pk_mul_f32 v[10:11], v[30:31], v[10:11] op_sel_hi:[0,1]
	v_mov_b32_e32 v56, v54
	v_pk_fma_f32 v[10:11], v[28:29], v[52:53], v[10:11] op_sel_hi:[0,1,1]
	v_pk_fma_f32 v[10:11], v[20:21], v[56:57], v[10:11] op_sel_hi:[0,1,1]
	v_pk_add_f32 v[10:11], v[24:25], v[10:11] op_sel_hi:[0,1]
	v_and_b32_e32 v38, 0xffff0000, v13
	v_pk_mul_f32 v[10:11], v[10:11], v[46:47]
	v_and_b32_e32 v47, 16, v13
	v_and_b32_e32 v46, 0xffff0000, v12
	v_lshlrev_b32_e32 v53, 16, v13
	v_mov_b32_e32 v52, v46
	v_pk_mov_b32 v[12:13], v[56:57], v[46:47] op_sel:[1,0]
	v_mov_b32_e32 v46, v53
	v_mov_b32_e32 v47, v38
	v_pk_mul_f32 v[12:13], v[30:31], v[12:13] op_sel_hi:[0,1]
	v_pk_mul_f32 v[46:47], v[30:31], v[46:47] op_sel_hi:[0,1]
	v_pk_fma_f32 v[12:13], v[28:29], v[56:57], v[12:13] op_sel_hi:[0,1,1]
	v_pk_fma_f32 v[46:47], v[28:29], v[52:53], v[46:47] op_sel_hi:[0,1,1]
	v_pk_fma_f32 v[12:13], v[20:21], v[52:53], v[12:13] op_sel_hi:[0,1,1]
	v_pk_fma_f32 v[38:39], v[20:21], v[38:39], v[46:47] op_sel_hi:[0,1,1]
	s_xor_b64 s[50:51], s[50:51], -1
	v_pk_add_f32 v[12:13], v[24:25], v[12:13] op_sel_hi:[0,1]
	v_pk_add_f32 v[38:39], v[24:25], v[38:39] op_sel_hi:[0,1]
	s_waitcnt lgkmcnt(0)
	v_pk_mul_f32 v[12:13], v[12:13], v[48:49]
	v_pk_mul_f32 v[38:39], v[38:39], v[50:51]
	s_mov_b64 s[0:1], -1
	s_and_b64 vcc, exec, s[50:51]
	s_cbranch_vccz .LBB0_548
	v_bfe_u32 v46, v15, 16, 1
	v_add3_u32 v47, v15, v46, s4
	v_bfe_u32 v46, v14, 16, 1
	v_bfe_u32 v48, v16, 16, 1
	v_bfe_u32 v50, v42, 16, 1
	v_bfe_u32 v34, v17, 16, 1
	v_bfe_u32 v49, v40, 16, 1
	v_add3_u32 v50, v42, v50, s4
	v_add3_u32 v48, v16, v48, s4
	v_add3_u32 v46, v14, v46, s4
	v_bfe_u32 v25, v43, 16, 1
	v_bfe_u32 v28, v41, 16, 1
	v_add3_u32 v34, v17, v34, s4
	v_add3_u32 v49, v40, v49, s4
	v_lshrrev_b32_e32 v51, 16, v46
	v_lshrrev_b32_e32 v52, 16, v48
	v_lshrrev_b32_e32 v48, 16, v50
	v_bfe_u32 v50, v11, 16, 1
	v_add3_u32 v28, v41, v28, s4
	v_add3_u32 v25, v43, v25, s4
	v_lshrrev_b32_e32 v46, 16, v49
	v_and_or_b32 v49, v34, s91, v52
	v_and_or_b32 v47, v47, s91, v51
	v_add3_u32 v51, v11, v50, s4
	v_bfe_u32 v50, v10, 16, 1
	v_bfe_u32 v52, v38, 16, 1
	v_bfe_u32 v53, v44, 16, 1
	v_bfe_u32 v54, v12, 16, 1
	v_lshl_add_u64 v[36:37], v[36:37], 1, s[70:71]
	v_and_or_b32 v48, v25, s91, v48
	v_and_or_b32 v46, v28, s91, v46
	v_bfe_u32 v25, v13, 16, 1
	v_bfe_u32 v28, v45, 16, 1
	v_bfe_u32 v34, v39, 16, 1
	v_add3_u32 v54, v12, v54, s4
	v_add3_u32 v53, v44, v53, s4
	v_add3_u32 v52, v38, v52, s4
	v_add3_u32 v50, v10, v50, s4
	v_add3_u32 v34, v39, v34, s4
	v_add3_u32 v28, v45, v28, s4
	v_add3_u32 v25, v13, v25, s4
	v_lshrrev_b32_e32 v55, 16, v50
	v_lshrrev_b32_e32 v56, 16, v52
	v_lshrrev_b32_e32 v50, 16, v53
	v_lshrrev_b32_e32 v52, 16, v54
	v_lshl_add_u64 v[32:33], v[32:33], 1, v[36:37]
	v_and_or_b32 v52, v25, s91, v52
	v_and_or_b32 v50, v28, s91, v50
	v_and_or_b32 v53, v34, s91, v56
	v_and_or_b32 v51, v51, s91, v55
	global_store_dwordx4 v[32:33], v[46:49], off
	global_store_dwordx4 v[32:33], v[50:53], off offset:16
	s_mov_b64 s[0:1], 0
